# speedup vs baseline: 1.0023x; 1.0023x over previous
; #define STAGE(P,BASE,LD,br,kt) do{long _g=(long)(br)*(LD)+(long)(kt)*BK; \
;     _Pragma("unroll") for(int _i=0;_i<2;++_i){int _b=tid*16+_i*8192;int _r,_c;stage_rc(_b,_r,_c); \
;       __builtin_amdgcn_global_load_lds((const unsigned*)((BASE)+_g+(long)_r*(LD)+_c), \
;         (unsigned*)((char*)(P)+_b),16,0,0);}}while(0)
; #define STAGE(P,BASE,LD,br,kt) do{long _g=(long)(br)*(LD)+(long)(kt)*BK; \
;     _Pragma("unroll") for(int _i=0;_i<2;++_i){int _b=tid*16+_i*8192;int _r,_c;stage_rc(_b,_r,_c); \
;       __builtin_amdgcn_global_load_lds((const unsigned*)((BASE)+_g+(long)_r*(LD)+_c), \
;         (unsigned*)((char*)(P)+_b),16,0,0);}}while(0)
; #define LDA(dst,b,h) _Pragma("unroll") for(int m=0;m<4;++m) _Pragma("unroll") for(int k=0;k<2;++k) \
;     dst[m][k]=*reinterpret_cast<const bf16x8*>((char*)SA(b,h)+lds_byte(wr*64+m*16+fr,k*32+fq*8))
; #define LDB(dst,b,h) _Pragma("unroll") for(int n=0;n<2;++n) _Pragma("unroll") for(int k=0;k<2;++k) \
;     dst[n][k]=*reinterpret_cast<const bf16x8*>((char*)SB(b,h)+lds_byte(wc*32+n*16+fr,k*32+fq*8))
; #define MMA(ai,bj,At_,Bt_) do{__builtin_amdgcn_s_setprio(1); \
;     _Pragma("unroll") for(int m=0;m<4;++m) _Pragma("unroll") for(int n=0;n<2;++n) _Pragma("unroll") for(int k=0;k<2;++k) \
;       acc[ai][bj][m][n]=__builtin_amdgcn_mfma_f32_16x16x32_bf16(Bt_[n][k],At_[m][k],acc[ai][bj][m][n],0,0,0); \
;     __builtin_amdgcn_s_setprio(0);}while(0)
; #define WAIT_L(n) asm volatile("s_waitcnt lgkmcnt(" #n ")":::"memory")
; #define BAR __builtin_amdgcn_s_barrier()
; #define SCHED __builtin_amdgcn_sched_barrier(0)
; DEVINL void gemm8_mainloop(const u16* A, long lda, const u16* Bt, long ldb, int K, int brow, int bcol, f32x4 (&acc)[2][2][4][2], char* smem, int tid) {
;     ...
;   for(int t=0;t<nt-2;t+=2){
;     LDB(B0,0,0); SCHED; LDA(At,0,0); STAGE(SA(1,1),A,lda,brow+HALF,t+1);
;     WAIT_L(8); BAR; WAIT_L(0); MMA(0,0,At,B0); BAR; SCHED;
;     LDB(B1,0,1); STAGE(SB(0,0),Bt,ldb,bcol,t+2);
;     BAR; WAIT_L(0); MMA(0,1,At,B1); BAR;
;     LDA(At,0,1); STAGE(SA(0,0),A,lda,brow,t+2);
;     BAR; WAIT_L(0); MMA(1,0,At,B0); BAR; SCHED;
.LBB0_269:
	s_barrier
	ds_read_b128 v[170:173], v161
	ds_read_b128 v[180:183], v161 offset:1024
	ds_read_b128 v[184:187], v161 offset:2048
	ds_read_b128 v[188:191], v161 offset:3072
	v_add_u32_e32 v178, 0xc000, v128
	v_lshl_add_u64 v[244:245], s[94:95], 0, v[148:149]
	v_readfirstlane_b32 s3, v178
	v_add_u32_e32 v179, 0xe000, v128
	v_add_u32_e32 v174, s41, v160
	v_add_u32_e32 v175, s45, v160
	v_add_u32_e32 v177, s47, v160
	v_lshl_add_u64 v[162:163], v[244:245], 0, s[12:13]
	s_mov_b32 m0, s3
	v_lshl_add_u64 v[246:247], s[94:95], 0, v[150:151]
	v_readfirstlane_b32 s3, v179
	ds_read_b128 v[192:195], v131
	ds_read_b128 v[196:199], v131 offset:1024
	ds_read_b128 v[200:203], v174
	ds_read_b128 v[204:207], v174 offset:1024
	ds_read_b128 v[208:211], v175
	ds_read_b128 v[212:215], v175 offset:1024
	ds_read_b128 v[216:219], v177
	ds_read_b128 v[220:223], v177 offset:1024
	global_load_lds_dwordx4 v[162:163], off
	v_lshl_add_u64 v[162:163], v[246:247], 0, s[12:13]
	s_mov_b32 m0, s3
	s_nop 0
	global_load_lds_dwordx4 v[162:163], off
	s_waitcnt lgkmcnt(8)
	s_barrier
	s_waitcnt lgkmcnt(0)
	s_setprio 1
	v_mfma_f32_16x16x32_bf16 v[124:127], v[170:173], v[192:195], v[124:127]
	v_mfma_f32_16x16x32_bf16 v[120:123], v[184:187], v[192:195], v[120:123]
	v_mfma_f32_16x16x32_bf16 v[116:119], v[170:173], v[200:203], v[116:119]
	v_mfma_f32_16x16x32_bf16 v[112:115], v[184:187], v[200:203], v[112:115]
	v_mfma_f32_16x16x32_bf16 v[108:111], v[170:173], v[208:211], v[108:111]
	v_mfma_f32_16x16x32_bf16 v[104:107], v[184:187], v[208:211], v[104:107]
	v_mfma_f32_16x16x32_bf16 v[100:103], v[170:173], v[216:219], v[100:103]
	v_mfma_f32_16x16x32_bf16 v[96:99], v[184:187], v[216:219], v[96:99]
	v_mfma_f32_16x16x32_bf16 v[124:127], v[180:183], v[196:199], v[124:127]
	v_mfma_f32_16x16x32_bf16 v[120:123], v[188:191], v[196:199], v[120:123]
	v_mfma_f32_16x16x32_bf16 v[116:119], v[180:183], v[204:207], v[116:119]
	v_mfma_f32_16x16x32_bf16 v[112:115], v[188:191], v[204:207], v[112:115]
	v_mfma_f32_16x16x32_bf16 v[108:111], v[180:183], v[212:215], v[108:111]
	v_mfma_f32_16x16x32_bf16 v[104:107], v[188:191], v[212:215], v[104:107]
	v_mfma_f32_16x16x32_bf16 v[100:103], v[180:183], v[220:223], v[100:103]
	v_mfma_f32_16x16x32_bf16 v[96:99], v[188:191], v[220:223], v[96:99]
	s_setprio 0
	s_barrier
	v_add_u32_e32 v162, s31, v153
	v_lshl_add_u64 v[248:249], s[94:95], 0, v[144:145]
	v_readfirstlane_b32 s3, v162
	v_add_u32_e32 v163, 0x2000, v162
	v_lshl_add_u64 v[240:241], v[248:249], 0, s[14:15]
	s_mov_b32 m0, s3
	v_lshl_add_u64 v[250:251], s[94:95], 0, v[146:147]
	v_readfirstlane_b32 s3, v163
	ds_read_b128 v[224:227], v158
	ds_read_b128 v[228:231], v158 offset:1024
	ds_read_b128 v[232:235], v158 offset:2048
	ds_read_b128 v[236:239], v158 offset:3072
	global_load_lds_dwordx4 v[240:241], off
	v_lshl_add_u64 v[240:241], v[250:251], 0, s[14:15]
	s_mov_b32 m0, s3
	s_nop 0
	global_load_lds_dwordx4 v[240:241], off
	s_barrier
	s_waitcnt lgkmcnt(0)
	s_setprio 1
	v_mfma_f32_16x16x32_bf16 v[92:95], v[224:227], v[192:195], v[92:95]
	v_mfma_f32_16x16x32_bf16 v[88:91], v[232:235], v[192:195], v[88:91]
	v_mfma_f32_16x16x32_bf16 v[84:87], v[224:227], v[200:203], v[84:87]
	v_mfma_f32_16x16x32_bf16 v[80:83], v[232:235], v[200:203], v[80:83]
	v_mfma_f32_16x16x32_bf16 v[76:79], v[224:227], v[208:211], v[76:79]
	v_mfma_f32_16x16x32_bf16 v[72:75], v[232:235], v[208:211], v[72:75]
	v_mfma_f32_16x16x32_bf16 v[68:71], v[224:227], v[216:219], v[68:71]
	v_mfma_f32_16x16x32_bf16 v[64:67], v[232:235], v[216:219], v[64:67]
	v_mfma_f32_16x16x32_bf16 v[92:95], v[228:231], v[196:199], v[92:95]
	v_mfma_f32_16x16x32_bf16 v[88:91], v[236:239], v[196:199], v[88:91]
	v_mfma_f32_16x16x32_bf16 v[84:87], v[228:231], v[204:207], v[84:87]
	v_mfma_f32_16x16x32_bf16 v[80:83], v[236:239], v[204:207], v[80:83]
	v_mfma_f32_16x16x32_bf16 v[76:79], v[228:231], v[212:215], v[76:79]
	v_mfma_f32_16x16x32_bf16 v[72:75], v[236:239], v[212:215], v[72:75]
	v_mfma_f32_16x16x32_bf16 v[68:71], v[228:231], v[220:223], v[68:71]
	v_mfma_f32_16x16x32_bf16 v[64:67], v[236:239], v[220:223], v[64:67]
	s_setprio 0
	v_readfirstlane_b32 s3, v128
	v_add_u32_e32 v169, 0x2000, v128
	v_lshl_add_u64 v[240:241], v[244:245], 0, s[16:17]
	s_mov_b32 m0, s3
	v_readfirstlane_b32 s3, v169
	s_barrier
	ds_read_b128 v[192:195], v131 offset:16384
	ds_read_b128 v[196:199], v131 offset:17408
	ds_read_b128 v[200:203], v174 offset:16384
	ds_read_b128 v[204:207], v174 offset:17408
	ds_read_b128 v[208:211], v175 offset:16384
	ds_read_b128 v[212:215], v175 offset:17408
	ds_read_b128 v[216:219], v177 offset:16384
	ds_read_b128 v[220:223], v177 offset:17408
	global_load_lds_dwordx4 v[240:241], off
	v_lshl_add_u64 v[240:241], v[246:247], 0, s[16:17]
	s_mov_b32 m0, s3
	s_nop 0
	global_load_lds_dwordx4 v[240:241], off
	s_barrier
	s_waitcnt lgkmcnt(0)
	s_setprio 1
	v_mfma_f32_16x16x32_bf16 v[60:63], v[170:173], v[192:195], v[60:63]
	v_mfma_f32_16x16x32_bf16 v[56:59], v[184:187], v[192:195], v[56:59]
	v_mfma_f32_16x16x32_bf16 v[52:55], v[170:173], v[200:203], v[52:55]
	v_mfma_f32_16x16x32_bf16 v[48:51], v[184:187], v[200:203], v[48:51]
	v_mfma_f32_16x16x32_bf16 v[44:47], v[170:173], v[208:211], v[44:47]
	v_mfma_f32_16x16x32_bf16 v[40:43], v[184:187], v[208:211], v[40:43]
	v_mfma_f32_16x16x32_bf16 v[36:39], v[170:173], v[216:219], v[36:39]
	v_mfma_f32_16x16x32_bf16 v[32:35], v[184:187], v[216:219], v[32:35]
	v_mfma_f32_16x16x32_bf16 v[60:63], v[180:183], v[196:199], v[60:63]
	v_mfma_f32_16x16x32_bf16 v[56:59], v[188:191], v[196:199], v[56:59]
	v_mfma_f32_16x16x32_bf16 v[52:55], v[180:183], v[204:207], v[52:55]
	v_mfma_f32_16x16x32_bf16 v[48:51], v[188:191], v[204:207], v[48:51]
	v_mfma_f32_16x16x32_bf16 v[44:47], v[180:183], v[212:215], v[44:47]
	v_mfma_f32_16x16x32_bf16 v[40:43], v[188:191], v[212:215], v[40:43]
	v_mfma_f32_16x16x32_bf16 v[36:39], v[180:183], v[220:223], v[36:39]
	v_mfma_f32_16x16x32_bf16 v[32:35], v[188:191], v[220:223], v[32:35]
	s_setprio 0
	s_barrier
; #define STAGE(P,BASE,LD,br,kt) do{long _g=(long)(br)*(LD)+(long)(kt)*BK; \
;     _Pragma("unroll") for(int _i=0;_i<2;++_i){int _b=tid*16+_i*8192;int _r,_c;stage_rc(_b,_r,_c); \
;       __builtin_amdgcn_global_load_lds((const unsigned*)((BASE)+_g+(long)_r*(LD)+_c), \
;         (unsigned*)((char*)(P)+_b),16,0,0);}}while(0)
; #define STAGE(P,BASE,LD,br,kt) do{long _g=(long)(br)*(LD)+(long)(kt)*BK; \
;     _Pragma("unroll") for(int _i=0;_i<2;++_i){int _b=tid*16+_i*8192;int _r,_c;stage_rc(_b,_r,_c); \
;       __builtin_amdgcn_global_load_lds((const unsigned*)((BASE)+_g+(long)_r*(LD)+_c), \
;         (unsigned*)((char*)(P)+_b),16,0,0);}}while(0)
; #define LDA(dst,b,h) _Pragma("unroll") for(int m=0;m<4;++m) _Pragma("unroll") for(int k=0;k<2;++k) \
;     dst[m][k]=*reinterpret_cast<const bf16x8*>((char*)SA(b,h)+lds_byte(wr*64+m*16+fr,k*32+fq*8))
; #define LDB(dst,b,h) _Pragma("unroll") for(int n=0;n<2;++n) _Pragma("unroll") for(int k=0;k<2;++k) \
;     dst[n][k]=*reinterpret_cast<const bf16x8*>((char*)SB(b,h)+lds_byte(wc*32+n*16+fr,k*32+fq*8))
; #define MMA(ai,bj,At_,Bt_) do{__builtin_amdgcn_s_setprio(1); \
;     _Pragma("unroll") for(int m=0;m<4;++m) _Pragma("unroll") for(int n=0;n<2;++n) _Pragma("unroll") for(int k=0;k<2;++k) \
;       acc[ai][bj][m][n]=__builtin_amdgcn_mfma_f32_16x16x32_bf16(Bt_[n][k],At_[m][k],acc[ai][bj][m][n],0,0,0); \
;     __builtin_amdgcn_s_setprio(0);}while(0)
; #define WAIT_V(n) asm volatile("s_waitcnt vmcnt(" #n ")":::"memory")
; #define WAIT_L(n) asm volatile("s_waitcnt lgkmcnt(" #n ")":::"memory")
; #define BAR __builtin_amdgcn_s_barrier()
; #define SCHED __builtin_amdgcn_sched_barrier(0)
; DEVINL void gemm8_mainloop(const u16* A, long lda, const u16* Bt, long ldb, int K, int brow, int bcol, f32x4 (&acc)[2][2][4][2], char* smem, int tid) {
;     ...
;     STAGE(SB(0,1),Bt,ldb,bcol+HALF,t+2);
;     WAIT_V(6); BAR; MMA(1,1,At,B1); BAR;
;     LDB(B0,1,0); SCHED; LDA(At,1,0); STAGE(SA(0,1),A,lda,brow+HALF,t+2);
;     WAIT_L(8); BAR; WAIT_L(0); MMA(0,0,At,B0); BAR; SCHED;
;     LDB(B1,1,1); STAGE(SB(1,0),Bt,ldb,bcol,t+3);
;     BAR; WAIT_L(0); MMA(0,1,At,B1); BAR;
;     LDA(At,1,1); STAGE(SA(1,0),A,lda,brow,t+3);
	v_add_u32_e32 v170, s33, v153
	v_add_u32_e32 v171, 0x2000, v170
	v_readfirstlane_b32 s3, v170
	v_lshl_add_u64 v[172:173], v[248:249], 0, s[18:19]
	s_mov_b32 m0, s3
	v_readfirstlane_b32 s3, v171
	global_load_lds_dwordx4 v[172:173], off
	v_lshl_add_u64 v[172:173], v[250:251], 0, s[18:19]
	s_mov_b32 m0, s3
	s_nop 0
	global_load_lds_dwordx4 v[172:173], off
	s_waitcnt vmcnt(6)
	s_barrier
	s_setprio 1
	v_mfma_f32_16x16x32_bf16 v[28:31], v[224:227], v[192:195], v[28:31]
	v_mfma_f32_16x16x32_bf16 v[24:27], v[232:235], v[192:195], v[24:27]
	v_mfma_f32_16x16x32_bf16 v[20:23], v[224:227], v[200:203], v[20:23]
	v_mfma_f32_16x16x32_bf16 v[16:19], v[232:235], v[200:203], v[16:19]
	v_mfma_f32_16x16x32_bf16 v[12:15], v[224:227], v[208:211], v[12:15]
	v_mfma_f32_16x16x32_bf16 v[8:11], v[232:235], v[208:211], v[8:11]
	v_mfma_f32_16x16x32_bf16 v[4:7], v[224:227], v[216:219], v[4:7]
	v_mfma_f32_16x16x32_bf16 v[0:3], v[232:235], v[216:219], v[0:3]
	v_mfma_f32_16x16x32_bf16 v[28:31], v[228:231], v[196:199], v[28:31]
	v_mfma_f32_16x16x32_bf16 v[24:27], v[236:239], v[196:199], v[24:27]
	v_mfma_f32_16x16x32_bf16 v[20:23], v[228:231], v[204:207], v[20:23]
	v_mfma_f32_16x16x32_bf16 v[16:19], v[236:239], v[204:207], v[16:19]
	v_mfma_f32_16x16x32_bf16 v[12:15], v[228:231], v[212:215], v[12:15]
	v_mfma_f32_16x16x32_bf16 v[8:11], v[236:239], v[212:215], v[8:11]
	v_mfma_f32_16x16x32_bf16 v[4:7], v[228:231], v[220:223], v[4:7]
	v_mfma_f32_16x16x32_bf16 v[0:3], v[236:239], v[220:223], v[0:3]
	s_setprio 0
	s_barrier
	ds_read_b128 v[180:183], v154
	ds_read_b128 v[184:187], v154 offset:1024
	ds_read_b128 v[188:191], v154 offset:2048
	ds_read_b128 v[192:195], v154 offset:3072
	v_add_u32_e32 v172, 0x4000, v128
	v_add_u32_e32 v173, 0x6000, v128
	v_readfirstlane_b32 s3, v172
	v_lshl_add_u64 v[228:229], v[244:245], 0, s[20:21]
	s_mov_b32 m0, s3
	v_readfirstlane_b32 s3, v173
	ds_read_b128 v[196:199], v131 offset:32768
	ds_read_b128 v[200:203], v131 offset:33792
	ds_read_b128 v[204:207], v174 offset:32768
	ds_read_b128 v[208:211], v174 offset:33792
	ds_read_b128 v[212:215], v175 offset:32768
	ds_read_b128 v[216:219], v175 offset:33792
	ds_read_b128 v[220:223], v177 offset:32768
	ds_read_b128 v[224:227], v177 offset:33792
	global_load_lds_dwordx4 v[228:229], off
	v_lshl_add_u64 v[228:229], v[246:247], 0, s[20:21]
	s_mov_b32 m0, s3
	s_nop 0
	global_load_lds_dwordx4 v[228:229], off
	s_waitcnt lgkmcnt(8)
	s_barrier
	s_waitcnt lgkmcnt(0)
	s_setprio 1
	v_mfma_f32_16x16x32_bf16 v[124:127], v[180:183], v[196:199], v[124:127]
	v_mfma_f32_16x16x32_bf16 v[120:123], v[188:191], v[196:199], v[120:123]
	v_mfma_f32_16x16x32_bf16 v[116:119], v[180:183], v[204:207], v[116:119]
	v_mfma_f32_16x16x32_bf16 v[112:115], v[188:191], v[204:207], v[112:115]
	v_mfma_f32_16x16x32_bf16 v[108:111], v[180:183], v[212:215], v[108:111]
	v_mfma_f32_16x16x32_bf16 v[104:107], v[188:191], v[212:215], v[104:107]
	v_mfma_f32_16x16x32_bf16 v[100:103], v[180:183], v[220:223], v[100:103]
	v_mfma_f32_16x16x32_bf16 v[96:99], v[188:191], v[220:223], v[96:99]
	v_mfma_f32_16x16x32_bf16 v[124:127], v[184:187], v[200:203], v[124:127]
	v_mfma_f32_16x16x32_bf16 v[120:123], v[192:195], v[200:203], v[120:123]
	v_mfma_f32_16x16x32_bf16 v[116:119], v[184:187], v[208:211], v[116:119]
	v_mfma_f32_16x16x32_bf16 v[112:115], v[192:195], v[208:211], v[112:115]
	v_mfma_f32_16x16x32_bf16 v[108:111], v[184:187], v[216:219], v[108:111]
	v_mfma_f32_16x16x32_bf16 v[104:107], v[192:195], v[216:219], v[104:107]
	v_mfma_f32_16x16x32_bf16 v[100:103], v[184:187], v[224:227], v[100:103]
	v_mfma_f32_16x16x32_bf16 v[96:99], v[192:195], v[224:227], v[96:99]
	s_setprio 0
	s_barrier
	v_readfirstlane_b32 s3, v155
	v_add_u32_e32 v165, 0x2000, v155
	v_lshl_add_u64 v[252:253], v[248:249], 0, s[22:23]
	s_mov_b32 m0, s3
	v_readfirstlane_b32 s3, v165
	ds_read_b128 v[228:231], v152
	ds_read_b128 v[232:235], v152 offset:1024
	ds_read_b128 v[236:239], v152 offset:2048
	ds_read_b128 v[240:243], v152 offset:3072
	global_load_lds_dwordx4 v[252:253], off
	v_lshl_add_u64 v[252:253], v[250:251], 0, s[22:23]
	s_mov_b32 m0, s3
	s_nop 0
	global_load_lds_dwordx4 v[252:253], off
	s_barrier
	s_waitcnt lgkmcnt(0)
	s_setprio 1
	v_mfma_f32_16x16x32_bf16 v[92:95], v[228:231], v[196:199], v[92:95]
	v_mfma_f32_16x16x32_bf16 v[88:91], v[236:239], v[196:199], v[88:91]
	v_mfma_f32_16x16x32_bf16 v[84:87], v[228:231], v[204:207], v[84:87]
	v_mfma_f32_16x16x32_bf16 v[80:83], v[236:239], v[204:207], v[80:83]
	v_mfma_f32_16x16x32_bf16 v[76:79], v[228:231], v[212:215], v[76:79]
	v_mfma_f32_16x16x32_bf16 v[72:75], v[236:239], v[212:215], v[72:75]
	v_mfma_f32_16x16x32_bf16 v[68:71], v[228:231], v[220:223], v[68:71]
	v_mfma_f32_16x16x32_bf16 v[64:67], v[236:239], v[220:223], v[64:67]
	v_mfma_f32_16x16x32_bf16 v[92:95], v[232:235], v[200:203], v[92:95]
	v_mfma_f32_16x16x32_bf16 v[88:91], v[240:243], v[200:203], v[88:91]
	v_mfma_f32_16x16x32_bf16 v[84:87], v[232:235], v[208:211], v[84:87]
	v_mfma_f32_16x16x32_bf16 v[80:83], v[240:243], v[208:211], v[80:83]
	v_mfma_f32_16x16x32_bf16 v[76:79], v[232:235], v[216:219], v[76:79]
	v_mfma_f32_16x16x32_bf16 v[72:75], v[240:243], v[216:219], v[72:75]
	v_mfma_f32_16x16x32_bf16 v[68:71], v[232:235], v[224:227], v[68:71]
	v_mfma_f32_16x16x32_bf16 v[64:67], v[240:243], v[224:227], v[64:67]
	s_setprio 0
	v_readfirstlane_b32 s3, v156
	v_lshl_add_u64 v[244:245], v[244:245], 0, s[24:25]
	s_mov_b32 m0, s3
	v_readfirstlane_b32 s3, v157
	s_barrier
; #define STAGE(P,BASE,LD,br,kt) do{long _g=(long)(br)*(LD)+(long)(kt)*BK; \
;     _Pragma("unroll") for(int _i=0;_i<2;++_i){int _b=tid*16+_i*8192;int _r,_c;stage_rc(_b,_r,_c); \
;       __builtin_amdgcn_global_load_lds((const unsigned*)((BASE)+_g+(long)_r*(LD)+_c), \
;         (unsigned*)((char*)(P)+_b),16,0,0);}}while(0)
; #define STAGE(P,BASE,LD,br,kt) do{long _g=(long)(br)*(LD)+(long)(kt)*BK; \
;     _Pragma("unroll") for(int _i=0;_i<2;++_i){int _b=tid*16+_i*8192;int _r,_c;stage_rc(_b,_r,_c); \
;       __builtin_amdgcn_global_load_lds((const unsigned*)((BASE)+_g+(long)_r*(LD)+_c), \
;         (unsigned*)((char*)(P)+_b),16,0,0);}}while(0)
; #define LDA(dst,b,h) _Pragma("unroll") for(int m=0;m<4;++m) _Pragma("unroll") for(int k=0;k<2;++k) \
;     dst[m][k]=*reinterpret_cast<const bf16x8*>((char*)SA(b,h)+lds_byte(wr*64+m*16+fr,k*32+fq*8))
; #define LDB(dst,b,h) _Pragma("unroll") for(int n=0;n<2;++n) _Pragma("unroll") for(int k=0;k<2;++k) \
;     dst[n][k]=*reinterpret_cast<const bf16x8*>((char*)SB(b,h)+lds_byte(wc*32+n*16+fr,k*32+fq*8))
; #define MMA(ai,bj,At_,Bt_) do{__builtin_amdgcn_s_setprio(1); \
;     _Pragma("unroll") for(int m=0;m<4;++m) _Pragma("unroll") for(int n=0;n<2;++n) _Pragma("unroll") for(int k=0;k<2;++k) \
;       acc[ai][bj][m][n]=__builtin_amdgcn_mfma_f32_16x16x32_bf16(Bt_[n][k],At_[m][k],acc[ai][bj][m][n],0,0,0); \
;     __builtin_amdgcn_s_setprio(0);}while(0)
; #define WAIT_V(n) asm volatile("s_waitcnt vmcnt(" #n ")":::"memory")
; #define WAIT_L(n) asm volatile("s_waitcnt lgkmcnt(" #n ")":::"memory")
; #define BAR __builtin_amdgcn_s_barrier()
; #define SCHED __builtin_amdgcn_sched_barrier(0)
; DEVINL void gemm8_mainloop(const u16* A, long lda, const u16* Bt, long ldb, int K, int brow, int bcol, f32x4 (&acc)[2][2][4][2], char* smem, int tid) {
;     ...
;     LDA(At,1,1); STAGE(SA(1,0),A,lda,brow,t+3);
;     BAR; WAIT_L(0); MMA(1,0,At,B0); BAR; SCHED;
;     STAGE(SB(1,1),Bt,ldb,bcol+HALF,t+3);
;     WAIT_V(6); BAR; MMA(1,1,At,B1); BAR;
;   }
;   { LDB(B0,0,0); LDA(At,0,0); STAGE(SA(1,1),A,lda,brow+HALF,nt-1);
;     BAR; WAIT_L(0); MMA(0,0,At,B0); BAR;
	ds_read_b128 v[196:199], v131 offset:49152
	ds_read_b128 v[200:203], v131 offset:50176
	ds_read_b128 v[204:207], v174 offset:49152
	ds_read_b128 v[208:211], v174 offset:50176
	ds_read_b128 v[212:215], v175 offset:49152
	ds_read_b128 v[216:219], v175 offset:50176
	ds_read_b128 v[220:223], v177 offset:49152
	ds_read_b128 v[224:227], v177 offset:50176
	global_load_lds_dwordx4 v[244:245], off
	v_lshl_add_u64 v[244:245], v[246:247], 0, s[24:25]
	s_mov_b32 m0, s3
	s_nop 0
	global_load_lds_dwordx4 v[244:245], off
	s_barrier
	s_waitcnt lgkmcnt(0)
	s_setprio 1
	v_mfma_f32_16x16x32_bf16 v[60:63], v[180:183], v[196:199], v[60:63]
	v_mfma_f32_16x16x32_bf16 v[56:59], v[188:191], v[196:199], v[56:59]
	v_mfma_f32_16x16x32_bf16 v[52:55], v[180:183], v[204:207], v[52:55]
	v_mfma_f32_16x16x32_bf16 v[48:51], v[188:191], v[204:207], v[48:51]
	v_mfma_f32_16x16x32_bf16 v[44:47], v[180:183], v[212:215], v[44:47]
	v_mfma_f32_16x16x32_bf16 v[40:43], v[188:191], v[212:215], v[40:43]
	v_mfma_f32_16x16x32_bf16 v[36:39], v[180:183], v[220:223], v[36:39]
	v_mfma_f32_16x16x32_bf16 v[32:35], v[188:191], v[220:223], v[32:35]
	v_mfma_f32_16x16x32_bf16 v[60:63], v[184:187], v[200:203], v[60:63]
	v_mfma_f32_16x16x32_bf16 v[56:59], v[192:195], v[200:203], v[56:59]
	v_mfma_f32_16x16x32_bf16 v[52:55], v[184:187], v[208:211], v[52:55]
	v_mfma_f32_16x16x32_bf16 v[48:51], v[192:195], v[208:211], v[48:51]
	v_mfma_f32_16x16x32_bf16 v[44:47], v[184:187], v[216:219], v[44:47]
	v_mfma_f32_16x16x32_bf16 v[40:43], v[192:195], v[216:219], v[40:43]
	v_mfma_f32_16x16x32_bf16 v[36:39], v[184:187], v[224:227], v[36:39]
	v_mfma_f32_16x16x32_bf16 v[32:35], v[192:195], v[224:227], v[32:35]
	s_setprio 0
	s_barrier
	v_readfirstlane_b32 s3, v159
	v_add_u32_e32 v165, 0x2000, v159
	v_lshl_add_u64 v[180:181], v[248:249], 0, s[26:27]
	s_mov_b32 m0, s3
	v_readfirstlane_b32 s3, v165
	global_load_lds_dwordx4 v[180:181], off
	v_lshl_add_u64 v[180:181], v[250:251], 0, s[26:27]
	s_mov_b32 m0, s3
	s_nop 0
	global_load_lds_dwordx4 v[180:181], off
	s_waitcnt vmcnt(6)
	s_barrier
	s_setprio 1
	v_mfma_f32_16x16x32_bf16 v[28:31], v[228:231], v[196:199], v[28:31]
	v_mfma_f32_16x16x32_bf16 v[24:27], v[236:239], v[196:199], v[24:27]
	v_mfma_f32_16x16x32_bf16 v[20:23], v[228:231], v[204:207], v[20:23]
	v_mfma_f32_16x16x32_bf16 v[16:19], v[236:239], v[204:207], v[16:19]
	v_mfma_f32_16x16x32_bf16 v[12:15], v[228:231], v[212:215], v[12:15]
	v_mfma_f32_16x16x32_bf16 v[8:11], v[236:239], v[212:215], v[8:11]
	v_mfma_f32_16x16x32_bf16 v[4:7], v[228:231], v[220:223], v[4:7]
	v_mfma_f32_16x16x32_bf16 v[0:3], v[236:239], v[220:223], v[0:3]
	v_mfma_f32_16x16x32_bf16 v[28:31], v[232:235], v[200:203], v[28:31]
	v_mfma_f32_16x16x32_bf16 v[24:27], v[240:243], v[200:203], v[24:27]
	v_mfma_f32_16x16x32_bf16 v[20:23], v[232:235], v[208:211], v[20:23]
	v_mfma_f32_16x16x32_bf16 v[16:19], v[240:243], v[208:211], v[16:19]
	v_mfma_f32_16x16x32_bf16 v[12:15], v[232:235], v[216:219], v[12:15]
	v_mfma_f32_16x16x32_bf16 v[8:11], v[240:243], v[216:219], v[8:11]
	v_mfma_f32_16x16x32_bf16 v[4:7], v[232:235], v[224:227], v[4:7]
	v_mfma_f32_16x16x32_bf16 v[0:3], v[240:243], v[224:227], v[0:3]
	s_setprio 0
	s_add_i32 s2, s2, 2
	v_lshl_add_u64 v[144:145], v[144:145], 0, s[14:15]
	v_lshl_add_u64 v[146:147], v[146:147], 0, s[14:15]
	v_lshl_add_u64 v[148:149], v[148:149], 0, s[14:15]
	s_cmp_lt_u32 s2, 28
	v_lshl_add_u64 v[150:151], v[150:151], 0, s[14:15]
	s_cbranch_scc1 .LBB0_269
	s_barrier
	s_or_b32 s2, s40, 0x80
	s_ashr_i32 s3, s2, 31
	s_lshl_b64 s[2:3], s[2:3], 12
	s_add_u32 s2, s90, s2
	s_addc_u32 s3, s91, s3
	v_lshl_add_u64 v[156:157], v[136:137], 1, s[2:3]
	v_lshl_add_u64 v[140:141], v[140:141], 1, v[156:157]
	v_readfirstlane_b32 s41, v178
	v_lshl_add_u64 v[140:141], v[140:141], 0, s[28:29]
	s_mov_b32 m0, s41
	ds_read_b128 v[144:147], v161
	ds_read_b128 v[148:151], v161 offset:1024
	ds_read_b128 v[180:183], v161 offset:2048
	ds_read_b128 v[184:187], v161 offset:3072
	ds_read_b128 v[188:191], v131
	ds_read_b128 v[192:195], v131 offset:1024
	ds_read_b128 v[196:199], v174
	ds_read_b128 v[200:203], v174 offset:1024
	ds_read_b128 v[204:207], v175
	ds_read_b128 v[208:211], v175 offset:1024
	ds_read_b128 v[212:215], v177
	ds_read_b128 v[216:219], v177 offset:1024
	global_load_lds_dwordx4 v[140:141], off
	v_lshl_add_u64 v[140:141], v[138:139], 1, s[2:3]
	v_lshl_add_u64 v[140:141], v[142:143], 1, v[140:141]
	v_readfirstlane_b32 s2, v179
	v_lshl_add_u64 v[140:141], v[140:141], 0, s[28:29]
	s_mov_b32 m0, s2
	s_nop 0
	global_load_lds_dwordx4 v[140:141], off
	s_barrier
	s_waitcnt lgkmcnt(0)
	s_setprio 1
	v_mfma_f32_16x16x32_bf16 v[124:127], v[144:147], v[188:191], v[124:127]
	v_mfma_f32_16x16x32_bf16 v[120:123], v[180:183], v[188:191], v[120:123]
	v_mfma_f32_16x16x32_bf16 v[108:111], v[144:147], v[204:207], v[108:111]
	v_mfma_f32_16x16x32_bf16 v[104:107], v[180:183], v[204:207], v[104:107]
	v_mfma_f32_16x16x32_bf16 v[124:127], v[148:151], v[192:195], v[124:127]
	v_mfma_f32_16x16x32_bf16 v[120:123], v[184:187], v[192:195], v[120:123]
	v_mfma_f32_16x16x32_bf16 v[116:119], v[144:147], v[196:199], v[116:119]
	v_mfma_f32_16x16x32_bf16 v[112:115], v[180:183], v[196:199], v[112:115]
	v_mfma_f32_16x16x32_bf16 v[108:111], v[148:151], v[208:211], v[108:111]
	v_mfma_f32_16x16x32_bf16 v[104:107], v[184:187], v[208:211], v[104:107]
	v_mfma_f32_16x16x32_bf16 v[100:103], v[144:147], v[212:215], v[100:103]
	v_mfma_f32_16x16x32_bf16 v[96:99], v[180:183], v[212:215], v[96:99]
	v_mfma_f32_16x16x32_bf16 v[140:143], v[148:151], v[200:203], v[116:119]
	v_mfma_f32_16x16x32_bf16 v[220:223], v[184:187], v[200:203], v[112:115]
	v_mfma_f32_16x16x32_bf16 v[224:227], v[148:151], v[216:219], v[100:103]
	v_mfma_f32_16x16x32_bf16 v[228:231], v[184:187], v[216:219], v[96:99]
	s_setprio 0
	s_barrier
; #define LDA(dst,b,h) _Pragma("unroll") for(int m=0;m<4;++m) _Pragma("unroll") for(int k=0;k<2;++k) \
;     dst[m][k]=*reinterpret_cast<const bf16x8*>((char*)SA(b,h)+lds_byte(wr*64+m*16+fr,k*32+fq*8))
; #define LDB(dst,b,h) _Pragma("unroll") for(int n=0;n<2;++n) _Pragma("unroll") for(int k=0;k<2;++k) \
;     dst[n][k]=*reinterpret_cast<const bf16x8*>((char*)SB(b,h)+lds_byte(wc*32+n*16+fr,k*32+fq*8))
; #define MMA(ai,bj,At_,Bt_) do{__builtin_amdgcn_s_setprio(1); \
;     _Pragma("unroll") for(int m=0;m<4;++m) _Pragma("unroll") for(int n=0;n<2;++n) _Pragma("unroll") for(int k=0;k<2;++k) \
;       acc[ai][bj][m][n]=__builtin_amdgcn_mfma_f32_16x16x32_bf16(Bt_[n][k],At_[m][k],acc[ai][bj][m][n],0,0,0); \
;     __builtin_amdgcn_s_setprio(0);}while(0)
; #define WAIT_V(n) asm volatile("s_waitcnt vmcnt(" #n ")":::"memory")
; #define WAIT_L(n) asm volatile("s_waitcnt lgkmcnt(" #n ")":::"memory")
; #define BAR __builtin_amdgcn_s_barrier()
; DEVINL void gemm8_mainloop(const u16* A, long lda, const u16* Bt, long ldb, int K, int brow, int bcol, f32x4 (&acc)[2][2][4][2], char* smem, int tid) {
;     ...
;     BAR; WAIT_L(0); MMA(0,0,At,B0); BAR;
;     LDB(B1,0,1); BAR; WAIT_L(0); MMA(0,1,At,B1); BAR;
;     LDA(At,0,1); WAIT_V(4); BAR; WAIT_L(0); MMA(1,0,At,B0); MMA(1,1,At,B1); BAR; }
;   { LDB(B0,1,0); LDA(At,1,0); WAIT_V(2); BAR; WAIT_L(0); MMA(0,0,At,B0); BAR;
	s_nop 1
	ds_read_b128 v[96:99], v158
	ds_read_b128 v[100:103], v158 offset:1024
	ds_read_b128 v[112:115], v158 offset:2048
	ds_read_b128 v[116:119], v158 offset:3072
	s_barrier
	s_waitcnt lgkmcnt(0)
	s_setprio 1
	v_mfma_f32_16x16x32_bf16 v[92:95], v[96:99], v[188:191], v[92:95]
	v_mfma_f32_16x16x32_bf16 v[88:91], v[112:115], v[188:191], v[88:91]
	v_mfma_f32_16x16x32_bf16 v[76:79], v[96:99], v[204:207], v[76:79]
	v_mfma_f32_16x16x32_bf16 v[72:75], v[112:115], v[204:207], v[72:75]
	v_mfma_f32_16x16x32_bf16 v[92:95], v[100:103], v[192:195], v[92:95]
	v_mfma_f32_16x16x32_bf16 v[88:91], v[116:119], v[192:195], v[88:91]
	v_mfma_f32_16x16x32_bf16 v[84:87], v[96:99], v[196:199], v[84:87]
	v_mfma_f32_16x16x32_bf16 v[80:83], v[112:115], v[196:199], v[80:83]
	v_mfma_f32_16x16x32_bf16 v[76:79], v[100:103], v[208:211], v[76:79]
	v_mfma_f32_16x16x32_bf16 v[72:75], v[116:119], v[208:211], v[72:75]
	v_mfma_f32_16x16x32_bf16 v[68:71], v[96:99], v[212:215], v[68:71]
	v_mfma_f32_16x16x32_bf16 v[64:67], v[112:115], v[212:215], v[64:67]
	v_mfma_f32_16x16x32_bf16 v[156:159], v[100:103], v[200:203], v[84:87]
	v_mfma_f32_16x16x32_bf16 v[188:191], v[116:119], v[200:203], v[80:83]
	v_mfma_f32_16x16x32_bf16 v[192:195], v[100:103], v[216:219], v[68:71]
	v_mfma_f32_16x16x32_bf16 v[196:199], v[116:119], v[216:219], v[64:67]
	s_setprio 0
	s_barrier
	s_nop 1
	ds_read_b128 v[64:67], v131 offset:16384
	ds_read_b128 v[68:71], v131 offset:17408
	ds_read_b128 v[80:83], v174 offset:16384
	ds_read_b128 v[84:87], v174 offset:17408
	ds_read_b128 v[200:203], v175 offset:16384
	ds_read_b128 v[204:207], v175 offset:17408
	ds_read_b128 v[208:211], v177 offset:16384
	ds_read_b128 v[212:215], v177 offset:17408
	s_waitcnt vmcnt(4)
	s_barrier
	s_waitcnt lgkmcnt(0)
	s_setprio 1
	v_mfma_f32_16x16x32_bf16 v[60:63], v[144:147], v[64:67], v[60:63]
	v_mfma_f32_16x16x32_bf16 v[52:55], v[144:147], v[80:83], v[52:55]
	v_mfma_f32_16x16x32_bf16 v[44:47], v[144:147], v[200:203], v[44:47]
	v_mfma_f32_16x16x32_bf16 v[40:43], v[180:183], v[200:203], v[40:43]
	v_mfma_f32_16x16x32_bf16 v[60:63], v[148:151], v[68:71], v[60:63]
	v_mfma_f32_16x16x32_bf16 v[56:59], v[180:183], v[64:67], v[56:59]
	v_mfma_f32_16x16x32_bf16 v[52:55], v[148:151], v[84:87], v[52:55]
	v_mfma_f32_16x16x32_bf16 v[48:51], v[180:183], v[80:83], v[48:51]
	v_mfma_f32_16x16x32_bf16 v[44:47], v[148:151], v[204:207], v[44:47]
	v_mfma_f32_16x16x32_bf16 v[40:43], v[184:187], v[204:207], v[40:43]
	v_mfma_f32_16x16x32_bf16 v[36:39], v[144:147], v[208:211], v[36:39]
	v_mfma_f32_16x16x32_bf16 v[32:35], v[180:183], v[208:211], v[32:35]
	v_mfma_f32_16x16x32_bf16 v[216:219], v[184:187], v[68:71], v[56:59]
	v_mfma_f32_16x16x32_bf16 v[232:235], v[184:187], v[84:87], v[48:51]
	v_mfma_f32_16x16x32_bf16 v[144:147], v[148:151], v[212:215], v[36:39]
	v_mfma_f32_16x16x32_bf16 v[148:151], v[184:187], v[212:215], v[32:35]
	s_setprio 0
	s_setprio 1
	v_mfma_f32_16x16x32_bf16 v[28:31], v[96:99], v[64:67], v[28:31]
	v_mfma_f32_16x16x32_bf16 v[20:23], v[96:99], v[80:83], v[20:23]
	v_mfma_f32_16x16x32_bf16 v[12:15], v[96:99], v[200:203], v[12:15]
	v_mfma_f32_16x16x32_bf16 v[4:7], v[96:99], v[208:211], v[4:7]
	v_mfma_f32_16x16x32_bf16 v[28:31], v[100:103], v[68:71], v[28:31]
	v_mfma_f32_16x16x32_bf16 v[24:27], v[112:115], v[64:67], v[24:27]
	v_mfma_f32_16x16x32_bf16 v[20:23], v[100:103], v[84:87], v[20:23]
	v_mfma_f32_16x16x32_bf16 v[16:19], v[112:115], v[80:83], v[16:19]
	v_mfma_f32_16x16x32_bf16 v[12:15], v[100:103], v[204:207], v[12:15]
	v_mfma_f32_16x16x32_bf16 v[8:11], v[112:115], v[200:203], v[8:11]
	v_mfma_f32_16x16x32_bf16 v[4:7], v[100:103], v[212:215], v[4:7]
	v_mfma_f32_16x16x32_bf16 v[0:3], v[112:115], v[208:211], v[0:3]
	v_mfma_f32_16x16x32_bf16 v[178:181], v[116:119], v[68:71], v[24:27]
	v_mfma_f32_16x16x32_bf16 v[182:185], v[116:119], v[84:87], v[16:19]
	v_mfma_f32_16x16x32_bf16 v[200:203], v[116:119], v[204:207], v[8:11]
	v_mfma_f32_16x16x32_bf16 v[204:207], v[116:119], v[212:215], v[0:3]
	s_setprio 0
	s_barrier
	s_nop 1
	ds_read_b128 v[0:3], v154
	ds_read_b128 v[8:11], v154 offset:1024
	ds_read_b128 v[208:211], v154 offset:2048
	ds_read_b128 v[212:215], v154 offset:3072
	ds_read_b128 v[16:19], v131 offset:32768
	ds_read_b128 v[24:27], v131 offset:33792
	ds_read_b128 v[32:35], v174 offset:32768
	ds_read_b128 v[36:39], v174 offset:33792
	ds_read_b128 v[48:51], v175 offset:32768
	ds_read_b128 v[56:59], v175 offset:33792
	ds_read_b128 v[236:239], v177 offset:32768
	ds_read_b128 v[240:243], v177 offset:33792
	s_waitcnt vmcnt(2)
	s_barrier
; #define LDA(dst,b,h) _Pragma("unroll") for(int m=0;m<4;++m) _Pragma("unroll") for(int k=0;k<2;++k) \
;     dst[m][k]=*reinterpret_cast<const bf16x8*>((char*)SA(b,h)+lds_byte(wr*64+m*16+fr,k*32+fq*8))
; #define LDB(dst,b,h) _Pragma("unroll") for(int n=0;n<2;++n) _Pragma("unroll") for(int k=0;k<2;++k) \
;     dst[n][k]=*reinterpret_cast<const bf16x8*>((char*)SB(b,h)+lds_byte(wc*32+n*16+fr,k*32+fq*8))
; #define MMA(ai,bj,At_,Bt_) do{__builtin_amdgcn_s_setprio(1); \
;     _Pragma("unroll") for(int m=0;m<4;++m) _Pragma("unroll") for(int n=0;n<2;++n) _Pragma("unroll") for(int k=0;k<2;++k) \
;       acc[ai][bj][m][n]=__builtin_amdgcn_mfma_f32_16x16x32_bf16(Bt_[n][k],At_[m][k],acc[ai][bj][m][n],0,0,0); \
;     __builtin_amdgcn_s_setprio(0);}while(0)
; #define WAIT_V(n) asm volatile("s_waitcnt vmcnt(" #n ")":::"memory")
; #define WAIT_L(n) asm volatile("s_waitcnt lgkmcnt(" #n ")":::"memory")
; #define BAR __builtin_amdgcn_s_barrier()
; DEVINL void gemm8_mainloop(const u16* A, long lda, const u16* Bt, long ldb, int K, int brow, int bcol, f32x4 (&acc)[2][2][4][2], char* smem, int tid) {
;     ...
;   { LDB(B0,1,0); LDA(At,1,0); WAIT_V(2); BAR; WAIT_L(0); MMA(0,0,At,B0); BAR;
;     LDB(B1,1,1); WAIT_V(0); BAR; WAIT_L(0); MMA(0,1,At,B1); BAR;
;     LDA(At,1,1); BAR; WAIT_L(0); MMA(1,0,At,B0); MMA(1,1,At,B1); BAR; }
;   if(wr==0)BAR;
;   __syncthreads();
	s_waitcnt lgkmcnt(0)
	s_setprio 1
	v_mfma_f32_16x16x32_bf16 v[64:67], v[0:3], v[16:19], v[124:127]
	v_mfma_f32_16x16x32_bf16 v[116:119], v[8:11], v[24:27], v[64:67]
	v_mfma_f32_16x16x32_bf16 v[64:67], v[208:211], v[16:19], v[120:123]
	v_mfma_f32_16x16x32_bf16 v[112:115], v[212:215], v[24:27], v[64:67]
	v_mfma_f32_16x16x32_bf16 v[64:67], v[0:3], v[32:35], v[140:143]
	v_mfma_f32_16x16x32_bf16 v[100:103], v[8:11], v[36:39], v[64:67]
	v_mfma_f32_16x16x32_bf16 v[64:67], v[208:211], v[32:35], v[220:223]
	v_mfma_f32_16x16x32_bf16 v[96:99], v[212:215], v[36:39], v[64:67]
	v_mfma_f32_16x16x32_bf16 v[64:67], v[0:3], v[48:51], v[108:111]
	v_mfma_f32_16x16x32_bf16 v[84:87], v[8:11], v[56:59], v[64:67]
	v_mfma_f32_16x16x32_bf16 v[64:67], v[208:211], v[48:51], v[104:107]
	v_mfma_f32_16x16x32_bf16 v[80:83], v[212:215], v[56:59], v[64:67]
	v_mfma_f32_16x16x32_bf16 v[64:67], v[0:3], v[236:239], v[224:227]
	v_mfma_f32_16x16x32_bf16 v[68:71], v[8:11], v[240:243], v[64:67]
	v_mfma_f32_16x16x32_bf16 v[64:67], v[208:211], v[236:239], v[228:231]
	v_mfma_f32_16x16x32_bf16 v[64:67], v[212:215], v[240:243], v[64:67]
	s_setprio 0
	s_barrier
	ds_read_b128 v[140:143], v152
	ds_read_b128 v[220:223], v152 offset:1024
	ds_read_b128 v[224:227], v152 offset:2048
	ds_read_b128 v[152:155], v152 offset:3072
	s_waitcnt vmcnt(0)
	s_barrier
	s_waitcnt lgkmcnt(0)
	s_setprio 1
	v_mfma_f32_16x16x32_bf16 v[92:95], v[140:143], v[16:19], v[92:95]
	v_mfma_f32_16x16x32_bf16 v[16:19], v[224:227], v[16:19], v[88:91]
	v_mfma_f32_16x16x32_bf16 v[120:123], v[152:155], v[24:27], v[16:19]
	v_mfma_f32_16x16x32_bf16 v[16:19], v[140:143], v[32:35], v[156:159]
	v_mfma_f32_16x16x32_bf16 v[104:107], v[220:223], v[36:39], v[16:19]
	v_mfma_f32_16x16x32_bf16 v[16:19], v[224:227], v[32:35], v[188:191]
	v_mfma_f32_16x16x32_bf16 v[108:111], v[152:155], v[36:39], v[16:19]
	v_mfma_f32_16x16x32_bf16 v[16:19], v[140:143], v[48:51], v[76:79]
	v_mfma_f32_16x16x32_bf16 v[124:127], v[220:223], v[24:27], v[92:95]
	v_mfma_f32_16x16x32_bf16 v[92:95], v[220:223], v[56:59], v[16:19]
	v_mfma_f32_16x16x32_bf16 v[16:19], v[224:227], v[48:51], v[72:75]
	v_mfma_f32_16x16x32_bf16 v[88:91], v[152:155], v[56:59], v[16:19]
	v_mfma_f32_16x16x32_bf16 v[16:19], v[140:143], v[236:239], v[192:195]
	v_mfma_f32_16x16x32_bf16 v[72:75], v[220:223], v[240:243], v[16:19]
	v_mfma_f32_16x16x32_bf16 v[16:19], v[224:227], v[236:239], v[196:199]
	v_mfma_f32_16x16x32_bf16 v[76:79], v[152:155], v[240:243], v[16:19]
	s_setprio 0
	s_barrier
	ds_read_b128 v[156:159], v131 offset:49152
	ds_read_b128 v[186:189], v131 offset:50176
	ds_read_b128 v[190:193], v174 offset:49152
	ds_read_b128 v[194:197], v174 offset:50176
	ds_read_b128 v[228:231], v175 offset:49152
	ds_read_b128 v[236:239], v175 offset:50176
	ds_read_b128 v[240:243], v177 offset:49152
	ds_read_b128 v[244:247], v177 offset:50176
	s_barrier
	s_waitcnt lgkmcnt(0)
	s_setprio 1
	v_mfma_f32_16x16x32_bf16 v[16:19], v[0:3], v[156:159], v[60:63]
	v_mfma_f32_16x16x32_bf16 v[56:59], v[8:11], v[186:189], v[16:19]
	v_mfma_f32_16x16x32_bf16 v[16:19], v[208:211], v[156:159], v[216:219]
	v_mfma_f32_16x16x32_bf16 v[48:51], v[212:215], v[186:189], v[16:19]
	v_mfma_f32_16x16x32_bf16 v[16:19], v[0:3], v[190:193], v[52:55]
	v_mfma_f32_16x16x32_bf16 v[36:39], v[8:11], v[194:197], v[16:19]
	v_mfma_f32_16x16x32_bf16 v[16:19], v[208:211], v[190:193], v[232:235]
	v_mfma_f32_16x16x32_bf16 v[32:35], v[212:215], v[194:197], v[16:19]
	v_mfma_f32_16x16x32_bf16 v[16:19], v[0:3], v[228:231], v[44:47]
	v_mfma_f32_16x16x32_bf16 v[0:3], v[0:3], v[240:243], v[144:147]
	v_mfma_f32_16x16x32_bf16 v[24:27], v[8:11], v[236:239], v[16:19]
	v_mfma_f32_16x16x32_bf16 v[16:19], v[208:211], v[228:231], v[40:43]
	v_mfma_f32_16x16x32_bf16 v[8:11], v[8:11], v[244:247], v[0:3]
	v_mfma_f32_16x16x32_bf16 v[0:3], v[208:211], v[240:243], v[148:151]
	v_mfma_f32_16x16x32_bf16 v[16:19], v[212:215], v[236:239], v[16:19]
	v_mfma_f32_16x16x32_bf16 v[0:3], v[212:215], v[244:247], v[0:3]
	s_setprio 0
	s_setprio 1
	v_mfma_f32_16x16x32_bf16 v[28:31], v[140:143], v[156:159], v[28:31]
	v_mfma_f32_16x16x32_bf16 v[60:63], v[220:223], v[186:189], v[28:31]
	v_mfma_f32_16x16x32_bf16 v[28:31], v[224:227], v[156:159], v[178:181]
	v_mfma_f32_16x16x32_bf16 v[20:23], v[140:143], v[190:193], v[20:23]
	v_mfma_f32_16x16x32_bf16 v[12:15], v[140:143], v[228:231], v[12:15]
	v_mfma_f32_16x16x32_bf16 v[52:55], v[152:155], v[186:189], v[28:31]
	v_mfma_f32_16x16x32_bf16 v[40:43], v[220:223], v[194:197], v[20:23]
	v_mfma_f32_16x16x32_bf16 v[20:23], v[224:227], v[190:193], v[182:185]
	v_mfma_f32_16x16x32_bf16 v[28:31], v[220:223], v[236:239], v[12:15]
	v_mfma_f32_16x16x32_bf16 v[12:15], v[224:227], v[228:231], v[200:203]
	v_mfma_f32_16x16x32_bf16 v[4:7], v[140:143], v[240:243], v[4:7]
	v_mfma_f32_16x16x32_bf16 v[44:47], v[152:155], v[194:197], v[20:23]
	v_mfma_f32_16x16x32_bf16 v[20:23], v[152:155], v[236:239], v[12:15]
	v_mfma_f32_16x16x32_bf16 v[12:15], v[220:223], v[244:247], v[4:7]
	v_mfma_f32_16x16x32_bf16 v[4:7], v[224:227], v[240:243], v[204:207]
	v_mfma_f32_16x16x32_bf16 v[4:7], v[152:155], v[244:247], v[4:7]
	s_setprio 0
	s_cmpk_gt_u32 s44, 0xff
	s_barrier
	s_cbranch_scc1 .LBB0_272
	s_barrier

; #define STAGE(P,BASE,LD,br,kt) do{long _g=(long)(br)*(LD)+(long)(kt)*BK; \
;     _Pragma("unroll") for(int _i=0;_i<2;++_i){int _b=tid*16+_i*8192;int _r,_c;stage_rc(_b,_r,_c); \
;       __builtin_amdgcn_global_load_lds((const unsigned*)((BASE)+_g+(long)_r*(LD)+_c), \
;         (unsigned*)((char*)(P)+_b),16,0,0);}}while(0)
; #define STAGE(P,BASE,LD,br,kt) do{long _g=(long)(br)*(LD)+(long)(kt)*BK; \
;     _Pragma("unroll") for(int _i=0;_i<2;++_i){int _b=tid*16+_i*8192;int _r,_c;stage_rc(_b,_r,_c); \
;       __builtin_amdgcn_global_load_lds((const unsigned*)((BASE)+_g+(long)_r*(LD)+_c), \
;         (unsigned*)((char*)(P)+_b),16,0,0);}}while(0)
; #define LDA(dst,b,h) _Pragma("unroll") for(int m=0;m<4;++m) _Pragma("unroll") for(int k=0;k<2;++k) \
;     dst[m][k]=*reinterpret_cast<const bf16x8*>((char*)SA(b,h)+lds_byte(wr*64+m*16+fr,k*32+fq*8))
; #define LDB(dst,b,h) _Pragma("unroll") for(int n=0;n<2;++n) _Pragma("unroll") for(int k=0;k<2;++k) \
;     dst[n][k]=*reinterpret_cast<const bf16x8*>((char*)SB(b,h)+lds_byte(wc*32+n*16+fr,k*32+fq*8))
; #define MMA(ai,bj,At_,Bt_) do{__builtin_amdgcn_s_setprio(1); \
;     _Pragma("unroll") for(int m=0;m<4;++m) _Pragma("unroll") for(int n=0;n<2;++n) _Pragma("unroll") for(int k=0;k<2;++k) \
;       acc[ai][bj][m][n]=__builtin_amdgcn_mfma_f32_16x16x32_bf16(Bt_[n][k],At_[m][k],acc[ai][bj][m][n],0,0,0); \
;     __builtin_amdgcn_s_setprio(0);}while(0)
; #define WAIT_L(n) asm volatile("s_waitcnt lgkmcnt(" #n ")":::"memory")
; #define BAR __builtin_amdgcn_s_barrier()
; #define SCHED __builtin_amdgcn_sched_barrier(0)
; DEVINL void gemm8_mainloop(const u16* A, long lda, const u16* Bt, long ldb, int K, int brow, int bcol, f32x4 (&acc)[2][2][4][2], char* smem, int tid) {
;     ...
;   for(int t=0;t<nt-2;t+=2){
;     LDB(B0,0,0); SCHED; LDA(At,0,0); STAGE(SA(1,1),A,lda,brow+HALF,t+1);
;     WAIT_L(8); BAR; WAIT_L(0); MMA(0,0,At,B0); BAR; SCHED;
;     LDB(B1,0,1); STAGE(SB(0,0),Bt,ldb,bcol,t+2);
;     BAR; WAIT_L(0); MMA(0,1,At,B1); BAR;
;     LDA(At,0,1); STAGE(SA(0,0),A,lda,brow,t+2);
;     BAR; WAIT_L(0); MMA(1,0,At,B0); BAR; SCHED;
.LBB0_849:
	s_barrier
	ds_read_b128 v[178:181], v163
	ds_read_b128 v[182:185], v163 offset:1024
	ds_read_b128 v[186:189], v163 offset:2048
	ds_read_b128 v[190:193], v163 offset:3072
	v_add_u32_e32 v174, 0xc000, v152
	v_lshl_add_u64 v[242:243], s[94:95], 0, v[146:147]
	v_readfirstlane_b32 s27, v174
	v_add_u32_e32 v175, 0xe000, v152
	v_add_u32_e32 v171, s0, v162
	v_add_u32_e32 v172, s1, v162
	v_add_u32_e32 v173, s29, v162
	v_lshl_add_u64 v[164:165], v[242:243], 0, s[4:5]
	s_mov_b32 m0, s27
	v_lshl_add_u64 v[244:245], s[94:95], 0, v[148:149]
	v_readfirstlane_b32 s27, v175
	ds_read_b128 v[166:169], v153
	ds_read_b128 v[194:197], v153 offset:1024
	ds_read_b128 v[198:201], v171
	ds_read_b128 v[202:205], v171 offset:1024
	ds_read_b128 v[206:209], v172
	ds_read_b128 v[210:213], v172 offset:1024
	ds_read_b128 v[214:217], v173
	ds_read_b128 v[218:221], v173 offset:1024
	global_load_lds_dwordx4 v[164:165], off
	v_lshl_add_u64 v[164:165], v[244:245], 0, s[4:5]
	s_mov_b32 m0, s27
	s_nop 0
	global_load_lds_dwordx4 v[164:165], off
	s_waitcnt lgkmcnt(8)
	s_barrier
	s_waitcnt lgkmcnt(0)
	s_setprio 1
	v_mfma_f32_16x16x32_bf16 v[124:127], v[178:181], v[166:169], v[124:127]
	v_mfma_f32_16x16x32_bf16 v[120:123], v[186:189], v[166:169], v[120:123]
	v_mfma_f32_16x16x32_bf16 v[116:119], v[178:181], v[198:201], v[116:119]
	v_mfma_f32_16x16x32_bf16 v[112:115], v[186:189], v[198:201], v[112:115]
	v_mfma_f32_16x16x32_bf16 v[108:111], v[178:181], v[206:209], v[108:111]
	v_mfma_f32_16x16x32_bf16 v[104:107], v[186:189], v[206:209], v[104:107]
	v_mfma_f32_16x16x32_bf16 v[100:103], v[178:181], v[214:217], v[100:103]
	v_mfma_f32_16x16x32_bf16 v[96:99], v[186:189], v[214:217], v[96:99]
	v_mfma_f32_16x16x32_bf16 v[124:127], v[182:185], v[194:197], v[124:127]
	v_mfma_f32_16x16x32_bf16 v[120:123], v[190:193], v[194:197], v[120:123]
	v_mfma_f32_16x16x32_bf16 v[116:119], v[182:185], v[202:205], v[116:119]
	v_mfma_f32_16x16x32_bf16 v[112:115], v[190:193], v[202:205], v[112:115]
	v_mfma_f32_16x16x32_bf16 v[108:111], v[182:185], v[210:213], v[108:111]
	v_mfma_f32_16x16x32_bf16 v[104:107], v[190:193], v[210:213], v[104:107]
	v_mfma_f32_16x16x32_bf16 v[100:103], v[182:185], v[218:221], v[100:103]
	v_mfma_f32_16x16x32_bf16 v[96:99], v[190:193], v[218:221], v[96:99]
	s_setprio 0
	s_barrier
	v_add_u32_e32 v164, s33, v154
	v_lshl_add_u64 v[246:247], s[94:95], 0, v[142:143]
	v_readfirstlane_b32 s27, v164
	v_add_u32_e32 v165, 0x2000, v164
	v_lshl_add_u64 v[238:239], v[246:247], 0, s[6:7]
	s_mov_b32 m0, s27
	v_lshl_add_u64 v[248:249], s[94:95], 0, v[144:145]
	v_readfirstlane_b32 s27, v165
	ds_read_b128 v[222:225], v160
	ds_read_b128 v[226:229], v160 offset:1024
	ds_read_b128 v[230:233], v160 offset:2048
	ds_read_b128 v[234:237], v160 offset:3072
	global_load_lds_dwordx4 v[238:239], off
	v_lshl_add_u64 v[238:239], v[248:249], 0, s[6:7]
	s_mov_b32 m0, s27
	s_nop 0
	global_load_lds_dwordx4 v[238:239], off
	s_barrier
	s_waitcnt lgkmcnt(0)
	s_setprio 1
	v_mfma_f32_16x16x32_bf16 v[92:95], v[222:225], v[166:169], v[92:95]
	v_mfma_f32_16x16x32_bf16 v[88:91], v[230:233], v[166:169], v[88:91]
	v_mfma_f32_16x16x32_bf16 v[84:87], v[222:225], v[198:201], v[84:87]
	v_mfma_f32_16x16x32_bf16 v[80:83], v[230:233], v[198:201], v[80:83]
	v_mfma_f32_16x16x32_bf16 v[76:79], v[222:225], v[206:209], v[76:79]
	v_mfma_f32_16x16x32_bf16 v[72:75], v[230:233], v[206:209], v[72:75]
	v_mfma_f32_16x16x32_bf16 v[68:71], v[222:225], v[214:217], v[68:71]
	v_mfma_f32_16x16x32_bf16 v[64:67], v[230:233], v[214:217], v[64:67]
	v_mfma_f32_16x16x32_bf16 v[92:95], v[226:229], v[194:197], v[92:95]
	v_mfma_f32_16x16x32_bf16 v[88:91], v[234:237], v[194:197], v[88:91]
	v_mfma_f32_16x16x32_bf16 v[84:87], v[226:229], v[202:205], v[84:87]
	v_mfma_f32_16x16x32_bf16 v[80:83], v[234:237], v[202:205], v[80:83]
	v_mfma_f32_16x16x32_bf16 v[76:79], v[226:229], v[210:213], v[76:79]
	v_mfma_f32_16x16x32_bf16 v[72:75], v[234:237], v[210:213], v[72:75]
	v_mfma_f32_16x16x32_bf16 v[68:71], v[226:229], v[218:221], v[68:71]
	v_mfma_f32_16x16x32_bf16 v[64:67], v[234:237], v[218:221], v[64:67]
	s_setprio 0
	v_readfirstlane_b32 s27, v152
	v_lshl_add_u64 v[166:167], v[242:243], 0, s[8:9]
	s_mov_b32 m0, s27
	s_barrier
	ds_read_b128 v[194:197], v153 offset:16384
	ds_read_b128 v[198:201], v153 offset:17408
	ds_read_b128 v[202:205], v171 offset:16384
	ds_read_b128 v[206:209], v171 offset:17408
	ds_read_b128 v[210:213], v172 offset:16384
	ds_read_b128 v[214:217], v172 offset:17408
	ds_read_b128 v[218:221], v173 offset:16384
	ds_read_b128 v[238:241], v173 offset:17408
	global_load_lds_dwordx4 v[166:167], off
	v_add_u32_e32 v166, 0x2000, v152
	v_lshl_add_u64 v[168:169], v[244:245], 0, s[8:9]
	v_readfirstlane_b32 s27, v166
	s_mov_b32 m0, s27
	s_nop 0
	global_load_lds_dwordx4 v[168:169], off
	s_barrier
	s_waitcnt lgkmcnt(0)
	s_setprio 1
	v_mfma_f32_16x16x32_bf16 v[60:63], v[178:181], v[194:197], v[60:63]
	v_mfma_f32_16x16x32_bf16 v[56:59], v[186:189], v[194:197], v[56:59]
	v_mfma_f32_16x16x32_bf16 v[52:55], v[178:181], v[202:205], v[52:55]
	v_mfma_f32_16x16x32_bf16 v[48:51], v[186:189], v[202:205], v[48:51]
	v_mfma_f32_16x16x32_bf16 v[44:47], v[178:181], v[210:213], v[44:47]
	v_mfma_f32_16x16x32_bf16 v[40:43], v[186:189], v[210:213], v[40:43]
	v_mfma_f32_16x16x32_bf16 v[36:39], v[178:181], v[218:221], v[36:39]
	v_mfma_f32_16x16x32_bf16 v[32:35], v[186:189], v[218:221], v[32:35]
	v_mfma_f32_16x16x32_bf16 v[60:63], v[182:185], v[198:201], v[60:63]
	v_mfma_f32_16x16x32_bf16 v[56:59], v[190:193], v[198:201], v[56:59]
	v_mfma_f32_16x16x32_bf16 v[52:55], v[182:185], v[206:209], v[52:55]
	v_mfma_f32_16x16x32_bf16 v[48:51], v[190:193], v[206:209], v[48:51]
	v_mfma_f32_16x16x32_bf16 v[44:47], v[182:185], v[214:217], v[44:47]
	v_mfma_f32_16x16x32_bf16 v[40:43], v[190:193], v[214:217], v[40:43]
	v_mfma_f32_16x16x32_bf16 v[36:39], v[182:185], v[238:241], v[36:39]
	v_mfma_f32_16x16x32_bf16 v[32:35], v[190:193], v[238:241], v[32:35]
	s_setprio 0
	s_barrier
; #define STAGE(P,BASE,LD,br,kt) do{long _g=(long)(br)*(LD)+(long)(kt)*BK; \
;     _Pragma("unroll") for(int _i=0;_i<2;++_i){int _b=tid*16+_i*8192;int _r,_c;stage_rc(_b,_r,_c); \
;       __builtin_amdgcn_global_load_lds((const unsigned*)((BASE)+_g+(long)_r*(LD)+_c), \
;         (unsigned*)((char*)(P)+_b),16,0,0);}}while(0)
; #define STAGE(P,BASE,LD,br,kt) do{long _g=(long)(br)*(LD)+(long)(kt)*BK; \
;     _Pragma("unroll") for(int _i=0;_i<2;++_i){int _b=tid*16+_i*8192;int _r,_c;stage_rc(_b,_r,_c); \
;       __builtin_amdgcn_global_load_lds((const unsigned*)((BASE)+_g+(long)_r*(LD)+_c), \
;         (unsigned*)((char*)(P)+_b),16,0,0);}}while(0)
; #define LDA(dst,b,h) _Pragma("unroll") for(int m=0;m<4;++m) _Pragma("unroll") for(int k=0;k<2;++k) \
;     dst[m][k]=*reinterpret_cast<const bf16x8*>((char*)SA(b,h)+lds_byte(wr*64+m*16+fr,k*32+fq*8))
; #define LDB(dst,b,h) _Pragma("unroll") for(int n=0;n<2;++n) _Pragma("unroll") for(int k=0;k<2;++k) \
;     dst[n][k]=*reinterpret_cast<const bf16x8*>((char*)SB(b,h)+lds_byte(wc*32+n*16+fr,k*32+fq*8))
; #define MMA(ai,bj,At_,Bt_) do{__builtin_amdgcn_s_setprio(1); \
;     _Pragma("unroll") for(int m=0;m<4;++m) _Pragma("unroll") for(int n=0;n<2;++n) _Pragma("unroll") for(int k=0;k<2;++k) \
;       acc[ai][bj][m][n]=__builtin_amdgcn_mfma_f32_16x16x32_bf16(Bt_[n][k],At_[m][k],acc[ai][bj][m][n],0,0,0); \
;     __builtin_amdgcn_s_setprio(0);}while(0)
; #define WAIT_V(n) asm volatile("s_waitcnt vmcnt(" #n ")":::"memory")
; #define WAIT_L(n) asm volatile("s_waitcnt lgkmcnt(" #n ")":::"memory")
; #define BAR __builtin_amdgcn_s_barrier()
; #define SCHED __builtin_amdgcn_sched_barrier(0)
; DEVINL void gemm8_mainloop(const u16* A, long lda, const u16* Bt, long ldb, int K, int brow, int bcol, f32x4 (&acc)[2][2][4][2], char* smem, int tid) {
;     ...
;     STAGE(SB(0,1),Bt,ldb,bcol+HALF,t+2);
;     WAIT_V(6); BAR; MMA(1,1,At,B1); BAR;
;     LDB(B0,1,0); SCHED; LDA(At,1,0); STAGE(SA(0,1),A,lda,brow+HALF,t+2);
;     WAIT_L(8); BAR; WAIT_L(0); MMA(0,0,At,B0); BAR; SCHED;
;     LDB(B1,1,1); STAGE(SB(1,0),Bt,ldb,bcol,t+3);
;     BAR; WAIT_L(0); MMA(0,1,At,B1); BAR;
;     LDA(At,1,1); STAGE(SA(1,0),A,lda,brow,t+3);
	v_add_u32_e32 v167, s34, v154
	v_lshl_add_u64 v[168:169], v[246:247], 0, s[10:11]
	v_readfirstlane_b32 s27, v167
	s_mov_b32 m0, s27
	v_lshl_add_u64 v[178:179], v[248:249], 0, s[10:11]
	global_load_lds_dwordx4 v[168:169], off
	v_add_u32_e32 v168, 0x2000, v167
	s_nop 0
	v_readfirstlane_b32 s27, v168
	s_mov_b32 m0, s27
	s_nop 0
	global_load_lds_dwordx4 v[178:179], off
	s_waitcnt vmcnt(6)
	s_barrier
	s_setprio 1
	v_mfma_f32_16x16x32_bf16 v[28:31], v[222:225], v[194:197], v[28:31]
	v_mfma_f32_16x16x32_bf16 v[24:27], v[230:233], v[194:197], v[24:27]
	v_mfma_f32_16x16x32_bf16 v[20:23], v[222:225], v[202:205], v[20:23]
	v_mfma_f32_16x16x32_bf16 v[16:19], v[230:233], v[202:205], v[16:19]
	v_mfma_f32_16x16x32_bf16 v[12:15], v[222:225], v[210:213], v[12:15]
	v_mfma_f32_16x16x32_bf16 v[8:11], v[230:233], v[210:213], v[8:11]
	v_mfma_f32_16x16x32_bf16 v[4:7], v[222:225], v[218:221], v[4:7]
	v_mfma_f32_16x16x32_bf16 v[0:3], v[230:233], v[218:221], v[0:3]
	v_mfma_f32_16x16x32_bf16 v[28:31], v[226:229], v[198:201], v[28:31]
	v_mfma_f32_16x16x32_bf16 v[24:27], v[234:237], v[198:201], v[24:27]
	v_mfma_f32_16x16x32_bf16 v[20:23], v[226:229], v[206:209], v[20:23]
	v_mfma_f32_16x16x32_bf16 v[16:19], v[234:237], v[206:209], v[16:19]
	v_mfma_f32_16x16x32_bf16 v[12:15], v[226:229], v[214:217], v[12:15]
	v_mfma_f32_16x16x32_bf16 v[8:11], v[234:237], v[214:217], v[8:11]
	v_mfma_f32_16x16x32_bf16 v[4:7], v[226:229], v[238:241], v[4:7]
	v_mfma_f32_16x16x32_bf16 v[0:3], v[234:237], v[238:241], v[0:3]
	s_setprio 0
	s_barrier
	ds_read_b128 v[178:181], v157
	ds_read_b128 v[182:185], v157 offset:1024
	ds_read_b128 v[186:189], v157 offset:2048
	ds_read_b128 v[190:193], v157 offset:3072
	v_add_u32_e32 v169, 0x4000, v152
	v_add_u32_e32 v170, 0x6000, v152
	v_readfirstlane_b32 s27, v169
	v_lshl_add_u64 v[226:227], v[242:243], 0, s[12:13]
	s_mov_b32 m0, s27
	v_readfirstlane_b32 s27, v170
	ds_read_b128 v[194:197], v153 offset:32768
	ds_read_b128 v[198:201], v153 offset:33792
	ds_read_b128 v[202:205], v171 offset:32768
	ds_read_b128 v[206:209], v171 offset:33792
	ds_read_b128 v[210:213], v172 offset:32768
	ds_read_b128 v[214:217], v172 offset:33792
	ds_read_b128 v[218:221], v173 offset:32768
	ds_read_b128 v[222:225], v173 offset:33792
	global_load_lds_dwordx4 v[226:227], off
	v_lshl_add_u64 v[226:227], v[244:245], 0, s[12:13]
	s_mov_b32 m0, s27
	s_nop 0
	global_load_lds_dwordx4 v[226:227], off
	s_waitcnt lgkmcnt(8)
	s_barrier
	s_waitcnt lgkmcnt(0)
	s_setprio 1
	v_mfma_f32_16x16x32_bf16 v[124:127], v[178:181], v[194:197], v[124:127]
	v_mfma_f32_16x16x32_bf16 v[120:123], v[186:189], v[194:197], v[120:123]
	v_mfma_f32_16x16x32_bf16 v[116:119], v[178:181], v[202:205], v[116:119]
	v_mfma_f32_16x16x32_bf16 v[112:115], v[186:189], v[202:205], v[112:115]
	v_mfma_f32_16x16x32_bf16 v[108:111], v[178:181], v[210:213], v[108:111]
	v_mfma_f32_16x16x32_bf16 v[104:107], v[186:189], v[210:213], v[104:107]
	v_mfma_f32_16x16x32_bf16 v[100:103], v[178:181], v[218:221], v[100:103]
	v_mfma_f32_16x16x32_bf16 v[96:99], v[186:189], v[218:221], v[96:99]
	v_mfma_f32_16x16x32_bf16 v[124:127], v[182:185], v[198:201], v[124:127]
	v_mfma_f32_16x16x32_bf16 v[120:123], v[190:193], v[198:201], v[120:123]
	v_mfma_f32_16x16x32_bf16 v[116:119], v[182:185], v[206:209], v[116:119]
	v_mfma_f32_16x16x32_bf16 v[112:115], v[190:193], v[206:209], v[112:115]
	v_mfma_f32_16x16x32_bf16 v[108:111], v[182:185], v[214:217], v[108:111]
	v_mfma_f32_16x16x32_bf16 v[104:107], v[190:193], v[214:217], v[104:107]
	v_mfma_f32_16x16x32_bf16 v[100:103], v[182:185], v[222:225], v[100:103]
	v_mfma_f32_16x16x32_bf16 v[96:99], v[190:193], v[222:225], v[96:99]
	s_setprio 0
	s_barrier
	v_readfirstlane_b32 s27, v156
	v_add_u32_e32 v177, 0x2000, v156
	v_lshl_add_u64 v[250:251], v[246:247], 0, s[14:15]
	s_mov_b32 m0, s27
	v_readfirstlane_b32 s27, v177
	ds_read_b128 v[226:229], v155
	ds_read_b128 v[230:233], v155 offset:1024
	ds_read_b128 v[234:237], v155 offset:2048
	ds_read_b128 v[238:241], v155 offset:3072
	global_load_lds_dwordx4 v[250:251], off
	v_lshl_add_u64 v[250:251], v[248:249], 0, s[14:15]
	s_mov_b32 m0, s27
	s_nop 0
	global_load_lds_dwordx4 v[250:251], off
	s_barrier
	s_waitcnt lgkmcnt(0)
	s_setprio 1
	v_mfma_f32_16x16x32_bf16 v[92:95], v[226:229], v[194:197], v[92:95]
	v_mfma_f32_16x16x32_bf16 v[88:91], v[234:237], v[194:197], v[88:91]
	v_mfma_f32_16x16x32_bf16 v[84:87], v[226:229], v[202:205], v[84:87]
	v_mfma_f32_16x16x32_bf16 v[80:83], v[234:237], v[202:205], v[80:83]
	v_mfma_f32_16x16x32_bf16 v[76:79], v[226:229], v[210:213], v[76:79]
	v_mfma_f32_16x16x32_bf16 v[72:75], v[234:237], v[210:213], v[72:75]
	v_mfma_f32_16x16x32_bf16 v[68:71], v[226:229], v[218:221], v[68:71]
	v_mfma_f32_16x16x32_bf16 v[64:67], v[234:237], v[218:221], v[64:67]
	v_mfma_f32_16x16x32_bf16 v[92:95], v[230:233], v[198:201], v[92:95]
	v_mfma_f32_16x16x32_bf16 v[88:91], v[238:241], v[198:201], v[88:91]
	v_mfma_f32_16x16x32_bf16 v[84:87], v[230:233], v[206:209], v[84:87]
	v_mfma_f32_16x16x32_bf16 v[80:83], v[238:241], v[206:209], v[80:83]
	v_mfma_f32_16x16x32_bf16 v[76:79], v[230:233], v[214:217], v[76:79]
	v_mfma_f32_16x16x32_bf16 v[72:75], v[238:241], v[214:217], v[72:75]
	v_mfma_f32_16x16x32_bf16 v[68:71], v[230:233], v[222:225], v[68:71]
	v_mfma_f32_16x16x32_bf16 v[64:67], v[238:241], v[222:225], v[64:67]
	s_setprio 0
	v_readfirstlane_b32 s27, v158
	v_lshl_add_u64 v[242:243], v[242:243], 0, s[16:17]
	s_mov_b32 m0, s27
	v_readfirstlane_b32 s27, v159
	s_barrier
; #define STAGE(P,BASE,LD,br,kt) do{long _g=(long)(br)*(LD)+(long)(kt)*BK; \
;     _Pragma("unroll") for(int _i=0;_i<2;++_i){int _b=tid*16+_i*8192;int _r,_c;stage_rc(_b,_r,_c); \
;       __builtin_amdgcn_global_load_lds((const unsigned*)((BASE)+_g+(long)_r*(LD)+_c), \
;         (unsigned*)((char*)(P)+_b),16,0,0);}}while(0)
; #define STAGE(P,BASE,LD,br,kt) do{long _g=(long)(br)*(LD)+(long)(kt)*BK; \
;     _Pragma("unroll") for(int _i=0;_i<2;++_i){int _b=tid*16+_i*8192;int _r,_c;stage_rc(_b,_r,_c); \
;       __builtin_amdgcn_global_load_lds((const unsigned*)((BASE)+_g+(long)_r*(LD)+_c), \
;         (unsigned*)((char*)(P)+_b),16,0,0);}}while(0)
; #define LDA(dst,b,h) _Pragma("unroll") for(int m=0;m<4;++m) _Pragma("unroll") for(int k=0;k<2;++k) \
;     dst[m][k]=*reinterpret_cast<const bf16x8*>((char*)SA(b,h)+lds_byte(wr*64+m*16+fr,k*32+fq*8))
; #define LDB(dst,b,h) _Pragma("unroll") for(int n=0;n<2;++n) _Pragma("unroll") for(int k=0;k<2;++k) \
;     dst[n][k]=*reinterpret_cast<const bf16x8*>((char*)SB(b,h)+lds_byte(wc*32+n*16+fr,k*32+fq*8))
; #define MMA(ai,bj,At_,Bt_) do{__builtin_amdgcn_s_setprio(1); \
;     _Pragma("unroll") for(int m=0;m<4;++m) _Pragma("unroll") for(int n=0;n<2;++n) _Pragma("unroll") for(int k=0;k<2;++k) \
;       acc[ai][bj][m][n]=__builtin_amdgcn_mfma_f32_16x16x32_bf16(Bt_[n][k],At_[m][k],acc[ai][bj][m][n],0,0,0); \
;     __builtin_amdgcn_s_setprio(0);}while(0)
; #define WAIT_V(n) asm volatile("s_waitcnt vmcnt(" #n ")":::"memory")
; #define WAIT_L(n) asm volatile("s_waitcnt lgkmcnt(" #n ")":::"memory")
; #define BAR __builtin_amdgcn_s_barrier()
; #define SCHED __builtin_amdgcn_sched_barrier(0)
; DEVINL void gemm8_mainloop(const u16* A, long lda, const u16* Bt, long ldb, int K, int brow, int bcol, f32x4 (&acc)[2][2][4][2], char* smem, int tid) {
;     ...
;     LDA(At,1,1); STAGE(SA(1,0),A,lda,brow,t+3);
;     BAR; WAIT_L(0); MMA(1,0,At,B0); BAR; SCHED;
;     STAGE(SB(1,1),Bt,ldb,bcol+HALF,t+3);
;     WAIT_V(6); BAR; MMA(1,1,At,B1); BAR;
;   }
;   { LDB(B0,0,0); LDA(At,0,0); STAGE(SA(1,1),A,lda,brow+HALF,nt-1);
;     BAR; WAIT_L(0); MMA(0,0,At,B0); BAR;
	ds_read_b128 v[194:197], v153 offset:49152
	ds_read_b128 v[198:201], v153 offset:50176
	ds_read_b128 v[202:205], v171 offset:49152
	ds_read_b128 v[206:209], v171 offset:50176
	ds_read_b128 v[210:213], v172 offset:49152
	ds_read_b128 v[214:217], v172 offset:50176
	ds_read_b128 v[218:221], v173 offset:49152
	ds_read_b128 v[222:225], v173 offset:50176
	global_load_lds_dwordx4 v[242:243], off
	v_lshl_add_u64 v[242:243], v[244:245], 0, s[16:17]
	s_mov_b32 m0, s27
	s_nop 0
	global_load_lds_dwordx4 v[242:243], off
	s_barrier
	s_waitcnt lgkmcnt(0)
	s_setprio 1
	v_mfma_f32_16x16x32_bf16 v[60:63], v[178:181], v[194:197], v[60:63]
	v_mfma_f32_16x16x32_bf16 v[56:59], v[186:189], v[194:197], v[56:59]
	v_mfma_f32_16x16x32_bf16 v[52:55], v[178:181], v[202:205], v[52:55]
	v_mfma_f32_16x16x32_bf16 v[48:51], v[186:189], v[202:205], v[48:51]
	v_mfma_f32_16x16x32_bf16 v[44:47], v[178:181], v[210:213], v[44:47]
	v_mfma_f32_16x16x32_bf16 v[40:43], v[186:189], v[210:213], v[40:43]
	v_mfma_f32_16x16x32_bf16 v[36:39], v[178:181], v[218:221], v[36:39]
	v_mfma_f32_16x16x32_bf16 v[32:35], v[186:189], v[218:221], v[32:35]
	v_mfma_f32_16x16x32_bf16 v[60:63], v[182:185], v[198:201], v[60:63]
	v_mfma_f32_16x16x32_bf16 v[56:59], v[190:193], v[198:201], v[56:59]
	v_mfma_f32_16x16x32_bf16 v[52:55], v[182:185], v[206:209], v[52:55]
	v_mfma_f32_16x16x32_bf16 v[48:51], v[190:193], v[206:209], v[48:51]
	v_mfma_f32_16x16x32_bf16 v[44:47], v[182:185], v[214:217], v[44:47]
	v_mfma_f32_16x16x32_bf16 v[40:43], v[190:193], v[214:217], v[40:43]
	v_mfma_f32_16x16x32_bf16 v[36:39], v[182:185], v[222:225], v[36:39]
	v_mfma_f32_16x16x32_bf16 v[32:35], v[190:193], v[222:225], v[32:35]
	s_setprio 0
	s_barrier
	v_readfirstlane_b32 s27, v161
	v_add_u32_e32 v177, 0x2000, v161
	v_lshl_add_u64 v[178:179], v[246:247], 0, s[18:19]
	s_mov_b32 m0, s27
	v_readfirstlane_b32 s27, v177
	global_load_lds_dwordx4 v[178:179], off
	v_lshl_add_u64 v[178:179], v[248:249], 0, s[18:19]
	s_mov_b32 m0, s27
	s_nop 0
	global_load_lds_dwordx4 v[178:179], off
	s_waitcnt vmcnt(6)
	s_barrier
	s_setprio 1
	v_mfma_f32_16x16x32_bf16 v[28:31], v[226:229], v[194:197], v[28:31]
	v_mfma_f32_16x16x32_bf16 v[24:27], v[234:237], v[194:197], v[24:27]
	v_mfma_f32_16x16x32_bf16 v[20:23], v[226:229], v[202:205], v[20:23]
	v_mfma_f32_16x16x32_bf16 v[16:19], v[234:237], v[202:205], v[16:19]
	v_mfma_f32_16x16x32_bf16 v[12:15], v[226:229], v[210:213], v[12:15]
	v_mfma_f32_16x16x32_bf16 v[8:11], v[234:237], v[210:213], v[8:11]
	v_mfma_f32_16x16x32_bf16 v[4:7], v[226:229], v[218:221], v[4:7]
	v_mfma_f32_16x16x32_bf16 v[0:3], v[234:237], v[218:221], v[0:3]
	v_mfma_f32_16x16x32_bf16 v[28:31], v[230:233], v[198:201], v[28:31]
	v_mfma_f32_16x16x32_bf16 v[24:27], v[238:241], v[198:201], v[24:27]
	v_mfma_f32_16x16x32_bf16 v[20:23], v[230:233], v[206:209], v[20:23]
	v_mfma_f32_16x16x32_bf16 v[16:19], v[238:241], v[206:209], v[16:19]
	v_mfma_f32_16x16x32_bf16 v[12:15], v[230:233], v[214:217], v[12:15]
	v_mfma_f32_16x16x32_bf16 v[8:11], v[238:241], v[214:217], v[8:11]
	v_mfma_f32_16x16x32_bf16 v[4:7], v[230:233], v[222:225], v[4:7]
	v_mfma_f32_16x16x32_bf16 v[0:3], v[238:241], v[222:225], v[0:3]
	s_setprio 0
	s_add_i32 s26, s26, 2
	v_lshl_add_u64 v[142:143], v[142:143], 0, s[20:21]
	v_lshl_add_u64 v[144:145], v[144:145], 0, s[20:21]
	v_lshl_add_u64 v[146:147], v[146:147], 0, s[20:21]
	s_cmp_lt_u32 s26, 28
	v_lshl_add_u64 v[148:149], v[148:149], 0, s[20:21]
	s_cbranch_scc1 .LBB0_849
	s_barrier
	s_or_b32 s0, s28, 0x80
	s_ashr_i32 s1, s0, 31
	s_lshl_b64 s[0:1], s[0:1], 12
	s_add_u32 s0, s58, s0
	s_addc_u32 s1, s59, s1
	v_lshl_add_u64 v[158:159], v[134:135], 1, s[0:1]
	v_lshl_add_u64 v[138:139], v[138:139], 1, v[158:159]
	v_readfirstlane_b32 s26, v174
	v_lshl_add_u64 v[138:139], v[138:139], 0, s[22:23]
	s_mov_b32 m0, s26
	ds_read_b128 v[142:145], v163
	ds_read_b128 v[146:149], v163 offset:1024
	ds_read_b128 v[178:181], v163 offset:2048
	ds_read_b128 v[182:185], v163 offset:3072
	ds_read_b128 v[186:189], v153
	ds_read_b128 v[190:193], v153 offset:1024
	ds_read_b128 v[194:197], v171
	ds_read_b128 v[198:201], v171 offset:1024
	ds_read_b128 v[202:205], v172
	ds_read_b128 v[206:209], v172 offset:1024
	ds_read_b128 v[210:213], v173
	ds_read_b128 v[214:217], v173 offset:1024
	global_load_lds_dwordx4 v[138:139], off
	v_lshl_add_u64 v[138:139], v[136:137], 1, s[0:1]
	v_lshl_add_u64 v[138:139], v[140:141], 1, v[138:139]
	v_readfirstlane_b32 s0, v175
	v_lshl_add_u64 v[138:139], v[138:139], 0, s[22:23]
	s_mov_b32 m0, s0
	s_nop 0
	global_load_lds_dwordx4 v[138:139], off
	s_barrier
	s_waitcnt lgkmcnt(0)
	s_setprio 1
	v_mfma_f32_16x16x32_bf16 v[124:127], v[142:145], v[186:189], v[124:127]
	v_mfma_f32_16x16x32_bf16 v[120:123], v[178:181], v[186:189], v[120:123]
	v_mfma_f32_16x16x32_bf16 v[112:115], v[178:181], v[194:197], v[112:115]
	v_mfma_f32_16x16x32_bf16 v[104:107], v[178:181], v[202:205], v[104:107]
	v_mfma_f32_16x16x32_bf16 v[96:99], v[178:181], v[210:213], v[96:99]
	v_mfma_f32_16x16x32_bf16 v[124:127], v[146:149], v[190:193], v[124:127]
	v_mfma_f32_16x16x32_bf16 v[120:123], v[182:185], v[190:193], v[120:123]
	v_mfma_f32_16x16x32_bf16 v[116:119], v[142:145], v[194:197], v[116:119]
	v_mfma_f32_16x16x32_bf16 v[112:115], v[182:185], v[198:201], v[112:115]
	v_mfma_f32_16x16x32_bf16 v[108:111], v[142:145], v[202:205], v[108:111]
	v_mfma_f32_16x16x32_bf16 v[104:107], v[182:185], v[206:209], v[104:107]
	v_mfma_f32_16x16x32_bf16 v[100:103], v[142:145], v[210:213], v[100:103]
	v_mfma_f32_16x16x32_bf16 v[96:99], v[182:185], v[214:217], v[96:99]
	v_mfma_f32_16x16x32_bf16 v[138:141], v[146:149], v[198:201], v[116:119]
	v_mfma_f32_16x16x32_bf16 v[218:221], v[146:149], v[206:209], v[108:111]
	v_mfma_f32_16x16x32_bf16 v[222:225], v[146:149], v[214:217], v[100:103]
	s_setprio 0
	s_barrier
; #define LDA(dst,b,h) _Pragma("unroll") for(int m=0;m<4;++m) _Pragma("unroll") for(int k=0;k<2;++k) \
;     dst[m][k]=*reinterpret_cast<const bf16x8*>((char*)SA(b,h)+lds_byte(wr*64+m*16+fr,k*32+fq*8))
; #define LDB(dst,b,h) _Pragma("unroll") for(int n=0;n<2;++n) _Pragma("unroll") for(int k=0;k<2;++k) \
;     dst[n][k]=*reinterpret_cast<const bf16x8*>((char*)SB(b,h)+lds_byte(wc*32+n*16+fr,k*32+fq*8))
; #define MMA(ai,bj,At_,Bt_) do{__builtin_amdgcn_s_setprio(1); \
;     _Pragma("unroll") for(int m=0;m<4;++m) _Pragma("unroll") for(int n=0;n<2;++n) _Pragma("unroll") for(int k=0;k<2;++k) \
;       acc[ai][bj][m][n]=__builtin_amdgcn_mfma_f32_16x16x32_bf16(Bt_[n][k],At_[m][k],acc[ai][bj][m][n],0,0,0); \
;     __builtin_amdgcn_s_setprio(0);}while(0)
; #define WAIT_V(n) asm volatile("s_waitcnt vmcnt(" #n ")":::"memory")
; #define WAIT_L(n) asm volatile("s_waitcnt lgkmcnt(" #n ")":::"memory")
; #define BAR __builtin_amdgcn_s_barrier()
; DEVINL void gemm8_mainloop(const u16* A, long lda, const u16* Bt, long ldb, int K, int brow, int bcol, f32x4 (&acc)[2][2][4][2], char* smem, int tid) {
;     ...
;     BAR; WAIT_L(0); MMA(0,0,At,B0); BAR;
;     LDB(B1,0,1); BAR; WAIT_L(0); MMA(0,1,At,B1); BAR;
;     LDA(At,0,1); WAIT_V(4); BAR; WAIT_L(0); MMA(1,0,At,B0); MMA(1,1,At,B1); BAR; }
;   { LDB(B0,1,0); LDA(At,1,0); WAIT_V(2); BAR; WAIT_L(0); MMA(0,0,At,B0); BAR;
	s_nop 1
	ds_read_b128 v[100:103], v160
	ds_read_b128 v[108:111], v160 offset:1024
	ds_read_b128 v[116:119], v160 offset:2048
	ds_read_b128 v[158:161], v160 offset:3072
	s_barrier
	s_waitcnt lgkmcnt(0)
	s_setprio 1
	v_mfma_f32_16x16x32_bf16 v[88:91], v[116:119], v[186:189], v[88:91]
	v_mfma_f32_16x16x32_bf16 v[80:83], v[116:119], v[194:197], v[80:83]
	v_mfma_f32_16x16x32_bf16 v[72:75], v[116:119], v[202:205], v[72:75]
	v_mfma_f32_16x16x32_bf16 v[64:67], v[116:119], v[210:213], v[64:67]
	v_mfma_f32_16x16x32_bf16 v[92:95], v[100:103], v[186:189], v[92:95]
	v_mfma_f32_16x16x32_bf16 v[88:91], v[158:161], v[190:193], v[88:91]
	v_mfma_f32_16x16x32_bf16 v[84:87], v[100:103], v[194:197], v[84:87]
	v_mfma_f32_16x16x32_bf16 v[80:83], v[158:161], v[198:201], v[80:83]
	v_mfma_f32_16x16x32_bf16 v[76:79], v[100:103], v[202:205], v[76:79]
	v_mfma_f32_16x16x32_bf16 v[72:75], v[158:161], v[206:209], v[72:75]
	v_mfma_f32_16x16x32_bf16 v[68:71], v[100:103], v[210:213], v[68:71]
	v_mfma_f32_16x16x32_bf16 v[64:67], v[158:161], v[214:217], v[64:67]
	v_mfma_f32_16x16x32_bf16 v[226:229], v[108:111], v[190:193], v[92:95]
	v_mfma_f32_16x16x32_bf16 v[186:189], v[108:111], v[198:201], v[84:87]
	v_mfma_f32_16x16x32_bf16 v[190:193], v[108:111], v[206:209], v[76:79]
	v_mfma_f32_16x16x32_bf16 v[194:197], v[108:111], v[214:217], v[68:71]
	s_setprio 0
	s_barrier
	s_nop 0
	ds_read_b128 v[68:71], v153 offset:16384
	ds_read_b128 v[76:79], v153 offset:17408
	ds_read_b128 v[84:87], v171 offset:16384
	ds_read_b128 v[92:95], v171 offset:17408
	ds_read_b128 v[198:201], v172 offset:16384
	ds_read_b128 v[202:205], v172 offset:17408
	ds_read_b128 v[206:209], v173 offset:16384
	ds_read_b128 v[210:213], v173 offset:17408
	s_waitcnt vmcnt(4)
	s_barrier
	s_waitcnt lgkmcnt(0)
	s_setprio 1
	v_mfma_f32_16x16x32_bf16 v[60:63], v[142:145], v[68:71], v[60:63]
	v_mfma_f32_16x16x32_bf16 v[56:59], v[178:181], v[68:71], v[56:59]
	v_mfma_f32_16x16x32_bf16 v[52:55], v[142:145], v[84:87], v[52:55]
	v_mfma_f32_16x16x32_bf16 v[48:51], v[178:181], v[84:87], v[48:51]
	v_mfma_f32_16x16x32_bf16 v[36:39], v[142:145], v[206:209], v[36:39]
	v_mfma_f32_16x16x32_bf16 v[32:35], v[178:181], v[206:209], v[32:35]
	v_mfma_f32_16x16x32_bf16 v[60:63], v[146:149], v[76:79], v[60:63]
	v_mfma_f32_16x16x32_bf16 v[56:59], v[182:185], v[76:79], v[56:59]
	v_mfma_f32_16x16x32_bf16 v[52:55], v[146:149], v[92:95], v[52:55]
	v_mfma_f32_16x16x32_bf16 v[48:51], v[182:185], v[92:95], v[48:51]
	v_mfma_f32_16x16x32_bf16 v[44:47], v[142:145], v[198:201], v[44:47]
	v_mfma_f32_16x16x32_bf16 v[40:43], v[178:181], v[198:201], v[40:43]
	v_mfma_f32_16x16x32_bf16 v[36:39], v[146:149], v[210:213], v[36:39]
	v_mfma_f32_16x16x32_bf16 v[32:35], v[182:185], v[210:213], v[32:35]
	v_mfma_f32_16x16x32_bf16 v[214:217], v[146:149], v[202:205], v[44:47]
	v_mfma_f32_16x16x32_bf16 v[230:233], v[182:185], v[202:205], v[40:43]
	s_setprio 0
	s_setprio 1
	v_mfma_f32_16x16x32_bf16 v[20:23], v[100:103], v[84:87], v[20:23]
	v_mfma_f32_16x16x32_bf16 v[16:19], v[116:119], v[84:87], v[16:19]
	v_mfma_f32_16x16x32_bf16 v[4:7], v[100:103], v[206:209], v[4:7]
	v_mfma_f32_16x16x32_bf16 v[0:3], v[116:119], v[206:209], v[0:3]
	v_mfma_f32_16x16x32_bf16 v[28:31], v[100:103], v[68:71], v[28:31]
	v_mfma_f32_16x16x32_bf16 v[24:27], v[116:119], v[68:71], v[24:27]
	v_mfma_f32_16x16x32_bf16 v[20:23], v[108:111], v[92:95], v[20:23]
	v_mfma_f32_16x16x32_bf16 v[16:19], v[158:161], v[92:95], v[16:19]
	v_mfma_f32_16x16x32_bf16 v[12:15], v[100:103], v[198:201], v[12:15]
	v_mfma_f32_16x16x32_bf16 v[8:11], v[116:119], v[198:201], v[8:11]
	v_mfma_f32_16x16x32_bf16 v[4:7], v[108:111], v[210:213], v[4:7]
	v_mfma_f32_16x16x32_bf16 v[0:3], v[158:161], v[210:213], v[0:3]
	v_mfma_f32_16x16x32_bf16 v[142:145], v[108:111], v[76:79], v[28:31]
	v_mfma_f32_16x16x32_bf16 v[146:149], v[158:161], v[76:79], v[24:27]
	v_mfma_f32_16x16x32_bf16 v[178:181], v[108:111], v[202:205], v[12:15]
	v_mfma_f32_16x16x32_bf16 v[182:185], v[158:161], v[202:205], v[8:11]
	s_setprio 0
	s_barrier
	s_nop 0
	ds_read_b128 v[8:11], v157
	ds_read_b128 v[12:15], v157 offset:1024
	ds_read_b128 v[158:161], v157 offset:2048
	ds_read_b128 v[198:201], v157 offset:3072
	ds_read_b128 v[24:27], v153 offset:32768
	ds_read_b128 v[28:31], v153 offset:33792
	ds_read_b128 v[40:43], v171 offset:32768
	ds_read_b128 v[44:47], v171 offset:33792
	ds_read_b128 v[202:205], v172 offset:32768
	ds_read_b128 v[206:209], v172 offset:33792
	ds_read_b128 v[210:213], v173 offset:32768
	ds_read_b128 v[234:237], v173 offset:33792
	s_waitcnt vmcnt(2)
	s_barrier
; #define LDA(dst,b,h) _Pragma("unroll") for(int m=0;m<4;++m) _Pragma("unroll") for(int k=0;k<2;++k) \
;     dst[m][k]=*reinterpret_cast<const bf16x8*>((char*)SA(b,h)+lds_byte(wr*64+m*16+fr,k*32+fq*8))
; #define LDB(dst,b,h) _Pragma("unroll") for(int n=0;n<2;++n) _Pragma("unroll") for(int k=0;k<2;++k) \
;     dst[n][k]=*reinterpret_cast<const bf16x8*>((char*)SB(b,h)+lds_byte(wc*32+n*16+fr,k*32+fq*8))
; #define MMA(ai,bj,At_,Bt_) do{__builtin_amdgcn_s_setprio(1); \
;     _Pragma("unroll") for(int m=0;m<4;++m) _Pragma("unroll") for(int n=0;n<2;++n) _Pragma("unroll") for(int k=0;k<2;++k) \
;       acc[ai][bj][m][n]=__builtin_amdgcn_mfma_f32_16x16x32_bf16(Bt_[n][k],At_[m][k],acc[ai][bj][m][n],0,0,0); \
;     __builtin_amdgcn_s_setprio(0);}while(0)
; #define WAIT_V(n) asm volatile("s_waitcnt vmcnt(" #n ")":::"memory")
; #define WAIT_L(n) asm volatile("s_waitcnt lgkmcnt(" #n ")":::"memory")
; #define BAR __builtin_amdgcn_s_barrier()
; DEVINL void gemm8_mainloop(const u16* A, long lda, const u16* Bt, long ldb, int K, int brow, int bcol, f32x4 (&acc)[2][2][4][2], char* smem, int tid) {
;     ...
;   { LDB(B0,1,0); LDA(At,1,0); WAIT_V(2); BAR; WAIT_L(0); MMA(0,0,At,B0); BAR;
;     LDB(B1,1,1); WAIT_V(0); BAR; WAIT_L(0); MMA(0,1,At,B1); BAR;
;     LDA(At,1,1); BAR; WAIT_L(0); MMA(1,0,At,B0); MMA(1,1,At,B1); BAR; }
;   if(wr==0)BAR;
;   __syncthreads();
	s_waitcnt lgkmcnt(0)
	s_setprio 1
	v_mfma_f32_16x16x32_bf16 v[68:71], v[8:11], v[24:27], v[124:127]
	v_mfma_f32_16x16x32_bf16 v[124:127], v[12:15], v[28:31], v[68:71]
	v_mfma_f32_16x16x32_bf16 v[68:71], v[158:161], v[24:27], v[120:123]
	v_mfma_f32_16x16x32_bf16 v[116:119], v[198:201], v[28:31], v[68:71]
	v_mfma_f32_16x16x32_bf16 v[68:71], v[8:11], v[40:43], v[138:141]
	v_mfma_f32_16x16x32_bf16 v[108:111], v[12:15], v[44:47], v[68:71]
	v_mfma_f32_16x16x32_bf16 v[68:71], v[158:161], v[40:43], v[112:115]
	v_mfma_f32_16x16x32_bf16 v[100:103], v[198:201], v[44:47], v[68:71]
	v_mfma_f32_16x16x32_bf16 v[68:71], v[8:11], v[202:205], v[218:221]
	v_mfma_f32_16x16x32_bf16 v[92:95], v[12:15], v[206:209], v[68:71]
	v_mfma_f32_16x16x32_bf16 v[68:71], v[158:161], v[202:205], v[104:107]
	v_mfma_f32_16x16x32_bf16 v[84:87], v[198:201], v[206:209], v[68:71]
	v_mfma_f32_16x16x32_bf16 v[68:71], v[8:11], v[210:213], v[222:225]
	v_mfma_f32_16x16x32_bf16 v[76:79], v[12:15], v[234:237], v[68:71]
	v_mfma_f32_16x16x32_bf16 v[68:71], v[158:161], v[210:213], v[96:99]
	v_mfma_f32_16x16x32_bf16 v[68:71], v[198:201], v[234:237], v[68:71]
	s_setprio 0
	s_barrier
	ds_read_b128 v[138:141], v155
	ds_read_b128 v[218:221], v155 offset:1024
	ds_read_b128 v[222:225], v155 offset:2048
	ds_read_b128 v[154:157], v155 offset:3072
	s_waitcnt vmcnt(0)
	s_barrier
	s_waitcnt lgkmcnt(0)
	s_setprio 1
	v_mfma_f32_16x16x32_bf16 v[96:99], v[138:141], v[24:27], v[226:229]
	v_mfma_f32_16x16x32_bf16 v[24:27], v[222:225], v[24:27], v[88:91]
	v_mfma_f32_16x16x32_bf16 v[112:115], v[154:157], v[28:31], v[24:27]
	v_mfma_f32_16x16x32_bf16 v[24:27], v[138:141], v[40:43], v[186:189]
	v_mfma_f32_16x16x32_bf16 v[104:107], v[218:221], v[44:47], v[24:27]
	v_mfma_f32_16x16x32_bf16 v[24:27], v[222:225], v[40:43], v[80:83]
	v_mfma_f32_16x16x32_bf16 v[120:123], v[218:221], v[28:31], v[96:99]
	v_mfma_f32_16x16x32_bf16 v[96:99], v[154:157], v[44:47], v[24:27]
	v_mfma_f32_16x16x32_bf16 v[24:27], v[138:141], v[202:205], v[190:193]
	v_mfma_f32_16x16x32_bf16 v[88:91], v[218:221], v[206:209], v[24:27]
	v_mfma_f32_16x16x32_bf16 v[24:27], v[222:225], v[202:205], v[72:75]
	v_mfma_f32_16x16x32_bf16 v[80:83], v[154:157], v[206:209], v[24:27]
	v_mfma_f32_16x16x32_bf16 v[24:27], v[138:141], v[210:213], v[194:197]
	v_mfma_f32_16x16x32_bf16 v[72:75], v[218:221], v[234:237], v[24:27]
	v_mfma_f32_16x16x32_bf16 v[24:27], v[222:225], v[210:213], v[64:67]
	v_mfma_f32_16x16x32_bf16 v[64:67], v[154:157], v[234:237], v[24:27]
	s_setprio 0
	s_barrier
	ds_read_b128 v[186:189], v153 offset:49152
	ds_read_b128 v[190:193], v153 offset:50176
	ds_read_b128 v[194:197], v171 offset:49152
	ds_read_b128 v[202:205], v171 offset:50176
	ds_read_b128 v[206:209], v172 offset:49152
	ds_read_b128 v[210:213], v172 offset:50176
	ds_read_b128 v[226:229], v173 offset:49152
	ds_read_b128 v[172:175], v173 offset:50176
	s_barrier
	s_waitcnt lgkmcnt(0)
	s_setprio 1
	v_mfma_f32_16x16x32_bf16 v[24:27], v[8:11], v[186:189], v[60:63]
	v_mfma_f32_16x16x32_bf16 v[60:63], v[12:15], v[190:193], v[24:27]
	v_mfma_f32_16x16x32_bf16 v[24:27], v[158:161], v[186:189], v[56:59]
	v_mfma_f32_16x16x32_bf16 v[56:59], v[198:201], v[190:193], v[24:27]
	v_mfma_f32_16x16x32_bf16 v[24:27], v[8:11], v[194:197], v[52:55]
	v_mfma_f32_16x16x32_bf16 v[44:47], v[12:15], v[202:205], v[24:27]
	v_mfma_f32_16x16x32_bf16 v[24:27], v[158:161], v[194:197], v[48:51]
	v_mfma_f32_16x16x32_bf16 v[40:43], v[198:201], v[202:205], v[24:27]
	v_mfma_f32_16x16x32_bf16 v[24:27], v[8:11], v[206:209], v[214:217]
	v_mfma_f32_16x16x32_bf16 v[8:11], v[8:11], v[226:229], v[36:39]
	v_mfma_f32_16x16x32_bf16 v[28:31], v[12:15], v[210:213], v[24:27]
	v_mfma_f32_16x16x32_bf16 v[24:27], v[158:161], v[206:209], v[230:233]
	v_mfma_f32_16x16x32_bf16 v[12:15], v[12:15], v[172:175], v[8:11]
	v_mfma_f32_16x16x32_bf16 v[8:11], v[158:161], v[226:229], v[32:35]
	v_mfma_f32_16x16x32_bf16 v[24:27], v[198:201], v[210:213], v[24:27]
	v_mfma_f32_16x16x32_bf16 v[8:11], v[198:201], v[172:175], v[8:11]
	s_setprio 0
	s_setprio 1
	v_mfma_f32_16x16x32_bf16 v[32:35], v[138:141], v[186:189], v[142:145]
	v_mfma_f32_16x16x32_bf16 v[52:55], v[218:221], v[190:193], v[32:35]
	v_mfma_f32_16x16x32_bf16 v[32:35], v[222:225], v[186:189], v[146:149]
	v_mfma_f32_16x16x32_bf16 v[16:19], v[222:225], v[194:197], v[16:19]
	v_mfma_f32_16x16x32_bf16 v[48:51], v[154:157], v[190:193], v[32:35]
	v_mfma_f32_16x16x32_bf16 v[20:23], v[138:141], v[194:197], v[20:23]
	v_mfma_f32_16x16x32_bf16 v[32:35], v[154:157], v[202:205], v[16:19]
	v_mfma_f32_16x16x32_bf16 v[16:19], v[138:141], v[206:209], v[178:181]
	v_mfma_f32_16x16x32_bf16 v[36:39], v[218:221], v[202:205], v[20:23]
	v_mfma_f32_16x16x32_bf16 v[20:23], v[218:221], v[210:213], v[16:19]
	v_mfma_f32_16x16x32_bf16 v[16:19], v[222:225], v[206:209], v[182:185]
	v_mfma_f32_16x16x32_bf16 v[4:7], v[138:141], v[226:229], v[4:7]
	v_mfma_f32_16x16x32_bf16 v[0:3], v[222:225], v[226:229], v[0:3]
	v_mfma_f32_16x16x32_bf16 v[16:19], v[154:157], v[210:213], v[16:19]
	v_mfma_f32_16x16x32_bf16 v[4:7], v[218:221], v[172:175], v[4:7]
	v_mfma_f32_16x16x32_bf16 v[0:3], v[154:157], v[172:175], v[0:3]
	s_setprio 0
	s_cmpk_gt_u32 s31, 0xff
	s_barrier
	s_cbranch_scc1 .LBB0_852
	s_barrier

; #define STAGE(P,BASE,LD,br,kt) do{long _g=(long)(br)*(LD)+(long)(kt)*BK; \
;     _Pragma("unroll") for(int _i=0;_i<2;++_i){int _b=tid*16+_i*8192;int _r,_c;stage_rc(_b,_r,_c); \
;       __builtin_amdgcn_global_load_lds((const unsigned*)((BASE)+_g+(long)_r*(LD)+_c), \
;         (unsigned*)((char*)(P)+_b),16,0,0);}}while(0)
; #define STAGE(P,BASE,LD,br,kt) do{long _g=(long)(br)*(LD)+(long)(kt)*BK; \
;     _Pragma("unroll") for(int _i=0;_i<2;++_i){int _b=tid*16+_i*8192;int _r,_c;stage_rc(_b,_r,_c); \
;       __builtin_amdgcn_global_load_lds((const unsigned*)((BASE)+_g+(long)_r*(LD)+_c), \
;         (unsigned*)((char*)(P)+_b),16,0,0);}}while(0)
; #define LDA(dst,b,h) _Pragma("unroll") for(int m=0;m<4;++m) _Pragma("unroll") for(int k=0;k<2;++k) \
;     dst[m][k]=*reinterpret_cast<const bf16x8*>((char*)SA(b,h)+lds_byte(wr*64+m*16+fr,k*32+fq*8))
; #define LDB(dst,b,h) _Pragma("unroll") for(int n=0;n<2;++n) _Pragma("unroll") for(int k=0;k<2;++k) \
;     dst[n][k]=*reinterpret_cast<const bf16x8*>((char*)SB(b,h)+lds_byte(wc*32+n*16+fr,k*32+fq*8))
; #define MMA(ai,bj,At_,Bt_) do{__builtin_amdgcn_s_setprio(1); \
;     _Pragma("unroll") for(int m=0;m<4;++m) _Pragma("unroll") for(int n=0;n<2;++n) _Pragma("unroll") for(int k=0;k<2;++k) \
;       acc[ai][bj][m][n]=__builtin_amdgcn_mfma_f32_16x16x32_bf16(Bt_[n][k],At_[m][k],acc[ai][bj][m][n],0,0,0); \
;     __builtin_amdgcn_s_setprio(0);}while(0)
; #define WAIT_L(n) asm volatile("s_waitcnt lgkmcnt(" #n ")":::"memory")
; #define BAR __builtin_amdgcn_s_barrier()
; #define SCHED __builtin_amdgcn_sched_barrier(0)
; DEVINL void gemm8_mainloop(const u16* A, long lda, const u16* Bt, long ldb, int K, int brow, int bcol, f32x4 (&acc)[2][2][4][2], char* smem, int tid) {
;     ...
;   for(int t=0;t<nt-2;t+=2){
;     LDB(B0,0,0); SCHED; LDA(At,0,0); STAGE(SA(1,1),A,lda,brow+HALF,t+1);
;     WAIT_L(8); BAR; WAIT_L(0); MMA(0,0,At,B0); BAR; SCHED;
;     LDB(B1,0,1); STAGE(SB(0,0),Bt,ldb,bcol,t+2);
;     BAR; WAIT_L(0); MMA(0,1,At,B1); BAR;
;     LDA(At,0,1); STAGE(SA(0,0),A,lda,brow,t+2);
;     BAR; WAIT_L(0); MMA(1,0,At,B0); BAR; SCHED;
.LBB0_916:
	s_barrier
	ds_read_b128 v[180:183], v165
	ds_read_b128 v[184:187], v165 offset:1024
	ds_read_b128 v[188:191], v165 offset:2048
	ds_read_b128 v[192:195], v165 offset:3072
	v_add_u32_e32 v177, 0xc000, v154
	v_lshl_add_u64 v[244:245], s[94:95], 0, v[146:147]
	v_readfirstlane_b32 s29, v177
	v_add_u32_e32 v178, 0xe000, v154
	v_add_u32_e32 v173, s1, v164
	v_add_u32_e32 v174, s25, v164
	v_add_u32_e32 v175, s37, v164
	v_lshl_add_u64 v[166:167], v[244:245], 0, s[4:5]
	s_mov_b32 m0, s29
	v_lshl_add_u64 v[246:247], s[94:95], 0, v[148:149]
	v_readfirstlane_b32 s29, v178
	ds_read_b128 v[168:171], v155
	ds_read_b128 v[196:199], v155 offset:1024
	ds_read_b128 v[200:203], v173
	ds_read_b128 v[204:207], v173 offset:1024
	ds_read_b128 v[208:211], v174
	ds_read_b128 v[212:215], v174 offset:1024
	ds_read_b128 v[216:219], v175
	ds_read_b128 v[220:223], v175 offset:1024
	global_load_lds_dwordx4 v[166:167], off
	v_lshl_add_u64 v[166:167], v[246:247], 0, s[4:5]
	s_mov_b32 m0, s29
	s_nop 0
	global_load_lds_dwordx4 v[166:167], off
	s_waitcnt lgkmcnt(8)
	s_barrier
	s_waitcnt lgkmcnt(0)
	s_setprio 1
	v_mfma_f32_16x16x32_bf16 v[124:127], v[180:183], v[168:171], v[124:127]
	v_mfma_f32_16x16x32_bf16 v[120:123], v[188:191], v[168:171], v[120:123]
	v_mfma_f32_16x16x32_bf16 v[116:119], v[180:183], v[200:203], v[116:119]
	v_mfma_f32_16x16x32_bf16 v[112:115], v[188:191], v[200:203], v[112:115]
	v_mfma_f32_16x16x32_bf16 v[108:111], v[180:183], v[208:211], v[108:111]
	v_mfma_f32_16x16x32_bf16 v[104:107], v[188:191], v[208:211], v[104:107]
	v_mfma_f32_16x16x32_bf16 v[100:103], v[180:183], v[216:219], v[100:103]
	v_mfma_f32_16x16x32_bf16 v[96:99], v[188:191], v[216:219], v[96:99]
	v_mfma_f32_16x16x32_bf16 v[124:127], v[184:187], v[196:199], v[124:127]
	v_mfma_f32_16x16x32_bf16 v[120:123], v[192:195], v[196:199], v[120:123]
	v_mfma_f32_16x16x32_bf16 v[116:119], v[184:187], v[204:207], v[116:119]
	v_mfma_f32_16x16x32_bf16 v[112:115], v[192:195], v[204:207], v[112:115]
	v_mfma_f32_16x16x32_bf16 v[108:111], v[184:187], v[212:215], v[108:111]
	v_mfma_f32_16x16x32_bf16 v[104:107], v[192:195], v[212:215], v[104:107]
	v_mfma_f32_16x16x32_bf16 v[100:103], v[184:187], v[220:223], v[100:103]
	v_mfma_f32_16x16x32_bf16 v[96:99], v[192:195], v[220:223], v[96:99]
	s_setprio 0
	s_barrier
	v_add_u32_e32 v166, s30, v157
	v_lshl_add_u64 v[248:249], s[94:95], 0, v[142:143]
	v_readfirstlane_b32 s29, v166
	v_add_u32_e32 v167, 0x2000, v166
	v_lshl_add_u64 v[240:241], v[248:249], 0, s[6:7]
	s_mov_b32 m0, s29
	v_lshl_add_u64 v[250:251], s[94:95], 0, v[144:145]
	v_readfirstlane_b32 s29, v167
	ds_read_b128 v[224:227], v162
	ds_read_b128 v[228:231], v162 offset:1024
	ds_read_b128 v[232:235], v162 offset:2048
	ds_read_b128 v[236:239], v162 offset:3072
	global_load_lds_dwordx4 v[240:241], off
	v_lshl_add_u64 v[240:241], v[250:251], 0, s[6:7]
	s_mov_b32 m0, s29
	s_nop 0
	global_load_lds_dwordx4 v[240:241], off
	s_barrier
	s_waitcnt lgkmcnt(0)
	s_setprio 1
	v_mfma_f32_16x16x32_bf16 v[92:95], v[224:227], v[168:171], v[92:95]
	v_mfma_f32_16x16x32_bf16 v[88:91], v[232:235], v[168:171], v[88:91]
	v_mfma_f32_16x16x32_bf16 v[84:87], v[224:227], v[200:203], v[84:87]
	v_mfma_f32_16x16x32_bf16 v[80:83], v[232:235], v[200:203], v[80:83]
	v_mfma_f32_16x16x32_bf16 v[76:79], v[224:227], v[208:211], v[76:79]
	v_mfma_f32_16x16x32_bf16 v[72:75], v[232:235], v[208:211], v[72:75]
	v_mfma_f32_16x16x32_bf16 v[68:71], v[224:227], v[216:219], v[68:71]
	v_mfma_f32_16x16x32_bf16 v[64:67], v[232:235], v[216:219], v[64:67]
	v_mfma_f32_16x16x32_bf16 v[92:95], v[228:231], v[196:199], v[92:95]
	v_mfma_f32_16x16x32_bf16 v[88:91], v[236:239], v[196:199], v[88:91]
	v_mfma_f32_16x16x32_bf16 v[84:87], v[228:231], v[204:207], v[84:87]
	v_mfma_f32_16x16x32_bf16 v[80:83], v[236:239], v[204:207], v[80:83]
	v_mfma_f32_16x16x32_bf16 v[76:79], v[228:231], v[212:215], v[76:79]
	v_mfma_f32_16x16x32_bf16 v[72:75], v[236:239], v[212:215], v[72:75]
	v_mfma_f32_16x16x32_bf16 v[68:71], v[228:231], v[220:223], v[68:71]
	v_mfma_f32_16x16x32_bf16 v[64:67], v[236:239], v[220:223], v[64:67]
	s_setprio 0
	v_readfirstlane_b32 s29, v154
	v_lshl_add_u64 v[168:169], v[244:245], 0, s[8:9]
	s_mov_b32 m0, s29
	s_barrier
	ds_read_b128 v[196:199], v155 offset:16384
	ds_read_b128 v[200:203], v155 offset:17408
	ds_read_b128 v[204:207], v173 offset:16384
	ds_read_b128 v[208:211], v173 offset:17408
	ds_read_b128 v[212:215], v174 offset:16384
	ds_read_b128 v[216:219], v174 offset:17408
	ds_read_b128 v[220:223], v175 offset:16384
	ds_read_b128 v[240:243], v175 offset:17408
	global_load_lds_dwordx4 v[168:169], off
	v_add_u32_e32 v168, 0x2000, v154
	v_lshl_add_u64 v[170:171], v[246:247], 0, s[8:9]
	v_readfirstlane_b32 s29, v168
	s_mov_b32 m0, s29
	s_nop 0
	global_load_lds_dwordx4 v[170:171], off
	s_barrier
	s_waitcnt lgkmcnt(0)
	s_setprio 1
	v_mfma_f32_16x16x32_bf16 v[60:63], v[180:183], v[196:199], v[60:63]
	v_mfma_f32_16x16x32_bf16 v[56:59], v[188:191], v[196:199], v[56:59]
	v_mfma_f32_16x16x32_bf16 v[52:55], v[180:183], v[204:207], v[52:55]
	v_mfma_f32_16x16x32_bf16 v[48:51], v[188:191], v[204:207], v[48:51]
	v_mfma_f32_16x16x32_bf16 v[44:47], v[180:183], v[212:215], v[44:47]
	v_mfma_f32_16x16x32_bf16 v[40:43], v[188:191], v[212:215], v[40:43]
	v_mfma_f32_16x16x32_bf16 v[36:39], v[180:183], v[220:223], v[36:39]
	v_mfma_f32_16x16x32_bf16 v[32:35], v[188:191], v[220:223], v[32:35]
	v_mfma_f32_16x16x32_bf16 v[60:63], v[184:187], v[200:203], v[60:63]
	v_mfma_f32_16x16x32_bf16 v[56:59], v[192:195], v[200:203], v[56:59]
	v_mfma_f32_16x16x32_bf16 v[52:55], v[184:187], v[208:211], v[52:55]
	v_mfma_f32_16x16x32_bf16 v[48:51], v[192:195], v[208:211], v[48:51]
	v_mfma_f32_16x16x32_bf16 v[44:47], v[184:187], v[216:219], v[44:47]
	v_mfma_f32_16x16x32_bf16 v[40:43], v[192:195], v[216:219], v[40:43]
	v_mfma_f32_16x16x32_bf16 v[36:39], v[184:187], v[240:243], v[36:39]
	v_mfma_f32_16x16x32_bf16 v[32:35], v[192:195], v[240:243], v[32:35]
	s_setprio 0
	s_barrier
; #define STAGE(P,BASE,LD,br,kt) do{long _g=(long)(br)*(LD)+(long)(kt)*BK; \
;     _Pragma("unroll") for(int _i=0;_i<2;++_i){int _b=tid*16+_i*8192;int _r,_c;stage_rc(_b,_r,_c); \
;       __builtin_amdgcn_global_load_lds((const unsigned*)((BASE)+_g+(long)_r*(LD)+_c), \
;         (unsigned*)((char*)(P)+_b),16,0,0);}}while(0)
; #define STAGE(P,BASE,LD,br,kt) do{long _g=(long)(br)*(LD)+(long)(kt)*BK; \
;     _Pragma("unroll") for(int _i=0;_i<2;++_i){int _b=tid*16+_i*8192;int _r,_c;stage_rc(_b,_r,_c); \
;       __builtin_amdgcn_global_load_lds((const unsigned*)((BASE)+_g+(long)_r*(LD)+_c), \
;         (unsigned*)((char*)(P)+_b),16,0,0);}}while(0)
; #define LDA(dst,b,h) _Pragma("unroll") for(int m=0;m<4;++m) _Pragma("unroll") for(int k=0;k<2;++k) \
;     dst[m][k]=*reinterpret_cast<const bf16x8*>((char*)SA(b,h)+lds_byte(wr*64+m*16+fr,k*32+fq*8))
; #define LDB(dst,b,h) _Pragma("unroll") for(int n=0;n<2;++n) _Pragma("unroll") for(int k=0;k<2;++k) \
;     dst[n][k]=*reinterpret_cast<const bf16x8*>((char*)SB(b,h)+lds_byte(wc*32+n*16+fr,k*32+fq*8))
; #define MMA(ai,bj,At_,Bt_) do{__builtin_amdgcn_s_setprio(1); \
;     _Pragma("unroll") for(int m=0;m<4;++m) _Pragma("unroll") for(int n=0;n<2;++n) _Pragma("unroll") for(int k=0;k<2;++k) \
;       acc[ai][bj][m][n]=__builtin_amdgcn_mfma_f32_16x16x32_bf16(Bt_[n][k],At_[m][k],acc[ai][bj][m][n],0,0,0); \
;     __builtin_amdgcn_s_setprio(0);}while(0)
; #define WAIT_V(n) asm volatile("s_waitcnt vmcnt(" #n ")":::"memory")
; #define WAIT_L(n) asm volatile("s_waitcnt lgkmcnt(" #n ")":::"memory")
; #define BAR __builtin_amdgcn_s_barrier()
; #define SCHED __builtin_amdgcn_sched_barrier(0)
; DEVINL void gemm8_mainloop(const u16* A, long lda, const u16* Bt, long ldb, int K, int brow, int bcol, f32x4 (&acc)[2][2][4][2], char* smem, int tid) {
;     ...
;     STAGE(SB(0,1),Bt,ldb,bcol+HALF,t+2);
;     WAIT_V(6); BAR; MMA(1,1,At,B1); BAR;
;     LDB(B0,1,0); SCHED; LDA(At,1,0); STAGE(SA(0,1),A,lda,brow+HALF,t+2);
;     WAIT_L(8); BAR; WAIT_L(0); MMA(0,0,At,B0); BAR; SCHED;
;     LDB(B1,1,1); STAGE(SB(1,0),Bt,ldb,bcol,t+3);
;     BAR; WAIT_L(0); MMA(0,1,At,B1); BAR;
;     LDA(At,1,1); STAGE(SA(1,0),A,lda,brow,t+3);
	v_add_u32_e32 v169, s31, v157
	v_lshl_add_u64 v[170:171], v[248:249], 0, s[10:11]
	v_readfirstlane_b32 s29, v169
	s_mov_b32 m0, s29
	v_lshl_add_u64 v[180:181], v[250:251], 0, s[10:11]
	global_load_lds_dwordx4 v[170:171], off
	v_add_u32_e32 v170, 0x2000, v169
	s_nop 0
	v_readfirstlane_b32 s29, v170
	s_mov_b32 m0, s29
	s_nop 0
	global_load_lds_dwordx4 v[180:181], off
	s_waitcnt vmcnt(6)
	s_barrier
	s_setprio 1
	v_mfma_f32_16x16x32_bf16 v[28:31], v[224:227], v[196:199], v[28:31]
	v_mfma_f32_16x16x32_bf16 v[24:27], v[232:235], v[196:199], v[24:27]
	v_mfma_f32_16x16x32_bf16 v[20:23], v[224:227], v[204:207], v[20:23]
	v_mfma_f32_16x16x32_bf16 v[16:19], v[232:235], v[204:207], v[16:19]
	v_mfma_f32_16x16x32_bf16 v[12:15], v[224:227], v[212:215], v[12:15]
	v_mfma_f32_16x16x32_bf16 v[8:11], v[232:235], v[212:215], v[8:11]
	v_mfma_f32_16x16x32_bf16 v[4:7], v[224:227], v[220:223], v[4:7]
	v_mfma_f32_16x16x32_bf16 v[0:3], v[232:235], v[220:223], v[0:3]
	v_mfma_f32_16x16x32_bf16 v[28:31], v[228:231], v[200:203], v[28:31]
	v_mfma_f32_16x16x32_bf16 v[24:27], v[236:239], v[200:203], v[24:27]
	v_mfma_f32_16x16x32_bf16 v[20:23], v[228:231], v[208:211], v[20:23]
	v_mfma_f32_16x16x32_bf16 v[16:19], v[236:239], v[208:211], v[16:19]
	v_mfma_f32_16x16x32_bf16 v[12:15], v[228:231], v[216:219], v[12:15]
	v_mfma_f32_16x16x32_bf16 v[8:11], v[236:239], v[216:219], v[8:11]
	v_mfma_f32_16x16x32_bf16 v[4:7], v[228:231], v[240:243], v[4:7]
	v_mfma_f32_16x16x32_bf16 v[0:3], v[236:239], v[240:243], v[0:3]
	s_setprio 0
	s_barrier
	ds_read_b128 v[180:183], v158
	ds_read_b128 v[184:187], v158 offset:1024
	ds_read_b128 v[188:191], v158 offset:2048
	ds_read_b128 v[192:195], v158 offset:3072
	v_add_u32_e32 v171, 0x4000, v154
	v_add_u32_e32 v172, 0x6000, v154
	v_readfirstlane_b32 s29, v171
	v_lshl_add_u64 v[228:229], v[244:245], 0, s[12:13]
	s_mov_b32 m0, s29
	v_readfirstlane_b32 s29, v172
	ds_read_b128 v[196:199], v155 offset:32768
	ds_read_b128 v[200:203], v155 offset:33792
	ds_read_b128 v[204:207], v173 offset:32768
	ds_read_b128 v[208:211], v173 offset:33792
	ds_read_b128 v[212:215], v174 offset:32768
	ds_read_b128 v[216:219], v174 offset:33792
	ds_read_b128 v[220:223], v175 offset:32768
	ds_read_b128 v[224:227], v175 offset:33792
	global_load_lds_dwordx4 v[228:229], off
	v_lshl_add_u64 v[228:229], v[246:247], 0, s[12:13]
	s_mov_b32 m0, s29
	s_nop 0
	global_load_lds_dwordx4 v[228:229], off
	s_waitcnt lgkmcnt(8)
	s_barrier
	s_waitcnt lgkmcnt(0)
	s_setprio 1
	v_mfma_f32_16x16x32_bf16 v[124:127], v[180:183], v[196:199], v[124:127]
	v_mfma_f32_16x16x32_bf16 v[120:123], v[188:191], v[196:199], v[120:123]
	v_mfma_f32_16x16x32_bf16 v[116:119], v[180:183], v[204:207], v[116:119]
	v_mfma_f32_16x16x32_bf16 v[112:115], v[188:191], v[204:207], v[112:115]
	v_mfma_f32_16x16x32_bf16 v[108:111], v[180:183], v[212:215], v[108:111]
	v_mfma_f32_16x16x32_bf16 v[104:107], v[188:191], v[212:215], v[104:107]
	v_mfma_f32_16x16x32_bf16 v[100:103], v[180:183], v[220:223], v[100:103]
	v_mfma_f32_16x16x32_bf16 v[96:99], v[188:191], v[220:223], v[96:99]
	v_mfma_f32_16x16x32_bf16 v[124:127], v[184:187], v[200:203], v[124:127]
	v_mfma_f32_16x16x32_bf16 v[120:123], v[192:195], v[200:203], v[120:123]
	v_mfma_f32_16x16x32_bf16 v[116:119], v[184:187], v[208:211], v[116:119]
	v_mfma_f32_16x16x32_bf16 v[112:115], v[192:195], v[208:211], v[112:115]
	v_mfma_f32_16x16x32_bf16 v[108:111], v[184:187], v[216:219], v[108:111]
	v_mfma_f32_16x16x32_bf16 v[104:107], v[192:195], v[216:219], v[104:107]
	v_mfma_f32_16x16x32_bf16 v[100:103], v[184:187], v[224:227], v[100:103]
	v_mfma_f32_16x16x32_bf16 v[96:99], v[192:195], v[224:227], v[96:99]
	s_setprio 0
	s_barrier
	v_readfirstlane_b32 s29, v159
	v_add_u32_e32 v179, 0x2000, v159
	v_lshl_add_u64 v[252:253], v[248:249], 0, s[14:15]
	s_mov_b32 m0, s29
	v_readfirstlane_b32 s29, v179
	ds_read_b128 v[228:231], v156
	ds_read_b128 v[232:235], v156 offset:1024
	ds_read_b128 v[236:239], v156 offset:2048
	ds_read_b128 v[240:243], v156 offset:3072
	global_load_lds_dwordx4 v[252:253], off
	v_lshl_add_u64 v[252:253], v[250:251], 0, s[14:15]
	s_mov_b32 m0, s29
	s_nop 0
	global_load_lds_dwordx4 v[252:253], off
	s_barrier
	s_waitcnt lgkmcnt(0)
	s_setprio 1
	v_mfma_f32_16x16x32_bf16 v[92:95], v[228:231], v[196:199], v[92:95]
	v_mfma_f32_16x16x32_bf16 v[88:91], v[236:239], v[196:199], v[88:91]
	v_mfma_f32_16x16x32_bf16 v[84:87], v[228:231], v[204:207], v[84:87]
	v_mfma_f32_16x16x32_bf16 v[80:83], v[236:239], v[204:207], v[80:83]
	v_mfma_f32_16x16x32_bf16 v[76:79], v[228:231], v[212:215], v[76:79]
	v_mfma_f32_16x16x32_bf16 v[72:75], v[236:239], v[212:215], v[72:75]
	v_mfma_f32_16x16x32_bf16 v[68:71], v[228:231], v[220:223], v[68:71]
	v_mfma_f32_16x16x32_bf16 v[64:67], v[236:239], v[220:223], v[64:67]
	v_mfma_f32_16x16x32_bf16 v[92:95], v[232:235], v[200:203], v[92:95]
	v_mfma_f32_16x16x32_bf16 v[88:91], v[240:243], v[200:203], v[88:91]
	v_mfma_f32_16x16x32_bf16 v[84:87], v[232:235], v[208:211], v[84:87]
	v_mfma_f32_16x16x32_bf16 v[80:83], v[240:243], v[208:211], v[80:83]
	v_mfma_f32_16x16x32_bf16 v[76:79], v[232:235], v[216:219], v[76:79]
	v_mfma_f32_16x16x32_bf16 v[72:75], v[240:243], v[216:219], v[72:75]
	v_mfma_f32_16x16x32_bf16 v[68:71], v[232:235], v[224:227], v[68:71]
	v_mfma_f32_16x16x32_bf16 v[64:67], v[240:243], v[224:227], v[64:67]
	s_setprio 0
	v_readfirstlane_b32 s29, v160
	v_lshl_add_u64 v[244:245], v[244:245], 0, s[16:17]
	s_mov_b32 m0, s29
	v_readfirstlane_b32 s29, v161
	s_barrier
; #define STAGE(P,BASE,LD,br,kt) do{long _g=(long)(br)*(LD)+(long)(kt)*BK; \
;     _Pragma("unroll") for(int _i=0;_i<2;++_i){int _b=tid*16+_i*8192;int _r,_c;stage_rc(_b,_r,_c); \
;       __builtin_amdgcn_global_load_lds((const unsigned*)((BASE)+_g+(long)_r*(LD)+_c), \
;         (unsigned*)((char*)(P)+_b),16,0,0);}}while(0)
; #define STAGE(P,BASE,LD,br,kt) do{long _g=(long)(br)*(LD)+(long)(kt)*BK; \
;     _Pragma("unroll") for(int _i=0;_i<2;++_i){int _b=tid*16+_i*8192;int _r,_c;stage_rc(_b,_r,_c); \
;       __builtin_amdgcn_global_load_lds((const unsigned*)((BASE)+_g+(long)_r*(LD)+_c), \
;         (unsigned*)((char*)(P)+_b),16,0,0);}}while(0)
; #define LDA(dst,b,h) _Pragma("unroll") for(int m=0;m<4;++m) _Pragma("unroll") for(int k=0;k<2;++k) \
;     dst[m][k]=*reinterpret_cast<const bf16x8*>((char*)SA(b,h)+lds_byte(wr*64+m*16+fr,k*32+fq*8))
; #define LDB(dst,b,h) _Pragma("unroll") for(int n=0;n<2;++n) _Pragma("unroll") for(int k=0;k<2;++k) \
;     dst[n][k]=*reinterpret_cast<const bf16x8*>((char*)SB(b,h)+lds_byte(wc*32+n*16+fr,k*32+fq*8))
; #define MMA(ai,bj,At_,Bt_) do{__builtin_amdgcn_s_setprio(1); \
;     _Pragma("unroll") for(int m=0;m<4;++m) _Pragma("unroll") for(int n=0;n<2;++n) _Pragma("unroll") for(int k=0;k<2;++k) \
;       acc[ai][bj][m][n]=__builtin_amdgcn_mfma_f32_16x16x32_bf16(Bt_[n][k],At_[m][k],acc[ai][bj][m][n],0,0,0); \
;     __builtin_amdgcn_s_setprio(0);}while(0)
; #define WAIT_V(n) asm volatile("s_waitcnt vmcnt(" #n ")":::"memory")
; #define WAIT_L(n) asm volatile("s_waitcnt lgkmcnt(" #n ")":::"memory")
; #define BAR __builtin_amdgcn_s_barrier()
; #define SCHED __builtin_amdgcn_sched_barrier(0)
; DEVINL void gemm8_mainloop(const u16* A, long lda, const u16* Bt, long ldb, int K, int brow, int bcol, f32x4 (&acc)[2][2][4][2], char* smem, int tid) {
;     ...
;     LDA(At,1,1); STAGE(SA(1,0),A,lda,brow,t+3);
;     BAR; WAIT_L(0); MMA(1,0,At,B0); BAR; SCHED;
;     STAGE(SB(1,1),Bt,ldb,bcol+HALF,t+3);
;     WAIT_V(6); BAR; MMA(1,1,At,B1); BAR;
;   }
;   { LDB(B0,0,0); LDA(At,0,0); STAGE(SA(1,1),A,lda,brow+HALF,nt-1);
;     BAR; WAIT_L(0); MMA(0,0,At,B0); BAR;
	ds_read_b128 v[196:199], v155 offset:49152
	ds_read_b128 v[200:203], v155 offset:50176
	ds_read_b128 v[204:207], v173 offset:49152
	ds_read_b128 v[208:211], v173 offset:50176
	ds_read_b128 v[212:215], v174 offset:49152
	ds_read_b128 v[216:219], v174 offset:50176
	ds_read_b128 v[220:223], v175 offset:49152
	ds_read_b128 v[224:227], v175 offset:50176
	global_load_lds_dwordx4 v[244:245], off
	v_lshl_add_u64 v[244:245], v[246:247], 0, s[16:17]
	s_mov_b32 m0, s29
	s_nop 0
	global_load_lds_dwordx4 v[244:245], off
	s_barrier
	s_waitcnt lgkmcnt(0)
	s_setprio 1
	v_mfma_f32_16x16x32_bf16 v[60:63], v[180:183], v[196:199], v[60:63]
	v_mfma_f32_16x16x32_bf16 v[56:59], v[188:191], v[196:199], v[56:59]
	v_mfma_f32_16x16x32_bf16 v[52:55], v[180:183], v[204:207], v[52:55]
	v_mfma_f32_16x16x32_bf16 v[48:51], v[188:191], v[204:207], v[48:51]
	v_mfma_f32_16x16x32_bf16 v[44:47], v[180:183], v[212:215], v[44:47]
	v_mfma_f32_16x16x32_bf16 v[40:43], v[188:191], v[212:215], v[40:43]
	v_mfma_f32_16x16x32_bf16 v[36:39], v[180:183], v[220:223], v[36:39]
	v_mfma_f32_16x16x32_bf16 v[32:35], v[188:191], v[220:223], v[32:35]
	v_mfma_f32_16x16x32_bf16 v[60:63], v[184:187], v[200:203], v[60:63]
	v_mfma_f32_16x16x32_bf16 v[56:59], v[192:195], v[200:203], v[56:59]
	v_mfma_f32_16x16x32_bf16 v[52:55], v[184:187], v[208:211], v[52:55]
	v_mfma_f32_16x16x32_bf16 v[48:51], v[192:195], v[208:211], v[48:51]
	v_mfma_f32_16x16x32_bf16 v[44:47], v[184:187], v[216:219], v[44:47]
	v_mfma_f32_16x16x32_bf16 v[40:43], v[192:195], v[216:219], v[40:43]
	v_mfma_f32_16x16x32_bf16 v[36:39], v[184:187], v[224:227], v[36:39]
	v_mfma_f32_16x16x32_bf16 v[32:35], v[192:195], v[224:227], v[32:35]
	s_setprio 0
	s_barrier
	v_readfirstlane_b32 s29, v163
	v_add_u32_e32 v179, 0x2000, v163
	v_lshl_add_u64 v[180:181], v[248:249], 0, s[18:19]
	s_mov_b32 m0, s29
	v_readfirstlane_b32 s29, v179
	global_load_lds_dwordx4 v[180:181], off
	v_lshl_add_u64 v[180:181], v[250:251], 0, s[18:19]
	s_mov_b32 m0, s29
	s_nop 0
	global_load_lds_dwordx4 v[180:181], off
	s_waitcnt vmcnt(6)
	s_barrier
	s_setprio 1
	v_mfma_f32_16x16x32_bf16 v[28:31], v[228:231], v[196:199], v[28:31]
	v_mfma_f32_16x16x32_bf16 v[24:27], v[236:239], v[196:199], v[24:27]
	v_mfma_f32_16x16x32_bf16 v[20:23], v[228:231], v[204:207], v[20:23]
	v_mfma_f32_16x16x32_bf16 v[16:19], v[236:239], v[204:207], v[16:19]
	v_mfma_f32_16x16x32_bf16 v[12:15], v[228:231], v[212:215], v[12:15]
	v_mfma_f32_16x16x32_bf16 v[8:11], v[236:239], v[212:215], v[8:11]
	v_mfma_f32_16x16x32_bf16 v[4:7], v[228:231], v[220:223], v[4:7]
	v_mfma_f32_16x16x32_bf16 v[0:3], v[236:239], v[220:223], v[0:3]
	v_mfma_f32_16x16x32_bf16 v[28:31], v[232:235], v[200:203], v[28:31]
	v_mfma_f32_16x16x32_bf16 v[24:27], v[240:243], v[200:203], v[24:27]
	v_mfma_f32_16x16x32_bf16 v[20:23], v[232:235], v[208:211], v[20:23]
	v_mfma_f32_16x16x32_bf16 v[16:19], v[240:243], v[208:211], v[16:19]
	v_mfma_f32_16x16x32_bf16 v[12:15], v[232:235], v[216:219], v[12:15]
	v_mfma_f32_16x16x32_bf16 v[8:11], v[240:243], v[216:219], v[8:11]
	v_mfma_f32_16x16x32_bf16 v[4:7], v[232:235], v[224:227], v[4:7]
	v_mfma_f32_16x16x32_bf16 v[0:3], v[240:243], v[224:227], v[0:3]
	s_setprio 0
	s_add_i32 s28, s28, 2
	v_lshl_add_u64 v[142:143], v[142:143], 0, s[20:21]
	v_lshl_add_u64 v[144:145], v[144:145], 0, s[20:21]
	v_lshl_add_u64 v[146:147], v[146:147], 0, s[20:21]
	s_cmp_lt_u32 s28, 28
	v_lshl_add_u64 v[148:149], v[148:149], 0, s[20:21]
	s_cbranch_scc1 .LBB0_916
	s_barrier
	s_or_b32 s28, s24, 0x80
	s_ashr_i32 s29, s28, 31
	s_lshl_b64 s[28:29], s[28:29], 12
	s_add_u32 s28, s90, s28
	s_addc_u32 s29, s91, s29
	v_lshl_add_u64 v[160:161], v[134:135], 1, s[28:29]
	v_lshl_add_u64 v[138:139], v[138:139], 1, v[160:161]
	v_readfirstlane_b32 s1, v177
	v_lshl_add_u64 v[138:139], v[138:139], 0, s[22:23]
	s_mov_b32 m0, s1
	ds_read_b128 v[142:145], v165
	ds_read_b128 v[146:149], v165 offset:1024
	ds_read_b128 v[180:183], v165 offset:2048
	ds_read_b128 v[184:187], v165 offset:3072
	ds_read_b128 v[188:191], v155
	ds_read_b128 v[192:195], v155 offset:1024
	ds_read_b128 v[196:199], v173
	ds_read_b128 v[200:203], v173 offset:1024
	ds_read_b128 v[204:207], v174
	ds_read_b128 v[208:211], v174 offset:1024
	ds_read_b128 v[212:215], v175
	ds_read_b128 v[216:219], v175 offset:1024
	global_load_lds_dwordx4 v[138:139], off
	v_lshl_add_u64 v[138:139], v[136:137], 1, s[28:29]
	v_lshl_add_u64 v[138:139], v[140:141], 1, v[138:139]
	v_readfirstlane_b32 s1, v178
	v_lshl_add_u64 v[138:139], v[138:139], 0, s[22:23]
	s_mov_b32 m0, s1
	s_nop 0
	global_load_lds_dwordx4 v[138:139], off
	s_barrier
	s_waitcnt lgkmcnt(0)
	s_setprio 1
	v_mfma_f32_16x16x32_bf16 v[124:127], v[142:145], v[188:191], v[124:127]
	v_mfma_f32_16x16x32_bf16 v[120:123], v[180:183], v[188:191], v[120:123]
	v_mfma_f32_16x16x32_bf16 v[116:119], v[142:145], v[196:199], v[116:119]
	v_mfma_f32_16x16x32_bf16 v[112:115], v[180:183], v[196:199], v[112:115]
	v_mfma_f32_16x16x32_bf16 v[104:107], v[180:183], v[204:207], v[104:107]
	v_mfma_f32_16x16x32_bf16 v[96:99], v[180:183], v[212:215], v[96:99]
	v_mfma_f32_16x16x32_bf16 v[124:127], v[146:149], v[192:195], v[124:127]
	v_mfma_f32_16x16x32_bf16 v[120:123], v[184:187], v[192:195], v[120:123]
	v_mfma_f32_16x16x32_bf16 v[116:119], v[146:149], v[200:203], v[116:119]
	v_mfma_f32_16x16x32_bf16 v[112:115], v[184:187], v[200:203], v[112:115]
	v_mfma_f32_16x16x32_bf16 v[108:111], v[142:145], v[204:207], v[108:111]
	v_mfma_f32_16x16x32_bf16 v[104:107], v[184:187], v[208:211], v[104:107]
	v_mfma_f32_16x16x32_bf16 v[100:103], v[142:145], v[212:215], v[100:103]
	v_mfma_f32_16x16x32_bf16 v[96:99], v[184:187], v[216:219], v[96:99]
	v_mfma_f32_16x16x32_bf16 v[138:141], v[146:149], v[208:211], v[108:111]
	v_mfma_f32_16x16x32_bf16 v[220:223], v[146:149], v[216:219], v[100:103]
	s_setprio 0
	s_barrier
; #define LDA(dst,b,h) _Pragma("unroll") for(int m=0;m<4;++m) _Pragma("unroll") for(int k=0;k<2;++k) \
;     dst[m][k]=*reinterpret_cast<const bf16x8*>((char*)SA(b,h)+lds_byte(wr*64+m*16+fr,k*32+fq*8))
; #define LDB(dst,b,h) _Pragma("unroll") for(int n=0;n<2;++n) _Pragma("unroll") for(int k=0;k<2;++k) \
;     dst[n][k]=*reinterpret_cast<const bf16x8*>((char*)SB(b,h)+lds_byte(wc*32+n*16+fr,k*32+fq*8))
; #define MMA(ai,bj,At_,Bt_) do{__builtin_amdgcn_s_setprio(1); \
;     _Pragma("unroll") for(int m=0;m<4;++m) _Pragma("unroll") for(int n=0;n<2;++n) _Pragma("unroll") for(int k=0;k<2;++k) \
;       acc[ai][bj][m][n]=__builtin_amdgcn_mfma_f32_16x16x32_bf16(Bt_[n][k],At_[m][k],acc[ai][bj][m][n],0,0,0); \
;     __builtin_amdgcn_s_setprio(0);}while(0)
; #define WAIT_V(n) asm volatile("s_waitcnt vmcnt(" #n ")":::"memory")
; #define WAIT_L(n) asm volatile("s_waitcnt lgkmcnt(" #n ")":::"memory")
; #define BAR __builtin_amdgcn_s_barrier()
; DEVINL void gemm8_mainloop(const u16* A, long lda, const u16* Bt, long ldb, int K, int brow, int bcol, f32x4 (&acc)[2][2][4][2], char* smem, int tid) {
;     ...
;     BAR; WAIT_L(0); MMA(0,0,At,B0); BAR;
;     LDB(B1,0,1); BAR; WAIT_L(0); MMA(0,1,At,B1); BAR;
;     LDA(At,0,1); WAIT_V(4); BAR; WAIT_L(0); MMA(1,0,At,B0); MMA(1,1,At,B1); BAR; }
;   { LDB(B0,1,0); LDA(At,1,0); WAIT_V(2); BAR; WAIT_L(0); MMA(0,0,At,B0); BAR;
	s_nop 2
	ds_read_b128 v[100:103], v162
	ds_read_b128 v[108:111], v162 offset:1024
	ds_read_b128 v[224:227], v162 offset:2048
	ds_read_b128 v[160:163], v162 offset:3072
	s_barrier
	s_waitcnt lgkmcnt(0)
	s_setprio 1
	v_mfma_f32_16x16x32_bf16 v[88:91], v[224:227], v[188:191], v[88:91]
	v_mfma_f32_16x16x32_bf16 v[80:83], v[224:227], v[196:199], v[80:83]
	v_mfma_f32_16x16x32_bf16 v[72:75], v[224:227], v[204:207], v[72:75]
	v_mfma_f32_16x16x32_bf16 v[64:67], v[224:227], v[212:215], v[64:67]
	v_mfma_f32_16x16x32_bf16 v[92:95], v[100:103], v[188:191], v[92:95]
	v_mfma_f32_16x16x32_bf16 v[88:91], v[160:163], v[192:195], v[88:91]
	v_mfma_f32_16x16x32_bf16 v[84:87], v[100:103], v[196:199], v[84:87]
	v_mfma_f32_16x16x32_bf16 v[80:83], v[160:163], v[200:203], v[80:83]
	v_mfma_f32_16x16x32_bf16 v[76:79], v[100:103], v[204:207], v[76:79]
	v_mfma_f32_16x16x32_bf16 v[72:75], v[160:163], v[208:211], v[72:75]
	v_mfma_f32_16x16x32_bf16 v[68:71], v[100:103], v[212:215], v[68:71]
	v_mfma_f32_16x16x32_bf16 v[64:67], v[160:163], v[216:219], v[64:67]
	v_mfma_f32_16x16x32_bf16 v[228:231], v[108:111], v[192:195], v[92:95]
	v_mfma_f32_16x16x32_bf16 v[188:191], v[108:111], v[200:203], v[84:87]
	v_mfma_f32_16x16x32_bf16 v[192:195], v[108:111], v[208:211], v[76:79]
	v_mfma_f32_16x16x32_bf16 v[196:199], v[108:111], v[216:219], v[68:71]
	s_setprio 0
	s_barrier
	s_nop 0
	ds_read_b128 v[68:71], v155 offset:16384
	ds_read_b128 v[76:79], v155 offset:17408
	ds_read_b128 v[84:87], v173 offset:16384
	ds_read_b128 v[92:95], v173 offset:17408
	ds_read_b128 v[200:203], v174 offset:16384
	ds_read_b128 v[204:207], v174 offset:17408
	ds_read_b128 v[208:211], v175 offset:16384
	ds_read_b128 v[212:215], v175 offset:17408
	s_waitcnt vmcnt(4)
	s_barrier
	s_waitcnt lgkmcnt(0)
	s_setprio 1
	v_mfma_f32_16x16x32_bf16 v[60:63], v[142:145], v[68:71], v[60:63]
	v_mfma_f32_16x16x32_bf16 v[56:59], v[180:183], v[68:71], v[56:59]
	v_mfma_f32_16x16x32_bf16 v[48:51], v[180:183], v[84:87], v[48:51]
	v_mfma_f32_16x16x32_bf16 v[40:43], v[180:183], v[200:203], v[40:43]
	v_mfma_f32_16x16x32_bf16 v[32:35], v[180:183], v[208:211], v[32:35]
	v_mfma_f32_16x16x32_bf16 v[60:63], v[146:149], v[76:79], v[60:63]
	v_mfma_f32_16x16x32_bf16 v[56:59], v[184:187], v[76:79], v[56:59]
	v_mfma_f32_16x16x32_bf16 v[52:55], v[142:145], v[84:87], v[52:55]
	v_mfma_f32_16x16x32_bf16 v[48:51], v[184:187], v[92:95], v[48:51]
	v_mfma_f32_16x16x32_bf16 v[44:47], v[142:145], v[200:203], v[44:47]
	v_mfma_f32_16x16x32_bf16 v[40:43], v[184:187], v[204:207], v[40:43]
	v_mfma_f32_16x16x32_bf16 v[36:39], v[142:145], v[208:211], v[36:39]
	v_mfma_f32_16x16x32_bf16 v[32:35], v[184:187], v[212:215], v[32:35]
	v_mfma_f32_16x16x32_bf16 v[216:219], v[146:149], v[92:95], v[52:55]
	v_mfma_f32_16x16x32_bf16 v[232:235], v[146:149], v[204:207], v[44:47]
	v_mfma_f32_16x16x32_bf16 v[142:145], v[146:149], v[212:215], v[36:39]
	s_setprio 0
	s_setprio 1
	v_mfma_f32_16x16x32_bf16 v[24:27], v[224:227], v[68:71], v[24:27]
	v_mfma_f32_16x16x32_bf16 v[16:19], v[224:227], v[84:87], v[16:19]
	v_mfma_f32_16x16x32_bf16 v[4:7], v[100:103], v[208:211], v[4:7]
	v_mfma_f32_16x16x32_bf16 v[0:3], v[224:227], v[208:211], v[0:3]
	v_mfma_f32_16x16x32_bf16 v[28:31], v[100:103], v[68:71], v[28:31]
	v_mfma_f32_16x16x32_bf16 v[24:27], v[160:163], v[76:79], v[24:27]
	v_mfma_f32_16x16x32_bf16 v[20:23], v[100:103], v[84:87], v[20:23]
	v_mfma_f32_16x16x32_bf16 v[16:19], v[160:163], v[92:95], v[16:19]
	v_mfma_f32_16x16x32_bf16 v[12:15], v[100:103], v[200:203], v[12:15]
	v_mfma_f32_16x16x32_bf16 v[8:11], v[224:227], v[200:203], v[8:11]
	v_mfma_f32_16x16x32_bf16 v[4:7], v[108:111], v[212:215], v[4:7]
	v_mfma_f32_16x16x32_bf16 v[0:3], v[160:163], v[212:215], v[0:3]
	v_mfma_f32_16x16x32_bf16 v[146:149], v[108:111], v[76:79], v[28:31]
	v_mfma_f32_16x16x32_bf16 v[178:181], v[108:111], v[92:95], v[20:23]
	v_mfma_f32_16x16x32_bf16 v[182:185], v[108:111], v[204:207], v[12:15]
	v_mfma_f32_16x16x32_bf16 v[200:203], v[160:163], v[204:207], v[8:11]
	s_setprio 0
	s_barrier
	s_nop 0
	ds_read_b128 v[8:11], v158
	ds_read_b128 v[12:15], v158 offset:1024
	ds_read_b128 v[160:163], v158 offset:2048
	ds_read_b128 v[204:207], v158 offset:3072
	ds_read_b128 v[20:23], v155 offset:32768
	ds_read_b128 v[28:31], v155 offset:33792
	ds_read_b128 v[36:39], v173 offset:32768
	ds_read_b128 v[44:47], v173 offset:33792
	ds_read_b128 v[52:55], v174 offset:32768
	ds_read_b128 v[208:211], v174 offset:33792
	ds_read_b128 v[212:215], v175 offset:32768
	ds_read_b128 v[224:227], v175 offset:33792
	s_waitcnt vmcnt(2)
	s_barrier
; #define LDA(dst,b,h) _Pragma("unroll") for(int m=0;m<4;++m) _Pragma("unroll") for(int k=0;k<2;++k) \
;     dst[m][k]=*reinterpret_cast<const bf16x8*>((char*)SA(b,h)+lds_byte(wr*64+m*16+fr,k*32+fq*8))
; #define LDB(dst,b,h) _Pragma("unroll") for(int n=0;n<2;++n) _Pragma("unroll") for(int k=0;k<2;++k) \
;     dst[n][k]=*reinterpret_cast<const bf16x8*>((char*)SB(b,h)+lds_byte(wc*32+n*16+fr,k*32+fq*8))
; #define MMA(ai,bj,At_,Bt_) do{__builtin_amdgcn_s_setprio(1); \
;     _Pragma("unroll") for(int m=0;m<4;++m) _Pragma("unroll") for(int n=0;n<2;++n) _Pragma("unroll") for(int k=0;k<2;++k) \
;       acc[ai][bj][m][n]=__builtin_amdgcn_mfma_f32_16x16x32_bf16(Bt_[n][k],At_[m][k],acc[ai][bj][m][n],0,0,0); \
;     __builtin_amdgcn_s_setprio(0);}while(0)
; #define WAIT_V(n) asm volatile("s_waitcnt vmcnt(" #n ")":::"memory")
; #define WAIT_L(n) asm volatile("s_waitcnt lgkmcnt(" #n ")":::"memory")
; #define BAR __builtin_amdgcn_s_barrier()
; DEVINL void gemm8_mainloop(const u16* A, long lda, const u16* Bt, long ldb, int K, int brow, int bcol, f32x4 (&acc)[2][2][4][2], char* smem, int tid) {
;     ...
;   { LDB(B0,1,0); LDA(At,1,0); WAIT_V(2); BAR; WAIT_L(0); MMA(0,0,At,B0); BAR;
;     LDB(B1,1,1); WAIT_V(0); BAR; WAIT_L(0); MMA(0,1,At,B1); BAR;
;     LDA(At,1,1); BAR; WAIT_L(0); MMA(1,0,At,B0); MMA(1,1,At,B1); BAR; }
;   if(wr==0)BAR;
;   __syncthreads();
	s_waitcnt lgkmcnt(0)
	s_setprio 1
	v_mfma_f32_16x16x32_bf16 v[68:71], v[8:11], v[20:23], v[124:127]
	v_mfma_f32_16x16x32_bf16 v[124:127], v[12:15], v[28:31], v[68:71]
	v_mfma_f32_16x16x32_bf16 v[68:71], v[160:163], v[20:23], v[120:123]
	v_mfma_f32_16x16x32_bf16 v[120:123], v[204:207], v[28:31], v[68:71]
	v_mfma_f32_16x16x32_bf16 v[68:71], v[8:11], v[36:39], v[116:119]
	v_mfma_f32_16x16x32_bf16 v[108:111], v[12:15], v[44:47], v[68:71]
	v_mfma_f32_16x16x32_bf16 v[68:71], v[160:163], v[36:39], v[112:115]
	v_mfma_f32_16x16x32_bf16 v[100:103], v[204:207], v[44:47], v[68:71]
	v_mfma_f32_16x16x32_bf16 v[68:71], v[8:11], v[52:55], v[138:141]
	v_mfma_f32_16x16x32_bf16 v[92:95], v[12:15], v[208:211], v[68:71]
	v_mfma_f32_16x16x32_bf16 v[68:71], v[160:163], v[52:55], v[104:107]
	v_mfma_f32_16x16x32_bf16 v[84:87], v[204:207], v[208:211], v[68:71]
	v_mfma_f32_16x16x32_bf16 v[68:71], v[8:11], v[212:215], v[220:223]
	v_mfma_f32_16x16x32_bf16 v[76:79], v[12:15], v[224:227], v[68:71]
	v_mfma_f32_16x16x32_bf16 v[68:71], v[160:163], v[212:215], v[96:99]
	v_mfma_f32_16x16x32_bf16 v[68:71], v[204:207], v[224:227], v[68:71]
	s_setprio 0
	s_barrier
	ds_read_b128 v[138:141], v156
	ds_read_b128 v[220:223], v156 offset:1024
	ds_read_b128 v[236:239], v156 offset:2048
	ds_read_b128 v[156:159], v156 offset:3072
	s_waitcnt vmcnt(0)
	s_barrier
	s_waitcnt lgkmcnt(0)
	s_setprio 1
	v_mfma_f32_16x16x32_bf16 v[96:99], v[138:141], v[20:23], v[228:231]
	v_mfma_f32_16x16x32_bf16 v[20:23], v[236:239], v[20:23], v[88:91]
	v_mfma_f32_16x16x32_bf16 v[112:115], v[156:159], v[28:31], v[20:23]
	v_mfma_f32_16x16x32_bf16 v[20:23], v[138:141], v[36:39], v[188:191]
	v_mfma_f32_16x16x32_bf16 v[104:107], v[220:223], v[44:47], v[20:23]
	v_mfma_f32_16x16x32_bf16 v[20:23], v[236:239], v[36:39], v[80:83]
	v_mfma_f32_16x16x32_bf16 v[116:119], v[220:223], v[28:31], v[96:99]
	v_mfma_f32_16x16x32_bf16 v[96:99], v[156:159], v[44:47], v[20:23]
	v_mfma_f32_16x16x32_bf16 v[20:23], v[138:141], v[52:55], v[192:195]
	v_mfma_f32_16x16x32_bf16 v[88:91], v[220:223], v[208:211], v[20:23]
	v_mfma_f32_16x16x32_bf16 v[20:23], v[236:239], v[52:55], v[72:75]
	v_mfma_f32_16x16x32_bf16 v[80:83], v[156:159], v[208:211], v[20:23]
	v_mfma_f32_16x16x32_bf16 v[20:23], v[138:141], v[212:215], v[196:199]
	v_mfma_f32_16x16x32_bf16 v[72:75], v[220:223], v[224:227], v[20:23]
	v_mfma_f32_16x16x32_bf16 v[20:23], v[236:239], v[212:215], v[64:67]
	v_mfma_f32_16x16x32_bf16 v[64:67], v[156:159], v[224:227], v[20:23]
	s_setprio 0
	s_barrier
	ds_read_b128 v[186:189], v155 offset:49152
	ds_read_b128 v[190:193], v155 offset:50176
	ds_read_b128 v[194:197], v173 offset:49152
	ds_read_b128 v[208:211], v173 offset:50176
	ds_read_b128 v[212:215], v174 offset:49152
	ds_read_b128 v[224:227], v174 offset:50176
	ds_read_b128 v[228:231], v175 offset:49152
	ds_read_b128 v[240:243], v175 offset:50176
	s_barrier
	s_waitcnt lgkmcnt(0)
	s_setprio 1
	v_mfma_f32_16x16x32_bf16 v[20:23], v[8:11], v[186:189], v[60:63]
	v_mfma_f32_16x16x32_bf16 v[60:63], v[12:15], v[190:193], v[20:23]
	v_mfma_f32_16x16x32_bf16 v[20:23], v[160:163], v[186:189], v[56:59]
	v_mfma_f32_16x16x32_bf16 v[52:55], v[204:207], v[190:193], v[20:23]
	v_mfma_f32_16x16x32_bf16 v[20:23], v[8:11], v[194:197], v[216:219]
	v_mfma_f32_16x16x32_bf16 v[44:47], v[12:15], v[208:211], v[20:23]
	v_mfma_f32_16x16x32_bf16 v[20:23], v[160:163], v[194:197], v[48:51]
	v_mfma_f32_16x16x32_bf16 v[36:39], v[204:207], v[208:211], v[20:23]
	v_mfma_f32_16x16x32_bf16 v[20:23], v[8:11], v[212:215], v[232:235]
	v_mfma_f32_16x16x32_bf16 v[8:11], v[8:11], v[228:231], v[142:145]
	v_mfma_f32_16x16x32_bf16 v[28:31], v[12:15], v[224:227], v[20:23]
	v_mfma_f32_16x16x32_bf16 v[20:23], v[160:163], v[212:215], v[40:43]
	v_mfma_f32_16x16x32_bf16 v[12:15], v[12:15], v[240:243], v[8:11]
	v_mfma_f32_16x16x32_bf16 v[8:11], v[160:163], v[228:231], v[32:35]
	v_mfma_f32_16x16x32_bf16 v[20:23], v[204:207], v[224:227], v[20:23]
	v_mfma_f32_16x16x32_bf16 v[8:11], v[204:207], v[240:243], v[8:11]
	s_setprio 0
	s_setprio 1
	v_mfma_f32_16x16x32_bf16 v[32:35], v[138:141], v[186:189], v[146:149]
	v_mfma_f32_16x16x32_bf16 v[24:27], v[236:239], v[186:189], v[24:27]
	v_mfma_f32_16x16x32_bf16 v[16:19], v[236:239], v[194:197], v[16:19]
	v_mfma_f32_16x16x32_bf16 v[56:59], v[220:223], v[190:193], v[32:35]
	v_mfma_f32_16x16x32_bf16 v[48:51], v[156:159], v[190:193], v[24:27]
	v_mfma_f32_16x16x32_bf16 v[24:27], v[138:141], v[194:197], v[178:181]
	v_mfma_f32_16x16x32_bf16 v[32:35], v[156:159], v[208:211], v[16:19]
	v_mfma_f32_16x16x32_bf16 v[16:19], v[138:141], v[212:215], v[182:185]
	v_mfma_f32_16x16x32_bf16 v[40:43], v[220:223], v[208:211], v[24:27]
	v_mfma_f32_16x16x32_bf16 v[24:27], v[220:223], v[224:227], v[16:19]
	v_mfma_f32_16x16x32_bf16 v[16:19], v[236:239], v[212:215], v[200:203]
	v_mfma_f32_16x16x32_bf16 v[4:7], v[138:141], v[228:231], v[4:7]
	v_mfma_f32_16x16x32_bf16 v[0:3], v[236:239], v[228:231], v[0:3]
	v_mfma_f32_16x16x32_bf16 v[16:19], v[156:159], v[224:227], v[16:19]
	v_mfma_f32_16x16x32_bf16 v[4:7], v[220:223], v[240:243], v[4:7]
	v_mfma_f32_16x16x32_bf16 v[0:3], v[156:159], v[240:243], v[0:3]
	s_setprio 0
	s_cmpk_gt_u32 s0, 0xff
	s_barrier
	s_cbranch_scc1 .LBB0_919
	s_barrier

; #define STAGE(P,BASE,LD,br,kt) do{long _g=(long)(br)*(LD)+(long)(kt)*BK; \
;     _Pragma("unroll") for(int _i=0;_i<2;++_i){int _b=tid*16+_i*8192;int _r,_c;stage_rc(_b,_r,_c); \
;       __builtin_amdgcn_global_load_lds((const unsigned*)((BASE)+_g+(long)_r*(LD)+_c), \
;         (unsigned*)((char*)(P)+_b),16,0,0);}}while(0)
; #define STAGE(P,BASE,LD,br,kt) do{long _g=(long)(br)*(LD)+(long)(kt)*BK; \
;     _Pragma("unroll") for(int _i=0;_i<2;++_i){int _b=tid*16+_i*8192;int _r,_c;stage_rc(_b,_r,_c); \
;       __builtin_amdgcn_global_load_lds((const unsigned*)((BASE)+_g+(long)_r*(LD)+_c), \
;         (unsigned*)((char*)(P)+_b),16,0,0);}}while(0)
; #define LDA(dst,b,h) _Pragma("unroll") for(int m=0;m<4;++m) _Pragma("unroll") for(int k=0;k<2;++k) \
;     dst[m][k]=*reinterpret_cast<const bf16x8*>((char*)SA(b,h)+lds_byte(wr*64+m*16+fr,k*32+fq*8))
; #define LDB(dst,b,h) _Pragma("unroll") for(int n=0;n<2;++n) _Pragma("unroll") for(int k=0;k<2;++k) \
;     dst[n][k]=*reinterpret_cast<const bf16x8*>((char*)SB(b,h)+lds_byte(wc*32+n*16+fr,k*32+fq*8))
; #define MMA(ai,bj,At_,Bt_) do{__builtin_amdgcn_s_setprio(1); \
;     _Pragma("unroll") for(int m=0;m<4;++m) _Pragma("unroll") for(int n=0;n<2;++n) _Pragma("unroll") for(int k=0;k<2;++k) \
;       acc[ai][bj][m][n]=__builtin_amdgcn_mfma_f32_16x16x32_bf16(Bt_[n][k],At_[m][k],acc[ai][bj][m][n],0,0,0); \
;     __builtin_amdgcn_s_setprio(0);}while(0)
; #define WAIT_L(n) asm volatile("s_waitcnt lgkmcnt(" #n ")":::"memory")
; #define BAR __builtin_amdgcn_s_barrier()
; #define SCHED __builtin_amdgcn_sched_barrier(0)
; DEVINL void gemm8_mainloop(const u16* A, long lda, const u16* Bt, long ldb, int K, int brow, int bcol, f32x4 (&acc)[2][2][4][2], char* smem, int tid) {
;     ...
;   for(int t=0;t<nt-2;t+=2){
;     LDB(B0,0,0); SCHED; LDA(At,0,0); STAGE(SA(1,1),A,lda,brow+HALF,t+1);
;     WAIT_L(8); BAR; WAIT_L(0); MMA(0,0,At,B0); BAR; SCHED;
;     LDB(B1,0,1); STAGE(SB(0,0),Bt,ldb,bcol,t+2);
;     BAR; WAIT_L(0); MMA(0,1,At,B1); BAR;
;     LDA(At,0,1); STAGE(SA(0,0),A,lda,brow,t+2);
;     BAR; WAIT_L(0); MMA(1,0,At,B0); BAR; SCHED;
.LBB0_965:
	s_barrier
	ds_read_b128 v[178:181], v163
	ds_read_b128 v[182:185], v163 offset:1024
	ds_read_b128 v[186:189], v163 offset:2048
	ds_read_b128 v[190:193], v163 offset:3072
	v_add_u32_e32 v174, 0xc000, v152
	v_lshl_add_u64 v[242:243], s[94:95], 0, v[146:147]
	v_readfirstlane_b32 s25, v174
	v_add_u32_e32 v175, 0xe000, v152
	v_add_u32_e32 v171, s0, v162
	v_add_u32_e32 v172, s1, v162
	v_add_u32_e32 v173, s27, v162
	v_lshl_add_u64 v[164:165], v[242:243], 0, s[4:5]
	s_mov_b32 m0, s25
	v_lshl_add_u64 v[244:245], s[94:95], 0, v[148:149]
	v_readfirstlane_b32 s25, v175
	ds_read_b128 v[166:169], v153
	ds_read_b128 v[194:197], v153 offset:1024
	ds_read_b128 v[198:201], v171
	ds_read_b128 v[202:205], v171 offset:1024
	ds_read_b128 v[206:209], v172
	ds_read_b128 v[210:213], v172 offset:1024
	ds_read_b128 v[214:217], v173
	ds_read_b128 v[218:221], v173 offset:1024
	global_load_lds_dwordx4 v[164:165], off
	v_lshl_add_u64 v[164:165], v[244:245], 0, s[4:5]
	s_mov_b32 m0, s25
	s_nop 0
	global_load_lds_dwordx4 v[164:165], off
	s_waitcnt lgkmcnt(8)
	s_barrier
	s_waitcnt lgkmcnt(0)
	s_setprio 1
	v_mfma_f32_16x16x32_bf16 v[124:127], v[178:181], v[166:169], v[124:127]
	v_mfma_f32_16x16x32_bf16 v[120:123], v[186:189], v[166:169], v[120:123]
	v_mfma_f32_16x16x32_bf16 v[116:119], v[178:181], v[198:201], v[116:119]
	v_mfma_f32_16x16x32_bf16 v[112:115], v[186:189], v[198:201], v[112:115]
	v_mfma_f32_16x16x32_bf16 v[108:111], v[178:181], v[206:209], v[108:111]
	v_mfma_f32_16x16x32_bf16 v[104:107], v[186:189], v[206:209], v[104:107]
	v_mfma_f32_16x16x32_bf16 v[100:103], v[178:181], v[214:217], v[100:103]
	v_mfma_f32_16x16x32_bf16 v[96:99], v[186:189], v[214:217], v[96:99]
	v_mfma_f32_16x16x32_bf16 v[124:127], v[182:185], v[194:197], v[124:127]
	v_mfma_f32_16x16x32_bf16 v[120:123], v[190:193], v[194:197], v[120:123]
	v_mfma_f32_16x16x32_bf16 v[116:119], v[182:185], v[202:205], v[116:119]
	v_mfma_f32_16x16x32_bf16 v[112:115], v[190:193], v[202:205], v[112:115]
	v_mfma_f32_16x16x32_bf16 v[108:111], v[182:185], v[210:213], v[108:111]
	v_mfma_f32_16x16x32_bf16 v[104:107], v[190:193], v[210:213], v[104:107]
	v_mfma_f32_16x16x32_bf16 v[100:103], v[182:185], v[218:221], v[100:103]
	v_mfma_f32_16x16x32_bf16 v[96:99], v[190:193], v[218:221], v[96:99]
	s_setprio 0
	s_barrier
	v_add_u32_e32 v164, s30, v154
	v_lshl_add_u64 v[246:247], s[94:95], 0, v[142:143]
	v_readfirstlane_b32 s25, v164
	v_add_u32_e32 v165, 0x2000, v164
	v_lshl_add_u64 v[238:239], v[246:247], 0, s[6:7]
	s_mov_b32 m0, s25
	v_lshl_add_u64 v[248:249], s[94:95], 0, v[144:145]
	v_readfirstlane_b32 s25, v165
	ds_read_b128 v[222:225], v160
	ds_read_b128 v[226:229], v160 offset:1024
	ds_read_b128 v[230:233], v160 offset:2048
	ds_read_b128 v[234:237], v160 offset:3072
	global_load_lds_dwordx4 v[238:239], off
	v_lshl_add_u64 v[238:239], v[248:249], 0, s[6:7]
	s_mov_b32 m0, s25
	s_nop 0
	global_load_lds_dwordx4 v[238:239], off
	s_barrier
	s_waitcnt lgkmcnt(0)
	s_setprio 1
	v_mfma_f32_16x16x32_bf16 v[92:95], v[222:225], v[166:169], v[92:95]
	v_mfma_f32_16x16x32_bf16 v[88:91], v[230:233], v[166:169], v[88:91]
	v_mfma_f32_16x16x32_bf16 v[84:87], v[222:225], v[198:201], v[84:87]
	v_mfma_f32_16x16x32_bf16 v[80:83], v[230:233], v[198:201], v[80:83]
	v_mfma_f32_16x16x32_bf16 v[76:79], v[222:225], v[206:209], v[76:79]
	v_mfma_f32_16x16x32_bf16 v[72:75], v[230:233], v[206:209], v[72:75]
	v_mfma_f32_16x16x32_bf16 v[68:71], v[222:225], v[214:217], v[68:71]
	v_mfma_f32_16x16x32_bf16 v[64:67], v[230:233], v[214:217], v[64:67]
	v_mfma_f32_16x16x32_bf16 v[92:95], v[226:229], v[194:197], v[92:95]
	v_mfma_f32_16x16x32_bf16 v[88:91], v[234:237], v[194:197], v[88:91]
	v_mfma_f32_16x16x32_bf16 v[84:87], v[226:229], v[202:205], v[84:87]
	v_mfma_f32_16x16x32_bf16 v[80:83], v[234:237], v[202:205], v[80:83]
	v_mfma_f32_16x16x32_bf16 v[76:79], v[226:229], v[210:213], v[76:79]
	v_mfma_f32_16x16x32_bf16 v[72:75], v[234:237], v[210:213], v[72:75]
	v_mfma_f32_16x16x32_bf16 v[68:71], v[226:229], v[218:221], v[68:71]
	v_mfma_f32_16x16x32_bf16 v[64:67], v[234:237], v[218:221], v[64:67]
	s_setprio 0
	v_readfirstlane_b32 s25, v152
	v_lshl_add_u64 v[166:167], v[242:243], 0, s[8:9]
	s_mov_b32 m0, s25
	s_barrier
	ds_read_b128 v[194:197], v153 offset:16384
	ds_read_b128 v[198:201], v153 offset:17408
	ds_read_b128 v[202:205], v171 offset:16384
	ds_read_b128 v[206:209], v171 offset:17408
	ds_read_b128 v[210:213], v172 offset:16384
	ds_read_b128 v[214:217], v172 offset:17408
	ds_read_b128 v[218:221], v173 offset:16384
	ds_read_b128 v[238:241], v173 offset:17408
	global_load_lds_dwordx4 v[166:167], off
	v_add_u32_e32 v166, 0x2000, v152
	v_lshl_add_u64 v[168:169], v[244:245], 0, s[8:9]
	v_readfirstlane_b32 s25, v166
	s_mov_b32 m0, s25
	s_nop 0
	global_load_lds_dwordx4 v[168:169], off
	s_barrier
	s_waitcnt lgkmcnt(0)
	s_setprio 1
	v_mfma_f32_16x16x32_bf16 v[60:63], v[178:181], v[194:197], v[60:63]
	v_mfma_f32_16x16x32_bf16 v[56:59], v[186:189], v[194:197], v[56:59]
	v_mfma_f32_16x16x32_bf16 v[52:55], v[178:181], v[202:205], v[52:55]
	v_mfma_f32_16x16x32_bf16 v[48:51], v[186:189], v[202:205], v[48:51]
	v_mfma_f32_16x16x32_bf16 v[44:47], v[178:181], v[210:213], v[44:47]
	v_mfma_f32_16x16x32_bf16 v[40:43], v[186:189], v[210:213], v[40:43]
	v_mfma_f32_16x16x32_bf16 v[36:39], v[178:181], v[218:221], v[36:39]
	v_mfma_f32_16x16x32_bf16 v[32:35], v[186:189], v[218:221], v[32:35]
	v_mfma_f32_16x16x32_bf16 v[60:63], v[182:185], v[198:201], v[60:63]
	v_mfma_f32_16x16x32_bf16 v[56:59], v[190:193], v[198:201], v[56:59]
	v_mfma_f32_16x16x32_bf16 v[52:55], v[182:185], v[206:209], v[52:55]
	v_mfma_f32_16x16x32_bf16 v[48:51], v[190:193], v[206:209], v[48:51]
	v_mfma_f32_16x16x32_bf16 v[44:47], v[182:185], v[214:217], v[44:47]
	v_mfma_f32_16x16x32_bf16 v[40:43], v[190:193], v[214:217], v[40:43]
	v_mfma_f32_16x16x32_bf16 v[36:39], v[182:185], v[238:241], v[36:39]
	v_mfma_f32_16x16x32_bf16 v[32:35], v[190:193], v[238:241], v[32:35]
	s_setprio 0
	s_barrier
; #define STAGE(P,BASE,LD,br,kt) do{long _g=(long)(br)*(LD)+(long)(kt)*BK; \
;     _Pragma("unroll") for(int _i=0;_i<2;++_i){int _b=tid*16+_i*8192;int _r,_c;stage_rc(_b,_r,_c); \
;       __builtin_amdgcn_global_load_lds((const unsigned*)((BASE)+_g+(long)_r*(LD)+_c), \
;         (unsigned*)((char*)(P)+_b),16,0,0);}}while(0)
; #define STAGE(P,BASE,LD,br,kt) do{long _g=(long)(br)*(LD)+(long)(kt)*BK; \
;     _Pragma("unroll") for(int _i=0;_i<2;++_i){int _b=tid*16+_i*8192;int _r,_c;stage_rc(_b,_r,_c); \
;       __builtin_amdgcn_global_load_lds((const unsigned*)((BASE)+_g+(long)_r*(LD)+_c), \
;         (unsigned*)((char*)(P)+_b),16,0,0);}}while(0)
; #define LDA(dst,b,h) _Pragma("unroll") for(int m=0;m<4;++m) _Pragma("unroll") for(int k=0;k<2;++k) \
;     dst[m][k]=*reinterpret_cast<const bf16x8*>((char*)SA(b,h)+lds_byte(wr*64+m*16+fr,k*32+fq*8))
; #define LDB(dst,b,h) _Pragma("unroll") for(int n=0;n<2;++n) _Pragma("unroll") for(int k=0;k<2;++k) \
;     dst[n][k]=*reinterpret_cast<const bf16x8*>((char*)SB(b,h)+lds_byte(wc*32+n*16+fr,k*32+fq*8))
; #define MMA(ai,bj,At_,Bt_) do{__builtin_amdgcn_s_setprio(1); \
;     _Pragma("unroll") for(int m=0;m<4;++m) _Pragma("unroll") for(int n=0;n<2;++n) _Pragma("unroll") for(int k=0;k<2;++k) \
;       acc[ai][bj][m][n]=__builtin_amdgcn_mfma_f32_16x16x32_bf16(Bt_[n][k],At_[m][k],acc[ai][bj][m][n],0,0,0); \
;     __builtin_amdgcn_s_setprio(0);}while(0)
; #define WAIT_V(n) asm volatile("s_waitcnt vmcnt(" #n ")":::"memory")
; #define WAIT_L(n) asm volatile("s_waitcnt lgkmcnt(" #n ")":::"memory")
; #define BAR __builtin_amdgcn_s_barrier()
; #define SCHED __builtin_amdgcn_sched_barrier(0)
; DEVINL void gemm8_mainloop(const u16* A, long lda, const u16* Bt, long ldb, int K, int brow, int bcol, f32x4 (&acc)[2][2][4][2], char* smem, int tid) {
;     ...
;     STAGE(SB(0,1),Bt,ldb,bcol+HALF,t+2);
;     WAIT_V(6); BAR; MMA(1,1,At,B1); BAR;
;     LDB(B0,1,0); SCHED; LDA(At,1,0); STAGE(SA(0,1),A,lda,brow+HALF,t+2);
;     WAIT_L(8); BAR; WAIT_L(0); MMA(0,0,At,B0); BAR; SCHED;
;     LDB(B1,1,1); STAGE(SB(1,0),Bt,ldb,bcol,t+3);
;     BAR; WAIT_L(0); MMA(0,1,At,B1); BAR;
;     LDA(At,1,1); STAGE(SA(1,0),A,lda,brow,t+3);
	v_add_u32_e32 v167, s31, v154
	v_lshl_add_u64 v[168:169], v[246:247], 0, s[10:11]
	v_readfirstlane_b32 s25, v167
	s_mov_b32 m0, s25
	v_lshl_add_u64 v[178:179], v[248:249], 0, s[10:11]
	global_load_lds_dwordx4 v[168:169], off
	v_add_u32_e32 v168, 0x2000, v167
	s_nop 0
	v_readfirstlane_b32 s25, v168
	s_mov_b32 m0, s25
	s_nop 0
	global_load_lds_dwordx4 v[178:179], off
	s_waitcnt vmcnt(6)
	s_barrier
	s_setprio 1
	v_mfma_f32_16x16x32_bf16 v[28:31], v[222:225], v[194:197], v[28:31]
	v_mfma_f32_16x16x32_bf16 v[24:27], v[230:233], v[194:197], v[24:27]
	v_mfma_f32_16x16x32_bf16 v[20:23], v[222:225], v[202:205], v[20:23]
	v_mfma_f32_16x16x32_bf16 v[16:19], v[230:233], v[202:205], v[16:19]
	v_mfma_f32_16x16x32_bf16 v[12:15], v[222:225], v[210:213], v[12:15]
	v_mfma_f32_16x16x32_bf16 v[8:11], v[230:233], v[210:213], v[8:11]
	v_mfma_f32_16x16x32_bf16 v[4:7], v[222:225], v[218:221], v[4:7]
	v_mfma_f32_16x16x32_bf16 v[0:3], v[230:233], v[218:221], v[0:3]
	v_mfma_f32_16x16x32_bf16 v[28:31], v[226:229], v[198:201], v[28:31]
	v_mfma_f32_16x16x32_bf16 v[24:27], v[234:237], v[198:201], v[24:27]
	v_mfma_f32_16x16x32_bf16 v[20:23], v[226:229], v[206:209], v[20:23]
	v_mfma_f32_16x16x32_bf16 v[16:19], v[234:237], v[206:209], v[16:19]
	v_mfma_f32_16x16x32_bf16 v[12:15], v[226:229], v[214:217], v[12:15]
	v_mfma_f32_16x16x32_bf16 v[8:11], v[234:237], v[214:217], v[8:11]
	v_mfma_f32_16x16x32_bf16 v[4:7], v[226:229], v[238:241], v[4:7]
	v_mfma_f32_16x16x32_bf16 v[0:3], v[234:237], v[238:241], v[0:3]
	s_setprio 0
	s_barrier
	ds_read_b128 v[178:181], v157
	ds_read_b128 v[182:185], v157 offset:1024
	ds_read_b128 v[186:189], v157 offset:2048
	ds_read_b128 v[190:193], v157 offset:3072
	v_add_u32_e32 v169, 0x4000, v152
	v_add_u32_e32 v170, 0x6000, v152
	v_readfirstlane_b32 s25, v169
	v_lshl_add_u64 v[226:227], v[242:243], 0, s[12:13]
	s_mov_b32 m0, s25
	v_readfirstlane_b32 s25, v170
	ds_read_b128 v[194:197], v153 offset:32768
	ds_read_b128 v[198:201], v153 offset:33792
	ds_read_b128 v[202:205], v171 offset:32768
	ds_read_b128 v[206:209], v171 offset:33792
	ds_read_b128 v[210:213], v172 offset:32768
	ds_read_b128 v[214:217], v172 offset:33792
	ds_read_b128 v[218:221], v173 offset:32768
	ds_read_b128 v[222:225], v173 offset:33792
	global_load_lds_dwordx4 v[226:227], off
	v_lshl_add_u64 v[226:227], v[244:245], 0, s[12:13]
	s_mov_b32 m0, s25
	s_nop 0
	global_load_lds_dwordx4 v[226:227], off
	s_waitcnt lgkmcnt(8)
	s_barrier
	s_waitcnt lgkmcnt(0)
	s_setprio 1
	v_mfma_f32_16x16x32_bf16 v[124:127], v[178:181], v[194:197], v[124:127]
	v_mfma_f32_16x16x32_bf16 v[120:123], v[186:189], v[194:197], v[120:123]
	v_mfma_f32_16x16x32_bf16 v[116:119], v[178:181], v[202:205], v[116:119]
	v_mfma_f32_16x16x32_bf16 v[112:115], v[186:189], v[202:205], v[112:115]
	v_mfma_f32_16x16x32_bf16 v[108:111], v[178:181], v[210:213], v[108:111]
	v_mfma_f32_16x16x32_bf16 v[104:107], v[186:189], v[210:213], v[104:107]
	v_mfma_f32_16x16x32_bf16 v[100:103], v[178:181], v[218:221], v[100:103]
	v_mfma_f32_16x16x32_bf16 v[96:99], v[186:189], v[218:221], v[96:99]
	v_mfma_f32_16x16x32_bf16 v[124:127], v[182:185], v[198:201], v[124:127]
	v_mfma_f32_16x16x32_bf16 v[120:123], v[190:193], v[198:201], v[120:123]
	v_mfma_f32_16x16x32_bf16 v[116:119], v[182:185], v[206:209], v[116:119]
	v_mfma_f32_16x16x32_bf16 v[112:115], v[190:193], v[206:209], v[112:115]
	v_mfma_f32_16x16x32_bf16 v[108:111], v[182:185], v[214:217], v[108:111]
	v_mfma_f32_16x16x32_bf16 v[104:107], v[190:193], v[214:217], v[104:107]
	v_mfma_f32_16x16x32_bf16 v[100:103], v[182:185], v[222:225], v[100:103]
	v_mfma_f32_16x16x32_bf16 v[96:99], v[190:193], v[222:225], v[96:99]
	s_setprio 0
	s_barrier
	v_readfirstlane_b32 s25, v156
	v_add_u32_e32 v177, 0x2000, v156
	v_lshl_add_u64 v[250:251], v[246:247], 0, s[14:15]
	s_mov_b32 m0, s25
	v_readfirstlane_b32 s25, v177
	ds_read_b128 v[226:229], v155
	ds_read_b128 v[230:233], v155 offset:1024
	ds_read_b128 v[234:237], v155 offset:2048
	ds_read_b128 v[238:241], v155 offset:3072
	global_load_lds_dwordx4 v[250:251], off
	v_lshl_add_u64 v[250:251], v[248:249], 0, s[14:15]
	s_mov_b32 m0, s25
	s_nop 0
	global_load_lds_dwordx4 v[250:251], off
	s_barrier
	s_waitcnt lgkmcnt(0)
	s_setprio 1
	v_mfma_f32_16x16x32_bf16 v[92:95], v[226:229], v[194:197], v[92:95]
	v_mfma_f32_16x16x32_bf16 v[88:91], v[234:237], v[194:197], v[88:91]
	v_mfma_f32_16x16x32_bf16 v[84:87], v[226:229], v[202:205], v[84:87]
	v_mfma_f32_16x16x32_bf16 v[80:83], v[234:237], v[202:205], v[80:83]
	v_mfma_f32_16x16x32_bf16 v[76:79], v[226:229], v[210:213], v[76:79]
	v_mfma_f32_16x16x32_bf16 v[72:75], v[234:237], v[210:213], v[72:75]
	v_mfma_f32_16x16x32_bf16 v[68:71], v[226:229], v[218:221], v[68:71]
	v_mfma_f32_16x16x32_bf16 v[64:67], v[234:237], v[218:221], v[64:67]
	v_mfma_f32_16x16x32_bf16 v[92:95], v[230:233], v[198:201], v[92:95]
	v_mfma_f32_16x16x32_bf16 v[88:91], v[238:241], v[198:201], v[88:91]
	v_mfma_f32_16x16x32_bf16 v[84:87], v[230:233], v[206:209], v[84:87]
	v_mfma_f32_16x16x32_bf16 v[80:83], v[238:241], v[206:209], v[80:83]
	v_mfma_f32_16x16x32_bf16 v[76:79], v[230:233], v[214:217], v[76:79]
	v_mfma_f32_16x16x32_bf16 v[72:75], v[238:241], v[214:217], v[72:75]
	v_mfma_f32_16x16x32_bf16 v[68:71], v[230:233], v[222:225], v[68:71]
	v_mfma_f32_16x16x32_bf16 v[64:67], v[238:241], v[222:225], v[64:67]
	s_setprio 0
	v_readfirstlane_b32 s25, v158
	v_lshl_add_u64 v[242:243], v[242:243], 0, s[16:17]
	s_mov_b32 m0, s25
	v_readfirstlane_b32 s25, v159
	s_barrier
; #define STAGE(P,BASE,LD,br,kt) do{long _g=(long)(br)*(LD)+(long)(kt)*BK; \
;     _Pragma("unroll") for(int _i=0;_i<2;++_i){int _b=tid*16+_i*8192;int _r,_c;stage_rc(_b,_r,_c); \
;       __builtin_amdgcn_global_load_lds((const unsigned*)((BASE)+_g+(long)_r*(LD)+_c), \
;         (unsigned*)((char*)(P)+_b),16,0,0);}}while(0)
; #define STAGE(P,BASE,LD,br,kt) do{long _g=(long)(br)*(LD)+(long)(kt)*BK; \
;     _Pragma("unroll") for(int _i=0;_i<2;++_i){int _b=tid*16+_i*8192;int _r,_c;stage_rc(_b,_r,_c); \
;       __builtin_amdgcn_global_load_lds((const unsigned*)((BASE)+_g+(long)_r*(LD)+_c), \
;         (unsigned*)((char*)(P)+_b),16,0,0);}}while(0)
; #define LDA(dst,b,h) _Pragma("unroll") for(int m=0;m<4;++m) _Pragma("unroll") for(int k=0;k<2;++k) \
;     dst[m][k]=*reinterpret_cast<const bf16x8*>((char*)SA(b,h)+lds_byte(wr*64+m*16+fr,k*32+fq*8))
; #define LDB(dst,b,h) _Pragma("unroll") for(int n=0;n<2;++n) _Pragma("unroll") for(int k=0;k<2;++k) \
;     dst[n][k]=*reinterpret_cast<const bf16x8*>((char*)SB(b,h)+lds_byte(wc*32+n*16+fr,k*32+fq*8))
; #define MMA(ai,bj,At_,Bt_) do{__builtin_amdgcn_s_setprio(1); \
;     _Pragma("unroll") for(int m=0;m<4;++m) _Pragma("unroll") for(int n=0;n<2;++n) _Pragma("unroll") for(int k=0;k<2;++k) \
;       acc[ai][bj][m][n]=__builtin_amdgcn_mfma_f32_16x16x32_bf16(Bt_[n][k],At_[m][k],acc[ai][bj][m][n],0,0,0); \
;     __builtin_amdgcn_s_setprio(0);}while(0)
; #define WAIT_V(n) asm volatile("s_waitcnt vmcnt(" #n ")":::"memory")
; #define WAIT_L(n) asm volatile("s_waitcnt lgkmcnt(" #n ")":::"memory")
; #define BAR __builtin_amdgcn_s_barrier()
; #define SCHED __builtin_amdgcn_sched_barrier(0)
; DEVINL void gemm8_mainloop(const u16* A, long lda, const u16* Bt, long ldb, int K, int brow, int bcol, f32x4 (&acc)[2][2][4][2], char* smem, int tid) {
;     ...
;     LDA(At,1,1); STAGE(SA(1,0),A,lda,brow,t+3);
;     BAR; WAIT_L(0); MMA(1,0,At,B0); BAR; SCHED;
;     STAGE(SB(1,1),Bt,ldb,bcol+HALF,t+3);
;     WAIT_V(6); BAR; MMA(1,1,At,B1); BAR;
;   }
;   { LDB(B0,0,0); LDA(At,0,0); STAGE(SA(1,1),A,lda,brow+HALF,nt-1);
;     BAR; WAIT_L(0); MMA(0,0,At,B0); BAR;
	ds_read_b128 v[194:197], v153 offset:49152
	ds_read_b128 v[198:201], v153 offset:50176
	ds_read_b128 v[202:205], v171 offset:49152
	ds_read_b128 v[206:209], v171 offset:50176
	ds_read_b128 v[210:213], v172 offset:49152
	ds_read_b128 v[214:217], v172 offset:50176
	ds_read_b128 v[218:221], v173 offset:49152
	ds_read_b128 v[222:225], v173 offset:50176
	global_load_lds_dwordx4 v[242:243], off
	v_lshl_add_u64 v[242:243], v[244:245], 0, s[16:17]
	s_mov_b32 m0, s25
	s_nop 0
	global_load_lds_dwordx4 v[242:243], off
	s_barrier
	s_waitcnt lgkmcnt(0)
	s_setprio 1
	v_mfma_f32_16x16x32_bf16 v[60:63], v[178:181], v[194:197], v[60:63]
	v_mfma_f32_16x16x32_bf16 v[56:59], v[186:189], v[194:197], v[56:59]
	v_mfma_f32_16x16x32_bf16 v[52:55], v[178:181], v[202:205], v[52:55]
	v_mfma_f32_16x16x32_bf16 v[48:51], v[186:189], v[202:205], v[48:51]
	v_mfma_f32_16x16x32_bf16 v[44:47], v[178:181], v[210:213], v[44:47]
	v_mfma_f32_16x16x32_bf16 v[40:43], v[186:189], v[210:213], v[40:43]
	v_mfma_f32_16x16x32_bf16 v[36:39], v[178:181], v[218:221], v[36:39]
	v_mfma_f32_16x16x32_bf16 v[32:35], v[186:189], v[218:221], v[32:35]
	v_mfma_f32_16x16x32_bf16 v[60:63], v[182:185], v[198:201], v[60:63]
	v_mfma_f32_16x16x32_bf16 v[56:59], v[190:193], v[198:201], v[56:59]
	v_mfma_f32_16x16x32_bf16 v[52:55], v[182:185], v[206:209], v[52:55]
	v_mfma_f32_16x16x32_bf16 v[48:51], v[190:193], v[206:209], v[48:51]
	v_mfma_f32_16x16x32_bf16 v[44:47], v[182:185], v[214:217], v[44:47]
	v_mfma_f32_16x16x32_bf16 v[40:43], v[190:193], v[214:217], v[40:43]
	v_mfma_f32_16x16x32_bf16 v[36:39], v[182:185], v[222:225], v[36:39]
	v_mfma_f32_16x16x32_bf16 v[32:35], v[190:193], v[222:225], v[32:35]
	s_setprio 0
	s_barrier
	v_readfirstlane_b32 s25, v161
	v_add_u32_e32 v177, 0x2000, v161
	v_lshl_add_u64 v[178:179], v[246:247], 0, s[18:19]
	s_mov_b32 m0, s25
	v_readfirstlane_b32 s25, v177
	global_load_lds_dwordx4 v[178:179], off
	v_lshl_add_u64 v[178:179], v[248:249], 0, s[18:19]
	s_mov_b32 m0, s25
	s_nop 0
	global_load_lds_dwordx4 v[178:179], off
	s_waitcnt vmcnt(6)
	s_barrier
	s_setprio 1
	v_mfma_f32_16x16x32_bf16 v[28:31], v[226:229], v[194:197], v[28:31]
	v_mfma_f32_16x16x32_bf16 v[24:27], v[234:237], v[194:197], v[24:27]
	v_mfma_f32_16x16x32_bf16 v[20:23], v[226:229], v[202:205], v[20:23]
	v_mfma_f32_16x16x32_bf16 v[16:19], v[234:237], v[202:205], v[16:19]
	v_mfma_f32_16x16x32_bf16 v[12:15], v[226:229], v[210:213], v[12:15]
	v_mfma_f32_16x16x32_bf16 v[8:11], v[234:237], v[210:213], v[8:11]
	v_mfma_f32_16x16x32_bf16 v[4:7], v[226:229], v[218:221], v[4:7]
	v_mfma_f32_16x16x32_bf16 v[0:3], v[234:237], v[218:221], v[0:3]
	v_mfma_f32_16x16x32_bf16 v[28:31], v[230:233], v[198:201], v[28:31]
	v_mfma_f32_16x16x32_bf16 v[24:27], v[238:241], v[198:201], v[24:27]
	v_mfma_f32_16x16x32_bf16 v[20:23], v[230:233], v[206:209], v[20:23]
	v_mfma_f32_16x16x32_bf16 v[16:19], v[238:241], v[206:209], v[16:19]
	v_mfma_f32_16x16x32_bf16 v[12:15], v[230:233], v[214:217], v[12:15]
	v_mfma_f32_16x16x32_bf16 v[8:11], v[238:241], v[214:217], v[8:11]
	v_mfma_f32_16x16x32_bf16 v[4:7], v[230:233], v[222:225], v[4:7]
	v_mfma_f32_16x16x32_bf16 v[0:3], v[238:241], v[222:225], v[0:3]
	s_setprio 0
	s_add_i32 s24, s24, 2
	v_lshl_add_u64 v[142:143], v[142:143], 0, s[20:21]
	v_lshl_add_u64 v[144:145], v[144:145], 0, s[20:21]
	v_lshl_add_u64 v[146:147], v[146:147], 0, s[20:21]
	s_cmpk_lt_u32 s24, 0x7c
	v_lshl_add_u64 v[148:149], v[148:149], 0, s[20:21]
	s_cbranch_scc1 .LBB0_965
	s_barrier
	s_or_b32 s0, s26, 0x80
	s_ashr_i32 s1, s0, 31
	s_lshl_b64 s[0:1], s[0:1], 14
	s_add_u32 s0, s62, s0
	s_addc_u32 s1, s63, s1
	s_add_u32 s0, s0, 0x3f80
	s_addc_u32 s1, s1, 0
	v_lshl_add_u64 v[158:159], v[134:135], 1, s[0:1]
	v_readfirstlane_b32 s24, v174
	v_lshl_add_u64 v[138:139], v[138:139], 1, v[158:159]
	s_mov_b32 m0, s24
	ds_read_b128 v[142:145], v163
	ds_read_b128 v[146:149], v163 offset:1024
	ds_read_b128 v[178:181], v163 offset:2048
	ds_read_b128 v[182:185], v163 offset:3072
	ds_read_b128 v[186:189], v153
	ds_read_b128 v[190:193], v153 offset:1024
	ds_read_b128 v[194:197], v171
	ds_read_b128 v[198:201], v171 offset:1024
	ds_read_b128 v[202:205], v172
	ds_read_b128 v[206:209], v172 offset:1024
	ds_read_b128 v[210:213], v173
	ds_read_b128 v[214:217], v173 offset:1024
	global_load_lds_dwordx4 v[138:139], off
	v_lshl_add_u64 v[138:139], v[136:137], 1, s[0:1]
	v_readfirstlane_b32 s0, v175
	v_lshl_add_u64 v[138:139], v[140:141], 1, v[138:139]
	s_mov_b32 m0, s0
	s_nop 0
	global_load_lds_dwordx4 v[138:139], off
	s_barrier
	s_waitcnt lgkmcnt(0)
	s_setprio 1
	v_mfma_f32_16x16x32_bf16 v[124:127], v[142:145], v[186:189], v[124:127]
	v_mfma_f32_16x16x32_bf16 v[120:123], v[178:181], v[186:189], v[120:123]
	v_mfma_f32_16x16x32_bf16 v[116:119], v[142:145], v[194:197], v[116:119]
	v_mfma_f32_16x16x32_bf16 v[112:115], v[178:181], v[194:197], v[112:115]
	v_mfma_f32_16x16x32_bf16 v[100:103], v[142:145], v[210:213], v[100:103]
	v_mfma_f32_16x16x32_bf16 v[96:99], v[178:181], v[210:213], v[96:99]
	v_mfma_f32_16x16x32_bf16 v[124:127], v[146:149], v[190:193], v[124:127]
	v_mfma_f32_16x16x32_bf16 v[120:123], v[182:185], v[190:193], v[120:123]
	v_mfma_f32_16x16x32_bf16 v[116:119], v[146:149], v[198:201], v[116:119]
	v_mfma_f32_16x16x32_bf16 v[112:115], v[182:185], v[198:201], v[112:115]
	v_mfma_f32_16x16x32_bf16 v[108:111], v[142:145], v[202:205], v[108:111]
	v_mfma_f32_16x16x32_bf16 v[104:107], v[178:181], v[202:205], v[104:107]
	v_mfma_f32_16x16x32_bf16 v[100:103], v[146:149], v[214:217], v[100:103]
	v_mfma_f32_16x16x32_bf16 v[96:99], v[182:185], v[214:217], v[96:99]
	v_mfma_f32_16x16x32_bf16 v[138:141], v[146:149], v[206:209], v[108:111]
	v_mfma_f32_16x16x32_bf16 v[218:221], v[182:185], v[206:209], v[104:107]
	s_setprio 0
	s_barrier
; #define LDA(dst,b,h) _Pragma("unroll") for(int m=0;m<4;++m) _Pragma("unroll") for(int k=0;k<2;++k) \
;     dst[m][k]=*reinterpret_cast<const bf16x8*>((char*)SA(b,h)+lds_byte(wr*64+m*16+fr,k*32+fq*8))
; #define LDB(dst,b,h) _Pragma("unroll") for(int n=0;n<2;++n) _Pragma("unroll") for(int k=0;k<2;++k) \
;     dst[n][k]=*reinterpret_cast<const bf16x8*>((char*)SB(b,h)+lds_byte(wc*32+n*16+fr,k*32+fq*8))
; #define MMA(ai,bj,At_,Bt_) do{__builtin_amdgcn_s_setprio(1); \
;     _Pragma("unroll") for(int m=0;m<4;++m) _Pragma("unroll") for(int n=0;n<2;++n) _Pragma("unroll") for(int k=0;k<2;++k) \
;       acc[ai][bj][m][n]=__builtin_amdgcn_mfma_f32_16x16x32_bf16(Bt_[n][k],At_[m][k],acc[ai][bj][m][n],0,0,0); \
;     __builtin_amdgcn_s_setprio(0);}while(0)
; #define WAIT_V(n) asm volatile("s_waitcnt vmcnt(" #n ")":::"memory")
; #define WAIT_L(n) asm volatile("s_waitcnt lgkmcnt(" #n ")":::"memory")
; #define BAR __builtin_amdgcn_s_barrier()
; DEVINL void gemm8_mainloop(const u16* A, long lda, const u16* Bt, long ldb, int K, int brow, int bcol, f32x4 (&acc)[2][2][4][2], char* smem, int tid) {
;     ...
;     LDB(B1,0,1); BAR; WAIT_L(0); MMA(0,1,At,B1); BAR;
;     LDA(At,0,1); WAIT_V(4); BAR; WAIT_L(0); MMA(1,0,At,B0); MMA(1,1,At,B1); BAR; }
;   { LDB(B0,1,0); LDA(At,1,0); WAIT_V(2); BAR; WAIT_L(0); MMA(0,0,At,B0); BAR;
	s_nop 1
	ds_read_b128 v[104:107], v160
	ds_read_b128 v[108:111], v160 offset:1024
	ds_read_b128 v[222:225], v160 offset:2048
	ds_read_b128 v[158:161], v160 offset:3072
	s_barrier
	s_waitcnt lgkmcnt(0)
	s_setprio 1
	v_mfma_f32_16x16x32_bf16 v[84:87], v[104:107], v[194:197], v[84:87]
	v_mfma_f32_16x16x32_bf16 v[80:83], v[222:225], v[194:197], v[80:83]
	v_mfma_f32_16x16x32_bf16 v[68:71], v[104:107], v[210:213], v[68:71]
	v_mfma_f32_16x16x32_bf16 v[92:95], v[104:107], v[186:189], v[92:95]
	v_mfma_f32_16x16x32_bf16 v[88:91], v[222:225], v[186:189], v[88:91]
	v_mfma_f32_16x16x32_bf16 v[84:87], v[108:111], v[198:201], v[84:87]
	v_mfma_f32_16x16x32_bf16 v[80:83], v[158:161], v[198:201], v[80:83]
	v_mfma_f32_16x16x32_bf16 v[76:79], v[104:107], v[202:205], v[76:79]
	v_mfma_f32_16x16x32_bf16 v[72:75], v[222:225], v[202:205], v[72:75]
	v_mfma_f32_16x16x32_bf16 v[68:71], v[108:111], v[214:217], v[68:71]
	v_mfma_f32_16x16x32_bf16 v[64:67], v[222:225], v[210:213], v[64:67]
	v_mfma_f32_16x16x32_bf16 v[226:229], v[108:111], v[190:193], v[92:95]
	v_mfma_f32_16x16x32_bf16 v[186:189], v[158:161], v[190:193], v[88:91]
	v_mfma_f32_16x16x32_bf16 v[190:193], v[108:111], v[206:209], v[76:79]
	v_mfma_f32_16x16x32_bf16 v[194:197], v[158:161], v[206:209], v[72:75]
	v_mfma_f32_16x16x32_bf16 v[198:201], v[158:161], v[214:217], v[64:67]
	s_setprio 0
	s_barrier
	s_nop 0
	ds_read_b128 v[64:67], v153 offset:16384
	ds_read_b128 v[72:75], v153 offset:17408
	ds_read_b128 v[76:79], v171 offset:16384
	ds_read_b128 v[88:91], v171 offset:17408
	ds_read_b128 v[92:95], v172 offset:16384
	ds_read_b128 v[202:205], v172 offset:17408
	ds_read_b128 v[206:209], v173 offset:16384
	ds_read_b128 v[210:213], v173 offset:17408
	s_waitcnt vmcnt(4)
	s_barrier
	s_waitcnt lgkmcnt(0)
	s_setprio 1
	v_mfma_f32_16x16x32_bf16 v[60:63], v[142:145], v[64:67], v[60:63]
	v_mfma_f32_16x16x32_bf16 v[56:59], v[178:181], v[64:67], v[56:59]
	v_mfma_f32_16x16x32_bf16 v[52:55], v[142:145], v[76:79], v[52:55]
	v_mfma_f32_16x16x32_bf16 v[48:51], v[178:181], v[76:79], v[48:51]
	v_mfma_f32_16x16x32_bf16 v[36:39], v[142:145], v[206:209], v[36:39]
	v_mfma_f32_16x16x32_bf16 v[32:35], v[178:181], v[206:209], v[32:35]
	v_mfma_f32_16x16x32_bf16 v[60:63], v[146:149], v[72:75], v[60:63]
	v_mfma_f32_16x16x32_bf16 v[56:59], v[182:185], v[72:75], v[56:59]
	v_mfma_f32_16x16x32_bf16 v[52:55], v[146:149], v[88:91], v[52:55]
	v_mfma_f32_16x16x32_bf16 v[48:51], v[182:185], v[88:91], v[48:51]
	v_mfma_f32_16x16x32_bf16 v[44:47], v[142:145], v[92:95], v[44:47]
	v_mfma_f32_16x16x32_bf16 v[40:43], v[178:181], v[92:95], v[40:43]
	v_mfma_f32_16x16x32_bf16 v[36:39], v[146:149], v[210:213], v[36:39]
	v_mfma_f32_16x16x32_bf16 v[32:35], v[182:185], v[210:213], v[32:35]
	v_mfma_f32_16x16x32_bf16 v[214:217], v[146:149], v[202:205], v[44:47]
	v_mfma_f32_16x16x32_bf16 v[230:233], v[182:185], v[202:205], v[40:43]
	s_setprio 0
	s_setprio 1
	v_mfma_f32_16x16x32_bf16 v[20:23], v[104:107], v[76:79], v[20:23]
	v_mfma_f32_16x16x32_bf16 v[16:19], v[222:225], v[76:79], v[16:19]
	v_mfma_f32_16x16x32_bf16 v[4:7], v[104:107], v[206:209], v[4:7]
	v_mfma_f32_16x16x32_bf16 v[0:3], v[222:225], v[206:209], v[0:3]
	v_mfma_f32_16x16x32_bf16 v[28:31], v[104:107], v[64:67], v[28:31]
	v_mfma_f32_16x16x32_bf16 v[24:27], v[222:225], v[64:67], v[24:27]
	v_mfma_f32_16x16x32_bf16 v[20:23], v[108:111], v[88:91], v[20:23]
	v_mfma_f32_16x16x32_bf16 v[16:19], v[158:161], v[88:91], v[16:19]
	v_mfma_f32_16x16x32_bf16 v[12:15], v[104:107], v[92:95], v[12:15]
	v_mfma_f32_16x16x32_bf16 v[8:11], v[222:225], v[92:95], v[8:11]
	v_mfma_f32_16x16x32_bf16 v[4:7], v[108:111], v[210:213], v[4:7]
	v_mfma_f32_16x16x32_bf16 v[0:3], v[158:161], v[210:213], v[0:3]
	v_mfma_f32_16x16x32_bf16 v[142:145], v[108:111], v[72:75], v[28:31]
	v_mfma_f32_16x16x32_bf16 v[146:149], v[158:161], v[72:75], v[24:27]
	v_mfma_f32_16x16x32_bf16 v[178:181], v[108:111], v[202:205], v[12:15]
	v_mfma_f32_16x16x32_bf16 v[182:185], v[158:161], v[202:205], v[8:11]
	s_setprio 0
	s_barrier
	s_nop 0
	ds_read_b128 v[8:11], v157
	ds_read_b128 v[12:15], v157 offset:1024
	ds_read_b128 v[158:161], v157 offset:2048
	ds_read_b128 v[202:205], v157 offset:3072
	ds_read_b128 v[24:27], v153 offset:32768
	ds_read_b128 v[28:31], v153 offset:33792
	ds_read_b128 v[40:43], v171 offset:32768
	ds_read_b128 v[44:47], v171 offset:33792
	ds_read_b128 v[64:67], v172 offset:32768
	ds_read_b128 v[206:209], v172 offset:33792
	ds_read_b128 v[210:213], v173 offset:32768
	ds_read_b128 v[222:225], v173 offset:33792
	s_waitcnt vmcnt(2)
	s_barrier
; #define LDA(dst,b,h) _Pragma("unroll") for(int m=0;m<4;++m) _Pragma("unroll") for(int k=0;k<2;++k) \
;     dst[m][k]=*reinterpret_cast<const bf16x8*>((char*)SA(b,h)+lds_byte(wr*64+m*16+fr,k*32+fq*8))
; #define LDB(dst,b,h) _Pragma("unroll") for(int n=0;n<2;++n) _Pragma("unroll") for(int k=0;k<2;++k) \
;     dst[n][k]=*reinterpret_cast<const bf16x8*>((char*)SB(b,h)+lds_byte(wc*32+n*16+fr,k*32+fq*8))
; #define MMA(ai,bj,At_,Bt_) do{__builtin_amdgcn_s_setprio(1); \
;     _Pragma("unroll") for(int m=0;m<4;++m) _Pragma("unroll") for(int n=0;n<2;++n) _Pragma("unroll") for(int k=0;k<2;++k) \
;       acc[ai][bj][m][n]=__builtin_amdgcn_mfma_f32_16x16x32_bf16(Bt_[n][k],At_[m][k],acc[ai][bj][m][n],0,0,0); \
;     __builtin_amdgcn_s_setprio(0);}while(0)
; #define WAIT_V(n) asm volatile("s_waitcnt vmcnt(" #n ")":::"memory")
; #define WAIT_L(n) asm volatile("s_waitcnt lgkmcnt(" #n ")":::"memory")
; #define BAR __builtin_amdgcn_s_barrier()
; DEVINL void gemm8_mainloop(const u16* A, long lda, const u16* Bt, long ldb, int K, int brow, int bcol, f32x4 (&acc)[2][2][4][2], char* smem, int tid) {
;     ...
;   { LDB(B0,1,0); LDA(At,1,0); WAIT_V(2); BAR; WAIT_L(0); MMA(0,0,At,B0); BAR;
;     LDB(B1,1,1); WAIT_V(0); BAR; WAIT_L(0); MMA(0,1,At,B1); BAR;
;     LDA(At,1,1); BAR; WAIT_L(0); MMA(1,0,At,B0); MMA(1,1,At,B1); BAR; }
;   if(wr==0)BAR;
;   __syncthreads();
	s_waitcnt lgkmcnt(0)
	s_setprio 1
	v_mfma_f32_16x16x32_bf16 v[72:75], v[8:11], v[24:27], v[124:127]
	v_mfma_f32_16x16x32_bf16 v[124:127], v[12:15], v[28:31], v[72:75]
	v_mfma_f32_16x16x32_bf16 v[72:75], v[158:161], v[24:27], v[120:123]
	v_mfma_f32_16x16x32_bf16 v[120:123], v[202:205], v[28:31], v[72:75]
	v_mfma_f32_16x16x32_bf16 v[72:75], v[8:11], v[40:43], v[116:119]
	v_mfma_f32_16x16x32_bf16 v[108:111], v[12:15], v[44:47], v[72:75]
	v_mfma_f32_16x16x32_bf16 v[72:75], v[158:161], v[40:43], v[112:115]
	v_mfma_f32_16x16x32_bf16 v[104:107], v[202:205], v[44:47], v[72:75]
	v_mfma_f32_16x16x32_bf16 v[72:75], v[8:11], v[64:67], v[138:141]
	v_mfma_f32_16x16x32_bf16 v[92:95], v[12:15], v[206:209], v[72:75]
	v_mfma_f32_16x16x32_bf16 v[72:75], v[158:161], v[64:67], v[218:221]
	v_mfma_f32_16x16x32_bf16 v[88:91], v[202:205], v[206:209], v[72:75]
	v_mfma_f32_16x16x32_bf16 v[72:75], v[8:11], v[210:213], v[100:103]
	v_mfma_f32_16x16x32_bf16 v[76:79], v[12:15], v[222:225], v[72:75]
	v_mfma_f32_16x16x32_bf16 v[72:75], v[158:161], v[210:213], v[96:99]
	v_mfma_f32_16x16x32_bf16 v[72:75], v[202:205], v[222:225], v[72:75]
	s_setprio 0
	s_barrier
	ds_read_b128 v[138:141], v155
	ds_read_b128 v[218:221], v155 offset:1024
	ds_read_b128 v[234:237], v155 offset:2048
	ds_read_b128 v[154:157], v155 offset:3072
	s_waitcnt vmcnt(0)
	s_barrier
	s_waitcnt lgkmcnt(0)
	s_setprio 1
	v_mfma_f32_16x16x32_bf16 v[96:99], v[138:141], v[24:27], v[226:229]
	v_mfma_f32_16x16x32_bf16 v[24:27], v[234:237], v[24:27], v[186:189]
	v_mfma_f32_16x16x32_bf16 v[116:119], v[154:157], v[28:31], v[24:27]
	v_mfma_f32_16x16x32_bf16 v[24:27], v[138:141], v[40:43], v[84:87]
	v_mfma_f32_16x16x32_bf16 v[112:115], v[218:221], v[28:31], v[96:99]
	v_mfma_f32_16x16x32_bf16 v[96:99], v[218:221], v[44:47], v[24:27]
	v_mfma_f32_16x16x32_bf16 v[24:27], v[234:237], v[40:43], v[80:83]
	v_mfma_f32_16x16x32_bf16 v[100:103], v[154:157], v[44:47], v[24:27]
	v_mfma_f32_16x16x32_bf16 v[24:27], v[138:141], v[64:67], v[190:193]
	v_mfma_f32_16x16x32_bf16 v[80:83], v[218:221], v[206:209], v[24:27]
	v_mfma_f32_16x16x32_bf16 v[24:27], v[234:237], v[64:67], v[194:197]
	v_mfma_f32_16x16x32_bf16 v[84:87], v[154:157], v[206:209], v[24:27]
	v_mfma_f32_16x16x32_bf16 v[24:27], v[138:141], v[210:213], v[68:71]
	v_mfma_f32_16x16x32_bf16 v[64:67], v[218:221], v[222:225], v[24:27]
	v_mfma_f32_16x16x32_bf16 v[24:27], v[234:237], v[210:213], v[198:201]
	v_mfma_f32_16x16x32_bf16 v[68:71], v[154:157], v[222:225], v[24:27]
	s_setprio 0
	s_barrier
	ds_read_b128 v[186:189], v153 offset:49152
	ds_read_b128 v[190:193], v153 offset:50176
	ds_read_b128 v[194:197], v171 offset:49152
	ds_read_b128 v[198:201], v171 offset:50176
	ds_read_b128 v[206:209], v172 offset:49152
	ds_read_b128 v[210:213], v172 offset:50176
	ds_read_b128 v[222:225], v173 offset:49152
	ds_read_b128 v[172:175], v173 offset:50176
	s_barrier
	s_waitcnt lgkmcnt(0)
	s_setprio 1
	v_mfma_f32_16x16x32_bf16 v[24:27], v[8:11], v[186:189], v[60:63]
	v_mfma_f32_16x16x32_bf16 v[60:63], v[12:15], v[190:193], v[24:27]
	v_mfma_f32_16x16x32_bf16 v[24:27], v[158:161], v[186:189], v[56:59]
	v_mfma_f32_16x16x32_bf16 v[56:59], v[202:205], v[190:193], v[24:27]
	v_mfma_f32_16x16x32_bf16 v[24:27], v[8:11], v[194:197], v[52:55]
	v_mfma_f32_16x16x32_bf16 v[44:47], v[12:15], v[198:201], v[24:27]
	v_mfma_f32_16x16x32_bf16 v[24:27], v[158:161], v[194:197], v[48:51]
	v_mfma_f32_16x16x32_bf16 v[40:43], v[202:205], v[198:201], v[24:27]
	v_mfma_f32_16x16x32_bf16 v[24:27], v[8:11], v[206:209], v[214:217]
	v_mfma_f32_16x16x32_bf16 v[8:11], v[8:11], v[222:225], v[36:39]
	v_mfma_f32_16x16x32_bf16 v[28:31], v[12:15], v[210:213], v[24:27]
	v_mfma_f32_16x16x32_bf16 v[24:27], v[158:161], v[206:209], v[230:233]
	v_mfma_f32_16x16x32_bf16 v[12:15], v[12:15], v[172:175], v[8:11]
	v_mfma_f32_16x16x32_bf16 v[8:11], v[158:161], v[222:225], v[32:35]
	v_mfma_f32_16x16x32_bf16 v[24:27], v[202:205], v[210:213], v[24:27]
	v_mfma_f32_16x16x32_bf16 v[8:11], v[202:205], v[172:175], v[8:11]
	s_setprio 0
	s_setprio 1
	v_mfma_f32_16x16x32_bf16 v[32:35], v[138:141], v[186:189], v[142:145]
	v_mfma_f32_16x16x32_bf16 v[48:51], v[218:221], v[190:193], v[32:35]
	v_mfma_f32_16x16x32_bf16 v[32:35], v[234:237], v[186:189], v[146:149]
	v_mfma_f32_16x16x32_bf16 v[20:23], v[138:141], v[194:197], v[20:23]
	v_mfma_f32_16x16x32_bf16 v[16:19], v[234:237], v[194:197], v[16:19]
	v_mfma_f32_16x16x32_bf16 v[52:55], v[154:157], v[190:193], v[32:35]
	v_mfma_f32_16x16x32_bf16 v[32:35], v[218:221], v[198:201], v[20:23]
	v_mfma_f32_16x16x32_bf16 v[36:39], v[154:157], v[198:201], v[16:19]
	v_mfma_f32_16x16x32_bf16 v[16:19], v[138:141], v[206:209], v[178:181]
	v_mfma_f32_16x16x32_bf16 v[20:23], v[234:237], v[206:209], v[182:185]
	v_mfma_f32_16x16x32_bf16 v[4:7], v[138:141], v[222:225], v[4:7]
	v_mfma_f32_16x16x32_bf16 v[0:3], v[234:237], v[222:225], v[0:3]
	v_mfma_f32_16x16x32_bf16 v[16:19], v[218:221], v[210:213], v[16:19]
	v_mfma_f32_16x16x32_bf16 v[20:23], v[154:157], v[210:213], v[20:23]
	v_mfma_f32_16x16x32_bf16 v[4:7], v[218:221], v[172:175], v[4:7]
	v_mfma_f32_16x16x32_bf16 v[0:3], v[154:157], v[172:175], v[0:3]
	s_setprio 0
	s_cmpk_gt_u32 s29, 0xff
	s_barrier
	s_cbranch_scc1 .LBB0_968
	s_barrier

; #define STAGE(P,BASE,LD,br,kt) do{long _g=(long)(br)*(LD)+(long)(kt)*BK; \
;     _Pragma("unroll") for(int _i=0;_i<2;++_i){int _b=tid*16+_i*8192;int _r,_c;stage_rc(_b,_r,_c); \
;       __builtin_amdgcn_global_load_lds((const unsigned*)((BASE)+_g+(long)_r*(LD)+_c), \
;         (unsigned*)((char*)(P)+_b),16,0,0);}}while(0)
; #define STAGE(P,BASE,LD,br,kt) do{long _g=(long)(br)*(LD)+(long)(kt)*BK; \
;     _Pragma("unroll") for(int _i=0;_i<2;++_i){int _b=tid*16+_i*8192;int _r,_c;stage_rc(_b,_r,_c); \
;       __builtin_amdgcn_global_load_lds((const unsigned*)((BASE)+_g+(long)_r*(LD)+_c), \
;         (unsigned*)((char*)(P)+_b),16,0,0);}}while(0)
; #define LDA(dst,b,h) _Pragma("unroll") for(int m=0;m<4;++m) _Pragma("unroll") for(int k=0;k<2;++k) \
;     dst[m][k]=*reinterpret_cast<const bf16x8*>((char*)SA(b,h)+lds_byte(wr*64+m*16+fr,k*32+fq*8))
; #define LDB(dst,b,h) _Pragma("unroll") for(int n=0;n<2;++n) _Pragma("unroll") for(int k=0;k<2;++k) \
;     dst[n][k]=*reinterpret_cast<const bf16x8*>((char*)SB(b,h)+lds_byte(wc*32+n*16+fr,k*32+fq*8))
; #define MMA(ai,bj,At_,Bt_) do{__builtin_amdgcn_s_setprio(1); \
;     _Pragma("unroll") for(int m=0;m<4;++m) _Pragma("unroll") for(int n=0;n<2;++n) _Pragma("unroll") for(int k=0;k<2;++k) \
;       acc[ai][bj][m][n]=__builtin_amdgcn_mfma_f32_16x16x32_bf16(Bt_[n][k],At_[m][k],acc[ai][bj][m][n],0,0,0); \
;     __builtin_amdgcn_s_setprio(0);}while(0)
; #define WAIT_L(n) asm volatile("s_waitcnt lgkmcnt(" #n ")":::"memory")
; #define BAR __builtin_amdgcn_s_barrier()
; #define SCHED __builtin_amdgcn_sched_barrier(0)
; DEVINL void gemm8_mainloop(const u16* A, long lda, const u16* Bt, long ldb, int K, int brow, int bcol, f32x4 (&acc)[2][2][4][2], char* smem, int tid) {
;     ...
;   for(int t=0;t<nt-2;t+=2){
;     LDB(B0,0,0); SCHED; LDA(At,0,0); STAGE(SA(1,1),A,lda,brow+HALF,t+1);
;     WAIT_L(8); BAR; WAIT_L(0); MMA(0,0,At,B0); BAR; SCHED;
;     LDB(B1,0,1); STAGE(SB(0,0),Bt,ldb,bcol,t+2);
;     BAR; WAIT_L(0); MMA(0,1,At,B1); BAR;
;     LDA(At,0,1); STAGE(SA(0,0),A,lda,brow,t+2);
;     BAR; WAIT_L(0); MMA(1,0,At,B0); BAR; SCHED;
.LBB0_1292:
	s_barrier
	ds_read_b128 v[170:173], v161
	ds_read_b128 v[180:183], v161 offset:1024
	ds_read_b128 v[184:187], v161 offset:2048
	ds_read_b128 v[188:191], v161 offset:3072
	v_add_u32_e32 v178, 0xc000, v128
	v_lshl_add_u64 v[244:245], s[94:95], 0, v[148:149]
	v_readfirstlane_b32 s5, v178
	v_add_u32_e32 v179, 0xe000, v128
	v_add_u32_e32 v174, s1, v160
	v_add_u32_e32 v175, s37, v160
	v_add_u32_e32 v177, s40, v160
	v_lshl_add_u64 v[162:163], v[244:245], 0, s[8:9]
	s_mov_b32 m0, s5
	v_lshl_add_u64 v[246:247], s[94:95], 0, v[150:151]
	v_readfirstlane_b32 s5, v179
	ds_read_b128 v[192:195], v131
	ds_read_b128 v[196:199], v131 offset:1024
	ds_read_b128 v[200:203], v174
	ds_read_b128 v[204:207], v174 offset:1024
	ds_read_b128 v[208:211], v175
	ds_read_b128 v[212:215], v175 offset:1024
	ds_read_b128 v[216:219], v177
	ds_read_b128 v[220:223], v177 offset:1024
	global_load_lds_dwordx4 v[162:163], off
	v_lshl_add_u64 v[162:163], v[246:247], 0, s[8:9]
	s_mov_b32 m0, s5
	s_nop 0
	global_load_lds_dwordx4 v[162:163], off
	s_waitcnt lgkmcnt(8)
	s_barrier
	s_waitcnt lgkmcnt(0)
	s_setprio 1
	v_mfma_f32_16x16x32_bf16 v[124:127], v[170:173], v[192:195], v[124:127]
	v_mfma_f32_16x16x32_bf16 v[120:123], v[184:187], v[192:195], v[120:123]
	v_mfma_f32_16x16x32_bf16 v[116:119], v[170:173], v[200:203], v[116:119]
	v_mfma_f32_16x16x32_bf16 v[112:115], v[184:187], v[200:203], v[112:115]
	v_mfma_f32_16x16x32_bf16 v[108:111], v[170:173], v[208:211], v[108:111]
	v_mfma_f32_16x16x32_bf16 v[104:107], v[184:187], v[208:211], v[104:107]
	v_mfma_f32_16x16x32_bf16 v[100:103], v[170:173], v[216:219], v[100:103]
	v_mfma_f32_16x16x32_bf16 v[96:99], v[184:187], v[216:219], v[96:99]
	v_mfma_f32_16x16x32_bf16 v[124:127], v[180:183], v[196:199], v[124:127]
	v_mfma_f32_16x16x32_bf16 v[120:123], v[188:191], v[196:199], v[120:123]
	v_mfma_f32_16x16x32_bf16 v[116:119], v[180:183], v[204:207], v[116:119]
	v_mfma_f32_16x16x32_bf16 v[112:115], v[188:191], v[204:207], v[112:115]
	v_mfma_f32_16x16x32_bf16 v[108:111], v[180:183], v[212:215], v[108:111]
	v_mfma_f32_16x16x32_bf16 v[104:107], v[188:191], v[212:215], v[104:107]
	v_mfma_f32_16x16x32_bf16 v[100:103], v[180:183], v[220:223], v[100:103]
	v_mfma_f32_16x16x32_bf16 v[96:99], v[188:191], v[220:223], v[96:99]
	s_setprio 0
	s_barrier
	v_add_u32_e32 v162, s27, v153
	v_lshl_add_u64 v[248:249], s[94:95], 0, v[144:145]
	v_readfirstlane_b32 s5, v162
	v_add_u32_e32 v163, 0x2000, v162
	v_lshl_add_u64 v[240:241], v[248:249], 0, s[10:11]
	s_mov_b32 m0, s5
	v_lshl_add_u64 v[250:251], s[94:95], 0, v[146:147]
	v_readfirstlane_b32 s5, v163
	ds_read_b128 v[224:227], v158
	ds_read_b128 v[228:231], v158 offset:1024
	ds_read_b128 v[232:235], v158 offset:2048
	ds_read_b128 v[236:239], v158 offset:3072
	global_load_lds_dwordx4 v[240:241], off
	v_lshl_add_u64 v[240:241], v[250:251], 0, s[10:11]
	s_mov_b32 m0, s5
	s_nop 0
	global_load_lds_dwordx4 v[240:241], off
	s_barrier
	s_waitcnt lgkmcnt(0)
	s_setprio 1
	v_mfma_f32_16x16x32_bf16 v[92:95], v[224:227], v[192:195], v[92:95]
	v_mfma_f32_16x16x32_bf16 v[88:91], v[232:235], v[192:195], v[88:91]
	v_mfma_f32_16x16x32_bf16 v[84:87], v[224:227], v[200:203], v[84:87]
	v_mfma_f32_16x16x32_bf16 v[80:83], v[232:235], v[200:203], v[80:83]
	v_mfma_f32_16x16x32_bf16 v[76:79], v[224:227], v[208:211], v[76:79]
	v_mfma_f32_16x16x32_bf16 v[72:75], v[232:235], v[208:211], v[72:75]
	v_mfma_f32_16x16x32_bf16 v[68:71], v[224:227], v[216:219], v[68:71]
	v_mfma_f32_16x16x32_bf16 v[64:67], v[232:235], v[216:219], v[64:67]
	v_mfma_f32_16x16x32_bf16 v[92:95], v[228:231], v[196:199], v[92:95]
	v_mfma_f32_16x16x32_bf16 v[88:91], v[236:239], v[196:199], v[88:91]
	v_mfma_f32_16x16x32_bf16 v[84:87], v[228:231], v[204:207], v[84:87]
	v_mfma_f32_16x16x32_bf16 v[80:83], v[236:239], v[204:207], v[80:83]
	v_mfma_f32_16x16x32_bf16 v[76:79], v[228:231], v[212:215], v[76:79]
	v_mfma_f32_16x16x32_bf16 v[72:75], v[236:239], v[212:215], v[72:75]
	v_mfma_f32_16x16x32_bf16 v[68:71], v[228:231], v[220:223], v[68:71]
	v_mfma_f32_16x16x32_bf16 v[64:67], v[236:239], v[220:223], v[64:67]
	s_setprio 0
	v_readfirstlane_b32 s5, v128
	v_add_u32_e32 v169, 0x2000, v128
	v_lshl_add_u64 v[240:241], v[244:245], 0, s[12:13]
	s_mov_b32 m0, s5
	v_readfirstlane_b32 s5, v169
	s_barrier
	ds_read_b128 v[192:195], v131 offset:16384
	ds_read_b128 v[196:199], v131 offset:17408
	ds_read_b128 v[200:203], v174 offset:16384
	ds_read_b128 v[204:207], v174 offset:17408
	ds_read_b128 v[208:211], v175 offset:16384
	ds_read_b128 v[212:215], v175 offset:17408
	ds_read_b128 v[216:219], v177 offset:16384
	ds_read_b128 v[220:223], v177 offset:17408
	global_load_lds_dwordx4 v[240:241], off
	v_lshl_add_u64 v[240:241], v[246:247], 0, s[12:13]
	s_mov_b32 m0, s5
	s_nop 0
	global_load_lds_dwordx4 v[240:241], off
	s_barrier
	s_waitcnt lgkmcnt(0)
	s_setprio 1
	v_mfma_f32_16x16x32_bf16 v[60:63], v[170:173], v[192:195], v[60:63]
	v_mfma_f32_16x16x32_bf16 v[56:59], v[184:187], v[192:195], v[56:59]
	v_mfma_f32_16x16x32_bf16 v[52:55], v[170:173], v[200:203], v[52:55]
	v_mfma_f32_16x16x32_bf16 v[48:51], v[184:187], v[200:203], v[48:51]
	v_mfma_f32_16x16x32_bf16 v[44:47], v[170:173], v[208:211], v[44:47]
	v_mfma_f32_16x16x32_bf16 v[40:43], v[184:187], v[208:211], v[40:43]
	v_mfma_f32_16x16x32_bf16 v[36:39], v[170:173], v[216:219], v[36:39]
	v_mfma_f32_16x16x32_bf16 v[32:35], v[184:187], v[216:219], v[32:35]
	v_mfma_f32_16x16x32_bf16 v[60:63], v[180:183], v[196:199], v[60:63]
	v_mfma_f32_16x16x32_bf16 v[56:59], v[188:191], v[196:199], v[56:59]
	v_mfma_f32_16x16x32_bf16 v[52:55], v[180:183], v[204:207], v[52:55]
	v_mfma_f32_16x16x32_bf16 v[48:51], v[188:191], v[204:207], v[48:51]
	v_mfma_f32_16x16x32_bf16 v[44:47], v[180:183], v[212:215], v[44:47]
	v_mfma_f32_16x16x32_bf16 v[40:43], v[188:191], v[212:215], v[40:43]
	v_mfma_f32_16x16x32_bf16 v[36:39], v[180:183], v[220:223], v[36:39]
	v_mfma_f32_16x16x32_bf16 v[32:35], v[188:191], v[220:223], v[32:35]
	s_setprio 0
	s_barrier
; #define STAGE(P,BASE,LD,br,kt) do{long _g=(long)(br)*(LD)+(long)(kt)*BK; \
;     _Pragma("unroll") for(int _i=0;_i<2;++_i){int _b=tid*16+_i*8192;int _r,_c;stage_rc(_b,_r,_c); \
;       __builtin_amdgcn_global_load_lds((const unsigned*)((BASE)+_g+(long)_r*(LD)+_c), \
;         (unsigned*)((char*)(P)+_b),16,0,0);}}while(0)
; #define STAGE(P,BASE,LD,br,kt) do{long _g=(long)(br)*(LD)+(long)(kt)*BK; \
;     _Pragma("unroll") for(int _i=0;_i<2;++_i){int _b=tid*16+_i*8192;int _r,_c;stage_rc(_b,_r,_c); \
;       __builtin_amdgcn_global_load_lds((const unsigned*)((BASE)+_g+(long)_r*(LD)+_c), \
;         (unsigned*)((char*)(P)+_b),16,0,0);}}while(0)
; #define LDA(dst,b,h) _Pragma("unroll") for(int m=0;m<4;++m) _Pragma("unroll") for(int k=0;k<2;++k) \
;     dst[m][k]=*reinterpret_cast<const bf16x8*>((char*)SA(b,h)+lds_byte(wr*64+m*16+fr,k*32+fq*8))
; #define LDB(dst,b,h) _Pragma("unroll") for(int n=0;n<2;++n) _Pragma("unroll") for(int k=0;k<2;++k) \
;     dst[n][k]=*reinterpret_cast<const bf16x8*>((char*)SB(b,h)+lds_byte(wc*32+n*16+fr,k*32+fq*8))
; #define MMA(ai,bj,At_,Bt_) do{__builtin_amdgcn_s_setprio(1); \
;     _Pragma("unroll") for(int m=0;m<4;++m) _Pragma("unroll") for(int n=0;n<2;++n) _Pragma("unroll") for(int k=0;k<2;++k) \
;       acc[ai][bj][m][n]=__builtin_amdgcn_mfma_f32_16x16x32_bf16(Bt_[n][k],At_[m][k],acc[ai][bj][m][n],0,0,0); \
;     __builtin_amdgcn_s_setprio(0);}while(0)
; #define WAIT_V(n) asm volatile("s_waitcnt vmcnt(" #n ")":::"memory")
; #define WAIT_L(n) asm volatile("s_waitcnt lgkmcnt(" #n ")":::"memory")
; #define BAR __builtin_amdgcn_s_barrier()
; #define SCHED __builtin_amdgcn_sched_barrier(0)
; DEVINL void gemm8_mainloop(const u16* A, long lda, const u16* Bt, long ldb, int K, int brow, int bcol, f32x4 (&acc)[2][2][4][2], char* smem, int tid) {
;     ...
;     STAGE(SB(0,1),Bt,ldb,bcol+HALF,t+2);
;     WAIT_V(6); BAR; MMA(1,1,At,B1); BAR;
;     LDB(B0,1,0); SCHED; LDA(At,1,0); STAGE(SA(0,1),A,lda,brow+HALF,t+2);
;     WAIT_L(8); BAR; WAIT_L(0); MMA(0,0,At,B0); BAR; SCHED;
;     LDB(B1,1,1); STAGE(SB(1,0),Bt,ldb,bcol,t+3);
;     BAR; WAIT_L(0); MMA(0,1,At,B1); BAR;
;     LDA(At,1,1); STAGE(SA(1,0),A,lda,brow,t+3);
	v_add_u32_e32 v170, s29, v153
	v_add_u32_e32 v171, 0x2000, v170
	v_readfirstlane_b32 s5, v170
	v_lshl_add_u64 v[172:173], v[248:249], 0, s[14:15]
	s_mov_b32 m0, s5
	v_readfirstlane_b32 s5, v171
	global_load_lds_dwordx4 v[172:173], off
	v_lshl_add_u64 v[172:173], v[250:251], 0, s[14:15]
	s_mov_b32 m0, s5
	s_nop 0
	global_load_lds_dwordx4 v[172:173], off
	s_waitcnt vmcnt(6)
	s_barrier
	s_setprio 1
	v_mfma_f32_16x16x32_bf16 v[28:31], v[224:227], v[192:195], v[28:31]
	v_mfma_f32_16x16x32_bf16 v[24:27], v[232:235], v[192:195], v[24:27]
	v_mfma_f32_16x16x32_bf16 v[20:23], v[224:227], v[200:203], v[20:23]
	v_mfma_f32_16x16x32_bf16 v[16:19], v[232:235], v[200:203], v[16:19]
	v_mfma_f32_16x16x32_bf16 v[12:15], v[224:227], v[208:211], v[12:15]
	v_mfma_f32_16x16x32_bf16 v[8:11], v[232:235], v[208:211], v[8:11]
	v_mfma_f32_16x16x32_bf16 v[4:7], v[224:227], v[216:219], v[4:7]
	v_mfma_f32_16x16x32_bf16 v[0:3], v[232:235], v[216:219], v[0:3]
	v_mfma_f32_16x16x32_bf16 v[28:31], v[228:231], v[196:199], v[28:31]
	v_mfma_f32_16x16x32_bf16 v[24:27], v[236:239], v[196:199], v[24:27]
	v_mfma_f32_16x16x32_bf16 v[20:23], v[228:231], v[204:207], v[20:23]
	v_mfma_f32_16x16x32_bf16 v[16:19], v[236:239], v[204:207], v[16:19]
	v_mfma_f32_16x16x32_bf16 v[12:15], v[228:231], v[212:215], v[12:15]
	v_mfma_f32_16x16x32_bf16 v[8:11], v[236:239], v[212:215], v[8:11]
	v_mfma_f32_16x16x32_bf16 v[4:7], v[228:231], v[220:223], v[4:7]
	v_mfma_f32_16x16x32_bf16 v[0:3], v[236:239], v[220:223], v[0:3]
	s_setprio 0
	s_barrier
	ds_read_b128 v[180:183], v154
	ds_read_b128 v[184:187], v154 offset:1024
	ds_read_b128 v[188:191], v154 offset:2048
	ds_read_b128 v[192:195], v154 offset:3072
	v_add_u32_e32 v172, 0x4000, v128
	v_add_u32_e32 v173, 0x6000, v128
	v_readfirstlane_b32 s5, v172
	v_lshl_add_u64 v[228:229], v[244:245], 0, s[16:17]
	s_mov_b32 m0, s5
	v_readfirstlane_b32 s5, v173
	ds_read_b128 v[196:199], v131 offset:32768
	ds_read_b128 v[200:203], v131 offset:33792
	ds_read_b128 v[204:207], v174 offset:32768
	ds_read_b128 v[208:211], v174 offset:33792
	ds_read_b128 v[212:215], v175 offset:32768
	ds_read_b128 v[216:219], v175 offset:33792
	ds_read_b128 v[220:223], v177 offset:32768
	ds_read_b128 v[224:227], v177 offset:33792
	global_load_lds_dwordx4 v[228:229], off
	v_lshl_add_u64 v[228:229], v[246:247], 0, s[16:17]
	s_mov_b32 m0, s5
	s_nop 0
	global_load_lds_dwordx4 v[228:229], off
	s_waitcnt lgkmcnt(8)
	s_barrier
	s_waitcnt lgkmcnt(0)
	s_setprio 1
	v_mfma_f32_16x16x32_bf16 v[124:127], v[180:183], v[196:199], v[124:127]
	v_mfma_f32_16x16x32_bf16 v[120:123], v[188:191], v[196:199], v[120:123]
	v_mfma_f32_16x16x32_bf16 v[116:119], v[180:183], v[204:207], v[116:119]
	v_mfma_f32_16x16x32_bf16 v[112:115], v[188:191], v[204:207], v[112:115]
	v_mfma_f32_16x16x32_bf16 v[108:111], v[180:183], v[212:215], v[108:111]
	v_mfma_f32_16x16x32_bf16 v[104:107], v[188:191], v[212:215], v[104:107]
	v_mfma_f32_16x16x32_bf16 v[100:103], v[180:183], v[220:223], v[100:103]
	v_mfma_f32_16x16x32_bf16 v[96:99], v[188:191], v[220:223], v[96:99]
	v_mfma_f32_16x16x32_bf16 v[124:127], v[184:187], v[200:203], v[124:127]
	v_mfma_f32_16x16x32_bf16 v[120:123], v[192:195], v[200:203], v[120:123]
	v_mfma_f32_16x16x32_bf16 v[116:119], v[184:187], v[208:211], v[116:119]
	v_mfma_f32_16x16x32_bf16 v[112:115], v[192:195], v[208:211], v[112:115]
	v_mfma_f32_16x16x32_bf16 v[108:111], v[184:187], v[216:219], v[108:111]
	v_mfma_f32_16x16x32_bf16 v[104:107], v[192:195], v[216:219], v[104:107]
	v_mfma_f32_16x16x32_bf16 v[100:103], v[184:187], v[224:227], v[100:103]
	v_mfma_f32_16x16x32_bf16 v[96:99], v[192:195], v[224:227], v[96:99]
	s_setprio 0
	s_barrier
	v_readfirstlane_b32 s5, v155
	v_add_u32_e32 v165, 0x2000, v155
	v_lshl_add_u64 v[252:253], v[248:249], 0, s[18:19]
	s_mov_b32 m0, s5
	v_readfirstlane_b32 s5, v165
	ds_read_b128 v[228:231], v152
	ds_read_b128 v[232:235], v152 offset:1024
	ds_read_b128 v[236:239], v152 offset:2048
	ds_read_b128 v[240:243], v152 offset:3072
	global_load_lds_dwordx4 v[252:253], off
	v_lshl_add_u64 v[252:253], v[250:251], 0, s[18:19]
	s_mov_b32 m0, s5
	s_nop 0
	global_load_lds_dwordx4 v[252:253], off
	s_barrier
	s_waitcnt lgkmcnt(0)
	s_setprio 1
	v_mfma_f32_16x16x32_bf16 v[92:95], v[228:231], v[196:199], v[92:95]
	v_mfma_f32_16x16x32_bf16 v[88:91], v[236:239], v[196:199], v[88:91]
	v_mfma_f32_16x16x32_bf16 v[84:87], v[228:231], v[204:207], v[84:87]
	v_mfma_f32_16x16x32_bf16 v[80:83], v[236:239], v[204:207], v[80:83]
	v_mfma_f32_16x16x32_bf16 v[76:79], v[228:231], v[212:215], v[76:79]
	v_mfma_f32_16x16x32_bf16 v[72:75], v[236:239], v[212:215], v[72:75]
	v_mfma_f32_16x16x32_bf16 v[68:71], v[228:231], v[220:223], v[68:71]
	v_mfma_f32_16x16x32_bf16 v[64:67], v[236:239], v[220:223], v[64:67]
	v_mfma_f32_16x16x32_bf16 v[92:95], v[232:235], v[200:203], v[92:95]
	v_mfma_f32_16x16x32_bf16 v[88:91], v[240:243], v[200:203], v[88:91]
	v_mfma_f32_16x16x32_bf16 v[84:87], v[232:235], v[208:211], v[84:87]
	v_mfma_f32_16x16x32_bf16 v[80:83], v[240:243], v[208:211], v[80:83]
	v_mfma_f32_16x16x32_bf16 v[76:79], v[232:235], v[216:219], v[76:79]
	v_mfma_f32_16x16x32_bf16 v[72:75], v[240:243], v[216:219], v[72:75]
	v_mfma_f32_16x16x32_bf16 v[68:71], v[232:235], v[224:227], v[68:71]
	v_mfma_f32_16x16x32_bf16 v[64:67], v[240:243], v[224:227], v[64:67]
	s_setprio 0
	v_readfirstlane_b32 s5, v156
	v_lshl_add_u64 v[244:245], v[244:245], 0, s[20:21]
	s_mov_b32 m0, s5
	v_readfirstlane_b32 s5, v157
	s_barrier
; #define STAGE(P,BASE,LD,br,kt) do{long _g=(long)(br)*(LD)+(long)(kt)*BK; \
;     _Pragma("unroll") for(int _i=0;_i<2;++_i){int _b=tid*16+_i*8192;int _r,_c;stage_rc(_b,_r,_c); \
;       __builtin_amdgcn_global_load_lds((const unsigned*)((BASE)+_g+(long)_r*(LD)+_c), \
;         (unsigned*)((char*)(P)+_b),16,0,0);}}while(0)
; #define STAGE(P,BASE,LD,br,kt) do{long _g=(long)(br)*(LD)+(long)(kt)*BK; \
;     _Pragma("unroll") for(int _i=0;_i<2;++_i){int _b=tid*16+_i*8192;int _r,_c;stage_rc(_b,_r,_c); \
;       __builtin_amdgcn_global_load_lds((const unsigned*)((BASE)+_g+(long)_r*(LD)+_c), \
;         (unsigned*)((char*)(P)+_b),16,0,0);}}while(0)
; #define LDA(dst,b,h) _Pragma("unroll") for(int m=0;m<4;++m) _Pragma("unroll") for(int k=0;k<2;++k) \
;     dst[m][k]=*reinterpret_cast<const bf16x8*>((char*)SA(b,h)+lds_byte(wr*64+m*16+fr,k*32+fq*8))
; #define LDB(dst,b,h) _Pragma("unroll") for(int n=0;n<2;++n) _Pragma("unroll") for(int k=0;k<2;++k) \
;     dst[n][k]=*reinterpret_cast<const bf16x8*>((char*)SB(b,h)+lds_byte(wc*32+n*16+fr,k*32+fq*8))
; #define MMA(ai,bj,At_,Bt_) do{__builtin_amdgcn_s_setprio(1); \
;     _Pragma("unroll") for(int m=0;m<4;++m) _Pragma("unroll") for(int n=0;n<2;++n) _Pragma("unroll") for(int k=0;k<2;++k) \
;       acc[ai][bj][m][n]=__builtin_amdgcn_mfma_f32_16x16x32_bf16(Bt_[n][k],At_[m][k],acc[ai][bj][m][n],0,0,0); \
;     __builtin_amdgcn_s_setprio(0);}while(0)
; #define WAIT_V(n) asm volatile("s_waitcnt vmcnt(" #n ")":::"memory")
; #define WAIT_L(n) asm volatile("s_waitcnt lgkmcnt(" #n ")":::"memory")
; #define BAR __builtin_amdgcn_s_barrier()
; #define SCHED __builtin_amdgcn_sched_barrier(0)
; DEVINL void gemm8_mainloop(const u16* A, long lda, const u16* Bt, long ldb, int K, int brow, int bcol, f32x4 (&acc)[2][2][4][2], char* smem, int tid) {
;     ...
;     LDA(At,1,1); STAGE(SA(1,0),A,lda,brow,t+3);
;     BAR; WAIT_L(0); MMA(1,0,At,B0); BAR; SCHED;
;     STAGE(SB(1,1),Bt,ldb,bcol+HALF,t+3);
;     WAIT_V(6); BAR; MMA(1,1,At,B1); BAR;
;   }
;   { LDB(B0,0,0); LDA(At,0,0); STAGE(SA(1,1),A,lda,brow+HALF,nt-1);
;     BAR; WAIT_L(0); MMA(0,0,At,B0); BAR;
	ds_read_b128 v[196:199], v131 offset:49152
	ds_read_b128 v[200:203], v131 offset:50176
	ds_read_b128 v[204:207], v174 offset:49152
	ds_read_b128 v[208:211], v174 offset:50176
	ds_read_b128 v[212:215], v175 offset:49152
	ds_read_b128 v[216:219], v175 offset:50176
	ds_read_b128 v[220:223], v177 offset:49152
	ds_read_b128 v[224:227], v177 offset:50176
	global_load_lds_dwordx4 v[244:245], off
	v_lshl_add_u64 v[244:245], v[246:247], 0, s[20:21]
	s_mov_b32 m0, s5
	s_nop 0
	global_load_lds_dwordx4 v[244:245], off
	s_barrier
	s_waitcnt lgkmcnt(0)
	s_setprio 1
	v_mfma_f32_16x16x32_bf16 v[60:63], v[180:183], v[196:199], v[60:63]
	v_mfma_f32_16x16x32_bf16 v[56:59], v[188:191], v[196:199], v[56:59]
	v_mfma_f32_16x16x32_bf16 v[52:55], v[180:183], v[204:207], v[52:55]
	v_mfma_f32_16x16x32_bf16 v[48:51], v[188:191], v[204:207], v[48:51]
	v_mfma_f32_16x16x32_bf16 v[44:47], v[180:183], v[212:215], v[44:47]
	v_mfma_f32_16x16x32_bf16 v[40:43], v[188:191], v[212:215], v[40:43]
	v_mfma_f32_16x16x32_bf16 v[36:39], v[180:183], v[220:223], v[36:39]
	v_mfma_f32_16x16x32_bf16 v[32:35], v[188:191], v[220:223], v[32:35]
	v_mfma_f32_16x16x32_bf16 v[60:63], v[184:187], v[200:203], v[60:63]
	v_mfma_f32_16x16x32_bf16 v[56:59], v[192:195], v[200:203], v[56:59]
	v_mfma_f32_16x16x32_bf16 v[52:55], v[184:187], v[208:211], v[52:55]
	v_mfma_f32_16x16x32_bf16 v[48:51], v[192:195], v[208:211], v[48:51]
	v_mfma_f32_16x16x32_bf16 v[44:47], v[184:187], v[216:219], v[44:47]
	v_mfma_f32_16x16x32_bf16 v[40:43], v[192:195], v[216:219], v[40:43]
	v_mfma_f32_16x16x32_bf16 v[36:39], v[184:187], v[224:227], v[36:39]
	v_mfma_f32_16x16x32_bf16 v[32:35], v[192:195], v[224:227], v[32:35]
	s_setprio 0
	s_barrier
	v_readfirstlane_b32 s5, v159
	v_add_u32_e32 v165, 0x2000, v159
	v_lshl_add_u64 v[180:181], v[248:249], 0, s[22:23]
	s_mov_b32 m0, s5
	v_readfirstlane_b32 s5, v165
	global_load_lds_dwordx4 v[180:181], off
	v_lshl_add_u64 v[180:181], v[250:251], 0, s[22:23]
	s_mov_b32 m0, s5
	s_nop 0
	global_load_lds_dwordx4 v[180:181], off
	s_waitcnt vmcnt(6)
	s_barrier
	s_setprio 1
	v_mfma_f32_16x16x32_bf16 v[28:31], v[228:231], v[196:199], v[28:31]
	v_mfma_f32_16x16x32_bf16 v[24:27], v[236:239], v[196:199], v[24:27]
	v_mfma_f32_16x16x32_bf16 v[20:23], v[228:231], v[204:207], v[20:23]
	v_mfma_f32_16x16x32_bf16 v[16:19], v[236:239], v[204:207], v[16:19]
	v_mfma_f32_16x16x32_bf16 v[12:15], v[228:231], v[212:215], v[12:15]
	v_mfma_f32_16x16x32_bf16 v[8:11], v[236:239], v[212:215], v[8:11]
	v_mfma_f32_16x16x32_bf16 v[4:7], v[228:231], v[220:223], v[4:7]
	v_mfma_f32_16x16x32_bf16 v[0:3], v[236:239], v[220:223], v[0:3]
	v_mfma_f32_16x16x32_bf16 v[28:31], v[232:235], v[200:203], v[28:31]
	v_mfma_f32_16x16x32_bf16 v[24:27], v[240:243], v[200:203], v[24:27]
	v_mfma_f32_16x16x32_bf16 v[20:23], v[232:235], v[208:211], v[20:23]
	v_mfma_f32_16x16x32_bf16 v[16:19], v[240:243], v[208:211], v[16:19]
	v_mfma_f32_16x16x32_bf16 v[12:15], v[232:235], v[216:219], v[12:15]
	v_mfma_f32_16x16x32_bf16 v[8:11], v[240:243], v[216:219], v[8:11]
	v_mfma_f32_16x16x32_bf16 v[4:7], v[232:235], v[224:227], v[4:7]
	v_mfma_f32_16x16x32_bf16 v[0:3], v[240:243], v[224:227], v[0:3]
	s_setprio 0
	s_add_i32 s4, s4, 2
	v_lshl_add_u64 v[144:145], v[144:145], 0, s[10:11]
	v_lshl_add_u64 v[146:147], v[146:147], 0, s[10:11]
	v_lshl_add_u64 v[148:149], v[148:149], 0, s[10:11]
	s_cmp_lt_u32 s4, 28
	v_lshl_add_u64 v[150:151], v[150:151], 0, s[10:11]
	s_cbranch_scc1 .LBB0_1292
	s_barrier
	s_or_b32 s4, s36, 0x80
	s_ashr_i32 s5, s4, 31
	s_lshl_b64 s[4:5], s[4:5], 12
	s_add_u32 s4, s90, s4
	s_addc_u32 s5, s91, s5
	v_lshl_add_u64 v[156:157], v[136:137], 1, s[4:5]
	v_lshl_add_u64 v[140:141], v[140:141], 1, v[156:157]
	v_readfirstlane_b32 s1, v178
	v_lshl_add_u64 v[140:141], v[140:141], 0, s[24:25]
	s_mov_b32 m0, s1
	ds_read_b128 v[144:147], v161
	ds_read_b128 v[148:151], v161 offset:1024
	ds_read_b128 v[180:183], v161 offset:2048
	ds_read_b128 v[184:187], v161 offset:3072
	ds_read_b128 v[188:191], v131
	ds_read_b128 v[192:195], v131 offset:1024
	ds_read_b128 v[196:199], v174
	ds_read_b128 v[200:203], v174 offset:1024
	ds_read_b128 v[204:207], v175
	ds_read_b128 v[208:211], v175 offset:1024
	ds_read_b128 v[212:215], v177
	ds_read_b128 v[216:219], v177 offset:1024
	global_load_lds_dwordx4 v[140:141], off
	v_lshl_add_u64 v[140:141], v[138:139], 1, s[4:5]
	v_lshl_add_u64 v[140:141], v[142:143], 1, v[140:141]
	v_readfirstlane_b32 s1, v179
	v_lshl_add_u64 v[140:141], v[140:141], 0, s[24:25]
	s_mov_b32 m0, s1
	s_nop 0
	global_load_lds_dwordx4 v[140:141], off
	s_barrier
	s_waitcnt lgkmcnt(0)
	s_setprio 1
	v_mfma_f32_16x16x32_bf16 v[124:127], v[144:147], v[188:191], v[124:127]
	v_mfma_f32_16x16x32_bf16 v[120:123], v[180:183], v[188:191], v[120:123]
	v_mfma_f32_16x16x32_bf16 v[108:111], v[144:147], v[204:207], v[108:111]
	v_mfma_f32_16x16x32_bf16 v[104:107], v[180:183], v[204:207], v[104:107]
	v_mfma_f32_16x16x32_bf16 v[124:127], v[148:151], v[192:195], v[124:127]
	v_mfma_f32_16x16x32_bf16 v[120:123], v[184:187], v[192:195], v[120:123]
	v_mfma_f32_16x16x32_bf16 v[116:119], v[144:147], v[196:199], v[116:119]
	v_mfma_f32_16x16x32_bf16 v[112:115], v[180:183], v[196:199], v[112:115]
	v_mfma_f32_16x16x32_bf16 v[108:111], v[148:151], v[208:211], v[108:111]
	v_mfma_f32_16x16x32_bf16 v[104:107], v[184:187], v[208:211], v[104:107]
	v_mfma_f32_16x16x32_bf16 v[100:103], v[144:147], v[212:215], v[100:103]
	v_mfma_f32_16x16x32_bf16 v[96:99], v[180:183], v[212:215], v[96:99]
	v_mfma_f32_16x16x32_bf16 v[140:143], v[148:151], v[200:203], v[116:119]
	v_mfma_f32_16x16x32_bf16 v[220:223], v[184:187], v[200:203], v[112:115]
	v_mfma_f32_16x16x32_bf16 v[224:227], v[148:151], v[216:219], v[100:103]
	v_mfma_f32_16x16x32_bf16 v[228:231], v[184:187], v[216:219], v[96:99]
	s_setprio 0
	s_barrier
; #define LDA(dst,b,h) _Pragma("unroll") for(int m=0;m<4;++m) _Pragma("unroll") for(int k=0;k<2;++k) \
;     dst[m][k]=*reinterpret_cast<const bf16x8*>((char*)SA(b,h)+lds_byte(wr*64+m*16+fr,k*32+fq*8))
; #define LDB(dst,b,h) _Pragma("unroll") for(int n=0;n<2;++n) _Pragma("unroll") for(int k=0;k<2;++k) \
;     dst[n][k]=*reinterpret_cast<const bf16x8*>((char*)SB(b,h)+lds_byte(wc*32+n*16+fr,k*32+fq*8))
; #define MMA(ai,bj,At_,Bt_) do{__builtin_amdgcn_s_setprio(1); \
;     _Pragma("unroll") for(int m=0;m<4;++m) _Pragma("unroll") for(int n=0;n<2;++n) _Pragma("unroll") for(int k=0;k<2;++k) \
;       acc[ai][bj][m][n]=__builtin_amdgcn_mfma_f32_16x16x32_bf16(Bt_[n][k],At_[m][k],acc[ai][bj][m][n],0,0,0); \
;     __builtin_amdgcn_s_setprio(0);}while(0)
; #define WAIT_V(n) asm volatile("s_waitcnt vmcnt(" #n ")":::"memory")
; #define WAIT_L(n) asm volatile("s_waitcnt lgkmcnt(" #n ")":::"memory")
; #define BAR __builtin_amdgcn_s_barrier()
; DEVINL void gemm8_mainloop(const u16* A, long lda, const u16* Bt, long ldb, int K, int brow, int bcol, f32x4 (&acc)[2][2][4][2], char* smem, int tid) {
;     ...
;     LDB(B1,0,1); BAR; WAIT_L(0); MMA(0,1,At,B1); BAR;
;     LDA(At,0,1); WAIT_V(4); BAR; WAIT_L(0); MMA(1,0,At,B0); MMA(1,1,At,B1); BAR; }
;   { LDB(B0,1,0); LDA(At,1,0); WAIT_V(2); BAR; WAIT_L(0); MMA(0,0,At,B0); BAR;
	s_nop 1
	ds_read_b128 v[96:99], v158
	ds_read_b128 v[100:103], v158 offset:1024
	ds_read_b128 v[112:115], v158 offset:2048
	ds_read_b128 v[116:119], v158 offset:3072
	s_barrier
	s_waitcnt lgkmcnt(0)
	s_setprio 1
	v_mfma_f32_16x16x32_bf16 v[92:95], v[96:99], v[188:191], v[92:95]
	v_mfma_f32_16x16x32_bf16 v[88:91], v[112:115], v[188:191], v[88:91]
	v_mfma_f32_16x16x32_bf16 v[76:79], v[96:99], v[204:207], v[76:79]
	v_mfma_f32_16x16x32_bf16 v[72:75], v[112:115], v[204:207], v[72:75]
	v_mfma_f32_16x16x32_bf16 v[92:95], v[100:103], v[192:195], v[92:95]
	v_mfma_f32_16x16x32_bf16 v[88:91], v[116:119], v[192:195], v[88:91]
	v_mfma_f32_16x16x32_bf16 v[84:87], v[96:99], v[196:199], v[84:87]
	v_mfma_f32_16x16x32_bf16 v[80:83], v[112:115], v[196:199], v[80:83]
	v_mfma_f32_16x16x32_bf16 v[76:79], v[100:103], v[208:211], v[76:79]
	v_mfma_f32_16x16x32_bf16 v[72:75], v[116:119], v[208:211], v[72:75]
	v_mfma_f32_16x16x32_bf16 v[68:71], v[96:99], v[212:215], v[68:71]
	v_mfma_f32_16x16x32_bf16 v[64:67], v[112:115], v[212:215], v[64:67]
	v_mfma_f32_16x16x32_bf16 v[156:159], v[100:103], v[200:203], v[84:87]
	v_mfma_f32_16x16x32_bf16 v[188:191], v[116:119], v[200:203], v[80:83]
	v_mfma_f32_16x16x32_bf16 v[192:195], v[100:103], v[216:219], v[68:71]
	v_mfma_f32_16x16x32_bf16 v[196:199], v[116:119], v[216:219], v[64:67]
	s_setprio 0
	s_barrier
	s_nop 1
	ds_read_b128 v[64:67], v131 offset:16384
	ds_read_b128 v[68:71], v131 offset:17408
	ds_read_b128 v[80:83], v174 offset:16384
	ds_read_b128 v[84:87], v174 offset:17408
	ds_read_b128 v[200:203], v175 offset:16384
	ds_read_b128 v[204:207], v175 offset:17408
	ds_read_b128 v[208:211], v177 offset:16384
	ds_read_b128 v[212:215], v177 offset:17408
	s_waitcnt vmcnt(4)
	s_barrier
	s_waitcnt lgkmcnt(0)
	s_setprio 1
	v_mfma_f32_16x16x32_bf16 v[60:63], v[144:147], v[64:67], v[60:63]
	v_mfma_f32_16x16x32_bf16 v[52:55], v[144:147], v[80:83], v[52:55]
	v_mfma_f32_16x16x32_bf16 v[44:47], v[144:147], v[200:203], v[44:47]
	v_mfma_f32_16x16x32_bf16 v[40:43], v[180:183], v[200:203], v[40:43]
	v_mfma_f32_16x16x32_bf16 v[60:63], v[148:151], v[68:71], v[60:63]
	v_mfma_f32_16x16x32_bf16 v[56:59], v[180:183], v[64:67], v[56:59]
	v_mfma_f32_16x16x32_bf16 v[52:55], v[148:151], v[84:87], v[52:55]
	v_mfma_f32_16x16x32_bf16 v[48:51], v[180:183], v[80:83], v[48:51]
	v_mfma_f32_16x16x32_bf16 v[44:47], v[148:151], v[204:207], v[44:47]
	v_mfma_f32_16x16x32_bf16 v[40:43], v[184:187], v[204:207], v[40:43]
	v_mfma_f32_16x16x32_bf16 v[36:39], v[144:147], v[208:211], v[36:39]
	v_mfma_f32_16x16x32_bf16 v[32:35], v[180:183], v[208:211], v[32:35]
	v_mfma_f32_16x16x32_bf16 v[216:219], v[184:187], v[68:71], v[56:59]
	v_mfma_f32_16x16x32_bf16 v[232:235], v[184:187], v[84:87], v[48:51]
	v_mfma_f32_16x16x32_bf16 v[144:147], v[148:151], v[212:215], v[36:39]
	v_mfma_f32_16x16x32_bf16 v[148:151], v[184:187], v[212:215], v[32:35]
	s_setprio 0
	s_setprio 1
	v_mfma_f32_16x16x32_bf16 v[28:31], v[96:99], v[64:67], v[28:31]
	v_mfma_f32_16x16x32_bf16 v[20:23], v[96:99], v[80:83], v[20:23]
	v_mfma_f32_16x16x32_bf16 v[12:15], v[96:99], v[200:203], v[12:15]
	v_mfma_f32_16x16x32_bf16 v[4:7], v[96:99], v[208:211], v[4:7]
	v_mfma_f32_16x16x32_bf16 v[28:31], v[100:103], v[68:71], v[28:31]
	v_mfma_f32_16x16x32_bf16 v[24:27], v[112:115], v[64:67], v[24:27]
	v_mfma_f32_16x16x32_bf16 v[20:23], v[100:103], v[84:87], v[20:23]
	v_mfma_f32_16x16x32_bf16 v[16:19], v[112:115], v[80:83], v[16:19]
	v_mfma_f32_16x16x32_bf16 v[12:15], v[100:103], v[204:207], v[12:15]
	v_mfma_f32_16x16x32_bf16 v[8:11], v[112:115], v[200:203], v[8:11]
	v_mfma_f32_16x16x32_bf16 v[4:7], v[100:103], v[212:215], v[4:7]
	v_mfma_f32_16x16x32_bf16 v[0:3], v[112:115], v[208:211], v[0:3]
	v_mfma_f32_16x16x32_bf16 v[178:181], v[116:119], v[68:71], v[24:27]
	v_mfma_f32_16x16x32_bf16 v[182:185], v[116:119], v[84:87], v[16:19]
	v_mfma_f32_16x16x32_bf16 v[200:203], v[116:119], v[204:207], v[8:11]
	v_mfma_f32_16x16x32_bf16 v[204:207], v[116:119], v[212:215], v[0:3]
	s_setprio 0
	s_barrier
	s_nop 1
	ds_read_b128 v[0:3], v154
	ds_read_b128 v[8:11], v154 offset:1024
	ds_read_b128 v[208:211], v154 offset:2048
	ds_read_b128 v[212:215], v154 offset:3072
	ds_read_b128 v[16:19], v131 offset:32768
	ds_read_b128 v[24:27], v131 offset:33792
	ds_read_b128 v[32:35], v174 offset:32768
	ds_read_b128 v[36:39], v174 offset:33792
	ds_read_b128 v[48:51], v175 offset:32768
	ds_read_b128 v[56:59], v175 offset:33792
	ds_read_b128 v[236:239], v177 offset:32768
	ds_read_b128 v[240:243], v177 offset:33792
	s_waitcnt vmcnt(2)
	s_barrier
; #define LDA(dst,b,h) _Pragma("unroll") for(int m=0;m<4;++m) _Pragma("unroll") for(int k=0;k<2;++k) \
;     dst[m][k]=*reinterpret_cast<const bf16x8*>((char*)SA(b,h)+lds_byte(wr*64+m*16+fr,k*32+fq*8))
; #define LDB(dst,b,h) _Pragma("unroll") for(int n=0;n<2;++n) _Pragma("unroll") for(int k=0;k<2;++k) \
;     dst[n][k]=*reinterpret_cast<const bf16x8*>((char*)SB(b,h)+lds_byte(wc*32+n*16+fr,k*32+fq*8))
; #define MMA(ai,bj,At_,Bt_) do{__builtin_amdgcn_s_setprio(1); \
;     _Pragma("unroll") for(int m=0;m<4;++m) _Pragma("unroll") for(int n=0;n<2;++n) _Pragma("unroll") for(int k=0;k<2;++k) \
;       acc[ai][bj][m][n]=__builtin_amdgcn_mfma_f32_16x16x32_bf16(Bt_[n][k],At_[m][k],acc[ai][bj][m][n],0,0,0); \
;     __builtin_amdgcn_s_setprio(0);}while(0)
; #define WAIT_V(n) asm volatile("s_waitcnt vmcnt(" #n ")":::"memory")
; #define WAIT_L(n) asm volatile("s_waitcnt lgkmcnt(" #n ")":::"memory")
; #define BAR __builtin_amdgcn_s_barrier()
; DEVINL void gemm8_mainloop(const u16* A, long lda, const u16* Bt, long ldb, int K, int brow, int bcol, f32x4 (&acc)[2][2][4][2], char* smem, int tid) {
;     ...
;   { LDB(B0,1,0); LDA(At,1,0); WAIT_V(2); BAR; WAIT_L(0); MMA(0,0,At,B0); BAR;
;     LDB(B1,1,1); WAIT_V(0); BAR; WAIT_L(0); MMA(0,1,At,B1); BAR;
;     LDA(At,1,1); BAR; WAIT_L(0); MMA(1,0,At,B0); MMA(1,1,At,B1); BAR; }
;   if(wr==0)BAR;
;   __syncthreads();
	s_waitcnt lgkmcnt(0)
	s_setprio 1
	v_mfma_f32_16x16x32_bf16 v[64:67], v[0:3], v[16:19], v[124:127]
	v_mfma_f32_16x16x32_bf16 v[116:119], v[8:11], v[24:27], v[64:67]
	v_mfma_f32_16x16x32_bf16 v[64:67], v[208:211], v[16:19], v[120:123]
	v_mfma_f32_16x16x32_bf16 v[112:115], v[212:215], v[24:27], v[64:67]
	v_mfma_f32_16x16x32_bf16 v[64:67], v[0:3], v[32:35], v[140:143]
	v_mfma_f32_16x16x32_bf16 v[100:103], v[8:11], v[36:39], v[64:67]
	v_mfma_f32_16x16x32_bf16 v[64:67], v[208:211], v[32:35], v[220:223]
	v_mfma_f32_16x16x32_bf16 v[96:99], v[212:215], v[36:39], v[64:67]
	v_mfma_f32_16x16x32_bf16 v[64:67], v[0:3], v[48:51], v[108:111]
	v_mfma_f32_16x16x32_bf16 v[84:87], v[8:11], v[56:59], v[64:67]
	v_mfma_f32_16x16x32_bf16 v[64:67], v[208:211], v[48:51], v[104:107]
	v_mfma_f32_16x16x32_bf16 v[80:83], v[212:215], v[56:59], v[64:67]
	v_mfma_f32_16x16x32_bf16 v[64:67], v[0:3], v[236:239], v[224:227]
	v_mfma_f32_16x16x32_bf16 v[68:71], v[8:11], v[240:243], v[64:67]
	v_mfma_f32_16x16x32_bf16 v[64:67], v[208:211], v[236:239], v[228:231]
	v_mfma_f32_16x16x32_bf16 v[64:67], v[212:215], v[240:243], v[64:67]
	s_setprio 0
	s_barrier
	ds_read_b128 v[140:143], v152
	ds_read_b128 v[220:223], v152 offset:1024
	ds_read_b128 v[224:227], v152 offset:2048
	ds_read_b128 v[152:155], v152 offset:3072
	s_waitcnt vmcnt(0)
	s_barrier
	s_waitcnt lgkmcnt(0)
	s_setprio 1
	v_mfma_f32_16x16x32_bf16 v[92:95], v[140:143], v[16:19], v[92:95]
	v_mfma_f32_16x16x32_bf16 v[16:19], v[224:227], v[16:19], v[88:91]
	v_mfma_f32_16x16x32_bf16 v[120:123], v[152:155], v[24:27], v[16:19]
	v_mfma_f32_16x16x32_bf16 v[16:19], v[140:143], v[32:35], v[156:159]
	v_mfma_f32_16x16x32_bf16 v[104:107], v[220:223], v[36:39], v[16:19]
	v_mfma_f32_16x16x32_bf16 v[16:19], v[224:227], v[32:35], v[188:191]
	v_mfma_f32_16x16x32_bf16 v[108:111], v[152:155], v[36:39], v[16:19]
	v_mfma_f32_16x16x32_bf16 v[16:19], v[140:143], v[48:51], v[76:79]
	v_mfma_f32_16x16x32_bf16 v[124:127], v[220:223], v[24:27], v[92:95]
	v_mfma_f32_16x16x32_bf16 v[92:95], v[220:223], v[56:59], v[16:19]
	v_mfma_f32_16x16x32_bf16 v[16:19], v[224:227], v[48:51], v[72:75]
	v_mfma_f32_16x16x32_bf16 v[88:91], v[152:155], v[56:59], v[16:19]
	v_mfma_f32_16x16x32_bf16 v[16:19], v[140:143], v[236:239], v[192:195]
	v_mfma_f32_16x16x32_bf16 v[72:75], v[220:223], v[240:243], v[16:19]
	v_mfma_f32_16x16x32_bf16 v[16:19], v[224:227], v[236:239], v[196:199]
	v_mfma_f32_16x16x32_bf16 v[76:79], v[152:155], v[240:243], v[16:19]
	s_setprio 0
	s_barrier
	ds_read_b128 v[156:159], v131 offset:49152
	ds_read_b128 v[186:189], v131 offset:50176
	ds_read_b128 v[190:193], v174 offset:49152
	ds_read_b128 v[194:197], v174 offset:50176
	ds_read_b128 v[228:231], v175 offset:49152
	ds_read_b128 v[236:239], v175 offset:50176
	ds_read_b128 v[240:243], v177 offset:49152
	ds_read_b128 v[244:247], v177 offset:50176
	s_barrier
	s_waitcnt lgkmcnt(0)
	s_setprio 1
	v_mfma_f32_16x16x32_bf16 v[16:19], v[0:3], v[156:159], v[60:63]
	v_mfma_f32_16x16x32_bf16 v[56:59], v[8:11], v[186:189], v[16:19]
	v_mfma_f32_16x16x32_bf16 v[16:19], v[208:211], v[156:159], v[216:219]
	v_mfma_f32_16x16x32_bf16 v[48:51], v[212:215], v[186:189], v[16:19]
	v_mfma_f32_16x16x32_bf16 v[16:19], v[0:3], v[190:193], v[52:55]
	v_mfma_f32_16x16x32_bf16 v[36:39], v[8:11], v[194:197], v[16:19]
	v_mfma_f32_16x16x32_bf16 v[16:19], v[208:211], v[190:193], v[232:235]
	v_mfma_f32_16x16x32_bf16 v[32:35], v[212:215], v[194:197], v[16:19]
	v_mfma_f32_16x16x32_bf16 v[16:19], v[0:3], v[228:231], v[44:47]
	v_mfma_f32_16x16x32_bf16 v[0:3], v[0:3], v[240:243], v[144:147]
	v_mfma_f32_16x16x32_bf16 v[24:27], v[8:11], v[236:239], v[16:19]
	v_mfma_f32_16x16x32_bf16 v[16:19], v[208:211], v[228:231], v[40:43]
	v_mfma_f32_16x16x32_bf16 v[8:11], v[8:11], v[244:247], v[0:3]
	v_mfma_f32_16x16x32_bf16 v[0:3], v[208:211], v[240:243], v[148:151]
	v_mfma_f32_16x16x32_bf16 v[16:19], v[212:215], v[236:239], v[16:19]
	v_mfma_f32_16x16x32_bf16 v[0:3], v[212:215], v[244:247], v[0:3]
	s_setprio 0
	s_setprio 1
	v_mfma_f32_16x16x32_bf16 v[28:31], v[140:143], v[156:159], v[28:31]
	v_mfma_f32_16x16x32_bf16 v[60:63], v[220:223], v[186:189], v[28:31]
	v_mfma_f32_16x16x32_bf16 v[28:31], v[224:227], v[156:159], v[178:181]
	v_mfma_f32_16x16x32_bf16 v[20:23], v[140:143], v[190:193], v[20:23]
	v_mfma_f32_16x16x32_bf16 v[12:15], v[140:143], v[228:231], v[12:15]
	v_mfma_f32_16x16x32_bf16 v[52:55], v[152:155], v[186:189], v[28:31]
	v_mfma_f32_16x16x32_bf16 v[40:43], v[220:223], v[194:197], v[20:23]
	v_mfma_f32_16x16x32_bf16 v[20:23], v[224:227], v[190:193], v[182:185]
	v_mfma_f32_16x16x32_bf16 v[28:31], v[220:223], v[236:239], v[12:15]
	v_mfma_f32_16x16x32_bf16 v[12:15], v[224:227], v[228:231], v[200:203]
	v_mfma_f32_16x16x32_bf16 v[4:7], v[140:143], v[240:243], v[4:7]
	v_mfma_f32_16x16x32_bf16 v[44:47], v[152:155], v[194:197], v[20:23]
	v_mfma_f32_16x16x32_bf16 v[20:23], v[152:155], v[236:239], v[12:15]
	v_mfma_f32_16x16x32_bf16 v[12:15], v[220:223], v[244:247], v[4:7]
	v_mfma_f32_16x16x32_bf16 v[4:7], v[224:227], v[240:243], v[204:207]
	v_mfma_f32_16x16x32_bf16 v[4:7], v[152:155], v[244:247], v[4:7]
	s_setprio 0
	s_cmpk_gt_u32 s0, 0xff
	s_barrier
	s_cbranch_scc1 .LBB0_1295
	s_barrier

; #define STAGE(P,BASE,LD,br,kt) do{long _g=(long)(br)*(LD)+(long)(kt)*BK; \
;     _Pragma("unroll") for(int _i=0;_i<2;++_i){int _b=tid*16+_i*8192;int _r,_c;stage_rc(_b,_r,_c); \
;       __builtin_amdgcn_global_load_lds((const unsigned*)((BASE)+_g+(long)_r*(LD)+_c), \
;         (unsigned*)((char*)(P)+_b),16,0,0);}}while(0)
; #define STAGE(P,BASE,LD,br,kt) do{long _g=(long)(br)*(LD)+(long)(kt)*BK; \
;     _Pragma("unroll") for(int _i=0;_i<2;++_i){int _b=tid*16+_i*8192;int _r,_c;stage_rc(_b,_r,_c); \
;       __builtin_amdgcn_global_load_lds((const unsigned*)((BASE)+_g+(long)_r*(LD)+_c), \
;         (unsigned*)((char*)(P)+_b),16,0,0);}}while(0)
; #define LDA(dst,b,h) _Pragma("unroll") for(int m=0;m<4;++m) _Pragma("unroll") for(int k=0;k<2;++k) \
;     dst[m][k]=*reinterpret_cast<const bf16x8*>((char*)SA(b,h)+lds_byte(wr*64+m*16+fr,k*32+fq*8))
; #define LDB(dst,b,h) _Pragma("unroll") for(int n=0;n<2;++n) _Pragma("unroll") for(int k=0;k<2;++k) \
;     dst[n][k]=*reinterpret_cast<const bf16x8*>((char*)SB(b,h)+lds_byte(wc*32+n*16+fr,k*32+fq*8))
; #define MMA(ai,bj,At_,Bt_) do{__builtin_amdgcn_s_setprio(1); \
;     _Pragma("unroll") for(int m=0;m<4;++m) _Pragma("unroll") for(int n=0;n<2;++n) _Pragma("unroll") for(int k=0;k<2;++k) \
;       acc[ai][bj][m][n]=__builtin_amdgcn_mfma_f32_16x16x32_bf16(Bt_[n][k],At_[m][k],acc[ai][bj][m][n],0,0,0); \
;     __builtin_amdgcn_s_setprio(0);}while(0)
; #define WAIT_L(n) asm volatile("s_waitcnt lgkmcnt(" #n ")":::"memory")
; #define BAR __builtin_amdgcn_s_barrier()
; #define SCHED __builtin_amdgcn_sched_barrier(0)
; DEVINL void gemm8_mainloop(const u16* A, long lda, const u16* Bt, long ldb, int K, int brow, int bcol, f32x4 (&acc)[2][2][4][2], char* smem, int tid) {
;     ...
;   for(int t=0;t<nt-2;t+=2){
;     LDB(B0,0,0); SCHED; LDA(At,0,0); STAGE(SA(1,1),A,lda,brow+HALF,t+1);
;     WAIT_L(8); BAR; WAIT_L(0); MMA(0,0,At,B0); BAR; SCHED;
;     LDB(B1,0,1); STAGE(SB(0,0),Bt,ldb,bcol,t+2);
;     BAR; WAIT_L(0); MMA(0,1,At,B1); BAR;
;     LDA(At,0,1); STAGE(SA(0,0),A,lda,brow,t+2);
;     BAR; WAIT_L(0); MMA(1,0,At,B0); BAR; SCHED;
.LBB0_1871:
	s_barrier
	ds_read_b128 v[178:181], v163
	ds_read_b128 v[182:185], v163 offset:1024
	ds_read_b128 v[186:189], v163 offset:2048
	ds_read_b128 v[190:193], v163 offset:3072
	v_add_u32_e32 v174, 0xc000, v152
	v_lshl_add_u64 v[242:243], s[94:95], 0, v[146:147]
	v_readfirstlane_b32 s27, v174
	v_add_u32_e32 v175, 0xe000, v152
	v_add_u32_e32 v171, s25, v162
	v_add_u32_e32 v172, s37, v162
	v_add_u32_e32 v173, s38, v162
	v_lshl_add_u64 v[164:165], v[242:243], 0, s[2:3]
	s_mov_b32 m0, s27
	v_lshl_add_u64 v[244:245], s[94:95], 0, v[148:149]
	v_readfirstlane_b32 s27, v175
	ds_read_b128 v[166:169], v153
	ds_read_b128 v[194:197], v153 offset:1024
	ds_read_b128 v[198:201], v171
	ds_read_b128 v[202:205], v171 offset:1024
	ds_read_b128 v[206:209], v172
	ds_read_b128 v[210:213], v172 offset:1024
	ds_read_b128 v[214:217], v173
	ds_read_b128 v[218:221], v173 offset:1024
	global_load_lds_dwordx4 v[164:165], off
	v_lshl_add_u64 v[164:165], v[244:245], 0, s[2:3]
	s_mov_b32 m0, s27
	s_nop 0
	global_load_lds_dwordx4 v[164:165], off
	s_waitcnt lgkmcnt(8)
	s_barrier
	s_waitcnt lgkmcnt(0)
	s_setprio 1
	v_mfma_f32_16x16x32_bf16 v[124:127], v[178:181], v[166:169], v[124:127]
	v_mfma_f32_16x16x32_bf16 v[120:123], v[186:189], v[166:169], v[120:123]
	v_mfma_f32_16x16x32_bf16 v[116:119], v[178:181], v[198:201], v[116:119]
	v_mfma_f32_16x16x32_bf16 v[112:115], v[186:189], v[198:201], v[112:115]
	v_mfma_f32_16x16x32_bf16 v[108:111], v[178:181], v[206:209], v[108:111]
	v_mfma_f32_16x16x32_bf16 v[104:107], v[186:189], v[206:209], v[104:107]
	v_mfma_f32_16x16x32_bf16 v[100:103], v[178:181], v[214:217], v[100:103]
	v_mfma_f32_16x16x32_bf16 v[96:99], v[186:189], v[214:217], v[96:99]
	v_mfma_f32_16x16x32_bf16 v[124:127], v[182:185], v[194:197], v[124:127]
	v_mfma_f32_16x16x32_bf16 v[120:123], v[190:193], v[194:197], v[120:123]
	v_mfma_f32_16x16x32_bf16 v[116:119], v[182:185], v[202:205], v[116:119]
	v_mfma_f32_16x16x32_bf16 v[112:115], v[190:193], v[202:205], v[112:115]
	v_mfma_f32_16x16x32_bf16 v[108:111], v[182:185], v[210:213], v[108:111]
	v_mfma_f32_16x16x32_bf16 v[104:107], v[190:193], v[210:213], v[104:107]
	v_mfma_f32_16x16x32_bf16 v[100:103], v[182:185], v[218:221], v[100:103]
	v_mfma_f32_16x16x32_bf16 v[96:99], v[190:193], v[218:221], v[96:99]
	s_setprio 0
	s_barrier
	v_add_u32_e32 v164, s30, v154
	v_lshl_add_u64 v[246:247], s[94:95], 0, v[142:143]
	v_readfirstlane_b32 s27, v164
	v_add_u32_e32 v165, 0x2000, v164
	v_lshl_add_u64 v[238:239], v[246:247], 0, s[4:5]
	s_mov_b32 m0, s27
	v_lshl_add_u64 v[248:249], s[94:95], 0, v[144:145]
	v_readfirstlane_b32 s27, v165
	ds_read_b128 v[222:225], v160
	ds_read_b128 v[226:229], v160 offset:1024
	ds_read_b128 v[230:233], v160 offset:2048
	ds_read_b128 v[234:237], v160 offset:3072
	global_load_lds_dwordx4 v[238:239], off
	v_lshl_add_u64 v[238:239], v[248:249], 0, s[4:5]
	s_mov_b32 m0, s27
	s_nop 0
	global_load_lds_dwordx4 v[238:239], off
	s_barrier
	s_waitcnt lgkmcnt(0)
	s_setprio 1
	v_mfma_f32_16x16x32_bf16 v[92:95], v[222:225], v[166:169], v[92:95]
	v_mfma_f32_16x16x32_bf16 v[88:91], v[230:233], v[166:169], v[88:91]
	v_mfma_f32_16x16x32_bf16 v[84:87], v[222:225], v[198:201], v[84:87]
	v_mfma_f32_16x16x32_bf16 v[80:83], v[230:233], v[198:201], v[80:83]
	v_mfma_f32_16x16x32_bf16 v[76:79], v[222:225], v[206:209], v[76:79]
	v_mfma_f32_16x16x32_bf16 v[72:75], v[230:233], v[206:209], v[72:75]
	v_mfma_f32_16x16x32_bf16 v[68:71], v[222:225], v[214:217], v[68:71]
	v_mfma_f32_16x16x32_bf16 v[64:67], v[230:233], v[214:217], v[64:67]
	v_mfma_f32_16x16x32_bf16 v[92:95], v[226:229], v[194:197], v[92:95]
	v_mfma_f32_16x16x32_bf16 v[88:91], v[234:237], v[194:197], v[88:91]
	v_mfma_f32_16x16x32_bf16 v[84:87], v[226:229], v[202:205], v[84:87]
	v_mfma_f32_16x16x32_bf16 v[80:83], v[234:237], v[202:205], v[80:83]
	v_mfma_f32_16x16x32_bf16 v[76:79], v[226:229], v[210:213], v[76:79]
	v_mfma_f32_16x16x32_bf16 v[72:75], v[234:237], v[210:213], v[72:75]
	v_mfma_f32_16x16x32_bf16 v[68:71], v[226:229], v[218:221], v[68:71]
	v_mfma_f32_16x16x32_bf16 v[64:67], v[234:237], v[218:221], v[64:67]
	s_setprio 0
	v_readfirstlane_b32 s27, v152
	v_lshl_add_u64 v[166:167], v[242:243], 0, s[6:7]
	s_mov_b32 m0, s27
	s_barrier
	ds_read_b128 v[194:197], v153 offset:16384
	ds_read_b128 v[198:201], v153 offset:17408
	ds_read_b128 v[202:205], v171 offset:16384
	ds_read_b128 v[206:209], v171 offset:17408
	ds_read_b128 v[210:213], v172 offset:16384
	ds_read_b128 v[214:217], v172 offset:17408
	ds_read_b128 v[218:221], v173 offset:16384
	ds_read_b128 v[238:241], v173 offset:17408
	global_load_lds_dwordx4 v[166:167], off
	v_add_u32_e32 v166, 0x2000, v152
	v_lshl_add_u64 v[168:169], v[244:245], 0, s[6:7]
	v_readfirstlane_b32 s27, v166
	s_mov_b32 m0, s27
	s_nop 0
	global_load_lds_dwordx4 v[168:169], off
	s_barrier
	s_waitcnt lgkmcnt(0)
	s_setprio 1
	v_mfma_f32_16x16x32_bf16 v[60:63], v[178:181], v[194:197], v[60:63]
	v_mfma_f32_16x16x32_bf16 v[56:59], v[186:189], v[194:197], v[56:59]
	v_mfma_f32_16x16x32_bf16 v[52:55], v[178:181], v[202:205], v[52:55]
	v_mfma_f32_16x16x32_bf16 v[48:51], v[186:189], v[202:205], v[48:51]
	v_mfma_f32_16x16x32_bf16 v[44:47], v[178:181], v[210:213], v[44:47]
	v_mfma_f32_16x16x32_bf16 v[40:43], v[186:189], v[210:213], v[40:43]
	v_mfma_f32_16x16x32_bf16 v[36:39], v[178:181], v[218:221], v[36:39]
	v_mfma_f32_16x16x32_bf16 v[32:35], v[186:189], v[218:221], v[32:35]
	v_mfma_f32_16x16x32_bf16 v[60:63], v[182:185], v[198:201], v[60:63]
	v_mfma_f32_16x16x32_bf16 v[56:59], v[190:193], v[198:201], v[56:59]
	v_mfma_f32_16x16x32_bf16 v[52:55], v[182:185], v[206:209], v[52:55]
	v_mfma_f32_16x16x32_bf16 v[48:51], v[190:193], v[206:209], v[48:51]
	v_mfma_f32_16x16x32_bf16 v[44:47], v[182:185], v[214:217], v[44:47]
	v_mfma_f32_16x16x32_bf16 v[40:43], v[190:193], v[214:217], v[40:43]
	v_mfma_f32_16x16x32_bf16 v[36:39], v[182:185], v[238:241], v[36:39]
	v_mfma_f32_16x16x32_bf16 v[32:35], v[190:193], v[238:241], v[32:35]
	s_setprio 0
	s_barrier
; #define STAGE(P,BASE,LD,br,kt) do{long _g=(long)(br)*(LD)+(long)(kt)*BK; \
;     _Pragma("unroll") for(int _i=0;_i<2;++_i){int _b=tid*16+_i*8192;int _r,_c;stage_rc(_b,_r,_c); \
;       __builtin_amdgcn_global_load_lds((const unsigned*)((BASE)+_g+(long)_r*(LD)+_c), \
;         (unsigned*)((char*)(P)+_b),16,0,0);}}while(0)
; #define STAGE(P,BASE,LD,br,kt) do{long _g=(long)(br)*(LD)+(long)(kt)*BK; \
;     _Pragma("unroll") for(int _i=0;_i<2;++_i){int _b=tid*16+_i*8192;int _r,_c;stage_rc(_b,_r,_c); \
;       __builtin_amdgcn_global_load_lds((const unsigned*)((BASE)+_g+(long)_r*(LD)+_c), \
;         (unsigned*)((char*)(P)+_b),16,0,0);}}while(0)
; #define LDA(dst,b,h) _Pragma("unroll") for(int m=0;m<4;++m) _Pragma("unroll") for(int k=0;k<2;++k) \
;     dst[m][k]=*reinterpret_cast<const bf16x8*>((char*)SA(b,h)+lds_byte(wr*64+m*16+fr,k*32+fq*8))
; #define LDB(dst,b,h) _Pragma("unroll") for(int n=0;n<2;++n) _Pragma("unroll") for(int k=0;k<2;++k) \
;     dst[n][k]=*reinterpret_cast<const bf16x8*>((char*)SB(b,h)+lds_byte(wc*32+n*16+fr,k*32+fq*8))
; #define MMA(ai,bj,At_,Bt_) do{__builtin_amdgcn_s_setprio(1); \
;     _Pragma("unroll") for(int m=0;m<4;++m) _Pragma("unroll") for(int n=0;n<2;++n) _Pragma("unroll") for(int k=0;k<2;++k) \
;       acc[ai][bj][m][n]=__builtin_amdgcn_mfma_f32_16x16x32_bf16(Bt_[n][k],At_[m][k],acc[ai][bj][m][n],0,0,0); \
;     __builtin_amdgcn_s_setprio(0);}while(0)
; #define WAIT_V(n) asm volatile("s_waitcnt vmcnt(" #n ")":::"memory")
; #define WAIT_L(n) asm volatile("s_waitcnt lgkmcnt(" #n ")":::"memory")
; #define BAR __builtin_amdgcn_s_barrier()
; #define SCHED __builtin_amdgcn_sched_barrier(0)
; DEVINL void gemm8_mainloop(const u16* A, long lda, const u16* Bt, long ldb, int K, int brow, int bcol, f32x4 (&acc)[2][2][4][2], char* smem, int tid) {
;     ...
;     STAGE(SB(0,1),Bt,ldb,bcol+HALF,t+2);
;     WAIT_V(6); BAR; MMA(1,1,At,B1); BAR;
;     LDB(B0,1,0); SCHED; LDA(At,1,0); STAGE(SA(0,1),A,lda,brow+HALF,t+2);
;     WAIT_L(8); BAR; WAIT_L(0); MMA(0,0,At,B0); BAR; SCHED;
;     LDB(B1,1,1); STAGE(SB(1,0),Bt,ldb,bcol,t+3);
;     BAR; WAIT_L(0); MMA(0,1,At,B1); BAR;
;     LDA(At,1,1); STAGE(SA(1,0),A,lda,brow,t+3);
	v_add_u32_e32 v167, s31, v154
	v_lshl_add_u64 v[168:169], v[246:247], 0, s[8:9]
	v_readfirstlane_b32 s27, v167
	s_mov_b32 m0, s27
	v_lshl_add_u64 v[178:179], v[248:249], 0, s[8:9]
	global_load_lds_dwordx4 v[168:169], off
	v_add_u32_e32 v168, 0x2000, v167
	s_nop 0
	v_readfirstlane_b32 s27, v168
	s_mov_b32 m0, s27
	s_nop 0
	global_load_lds_dwordx4 v[178:179], off
	s_waitcnt vmcnt(6)
	s_barrier
	s_setprio 1
	v_mfma_f32_16x16x32_bf16 v[28:31], v[222:225], v[194:197], v[28:31]
	v_mfma_f32_16x16x32_bf16 v[24:27], v[230:233], v[194:197], v[24:27]
	v_mfma_f32_16x16x32_bf16 v[20:23], v[222:225], v[202:205], v[20:23]
	v_mfma_f32_16x16x32_bf16 v[16:19], v[230:233], v[202:205], v[16:19]
	v_mfma_f32_16x16x32_bf16 v[12:15], v[222:225], v[210:213], v[12:15]
	v_mfma_f32_16x16x32_bf16 v[8:11], v[230:233], v[210:213], v[8:11]
	v_mfma_f32_16x16x32_bf16 v[4:7], v[222:225], v[218:221], v[4:7]
	v_mfma_f32_16x16x32_bf16 v[0:3], v[230:233], v[218:221], v[0:3]
	v_mfma_f32_16x16x32_bf16 v[28:31], v[226:229], v[198:201], v[28:31]
	v_mfma_f32_16x16x32_bf16 v[24:27], v[234:237], v[198:201], v[24:27]
	v_mfma_f32_16x16x32_bf16 v[20:23], v[226:229], v[206:209], v[20:23]
	v_mfma_f32_16x16x32_bf16 v[16:19], v[234:237], v[206:209], v[16:19]
	v_mfma_f32_16x16x32_bf16 v[12:15], v[226:229], v[214:217], v[12:15]
	v_mfma_f32_16x16x32_bf16 v[8:11], v[234:237], v[214:217], v[8:11]
	v_mfma_f32_16x16x32_bf16 v[4:7], v[226:229], v[238:241], v[4:7]
	v_mfma_f32_16x16x32_bf16 v[0:3], v[234:237], v[238:241], v[0:3]
	s_setprio 0
	s_barrier
	ds_read_b128 v[178:181], v156
	ds_read_b128 v[182:185], v156 offset:1024
	ds_read_b128 v[186:189], v156 offset:2048
	ds_read_b128 v[190:193], v156 offset:3072
	v_add_u32_e32 v169, 0x4000, v152
	v_add_u32_e32 v170, 0x6000, v152
	v_readfirstlane_b32 s27, v169
	v_lshl_add_u64 v[226:227], v[242:243], 0, s[10:11]
	s_mov_b32 m0, s27
	v_readfirstlane_b32 s27, v170
	ds_read_b128 v[194:197], v153 offset:32768
	ds_read_b128 v[198:201], v153 offset:33792
	ds_read_b128 v[202:205], v171 offset:32768
	ds_read_b128 v[206:209], v171 offset:33792
	ds_read_b128 v[210:213], v172 offset:32768
	ds_read_b128 v[214:217], v172 offset:33792
	ds_read_b128 v[218:221], v173 offset:32768
	ds_read_b128 v[222:225], v173 offset:33792
	global_load_lds_dwordx4 v[226:227], off
	v_lshl_add_u64 v[226:227], v[244:245], 0, s[10:11]
	s_mov_b32 m0, s27
	s_nop 0
	global_load_lds_dwordx4 v[226:227], off
	s_waitcnt lgkmcnt(8)
	s_barrier
	s_waitcnt lgkmcnt(0)
	s_setprio 1
	v_mfma_f32_16x16x32_bf16 v[124:127], v[178:181], v[194:197], v[124:127]
	v_mfma_f32_16x16x32_bf16 v[120:123], v[186:189], v[194:197], v[120:123]
	v_mfma_f32_16x16x32_bf16 v[116:119], v[178:181], v[202:205], v[116:119]
	v_mfma_f32_16x16x32_bf16 v[112:115], v[186:189], v[202:205], v[112:115]
	v_mfma_f32_16x16x32_bf16 v[108:111], v[178:181], v[210:213], v[108:111]
	v_mfma_f32_16x16x32_bf16 v[104:107], v[186:189], v[210:213], v[104:107]
	v_mfma_f32_16x16x32_bf16 v[100:103], v[178:181], v[218:221], v[100:103]
	v_mfma_f32_16x16x32_bf16 v[96:99], v[186:189], v[218:221], v[96:99]
	v_mfma_f32_16x16x32_bf16 v[124:127], v[182:185], v[198:201], v[124:127]
	v_mfma_f32_16x16x32_bf16 v[120:123], v[190:193], v[198:201], v[120:123]
	v_mfma_f32_16x16x32_bf16 v[116:119], v[182:185], v[206:209], v[116:119]
	v_mfma_f32_16x16x32_bf16 v[112:115], v[190:193], v[206:209], v[112:115]
	v_mfma_f32_16x16x32_bf16 v[108:111], v[182:185], v[214:217], v[108:111]
	v_mfma_f32_16x16x32_bf16 v[104:107], v[190:193], v[214:217], v[104:107]
	v_mfma_f32_16x16x32_bf16 v[100:103], v[182:185], v[222:225], v[100:103]
	v_mfma_f32_16x16x32_bf16 v[96:99], v[190:193], v[222:225], v[96:99]
	s_setprio 0
	s_barrier
	v_readfirstlane_b32 s27, v157
	v_add_u32_e32 v177, 0x2000, v157
	v_lshl_add_u64 v[250:251], v[246:247], 0, s[12:13]
	s_mov_b32 m0, s27
	v_readfirstlane_b32 s27, v177
	ds_read_b128 v[226:229], v155
	ds_read_b128 v[230:233], v155 offset:1024
	ds_read_b128 v[234:237], v155 offset:2048
	ds_read_b128 v[238:241], v155 offset:3072
	global_load_lds_dwordx4 v[250:251], off
	v_lshl_add_u64 v[250:251], v[248:249], 0, s[12:13]
	s_mov_b32 m0, s27
	s_nop 0
	global_load_lds_dwordx4 v[250:251], off
	s_barrier
	s_waitcnt lgkmcnt(0)
	s_setprio 1
	v_mfma_f32_16x16x32_bf16 v[92:95], v[226:229], v[194:197], v[92:95]
	v_mfma_f32_16x16x32_bf16 v[88:91], v[234:237], v[194:197], v[88:91]
	v_mfma_f32_16x16x32_bf16 v[84:87], v[226:229], v[202:205], v[84:87]
	v_mfma_f32_16x16x32_bf16 v[80:83], v[234:237], v[202:205], v[80:83]
	v_mfma_f32_16x16x32_bf16 v[76:79], v[226:229], v[210:213], v[76:79]
	v_mfma_f32_16x16x32_bf16 v[72:75], v[234:237], v[210:213], v[72:75]
	v_mfma_f32_16x16x32_bf16 v[68:71], v[226:229], v[218:221], v[68:71]
	v_mfma_f32_16x16x32_bf16 v[64:67], v[234:237], v[218:221], v[64:67]
	v_mfma_f32_16x16x32_bf16 v[92:95], v[230:233], v[198:201], v[92:95]
	v_mfma_f32_16x16x32_bf16 v[88:91], v[238:241], v[198:201], v[88:91]
	v_mfma_f32_16x16x32_bf16 v[84:87], v[230:233], v[206:209], v[84:87]
	v_mfma_f32_16x16x32_bf16 v[80:83], v[238:241], v[206:209], v[80:83]
	v_mfma_f32_16x16x32_bf16 v[76:79], v[230:233], v[214:217], v[76:79]
	v_mfma_f32_16x16x32_bf16 v[72:75], v[238:241], v[214:217], v[72:75]
	v_mfma_f32_16x16x32_bf16 v[68:71], v[230:233], v[222:225], v[68:71]
	v_mfma_f32_16x16x32_bf16 v[64:67], v[238:241], v[222:225], v[64:67]
	s_setprio 0
	v_readfirstlane_b32 s27, v158
	v_lshl_add_u64 v[242:243], v[242:243], 0, s[14:15]
	s_mov_b32 m0, s27
	v_readfirstlane_b32 s27, v159
	s_barrier
; #define STAGE(P,BASE,LD,br,kt) do{long _g=(long)(br)*(LD)+(long)(kt)*BK; \
;     _Pragma("unroll") for(int _i=0;_i<2;++_i){int _b=tid*16+_i*8192;int _r,_c;stage_rc(_b,_r,_c); \
;       __builtin_amdgcn_global_load_lds((const unsigned*)((BASE)+_g+(long)_r*(LD)+_c), \
;         (unsigned*)((char*)(P)+_b),16,0,0);}}while(0)
; #define STAGE(P,BASE,LD,br,kt) do{long _g=(long)(br)*(LD)+(long)(kt)*BK; \
;     _Pragma("unroll") for(int _i=0;_i<2;++_i){int _b=tid*16+_i*8192;int _r,_c;stage_rc(_b,_r,_c); \
;       __builtin_amdgcn_global_load_lds((const unsigned*)((BASE)+_g+(long)_r*(LD)+_c), \
;         (unsigned*)((char*)(P)+_b),16,0,0);}}while(0)
; #define LDA(dst,b,h) _Pragma("unroll") for(int m=0;m<4;++m) _Pragma("unroll") for(int k=0;k<2;++k) \
;     dst[m][k]=*reinterpret_cast<const bf16x8*>((char*)SA(b,h)+lds_byte(wr*64+m*16+fr,k*32+fq*8))
; #define LDB(dst,b,h) _Pragma("unroll") for(int n=0;n<2;++n) _Pragma("unroll") for(int k=0;k<2;++k) \
;     dst[n][k]=*reinterpret_cast<const bf16x8*>((char*)SB(b,h)+lds_byte(wc*32+n*16+fr,k*32+fq*8))
; #define MMA(ai,bj,At_,Bt_) do{__builtin_amdgcn_s_setprio(1); \
;     _Pragma("unroll") for(int m=0;m<4;++m) _Pragma("unroll") for(int n=0;n<2;++n) _Pragma("unroll") for(int k=0;k<2;++k) \
;       acc[ai][bj][m][n]=__builtin_amdgcn_mfma_f32_16x16x32_bf16(Bt_[n][k],At_[m][k],acc[ai][bj][m][n],0,0,0); \
;     __builtin_amdgcn_s_setprio(0);}while(0)
; #define WAIT_V(n) asm volatile("s_waitcnt vmcnt(" #n ")":::"memory")
; #define WAIT_L(n) asm volatile("s_waitcnt lgkmcnt(" #n ")":::"memory")
; #define BAR __builtin_amdgcn_s_barrier()
; #define SCHED __builtin_amdgcn_sched_barrier(0)
; DEVINL void gemm8_mainloop(const u16* A, long lda, const u16* Bt, long ldb, int K, int brow, int bcol, f32x4 (&acc)[2][2][4][2], char* smem, int tid) {
;     ...
;     LDA(At,1,1); STAGE(SA(1,0),A,lda,brow,t+3);
;     BAR; WAIT_L(0); MMA(1,0,At,B0); BAR; SCHED;
;     STAGE(SB(1,1),Bt,ldb,bcol+HALF,t+3);
;     WAIT_V(6); BAR; MMA(1,1,At,B1); BAR;
;   }
;   { LDB(B0,0,0); LDA(At,0,0); STAGE(SA(1,1),A,lda,brow+HALF,nt-1);
;     BAR; WAIT_L(0); MMA(0,0,At,B0); BAR;
	ds_read_b128 v[194:197], v153 offset:49152
	ds_read_b128 v[198:201], v153 offset:50176
	ds_read_b128 v[202:205], v171 offset:49152
	ds_read_b128 v[206:209], v171 offset:50176
	ds_read_b128 v[210:213], v172 offset:49152
	ds_read_b128 v[214:217], v172 offset:50176
	ds_read_b128 v[218:221], v173 offset:49152
	ds_read_b128 v[222:225], v173 offset:50176
	global_load_lds_dwordx4 v[242:243], off
	v_lshl_add_u64 v[242:243], v[244:245], 0, s[14:15]
	s_mov_b32 m0, s27
	s_nop 0
	global_load_lds_dwordx4 v[242:243], off
	s_barrier
	s_waitcnt lgkmcnt(0)
	s_setprio 1
	v_mfma_f32_16x16x32_bf16 v[60:63], v[178:181], v[194:197], v[60:63]
	v_mfma_f32_16x16x32_bf16 v[56:59], v[186:189], v[194:197], v[56:59]
	v_mfma_f32_16x16x32_bf16 v[52:55], v[178:181], v[202:205], v[52:55]
	v_mfma_f32_16x16x32_bf16 v[48:51], v[186:189], v[202:205], v[48:51]
	v_mfma_f32_16x16x32_bf16 v[44:47], v[178:181], v[210:213], v[44:47]
	v_mfma_f32_16x16x32_bf16 v[40:43], v[186:189], v[210:213], v[40:43]
	v_mfma_f32_16x16x32_bf16 v[36:39], v[178:181], v[218:221], v[36:39]
	v_mfma_f32_16x16x32_bf16 v[32:35], v[186:189], v[218:221], v[32:35]
	v_mfma_f32_16x16x32_bf16 v[60:63], v[182:185], v[198:201], v[60:63]
	v_mfma_f32_16x16x32_bf16 v[56:59], v[190:193], v[198:201], v[56:59]
	v_mfma_f32_16x16x32_bf16 v[52:55], v[182:185], v[206:209], v[52:55]
	v_mfma_f32_16x16x32_bf16 v[48:51], v[190:193], v[206:209], v[48:51]
	v_mfma_f32_16x16x32_bf16 v[44:47], v[182:185], v[214:217], v[44:47]
	v_mfma_f32_16x16x32_bf16 v[40:43], v[190:193], v[214:217], v[40:43]
	v_mfma_f32_16x16x32_bf16 v[36:39], v[182:185], v[222:225], v[36:39]
	v_mfma_f32_16x16x32_bf16 v[32:35], v[190:193], v[222:225], v[32:35]
	s_setprio 0
	s_barrier
	v_readfirstlane_b32 s27, v161
	v_add_u32_e32 v177, 0x2000, v161
	v_lshl_add_u64 v[178:179], v[246:247], 0, s[16:17]
	s_mov_b32 m0, s27
	v_readfirstlane_b32 s27, v177
	global_load_lds_dwordx4 v[178:179], off
	v_lshl_add_u64 v[178:179], v[248:249], 0, s[16:17]
	s_mov_b32 m0, s27
	s_nop 0
	global_load_lds_dwordx4 v[178:179], off
	s_waitcnt vmcnt(6)
	s_barrier
	s_setprio 1
	v_mfma_f32_16x16x32_bf16 v[28:31], v[226:229], v[194:197], v[28:31]
	v_mfma_f32_16x16x32_bf16 v[24:27], v[234:237], v[194:197], v[24:27]
	v_mfma_f32_16x16x32_bf16 v[20:23], v[226:229], v[202:205], v[20:23]
	v_mfma_f32_16x16x32_bf16 v[16:19], v[234:237], v[202:205], v[16:19]
	v_mfma_f32_16x16x32_bf16 v[12:15], v[226:229], v[210:213], v[12:15]
	v_mfma_f32_16x16x32_bf16 v[8:11], v[234:237], v[210:213], v[8:11]
	v_mfma_f32_16x16x32_bf16 v[4:7], v[226:229], v[218:221], v[4:7]
	v_mfma_f32_16x16x32_bf16 v[0:3], v[234:237], v[218:221], v[0:3]
	v_mfma_f32_16x16x32_bf16 v[28:31], v[230:233], v[198:201], v[28:31]
	v_mfma_f32_16x16x32_bf16 v[24:27], v[238:241], v[198:201], v[24:27]
	v_mfma_f32_16x16x32_bf16 v[20:23], v[230:233], v[206:209], v[20:23]
	v_mfma_f32_16x16x32_bf16 v[16:19], v[238:241], v[206:209], v[16:19]
	v_mfma_f32_16x16x32_bf16 v[12:15], v[230:233], v[214:217], v[12:15]
	v_mfma_f32_16x16x32_bf16 v[8:11], v[238:241], v[214:217], v[8:11]
	v_mfma_f32_16x16x32_bf16 v[4:7], v[230:233], v[222:225], v[4:7]
	v_mfma_f32_16x16x32_bf16 v[0:3], v[238:241], v[222:225], v[0:3]
	s_setprio 0
	s_add_i32 s26, s26, 2
	v_lshl_add_u64 v[142:143], v[142:143], 0, s[18:19]
	v_lshl_add_u64 v[144:145], v[144:145], 0, s[18:19]
	v_lshl_add_u64 v[146:147], v[146:147], 0, s[18:19]
	s_cmp_lt_u32 s26, 28
	v_lshl_add_u64 v[148:149], v[148:149], 0, s[18:19]
	s_cbranch_scc1 .LBB0_1871
	s_barrier
	s_or_b32 s26, s24, 0x80
	s_ashr_i32 s27, s26, 31
	s_lshl_b64 s[26:27], s[26:27], 12
	s_add_u32 s26, s47, s26
	s_addc_u32 s27, s48, s27
	v_lshl_add_u64 v[158:159], v[134:135], 1, s[26:27]
	v_lshl_add_u64 v[138:139], v[138:139], 1, v[158:159]
	v_readfirstlane_b32 s25, v174
	v_lshl_add_u64 v[138:139], v[138:139], 0, s[20:21]
	s_mov_b32 m0, s25
	ds_read_b128 v[142:145], v163
	ds_read_b128 v[146:149], v163 offset:1024
	ds_read_b128 v[178:181], v163 offset:2048
	ds_read_b128 v[182:185], v163 offset:3072
	ds_read_b128 v[186:189], v153
	ds_read_b128 v[190:193], v153 offset:1024
	ds_read_b128 v[194:197], v171
	ds_read_b128 v[198:201], v171 offset:1024
	ds_read_b128 v[202:205], v172
	ds_read_b128 v[206:209], v172 offset:1024
	ds_read_b128 v[210:213], v173
	ds_read_b128 v[214:217], v173 offset:1024
	global_load_lds_dwordx4 v[138:139], off
	v_lshl_add_u64 v[138:139], v[136:137], 1, s[26:27]
	v_lshl_add_u64 v[138:139], v[140:141], 1, v[138:139]
	v_readfirstlane_b32 s25, v175
	v_lshl_add_u64 v[138:139], v[138:139], 0, s[20:21]
	s_mov_b32 m0, s25
	s_nop 0
	global_load_lds_dwordx4 v[138:139], off
	s_barrier
	s_waitcnt lgkmcnt(0)
	s_setprio 1
	v_mfma_f32_16x16x32_bf16 v[124:127], v[142:145], v[186:189], v[124:127]
	v_mfma_f32_16x16x32_bf16 v[120:123], v[178:181], v[186:189], v[120:123]
	v_mfma_f32_16x16x32_bf16 v[116:119], v[142:145], v[194:197], v[116:119]
	v_mfma_f32_16x16x32_bf16 v[112:115], v[178:181], v[194:197], v[112:115]
	v_mfma_f32_16x16x32_bf16 v[100:103], v[142:145], v[210:213], v[100:103]
	v_mfma_f32_16x16x32_bf16 v[96:99], v[178:181], v[210:213], v[96:99]
	v_mfma_f32_16x16x32_bf16 v[124:127], v[146:149], v[190:193], v[124:127]
	v_mfma_f32_16x16x32_bf16 v[120:123], v[182:185], v[190:193], v[120:123]
	v_mfma_f32_16x16x32_bf16 v[116:119], v[146:149], v[198:201], v[116:119]
	v_mfma_f32_16x16x32_bf16 v[112:115], v[182:185], v[198:201], v[112:115]
	v_mfma_f32_16x16x32_bf16 v[108:111], v[142:145], v[202:205], v[108:111]
	v_mfma_f32_16x16x32_bf16 v[104:107], v[178:181], v[202:205], v[104:107]
	v_mfma_f32_16x16x32_bf16 v[100:103], v[146:149], v[214:217], v[100:103]
	v_mfma_f32_16x16x32_bf16 v[96:99], v[182:185], v[214:217], v[96:99]
	v_mfma_f32_16x16x32_bf16 v[138:141], v[146:149], v[206:209], v[108:111]
	v_mfma_f32_16x16x32_bf16 v[218:221], v[182:185], v[206:209], v[104:107]
	s_setprio 0
	s_barrier
; #define LDA(dst,b,h) _Pragma("unroll") for(int m=0;m<4;++m) _Pragma("unroll") for(int k=0;k<2;++k) \
;     dst[m][k]=*reinterpret_cast<const bf16x8*>((char*)SA(b,h)+lds_byte(wr*64+m*16+fr,k*32+fq*8))
; #define LDB(dst,b,h) _Pragma("unroll") for(int n=0;n<2;++n) _Pragma("unroll") for(int k=0;k<2;++k) \
;     dst[n][k]=*reinterpret_cast<const bf16x8*>((char*)SB(b,h)+lds_byte(wc*32+n*16+fr,k*32+fq*8))
; #define MMA(ai,bj,At_,Bt_) do{__builtin_amdgcn_s_setprio(1); \
;     _Pragma("unroll") for(int m=0;m<4;++m) _Pragma("unroll") for(int n=0;n<2;++n) _Pragma("unroll") for(int k=0;k<2;++k) \
;       acc[ai][bj][m][n]=__builtin_amdgcn_mfma_f32_16x16x32_bf16(Bt_[n][k],At_[m][k],acc[ai][bj][m][n],0,0,0); \
;     __builtin_amdgcn_s_setprio(0);}while(0)
; #define WAIT_V(n) asm volatile("s_waitcnt vmcnt(" #n ")":::"memory")
; #define WAIT_L(n) asm volatile("s_waitcnt lgkmcnt(" #n ")":::"memory")
; #define BAR __builtin_amdgcn_s_barrier()
; DEVINL void gemm8_mainloop(const u16* A, long lda, const u16* Bt, long ldb, int K, int brow, int bcol, f32x4 (&acc)[2][2][4][2], char* smem, int tid) {
;     ...
;     LDB(B1,0,1); BAR; WAIT_L(0); MMA(0,1,At,B1); BAR;
;     LDA(At,0,1); WAIT_V(4); BAR; WAIT_L(0); MMA(1,0,At,B0); MMA(1,1,At,B1); BAR; }
;   { LDB(B0,1,0); LDA(At,1,0); WAIT_V(2); BAR; WAIT_L(0); MMA(0,0,At,B0); BAR;
	s_nop 1
	ds_read_b128 v[104:107], v160
	ds_read_b128 v[108:111], v160 offset:1024
	ds_read_b128 v[222:225], v160 offset:2048
	ds_read_b128 v[158:161], v160 offset:3072
	s_barrier
	s_waitcnt lgkmcnt(0)
	s_setprio 1
	v_mfma_f32_16x16x32_bf16 v[84:87], v[104:107], v[194:197], v[84:87]
	v_mfma_f32_16x16x32_bf16 v[80:83], v[222:225], v[194:197], v[80:83]
	v_mfma_f32_16x16x32_bf16 v[68:71], v[104:107], v[210:213], v[68:71]
	v_mfma_f32_16x16x32_bf16 v[92:95], v[104:107], v[186:189], v[92:95]
	v_mfma_f32_16x16x32_bf16 v[88:91], v[222:225], v[186:189], v[88:91]
	v_mfma_f32_16x16x32_bf16 v[84:87], v[108:111], v[198:201], v[84:87]
	v_mfma_f32_16x16x32_bf16 v[80:83], v[158:161], v[198:201], v[80:83]
	v_mfma_f32_16x16x32_bf16 v[76:79], v[104:107], v[202:205], v[76:79]
	v_mfma_f32_16x16x32_bf16 v[72:75], v[222:225], v[202:205], v[72:75]
	v_mfma_f32_16x16x32_bf16 v[68:71], v[108:111], v[214:217], v[68:71]
	v_mfma_f32_16x16x32_bf16 v[64:67], v[222:225], v[210:213], v[64:67]
	v_mfma_f32_16x16x32_bf16 v[226:229], v[108:111], v[190:193], v[92:95]
	v_mfma_f32_16x16x32_bf16 v[186:189], v[158:161], v[190:193], v[88:91]
	v_mfma_f32_16x16x32_bf16 v[190:193], v[108:111], v[206:209], v[76:79]
	v_mfma_f32_16x16x32_bf16 v[194:197], v[158:161], v[206:209], v[72:75]
	v_mfma_f32_16x16x32_bf16 v[198:201], v[158:161], v[214:217], v[64:67]
	s_setprio 0
	s_barrier
	s_nop 0
	ds_read_b128 v[64:67], v153 offset:16384
	ds_read_b128 v[72:75], v153 offset:17408
	ds_read_b128 v[76:79], v171 offset:16384
	ds_read_b128 v[88:91], v171 offset:17408
	ds_read_b128 v[92:95], v172 offset:16384
	ds_read_b128 v[202:205], v172 offset:17408
	ds_read_b128 v[206:209], v173 offset:16384
	ds_read_b128 v[210:213], v173 offset:17408
	s_waitcnt vmcnt(4)
	s_barrier
	s_waitcnt lgkmcnt(0)
	s_setprio 1
	v_mfma_f32_16x16x32_bf16 v[60:63], v[142:145], v[64:67], v[60:63]
	v_mfma_f32_16x16x32_bf16 v[56:59], v[178:181], v[64:67], v[56:59]
	v_mfma_f32_16x16x32_bf16 v[52:55], v[142:145], v[76:79], v[52:55]
	v_mfma_f32_16x16x32_bf16 v[48:51], v[178:181], v[76:79], v[48:51]
	v_mfma_f32_16x16x32_bf16 v[36:39], v[142:145], v[206:209], v[36:39]
	v_mfma_f32_16x16x32_bf16 v[32:35], v[178:181], v[206:209], v[32:35]
	v_mfma_f32_16x16x32_bf16 v[60:63], v[146:149], v[72:75], v[60:63]
	v_mfma_f32_16x16x32_bf16 v[56:59], v[182:185], v[72:75], v[56:59]
	v_mfma_f32_16x16x32_bf16 v[52:55], v[146:149], v[88:91], v[52:55]
	v_mfma_f32_16x16x32_bf16 v[48:51], v[182:185], v[88:91], v[48:51]
	v_mfma_f32_16x16x32_bf16 v[44:47], v[142:145], v[92:95], v[44:47]
	v_mfma_f32_16x16x32_bf16 v[40:43], v[178:181], v[92:95], v[40:43]
	v_mfma_f32_16x16x32_bf16 v[36:39], v[146:149], v[210:213], v[36:39]
	v_mfma_f32_16x16x32_bf16 v[32:35], v[182:185], v[210:213], v[32:35]
	v_mfma_f32_16x16x32_bf16 v[214:217], v[146:149], v[202:205], v[44:47]
	v_mfma_f32_16x16x32_bf16 v[230:233], v[182:185], v[202:205], v[40:43]
	s_setprio 0
	s_setprio 1
	v_mfma_f32_16x16x32_bf16 v[20:23], v[104:107], v[76:79], v[20:23]
	v_mfma_f32_16x16x32_bf16 v[16:19], v[222:225], v[76:79], v[16:19]
	v_mfma_f32_16x16x32_bf16 v[4:7], v[104:107], v[206:209], v[4:7]
	v_mfma_f32_16x16x32_bf16 v[28:31], v[104:107], v[64:67], v[28:31]
	v_mfma_f32_16x16x32_bf16 v[24:27], v[222:225], v[64:67], v[24:27]
	v_mfma_f32_16x16x32_bf16 v[20:23], v[108:111], v[88:91], v[20:23]
	v_mfma_f32_16x16x32_bf16 v[16:19], v[158:161], v[88:91], v[16:19]
	v_mfma_f32_16x16x32_bf16 v[12:15], v[104:107], v[92:95], v[12:15]
	v_mfma_f32_16x16x32_bf16 v[8:11], v[222:225], v[92:95], v[8:11]
	v_mfma_f32_16x16x32_bf16 v[4:7], v[108:111], v[210:213], v[4:7]
	v_mfma_f32_16x16x32_bf16 v[0:3], v[222:225], v[206:209], v[0:3]
	v_mfma_f32_16x16x32_bf16 v[142:145], v[108:111], v[72:75], v[28:31]
	v_mfma_f32_16x16x32_bf16 v[146:149], v[158:161], v[72:75], v[24:27]
	v_mfma_f32_16x16x32_bf16 v[178:181], v[108:111], v[202:205], v[12:15]
	v_mfma_f32_16x16x32_bf16 v[182:185], v[158:161], v[202:205], v[8:11]
	v_mfma_f32_16x16x32_bf16 v[158:161], v[158:161], v[210:213], v[0:3]
	s_setprio 0
	s_barrier
	s_nop 0
	ds_read_b128 v[0:3], v156
	ds_read_b128 v[8:11], v156 offset:1024
	ds_read_b128 v[202:205], v156 offset:2048
	ds_read_b128 v[206:209], v156 offset:3072
	ds_read_b128 v[12:15], v153 offset:32768
	ds_read_b128 v[24:27], v153 offset:33792
	ds_read_b128 v[28:31], v171 offset:32768
	ds_read_b128 v[40:43], v171 offset:33792
	ds_read_b128 v[44:47], v172 offset:32768
	ds_read_b128 v[64:67], v172 offset:33792
	ds_read_b128 v[210:213], v173 offset:32768
	ds_read_b128 v[222:225], v173 offset:33792
	s_waitcnt vmcnt(2)
	s_barrier
; #define LDA(dst,b,h) _Pragma("unroll") for(int m=0;m<4;++m) _Pragma("unroll") for(int k=0;k<2;++k) \
;     dst[m][k]=*reinterpret_cast<const bf16x8*>((char*)SA(b,h)+lds_byte(wr*64+m*16+fr,k*32+fq*8))
; #define LDB(dst,b,h) _Pragma("unroll") for(int n=0;n<2;++n) _Pragma("unroll") for(int k=0;k<2;++k) \
;     dst[n][k]=*reinterpret_cast<const bf16x8*>((char*)SB(b,h)+lds_byte(wc*32+n*16+fr,k*32+fq*8))
; #define MMA(ai,bj,At_,Bt_) do{__builtin_amdgcn_s_setprio(1); \
;     _Pragma("unroll") for(int m=0;m<4;++m) _Pragma("unroll") for(int n=0;n<2;++n) _Pragma("unroll") for(int k=0;k<2;++k) \
;       acc[ai][bj][m][n]=__builtin_amdgcn_mfma_f32_16x16x32_bf16(Bt_[n][k],At_[m][k],acc[ai][bj][m][n],0,0,0); \
;     __builtin_amdgcn_s_setprio(0);}while(0)
; #define WAIT_V(n) asm volatile("s_waitcnt vmcnt(" #n ")":::"memory")
; #define WAIT_L(n) asm volatile("s_waitcnt lgkmcnt(" #n ")":::"memory")
; #define BAR __builtin_amdgcn_s_barrier()
; DEVINL void gemm8_mainloop(const u16* A, long lda, const u16* Bt, long ldb, int K, int brow, int bcol, f32x4 (&acc)[2][2][4][2], char* smem, int tid) {
;     ...
;   { LDB(B0,1,0); LDA(At,1,0); WAIT_V(2); BAR; WAIT_L(0); MMA(0,0,At,B0); BAR;
;     LDB(B1,1,1); WAIT_V(0); BAR; WAIT_L(0); MMA(0,1,At,B1); BAR;
;     LDA(At,1,1); BAR; WAIT_L(0); MMA(1,0,At,B0); MMA(1,1,At,B1); BAR; }
;   if(wr==0)BAR;
;   __syncthreads();
	s_waitcnt lgkmcnt(0)
	s_setprio 1
	v_mfma_f32_16x16x32_bf16 v[72:75], v[0:3], v[12:15], v[124:127]
	v_mfma_f32_16x16x32_bf16 v[124:127], v[8:11], v[24:27], v[72:75]
	v_mfma_f32_16x16x32_bf16 v[72:75], v[202:205], v[12:15], v[120:123]
	v_mfma_f32_16x16x32_bf16 v[120:123], v[206:209], v[24:27], v[72:75]
	v_mfma_f32_16x16x32_bf16 v[72:75], v[0:3], v[28:31], v[116:119]
	v_mfma_f32_16x16x32_bf16 v[108:111], v[8:11], v[40:43], v[72:75]
	v_mfma_f32_16x16x32_bf16 v[72:75], v[202:205], v[28:31], v[112:115]
	v_mfma_f32_16x16x32_bf16 v[104:107], v[206:209], v[40:43], v[72:75]
	v_mfma_f32_16x16x32_bf16 v[72:75], v[0:3], v[44:47], v[138:141]
	v_mfma_f32_16x16x32_bf16 v[92:95], v[8:11], v[64:67], v[72:75]
	v_mfma_f32_16x16x32_bf16 v[72:75], v[202:205], v[44:47], v[218:221]
	v_mfma_f32_16x16x32_bf16 v[88:91], v[206:209], v[64:67], v[72:75]
	v_mfma_f32_16x16x32_bf16 v[72:75], v[0:3], v[210:213], v[100:103]
	v_mfma_f32_16x16x32_bf16 v[76:79], v[8:11], v[222:225], v[72:75]
	v_mfma_f32_16x16x32_bf16 v[72:75], v[202:205], v[210:213], v[96:99]
	v_mfma_f32_16x16x32_bf16 v[72:75], v[206:209], v[222:225], v[72:75]
	s_setprio 0
	s_barrier
	ds_read_b128 v[138:141], v155
	ds_read_b128 v[218:221], v155 offset:1024
	ds_read_b128 v[234:237], v155 offset:2048
	ds_read_b128 v[154:157], v155 offset:3072
	s_waitcnt vmcnt(0)
	s_barrier
	s_waitcnt lgkmcnt(0)
	s_setprio 1
	v_mfma_f32_16x16x32_bf16 v[96:99], v[138:141], v[12:15], v[226:229]
	v_mfma_f32_16x16x32_bf16 v[12:15], v[234:237], v[12:15], v[186:189]
	v_mfma_f32_16x16x32_bf16 v[116:119], v[154:157], v[24:27], v[12:15]
	v_mfma_f32_16x16x32_bf16 v[12:15], v[138:141], v[28:31], v[84:87]
	v_mfma_f32_16x16x32_bf16 v[112:115], v[218:221], v[24:27], v[96:99]
	v_mfma_f32_16x16x32_bf16 v[96:99], v[218:221], v[40:43], v[12:15]
	v_mfma_f32_16x16x32_bf16 v[12:15], v[234:237], v[28:31], v[80:83]
	v_mfma_f32_16x16x32_bf16 v[100:103], v[154:157], v[40:43], v[12:15]
	v_mfma_f32_16x16x32_bf16 v[12:15], v[138:141], v[44:47], v[190:193]
	v_mfma_f32_16x16x32_bf16 v[80:83], v[218:221], v[64:67], v[12:15]
	v_mfma_f32_16x16x32_bf16 v[12:15], v[234:237], v[44:47], v[194:197]
	v_mfma_f32_16x16x32_bf16 v[84:87], v[154:157], v[64:67], v[12:15]
	v_mfma_f32_16x16x32_bf16 v[12:15], v[138:141], v[210:213], v[68:71]
	v_mfma_f32_16x16x32_bf16 v[64:67], v[218:221], v[222:225], v[12:15]
	v_mfma_f32_16x16x32_bf16 v[12:15], v[234:237], v[210:213], v[198:201]
	v_mfma_f32_16x16x32_bf16 v[68:71], v[154:157], v[222:225], v[12:15]
	s_setprio 0
	s_barrier
	ds_read_b128 v[186:189], v153 offset:49152
	ds_read_b128 v[190:193], v153 offset:50176
	ds_read_b128 v[194:197], v171 offset:49152
	ds_read_b128 v[198:201], v171 offset:50176
	ds_read_b128 v[210:213], v172 offset:49152
	ds_read_b128 v[222:225], v172 offset:50176
	ds_read_b128 v[226:229], v173 offset:49152
	ds_read_b128 v[172:175], v173 offset:50176
	s_barrier
	s_waitcnt lgkmcnt(0)
	s_setprio 1
	v_mfma_f32_16x16x32_bf16 v[12:15], v[0:3], v[186:189], v[60:63]
	v_mfma_f32_16x16x32_bf16 v[60:63], v[8:11], v[190:193], v[12:15]
	v_mfma_f32_16x16x32_bf16 v[12:15], v[202:205], v[186:189], v[56:59]
	v_mfma_f32_16x16x32_bf16 v[56:59], v[206:209], v[190:193], v[12:15]
	v_mfma_f32_16x16x32_bf16 v[12:15], v[0:3], v[194:197], v[52:55]
	v_mfma_f32_16x16x32_bf16 v[44:47], v[8:11], v[198:201], v[12:15]
	v_mfma_f32_16x16x32_bf16 v[12:15], v[202:205], v[194:197], v[48:51]
	v_mfma_f32_16x16x32_bf16 v[40:43], v[206:209], v[198:201], v[12:15]
	v_mfma_f32_16x16x32_bf16 v[12:15], v[0:3], v[210:213], v[214:217]
	v_mfma_f32_16x16x32_bf16 v[28:31], v[8:11], v[222:225], v[12:15]
	v_mfma_f32_16x16x32_bf16 v[12:15], v[202:205], v[210:213], v[230:233]
	v_mfma_f32_16x16x32_bf16 v[0:3], v[0:3], v[226:229], v[36:39]
	v_mfma_f32_16x16x32_bf16 v[24:27], v[206:209], v[222:225], v[12:15]
	v_mfma_f32_16x16x32_bf16 v[12:15], v[8:11], v[172:175], v[0:3]
	v_mfma_f32_16x16x32_bf16 v[0:3], v[202:205], v[226:229], v[32:35]
	v_mfma_f32_16x16x32_bf16 v[8:11], v[206:209], v[172:175], v[0:3]
	s_setprio 0
	s_setprio 1
	v_mfma_f32_16x16x32_bf16 v[0:3], v[138:141], v[186:189], v[142:145]
	v_mfma_f32_16x16x32_bf16 v[48:51], v[218:221], v[190:193], v[0:3]
	v_mfma_f32_16x16x32_bf16 v[0:3], v[234:237], v[186:189], v[146:149]
	v_mfma_f32_16x16x32_bf16 v[52:55], v[154:157], v[190:193], v[0:3]
	v_mfma_f32_16x16x32_bf16 v[0:3], v[138:141], v[194:197], v[20:23]
	v_mfma_f32_16x16x32_bf16 v[32:35], v[218:221], v[198:201], v[0:3]
	v_mfma_f32_16x16x32_bf16 v[0:3], v[234:237], v[194:197], v[16:19]
	v_mfma_f32_16x16x32_bf16 v[36:39], v[154:157], v[198:201], v[0:3]
	v_mfma_f32_16x16x32_bf16 v[0:3], v[138:141], v[210:213], v[178:181]
	v_mfma_f32_16x16x32_bf16 v[16:19], v[218:221], v[222:225], v[0:3]
	v_mfma_f32_16x16x32_bf16 v[0:3], v[234:237], v[210:213], v[182:185]
	v_mfma_f32_16x16x32_bf16 v[20:23], v[154:157], v[222:225], v[0:3]
	v_mfma_f32_16x16x32_bf16 v[0:3], v[138:141], v[226:229], v[4:7]
	v_mfma_f32_16x16x32_bf16 v[4:7], v[234:237], v[226:229], v[158:161]
	v_mfma_f32_16x16x32_bf16 v[0:3], v[218:221], v[172:175], v[0:3]
	v_mfma_f32_16x16x32_bf16 v[4:7], v[154:157], v[172:175], v[4:7]
	s_setprio 0
	s_cmpk_gt_u32 s29, 0xff
	s_barrier
	s_cbranch_scc1 .LBB0_1874
	s_barrier

; #define STAGE(P,BASE,LD,br,kt) do{long _g=(long)(br)*(LD)+(long)(kt)*BK; \
;     _Pragma("unroll") for(int _i=0;_i<2;++_i){int _b=tid*16+_i*8192;int _r,_c;stage_rc(_b,_r,_c); \
;       __builtin_amdgcn_global_load_lds((const unsigned*)((BASE)+_g+(long)_r*(LD)+_c), \
;         (unsigned*)((char*)(P)+_b),16,0,0);}}while(0)
; #define STAGE(P,BASE,LD,br,kt) do{long _g=(long)(br)*(LD)+(long)(kt)*BK; \
;     _Pragma("unroll") for(int _i=0;_i<2;++_i){int _b=tid*16+_i*8192;int _r,_c;stage_rc(_b,_r,_c); \
;       __builtin_amdgcn_global_load_lds((const unsigned*)((BASE)+_g+(long)_r*(LD)+_c), \
;         (unsigned*)((char*)(P)+_b),16,0,0);}}while(0)
; #define LDA(dst,b,h) _Pragma("unroll") for(int m=0;m<4;++m) _Pragma("unroll") for(int k=0;k<2;++k) \
;     dst[m][k]=*reinterpret_cast<const bf16x8*>((char*)SA(b,h)+lds_byte(wr*64+m*16+fr,k*32+fq*8))
; #define LDB(dst,b,h) _Pragma("unroll") for(int n=0;n<2;++n) _Pragma("unroll") for(int k=0;k<2;++k) \
;     dst[n][k]=*reinterpret_cast<const bf16x8*>((char*)SB(b,h)+lds_byte(wc*32+n*16+fr,k*32+fq*8))
; #define MMA(ai,bj,At_,Bt_) do{__builtin_amdgcn_s_setprio(1); \
;     _Pragma("unroll") for(int m=0;m<4;++m) _Pragma("unroll") for(int n=0;n<2;++n) _Pragma("unroll") for(int k=0;k<2;++k) \
;       acc[ai][bj][m][n]=__builtin_amdgcn_mfma_f32_16x16x32_bf16(Bt_[n][k],At_[m][k],acc[ai][bj][m][n],0,0,0); \
;     __builtin_amdgcn_s_setprio(0);}while(0)
; #define WAIT_L(n) asm volatile("s_waitcnt lgkmcnt(" #n ")":::"memory")
; #define BAR __builtin_amdgcn_s_barrier()
; #define SCHED __builtin_amdgcn_sched_barrier(0)
; DEVINL void gemm8_mainloop(const u16* A, long lda, const u16* Bt, long ldb, int K, int brow, int bcol, f32x4 (&acc)[2][2][4][2], char* smem, int tid) {
;     ...
;   for(int t=0;t<nt-2;t+=2){
;     LDB(B0,0,0); SCHED; LDA(At,0,0); STAGE(SA(1,1),A,lda,brow+HALF,t+1);
;     WAIT_L(8); BAR; WAIT_L(0); MMA(0,0,At,B0); BAR; SCHED;
;     LDB(B1,0,1); STAGE(SB(0,0),Bt,ldb,bcol,t+2);
;     BAR; WAIT_L(0); MMA(0,1,At,B1); BAR;
;     LDA(At,0,1); STAGE(SA(0,0),A,lda,brow,t+2);
;     BAR; WAIT_L(0); MMA(1,0,At,B0); BAR; SCHED;
.LBB0_1938:
	s_barrier
	ds_read_b128 v[180:183], v165
	ds_read_b128 v[184:187], v165 offset:1024
	ds_read_b128 v[188:191], v165 offset:2048
	ds_read_b128 v[192:195], v165 offset:3072
	v_add_u32_e32 v177, 0xc000, v154
	v_lshl_add_u64 v[244:245], s[94:95], 0, v[146:147]
	v_readfirstlane_b32 s27, v177
	v_add_u32_e32 v178, 0xe000, v154
	v_add_u32_e32 v173, s23, v164
	v_add_u32_e32 v174, s38, v164
	v_add_u32_e32 v175, s39, v164
	v_lshl_add_u64 v[166:167], v[244:245], 0, s[2:3]
	s_mov_b32 m0, s27
	v_lshl_add_u64 v[246:247], s[94:95], 0, v[148:149]
	v_readfirstlane_b32 s27, v178
	ds_read_b128 v[168:171], v155
	ds_read_b128 v[196:199], v155 offset:1024
	ds_read_b128 v[200:203], v173
	ds_read_b128 v[204:207], v173 offset:1024
	ds_read_b128 v[208:211], v174
	ds_read_b128 v[212:215], v174 offset:1024
	ds_read_b128 v[216:219], v175
	ds_read_b128 v[220:223], v175 offset:1024
	global_load_lds_dwordx4 v[166:167], off
	v_lshl_add_u64 v[166:167], v[246:247], 0, s[2:3]
	s_mov_b32 m0, s27
	s_nop 0
	global_load_lds_dwordx4 v[166:167], off
	s_waitcnt lgkmcnt(8)
	s_barrier
	s_waitcnt lgkmcnt(0)
	s_setprio 1
	v_mfma_f32_16x16x32_bf16 v[124:127], v[180:183], v[168:171], v[124:127]
	v_mfma_f32_16x16x32_bf16 v[120:123], v[188:191], v[168:171], v[120:123]
	v_mfma_f32_16x16x32_bf16 v[116:119], v[180:183], v[200:203], v[116:119]
	v_mfma_f32_16x16x32_bf16 v[112:115], v[188:191], v[200:203], v[112:115]
	v_mfma_f32_16x16x32_bf16 v[108:111], v[180:183], v[208:211], v[108:111]
	v_mfma_f32_16x16x32_bf16 v[104:107], v[188:191], v[208:211], v[104:107]
	v_mfma_f32_16x16x32_bf16 v[100:103], v[180:183], v[216:219], v[100:103]
	v_mfma_f32_16x16x32_bf16 v[96:99], v[188:191], v[216:219], v[96:99]
	v_mfma_f32_16x16x32_bf16 v[124:127], v[184:187], v[196:199], v[124:127]
	v_mfma_f32_16x16x32_bf16 v[120:123], v[192:195], v[196:199], v[120:123]
	v_mfma_f32_16x16x32_bf16 v[116:119], v[184:187], v[204:207], v[116:119]
	v_mfma_f32_16x16x32_bf16 v[112:115], v[192:195], v[204:207], v[112:115]
	v_mfma_f32_16x16x32_bf16 v[108:111], v[184:187], v[212:215], v[108:111]
	v_mfma_f32_16x16x32_bf16 v[104:107], v[192:195], v[212:215], v[104:107]
	v_mfma_f32_16x16x32_bf16 v[100:103], v[184:187], v[220:223], v[100:103]
	v_mfma_f32_16x16x32_bf16 v[96:99], v[192:195], v[220:223], v[96:99]
	s_setprio 0
	s_barrier
	v_add_u32_e32 v166, s28, v157
	v_lshl_add_u64 v[248:249], s[94:95], 0, v[142:143]
	v_readfirstlane_b32 s27, v166
	v_add_u32_e32 v167, 0x2000, v166
	v_lshl_add_u64 v[240:241], v[248:249], 0, s[4:5]
	s_mov_b32 m0, s27
	v_lshl_add_u64 v[250:251], s[94:95], 0, v[144:145]
	v_readfirstlane_b32 s27, v167
	ds_read_b128 v[224:227], v161
	ds_read_b128 v[228:231], v161 offset:1024
	ds_read_b128 v[232:235], v161 offset:2048
	ds_read_b128 v[236:239], v161 offset:3072
	global_load_lds_dwordx4 v[240:241], off
	v_lshl_add_u64 v[240:241], v[250:251], 0, s[4:5]
	s_mov_b32 m0, s27
	s_nop 0
	global_load_lds_dwordx4 v[240:241], off
	s_barrier
	s_waitcnt lgkmcnt(0)
	s_setprio 1
	v_mfma_f32_16x16x32_bf16 v[92:95], v[224:227], v[168:171], v[92:95]
	v_mfma_f32_16x16x32_bf16 v[88:91], v[232:235], v[168:171], v[88:91]
	v_mfma_f32_16x16x32_bf16 v[84:87], v[224:227], v[200:203], v[84:87]
	v_mfma_f32_16x16x32_bf16 v[80:83], v[232:235], v[200:203], v[80:83]
	v_mfma_f32_16x16x32_bf16 v[76:79], v[224:227], v[208:211], v[76:79]
	v_mfma_f32_16x16x32_bf16 v[72:75], v[232:235], v[208:211], v[72:75]
	v_mfma_f32_16x16x32_bf16 v[68:71], v[224:227], v[216:219], v[68:71]
	v_mfma_f32_16x16x32_bf16 v[64:67], v[232:235], v[216:219], v[64:67]
	v_mfma_f32_16x16x32_bf16 v[92:95], v[228:231], v[196:199], v[92:95]
	v_mfma_f32_16x16x32_bf16 v[88:91], v[236:239], v[196:199], v[88:91]
	v_mfma_f32_16x16x32_bf16 v[84:87], v[228:231], v[204:207], v[84:87]
	v_mfma_f32_16x16x32_bf16 v[80:83], v[236:239], v[204:207], v[80:83]
	v_mfma_f32_16x16x32_bf16 v[76:79], v[228:231], v[212:215], v[76:79]
	v_mfma_f32_16x16x32_bf16 v[72:75], v[236:239], v[212:215], v[72:75]
	v_mfma_f32_16x16x32_bf16 v[68:71], v[228:231], v[220:223], v[68:71]
	v_mfma_f32_16x16x32_bf16 v[64:67], v[236:239], v[220:223], v[64:67]
	s_setprio 0
	v_readfirstlane_b32 s27, v154
	v_lshl_add_u64 v[168:169], v[244:245], 0, s[6:7]
	s_mov_b32 m0, s27
	s_barrier
	ds_read_b128 v[196:199], v155 offset:16384
	ds_read_b128 v[200:203], v155 offset:17408
	ds_read_b128 v[204:207], v173 offset:16384
	ds_read_b128 v[208:211], v173 offset:17408
	ds_read_b128 v[212:215], v174 offset:16384
	ds_read_b128 v[216:219], v174 offset:17408
	ds_read_b128 v[220:223], v175 offset:16384
	ds_read_b128 v[240:243], v175 offset:17408
	global_load_lds_dwordx4 v[168:169], off
	v_add_u32_e32 v168, 0x2000, v154
	v_lshl_add_u64 v[170:171], v[246:247], 0, s[6:7]
	v_readfirstlane_b32 s27, v168
	s_mov_b32 m0, s27
	s_nop 0
	global_load_lds_dwordx4 v[170:171], off
	s_barrier
	s_waitcnt lgkmcnt(0)
	s_setprio 1
	v_mfma_f32_16x16x32_bf16 v[60:63], v[180:183], v[196:199], v[60:63]
	v_mfma_f32_16x16x32_bf16 v[56:59], v[188:191], v[196:199], v[56:59]
	v_mfma_f32_16x16x32_bf16 v[52:55], v[180:183], v[204:207], v[52:55]
	v_mfma_f32_16x16x32_bf16 v[48:51], v[188:191], v[204:207], v[48:51]
	v_mfma_f32_16x16x32_bf16 v[44:47], v[180:183], v[212:215], v[44:47]
	v_mfma_f32_16x16x32_bf16 v[40:43], v[188:191], v[212:215], v[40:43]
	v_mfma_f32_16x16x32_bf16 v[36:39], v[180:183], v[220:223], v[36:39]
	v_mfma_f32_16x16x32_bf16 v[32:35], v[188:191], v[220:223], v[32:35]
	v_mfma_f32_16x16x32_bf16 v[60:63], v[184:187], v[200:203], v[60:63]
	v_mfma_f32_16x16x32_bf16 v[56:59], v[192:195], v[200:203], v[56:59]
	v_mfma_f32_16x16x32_bf16 v[52:55], v[184:187], v[208:211], v[52:55]
	v_mfma_f32_16x16x32_bf16 v[48:51], v[192:195], v[208:211], v[48:51]
	v_mfma_f32_16x16x32_bf16 v[44:47], v[184:187], v[216:219], v[44:47]
	v_mfma_f32_16x16x32_bf16 v[40:43], v[192:195], v[216:219], v[40:43]
	v_mfma_f32_16x16x32_bf16 v[36:39], v[184:187], v[240:243], v[36:39]
	v_mfma_f32_16x16x32_bf16 v[32:35], v[192:195], v[240:243], v[32:35]
	s_setprio 0
	s_barrier
; #define STAGE(P,BASE,LD,br,kt) do{long _g=(long)(br)*(LD)+(long)(kt)*BK; \
;     _Pragma("unroll") for(int _i=0;_i<2;++_i){int _b=tid*16+_i*8192;int _r,_c;stage_rc(_b,_r,_c); \
;       __builtin_amdgcn_global_load_lds((const unsigned*)((BASE)+_g+(long)_r*(LD)+_c), \
;         (unsigned*)((char*)(P)+_b),16,0,0);}}while(0)
; #define STAGE(P,BASE,LD,br,kt) do{long _g=(long)(br)*(LD)+(long)(kt)*BK; \
;     _Pragma("unroll") for(int _i=0;_i<2;++_i){int _b=tid*16+_i*8192;int _r,_c;stage_rc(_b,_r,_c); \
;       __builtin_amdgcn_global_load_lds((const unsigned*)((BASE)+_g+(long)_r*(LD)+_c), \
;         (unsigned*)((char*)(P)+_b),16,0,0);}}while(0)
; #define LDA(dst,b,h) _Pragma("unroll") for(int m=0;m<4;++m) _Pragma("unroll") for(int k=0;k<2;++k) \
;     dst[m][k]=*reinterpret_cast<const bf16x8*>((char*)SA(b,h)+lds_byte(wr*64+m*16+fr,k*32+fq*8))
; #define LDB(dst,b,h) _Pragma("unroll") for(int n=0;n<2;++n) _Pragma("unroll") for(int k=0;k<2;++k) \
;     dst[n][k]=*reinterpret_cast<const bf16x8*>((char*)SB(b,h)+lds_byte(wc*32+n*16+fr,k*32+fq*8))
; #define MMA(ai,bj,At_,Bt_) do{__builtin_amdgcn_s_setprio(1); \
;     _Pragma("unroll") for(int m=0;m<4;++m) _Pragma("unroll") for(int n=0;n<2;++n) _Pragma("unroll") for(int k=0;k<2;++k) \
;       acc[ai][bj][m][n]=__builtin_amdgcn_mfma_f32_16x16x32_bf16(Bt_[n][k],At_[m][k],acc[ai][bj][m][n],0,0,0); \
;     __builtin_amdgcn_s_setprio(0);}while(0)
; #define WAIT_V(n) asm volatile("s_waitcnt vmcnt(" #n ")":::"memory")
; #define WAIT_L(n) asm volatile("s_waitcnt lgkmcnt(" #n ")":::"memory")
; #define BAR __builtin_amdgcn_s_barrier()
; #define SCHED __builtin_amdgcn_sched_barrier(0)
; DEVINL void gemm8_mainloop(const u16* A, long lda, const u16* Bt, long ldb, int K, int brow, int bcol, f32x4 (&acc)[2][2][4][2], char* smem, int tid) {
;     ...
;     STAGE(SB(0,1),Bt,ldb,bcol+HALF,t+2);
;     WAIT_V(6); BAR; MMA(1,1,At,B1); BAR;
;     LDB(B0,1,0); SCHED; LDA(At,1,0); STAGE(SA(0,1),A,lda,brow+HALF,t+2);
;     WAIT_L(8); BAR; WAIT_L(0); MMA(0,0,At,B0); BAR; SCHED;
;     LDB(B1,1,1); STAGE(SB(1,0),Bt,ldb,bcol,t+3);
;     BAR; WAIT_L(0); MMA(0,1,At,B1); BAR;
;     LDA(At,1,1); STAGE(SA(1,0),A,lda,brow,t+3);
	v_add_u32_e32 v169, s29, v157
	v_lshl_add_u64 v[170:171], v[248:249], 0, s[8:9]
	v_readfirstlane_b32 s27, v169
	s_mov_b32 m0, s27
	v_lshl_add_u64 v[180:181], v[250:251], 0, s[8:9]
	global_load_lds_dwordx4 v[170:171], off
	v_add_u32_e32 v170, 0x2000, v169
	s_nop 0
	v_readfirstlane_b32 s27, v170
	s_mov_b32 m0, s27
	s_nop 0
	global_load_lds_dwordx4 v[180:181], off
	s_waitcnt vmcnt(6)
	s_barrier
	s_setprio 1
	v_mfma_f32_16x16x32_bf16 v[28:31], v[224:227], v[196:199], v[28:31]
	v_mfma_f32_16x16x32_bf16 v[24:27], v[232:235], v[196:199], v[24:27]
	v_mfma_f32_16x16x32_bf16 v[20:23], v[224:227], v[204:207], v[20:23]
	v_mfma_f32_16x16x32_bf16 v[16:19], v[232:235], v[204:207], v[16:19]
	v_mfma_f32_16x16x32_bf16 v[12:15], v[224:227], v[212:215], v[12:15]
	v_mfma_f32_16x16x32_bf16 v[8:11], v[232:235], v[212:215], v[8:11]
	v_mfma_f32_16x16x32_bf16 v[4:7], v[224:227], v[220:223], v[4:7]
	v_mfma_f32_16x16x32_bf16 v[0:3], v[232:235], v[220:223], v[0:3]
	v_mfma_f32_16x16x32_bf16 v[28:31], v[228:231], v[200:203], v[28:31]
	v_mfma_f32_16x16x32_bf16 v[24:27], v[236:239], v[200:203], v[24:27]
	v_mfma_f32_16x16x32_bf16 v[20:23], v[228:231], v[208:211], v[20:23]
	v_mfma_f32_16x16x32_bf16 v[16:19], v[236:239], v[208:211], v[16:19]
	v_mfma_f32_16x16x32_bf16 v[12:15], v[228:231], v[216:219], v[12:15]
	v_mfma_f32_16x16x32_bf16 v[8:11], v[236:239], v[216:219], v[8:11]
	v_mfma_f32_16x16x32_bf16 v[4:7], v[228:231], v[240:243], v[4:7]
	v_mfma_f32_16x16x32_bf16 v[0:3], v[236:239], v[240:243], v[0:3]
	s_setprio 0
	s_barrier
	ds_read_b128 v[180:183], v158
	ds_read_b128 v[184:187], v158 offset:1024
	ds_read_b128 v[188:191], v158 offset:2048
	ds_read_b128 v[192:195], v158 offset:3072
	v_add_u32_e32 v171, 0x4000, v154
	v_add_u32_e32 v172, 0x6000, v154
	v_readfirstlane_b32 s27, v171
	v_lshl_add_u64 v[228:229], v[244:245], 0, s[10:11]
	s_mov_b32 m0, s27
	v_readfirstlane_b32 s27, v172
	ds_read_b128 v[196:199], v155 offset:32768
	ds_read_b128 v[200:203], v155 offset:33792
	ds_read_b128 v[204:207], v173 offset:32768
	ds_read_b128 v[208:211], v173 offset:33792
	ds_read_b128 v[212:215], v174 offset:32768
	ds_read_b128 v[216:219], v174 offset:33792
	ds_read_b128 v[220:223], v175 offset:32768
	ds_read_b128 v[224:227], v175 offset:33792
	global_load_lds_dwordx4 v[228:229], off
	v_lshl_add_u64 v[228:229], v[246:247], 0, s[10:11]
	s_mov_b32 m0, s27
	s_nop 0
	global_load_lds_dwordx4 v[228:229], off
	s_waitcnt lgkmcnt(8)
	s_barrier
	s_waitcnt lgkmcnt(0)
	s_setprio 1
	v_mfma_f32_16x16x32_bf16 v[124:127], v[180:183], v[196:199], v[124:127]
	v_mfma_f32_16x16x32_bf16 v[120:123], v[188:191], v[196:199], v[120:123]
	v_mfma_f32_16x16x32_bf16 v[116:119], v[180:183], v[204:207], v[116:119]
	v_mfma_f32_16x16x32_bf16 v[112:115], v[188:191], v[204:207], v[112:115]
	v_mfma_f32_16x16x32_bf16 v[108:111], v[180:183], v[212:215], v[108:111]
	v_mfma_f32_16x16x32_bf16 v[104:107], v[188:191], v[212:215], v[104:107]
	v_mfma_f32_16x16x32_bf16 v[100:103], v[180:183], v[220:223], v[100:103]
	v_mfma_f32_16x16x32_bf16 v[96:99], v[188:191], v[220:223], v[96:99]
	v_mfma_f32_16x16x32_bf16 v[124:127], v[184:187], v[200:203], v[124:127]
	v_mfma_f32_16x16x32_bf16 v[120:123], v[192:195], v[200:203], v[120:123]
	v_mfma_f32_16x16x32_bf16 v[116:119], v[184:187], v[208:211], v[116:119]
	v_mfma_f32_16x16x32_bf16 v[112:115], v[192:195], v[208:211], v[112:115]
	v_mfma_f32_16x16x32_bf16 v[108:111], v[184:187], v[216:219], v[108:111]
	v_mfma_f32_16x16x32_bf16 v[104:107], v[192:195], v[216:219], v[104:107]
	v_mfma_f32_16x16x32_bf16 v[100:103], v[184:187], v[224:227], v[100:103]
	v_mfma_f32_16x16x32_bf16 v[96:99], v[192:195], v[224:227], v[96:99]
	s_setprio 0
	s_barrier
	v_readfirstlane_b32 s27, v159
	v_add_u32_e32 v179, 0x2000, v159
	v_lshl_add_u64 v[252:253], v[248:249], 0, s[12:13]
	s_mov_b32 m0, s27
	v_readfirstlane_b32 s27, v179
	ds_read_b128 v[228:231], v156
	ds_read_b128 v[232:235], v156 offset:1024
	ds_read_b128 v[236:239], v156 offset:2048
	ds_read_b128 v[240:243], v156 offset:3072
	global_load_lds_dwordx4 v[252:253], off
	v_lshl_add_u64 v[252:253], v[250:251], 0, s[12:13]
	s_mov_b32 m0, s27
	s_nop 0
	global_load_lds_dwordx4 v[252:253], off
	s_barrier
	s_waitcnt lgkmcnt(0)
	s_setprio 1
	v_mfma_f32_16x16x32_bf16 v[92:95], v[228:231], v[196:199], v[92:95]
	v_mfma_f32_16x16x32_bf16 v[88:91], v[236:239], v[196:199], v[88:91]
	v_mfma_f32_16x16x32_bf16 v[84:87], v[228:231], v[204:207], v[84:87]
	v_mfma_f32_16x16x32_bf16 v[80:83], v[236:239], v[204:207], v[80:83]
	v_mfma_f32_16x16x32_bf16 v[76:79], v[228:231], v[212:215], v[76:79]
	v_mfma_f32_16x16x32_bf16 v[72:75], v[236:239], v[212:215], v[72:75]
	v_mfma_f32_16x16x32_bf16 v[68:71], v[228:231], v[220:223], v[68:71]
	v_mfma_f32_16x16x32_bf16 v[64:67], v[236:239], v[220:223], v[64:67]
	v_mfma_f32_16x16x32_bf16 v[92:95], v[232:235], v[200:203], v[92:95]
	v_mfma_f32_16x16x32_bf16 v[88:91], v[240:243], v[200:203], v[88:91]
	v_mfma_f32_16x16x32_bf16 v[84:87], v[232:235], v[208:211], v[84:87]
	v_mfma_f32_16x16x32_bf16 v[80:83], v[240:243], v[208:211], v[80:83]
	v_mfma_f32_16x16x32_bf16 v[76:79], v[232:235], v[216:219], v[76:79]
	v_mfma_f32_16x16x32_bf16 v[72:75], v[240:243], v[216:219], v[72:75]
	v_mfma_f32_16x16x32_bf16 v[68:71], v[232:235], v[224:227], v[68:71]
	v_mfma_f32_16x16x32_bf16 v[64:67], v[240:243], v[224:227], v[64:67]
	s_setprio 0
	v_readfirstlane_b32 s27, v160
	v_lshl_add_u64 v[244:245], v[244:245], 0, s[14:15]
	s_mov_b32 m0, s27
	v_readfirstlane_b32 s27, v162
	s_barrier
; #define STAGE(P,BASE,LD,br,kt) do{long _g=(long)(br)*(LD)+(long)(kt)*BK; \
;     _Pragma("unroll") for(int _i=0;_i<2;++_i){int _b=tid*16+_i*8192;int _r,_c;stage_rc(_b,_r,_c); \
;       __builtin_amdgcn_global_load_lds((const unsigned*)((BASE)+_g+(long)_r*(LD)+_c), \
;         (unsigned*)((char*)(P)+_b),16,0,0);}}while(0)
; #define STAGE(P,BASE,LD,br,kt) do{long _g=(long)(br)*(LD)+(long)(kt)*BK; \
;     _Pragma("unroll") for(int _i=0;_i<2;++_i){int _b=tid*16+_i*8192;int _r,_c;stage_rc(_b,_r,_c); \
;       __builtin_amdgcn_global_load_lds((const unsigned*)((BASE)+_g+(long)_r*(LD)+_c), \
;         (unsigned*)((char*)(P)+_b),16,0,0);}}while(0)
; #define LDA(dst,b,h) _Pragma("unroll") for(int m=0;m<4;++m) _Pragma("unroll") for(int k=0;k<2;++k) \
;     dst[m][k]=*reinterpret_cast<const bf16x8*>((char*)SA(b,h)+lds_byte(wr*64+m*16+fr,k*32+fq*8))
; #define LDB(dst,b,h) _Pragma("unroll") for(int n=0;n<2;++n) _Pragma("unroll") for(int k=0;k<2;++k) \
;     dst[n][k]=*reinterpret_cast<const bf16x8*>((char*)SB(b,h)+lds_byte(wc*32+n*16+fr,k*32+fq*8))
; #define MMA(ai,bj,At_,Bt_) do{__builtin_amdgcn_s_setprio(1); \
;     _Pragma("unroll") for(int m=0;m<4;++m) _Pragma("unroll") for(int n=0;n<2;++n) _Pragma("unroll") for(int k=0;k<2;++k) \
;       acc[ai][bj][m][n]=__builtin_amdgcn_mfma_f32_16x16x32_bf16(Bt_[n][k],At_[m][k],acc[ai][bj][m][n],0,0,0); \
;     __builtin_amdgcn_s_setprio(0);}while(0)
; #define WAIT_V(n) asm volatile("s_waitcnt vmcnt(" #n ")":::"memory")
; #define WAIT_L(n) asm volatile("s_waitcnt lgkmcnt(" #n ")":::"memory")
; #define BAR __builtin_amdgcn_s_barrier()
; #define SCHED __builtin_amdgcn_sched_barrier(0)
; DEVINL void gemm8_mainloop(const u16* A, long lda, const u16* Bt, long ldb, int K, int brow, int bcol, f32x4 (&acc)[2][2][4][2], char* smem, int tid) {
;     ...
;     LDA(At,1,1); STAGE(SA(1,0),A,lda,brow,t+3);
;     BAR; WAIT_L(0); MMA(1,0,At,B0); BAR; SCHED;
;     STAGE(SB(1,1),Bt,ldb,bcol+HALF,t+3);
;     WAIT_V(6); BAR; MMA(1,1,At,B1); BAR;
;   }
;   { LDB(B0,0,0); LDA(At,0,0); STAGE(SA(1,1),A,lda,brow+HALF,nt-1);
;     BAR; WAIT_L(0); MMA(0,0,At,B0); BAR;
	ds_read_b128 v[196:199], v155 offset:49152
	ds_read_b128 v[200:203], v155 offset:50176
	ds_read_b128 v[204:207], v173 offset:49152
	ds_read_b128 v[208:211], v173 offset:50176
	ds_read_b128 v[212:215], v174 offset:49152
	ds_read_b128 v[216:219], v174 offset:50176
	ds_read_b128 v[220:223], v175 offset:49152
	ds_read_b128 v[224:227], v175 offset:50176
	global_load_lds_dwordx4 v[244:245], off
	v_lshl_add_u64 v[244:245], v[246:247], 0, s[14:15]
	s_mov_b32 m0, s27
	s_nop 0
	global_load_lds_dwordx4 v[244:245], off
	s_barrier
	s_waitcnt lgkmcnt(0)
	s_setprio 1
	v_mfma_f32_16x16x32_bf16 v[60:63], v[180:183], v[196:199], v[60:63]
	v_mfma_f32_16x16x32_bf16 v[56:59], v[188:191], v[196:199], v[56:59]
	v_mfma_f32_16x16x32_bf16 v[52:55], v[180:183], v[204:207], v[52:55]
	v_mfma_f32_16x16x32_bf16 v[48:51], v[188:191], v[204:207], v[48:51]
	v_mfma_f32_16x16x32_bf16 v[44:47], v[180:183], v[212:215], v[44:47]
	v_mfma_f32_16x16x32_bf16 v[40:43], v[188:191], v[212:215], v[40:43]
	v_mfma_f32_16x16x32_bf16 v[36:39], v[180:183], v[220:223], v[36:39]
	v_mfma_f32_16x16x32_bf16 v[32:35], v[188:191], v[220:223], v[32:35]
	v_mfma_f32_16x16x32_bf16 v[60:63], v[184:187], v[200:203], v[60:63]
	v_mfma_f32_16x16x32_bf16 v[56:59], v[192:195], v[200:203], v[56:59]
	v_mfma_f32_16x16x32_bf16 v[52:55], v[184:187], v[208:211], v[52:55]
	v_mfma_f32_16x16x32_bf16 v[48:51], v[192:195], v[208:211], v[48:51]
	v_mfma_f32_16x16x32_bf16 v[44:47], v[184:187], v[216:219], v[44:47]
	v_mfma_f32_16x16x32_bf16 v[40:43], v[192:195], v[216:219], v[40:43]
	v_mfma_f32_16x16x32_bf16 v[36:39], v[184:187], v[224:227], v[36:39]
	v_mfma_f32_16x16x32_bf16 v[32:35], v[192:195], v[224:227], v[32:35]
	s_setprio 0
	s_barrier
	v_readfirstlane_b32 s27, v163
	v_add_u32_e32 v179, 0x2000, v163
	v_lshl_add_u64 v[180:181], v[248:249], 0, s[16:17]
	s_mov_b32 m0, s27
	v_readfirstlane_b32 s27, v179
	global_load_lds_dwordx4 v[180:181], off
	v_lshl_add_u64 v[180:181], v[250:251], 0, s[16:17]
	s_mov_b32 m0, s27
	s_nop 0
	global_load_lds_dwordx4 v[180:181], off
	s_waitcnt vmcnt(6)
	s_barrier
	s_setprio 1
	v_mfma_f32_16x16x32_bf16 v[28:31], v[228:231], v[196:199], v[28:31]
	v_mfma_f32_16x16x32_bf16 v[24:27], v[236:239], v[196:199], v[24:27]
	v_mfma_f32_16x16x32_bf16 v[20:23], v[228:231], v[204:207], v[20:23]
	v_mfma_f32_16x16x32_bf16 v[16:19], v[236:239], v[204:207], v[16:19]
	v_mfma_f32_16x16x32_bf16 v[12:15], v[228:231], v[212:215], v[12:15]
	v_mfma_f32_16x16x32_bf16 v[8:11], v[236:239], v[212:215], v[8:11]
	v_mfma_f32_16x16x32_bf16 v[4:7], v[228:231], v[220:223], v[4:7]
	v_mfma_f32_16x16x32_bf16 v[0:3], v[236:239], v[220:223], v[0:3]
	v_mfma_f32_16x16x32_bf16 v[28:31], v[232:235], v[200:203], v[28:31]
	v_mfma_f32_16x16x32_bf16 v[24:27], v[240:243], v[200:203], v[24:27]
	v_mfma_f32_16x16x32_bf16 v[20:23], v[232:235], v[208:211], v[20:23]
	v_mfma_f32_16x16x32_bf16 v[16:19], v[240:243], v[208:211], v[16:19]
	v_mfma_f32_16x16x32_bf16 v[12:15], v[232:235], v[216:219], v[12:15]
	v_mfma_f32_16x16x32_bf16 v[8:11], v[240:243], v[216:219], v[8:11]
	v_mfma_f32_16x16x32_bf16 v[4:7], v[232:235], v[224:227], v[4:7]
	v_mfma_f32_16x16x32_bf16 v[0:3], v[240:243], v[224:227], v[0:3]
	s_setprio 0
	s_add_i32 s26, s26, 2
	v_lshl_add_u64 v[142:143], v[142:143], 0, s[18:19]
	v_lshl_add_u64 v[144:145], v[144:145], 0, s[18:19]
	v_lshl_add_u64 v[146:147], v[146:147], 0, s[18:19]
	s_cmp_lt_u32 s26, 28
	v_lshl_add_u64 v[148:149], v[148:149], 0, s[18:19]
	s_cbranch_scc1 .LBB0_1938
	s_barrier
	s_or_b32 s26, s22, 0x80
	s_ashr_i32 s27, s26, 31
	s_lshl_b64 s[26:27], s[26:27], 12
	s_add_u32 s26, s90, s26
	s_addc_u32 s27, s91, s27
	v_lshl_add_u64 v[216:217], v[134:135], 1, s[26:27]
	v_lshl_add_u64 v[138:139], v[138:139], 1, v[216:217]
	v_readfirstlane_b32 s23, v177
	v_lshl_add_u64 v[138:139], v[138:139], 0, s[20:21]
	s_mov_b32 m0, s23
	ds_read_b128 v[142:145], v165
	ds_read_b128 v[146:149], v165 offset:1024
	ds_read_b128 v[180:183], v165 offset:2048
	ds_read_b128 v[162:165], v165 offset:3072
	ds_read_b128 v[184:187], v155
	ds_read_b128 v[188:191], v155 offset:1024
	ds_read_b128 v[192:195], v173
	ds_read_b128 v[196:199], v173 offset:1024
	ds_read_b128 v[200:203], v174
	ds_read_b128 v[204:207], v174 offset:1024
	ds_read_b128 v[208:211], v175
	ds_read_b128 v[212:215], v175 offset:1024
	global_load_lds_dwordx4 v[138:139], off
	v_lshl_add_u64 v[138:139], v[136:137], 1, s[26:27]
	v_lshl_add_u64 v[138:139], v[140:141], 1, v[138:139]
	v_readfirstlane_b32 s23, v178
	v_lshl_add_u64 v[138:139], v[138:139], 0, s[20:21]
	s_mov_b32 m0, s23
	s_nop 0
	global_load_lds_dwordx4 v[138:139], off
	s_barrier
	s_waitcnt lgkmcnt(0)
	s_setprio 1
	v_mfma_f32_16x16x32_bf16 v[124:127], v[142:145], v[184:187], v[124:127]
	v_mfma_f32_16x16x32_bf16 v[120:123], v[180:183], v[184:187], v[120:123]
	v_mfma_f32_16x16x32_bf16 v[116:119], v[142:145], v[192:195], v[116:119]
	v_mfma_f32_16x16x32_bf16 v[112:115], v[180:183], v[192:195], v[112:115]
	v_mfma_f32_16x16x32_bf16 v[104:107], v[180:183], v[200:203], v[104:107]
	v_mfma_f32_16x16x32_bf16 v[96:99], v[180:183], v[208:211], v[96:99]
	v_mfma_f32_16x16x32_bf16 v[124:127], v[146:149], v[188:191], v[124:127]
	v_mfma_f32_16x16x32_bf16 v[120:123], v[162:165], v[188:191], v[120:123]
	v_mfma_f32_16x16x32_bf16 v[116:119], v[146:149], v[196:199], v[116:119]
	v_mfma_f32_16x16x32_bf16 v[112:115], v[162:165], v[196:199], v[112:115]
	v_mfma_f32_16x16x32_bf16 v[108:111], v[142:145], v[200:203], v[108:111]
	v_mfma_f32_16x16x32_bf16 v[104:107], v[162:165], v[204:207], v[104:107]
	v_mfma_f32_16x16x32_bf16 v[100:103], v[142:145], v[208:211], v[100:103]
	v_mfma_f32_16x16x32_bf16 v[96:99], v[162:165], v[212:215], v[96:99]
	v_mfma_f32_16x16x32_bf16 v[138:141], v[146:149], v[204:207], v[108:111]
	v_mfma_f32_16x16x32_bf16 v[216:219], v[146:149], v[212:215], v[100:103]
	s_setprio 0
	s_barrier
; #define LDA(dst,b,h) _Pragma("unroll") for(int m=0;m<4;++m) _Pragma("unroll") for(int k=0;k<2;++k) \
;     dst[m][k]=*reinterpret_cast<const bf16x8*>((char*)SA(b,h)+lds_byte(wr*64+m*16+fr,k*32+fq*8))
; #define LDB(dst,b,h) _Pragma("unroll") for(int n=0;n<2;++n) _Pragma("unroll") for(int k=0;k<2;++k) \
;     dst[n][k]=*reinterpret_cast<const bf16x8*>((char*)SB(b,h)+lds_byte(wc*32+n*16+fr,k*32+fq*8))
; #define MMA(ai,bj,At_,Bt_) do{__builtin_amdgcn_s_setprio(1); \
;     _Pragma("unroll") for(int m=0;m<4;++m) _Pragma("unroll") for(int n=0;n<2;++n) _Pragma("unroll") for(int k=0;k<2;++k) \
;       acc[ai][bj][m][n]=__builtin_amdgcn_mfma_f32_16x16x32_bf16(Bt_[n][k],At_[m][k],acc[ai][bj][m][n],0,0,0); \
;     __builtin_amdgcn_s_setprio(0);}while(0)
; #define WAIT_V(n) asm volatile("s_waitcnt vmcnt(" #n ")":::"memory")
; #define WAIT_L(n) asm volatile("s_waitcnt lgkmcnt(" #n ")":::"memory")
; #define BAR __builtin_amdgcn_s_barrier()
; DEVINL void gemm8_mainloop(const u16* A, long lda, const u16* Bt, long ldb, int K, int brow, int bcol, f32x4 (&acc)[2][2][4][2], char* smem, int tid) {
;     ...
;     LDB(B1,0,1); BAR; WAIT_L(0); MMA(0,1,At,B1); BAR;
;     LDA(At,0,1); WAIT_V(4); BAR; WAIT_L(0); MMA(1,0,At,B0); MMA(1,1,At,B1); BAR; }
;   { LDB(B0,1,0); LDA(At,1,0); WAIT_V(2); BAR; WAIT_L(0); MMA(0,0,At,B0); BAR;
	s_nop 2
	ds_read_b128 v[100:103], v161
	ds_read_b128 v[108:111], v161 offset:1024
	ds_read_b128 v[220:223], v161 offset:2048
	ds_read_b128 v[224:227], v161 offset:3072
	s_barrier
	s_waitcnt lgkmcnt(0)
	s_setprio 1
	v_mfma_f32_16x16x32_bf16 v[88:91], v[220:223], v[184:187], v[88:91]
	v_mfma_f32_16x16x32_bf16 v[80:83], v[220:223], v[192:195], v[80:83]
	v_mfma_f32_16x16x32_bf16 v[72:75], v[220:223], v[200:203], v[72:75]
	v_mfma_f32_16x16x32_bf16 v[64:67], v[220:223], v[208:211], v[64:67]
	v_mfma_f32_16x16x32_bf16 v[92:95], v[100:103], v[184:187], v[92:95]
	v_mfma_f32_16x16x32_bf16 v[88:91], v[224:227], v[188:191], v[88:91]
	v_mfma_f32_16x16x32_bf16 v[84:87], v[100:103], v[192:195], v[84:87]
	v_mfma_f32_16x16x32_bf16 v[80:83], v[224:227], v[196:199], v[80:83]
	v_mfma_f32_16x16x32_bf16 v[76:79], v[100:103], v[200:203], v[76:79]
	v_mfma_f32_16x16x32_bf16 v[72:75], v[224:227], v[204:207], v[72:75]
	v_mfma_f32_16x16x32_bf16 v[68:71], v[100:103], v[208:211], v[68:71]
	v_mfma_f32_16x16x32_bf16 v[64:67], v[224:227], v[212:215], v[64:67]
	v_mfma_f32_16x16x32_bf16 v[228:231], v[108:111], v[188:191], v[92:95]
	v_mfma_f32_16x16x32_bf16 v[184:187], v[108:111], v[196:199], v[84:87]
	v_mfma_f32_16x16x32_bf16 v[188:191], v[108:111], v[204:207], v[76:79]
	v_mfma_f32_16x16x32_bf16 v[192:195], v[108:111], v[212:215], v[68:71]
	s_setprio 0
	s_barrier
	s_nop 0
	ds_read_b128 v[68:71], v155 offset:16384
	ds_read_b128 v[76:79], v155 offset:17408
	ds_read_b128 v[84:87], v173 offset:16384
	ds_read_b128 v[92:95], v173 offset:17408
	ds_read_b128 v[196:199], v174 offset:16384
	ds_read_b128 v[200:203], v174 offset:17408
	ds_read_b128 v[204:207], v175 offset:16384
	ds_read_b128 v[208:211], v175 offset:17408
	s_waitcnt vmcnt(4)
	s_barrier
	s_waitcnt lgkmcnt(0)
	s_setprio 1
	v_mfma_f32_16x16x32_bf16 v[60:63], v[142:145], v[68:71], v[60:63]
	v_mfma_f32_16x16x32_bf16 v[56:59], v[180:183], v[68:71], v[56:59]
	v_mfma_f32_16x16x32_bf16 v[48:51], v[180:183], v[84:87], v[48:51]
	v_mfma_f32_16x16x32_bf16 v[40:43], v[180:183], v[196:199], v[40:43]
	v_mfma_f32_16x16x32_bf16 v[32:35], v[180:183], v[204:207], v[32:35]
	v_mfma_f32_16x16x32_bf16 v[60:63], v[146:149], v[76:79], v[60:63]
	v_mfma_f32_16x16x32_bf16 v[56:59], v[162:165], v[76:79], v[56:59]
	v_mfma_f32_16x16x32_bf16 v[52:55], v[142:145], v[84:87], v[52:55]
	v_mfma_f32_16x16x32_bf16 v[48:51], v[162:165], v[92:95], v[48:51]
	v_mfma_f32_16x16x32_bf16 v[44:47], v[142:145], v[196:199], v[44:47]
	v_mfma_f32_16x16x32_bf16 v[40:43], v[162:165], v[200:203], v[40:43]
	v_mfma_f32_16x16x32_bf16 v[36:39], v[142:145], v[204:207], v[36:39]
	v_mfma_f32_16x16x32_bf16 v[32:35], v[162:165], v[208:211], v[32:35]
	v_mfma_f32_16x16x32_bf16 v[212:215], v[146:149], v[92:95], v[52:55]
	v_mfma_f32_16x16x32_bf16 v[232:235], v[146:149], v[200:203], v[44:47]
	v_mfma_f32_16x16x32_bf16 v[142:145], v[146:149], v[208:211], v[36:39]
	s_setprio 0
	s_setprio 1
	v_mfma_f32_16x16x32_bf16 v[24:27], v[220:223], v[68:71], v[24:27]
	v_mfma_f32_16x16x32_bf16 v[16:19], v[220:223], v[84:87], v[16:19]
	v_mfma_f32_16x16x32_bf16 v[4:7], v[100:103], v[204:207], v[4:7]
	v_mfma_f32_16x16x32_bf16 v[0:3], v[220:223], v[204:207], v[0:3]
	v_mfma_f32_16x16x32_bf16 v[28:31], v[100:103], v[68:71], v[28:31]
	v_mfma_f32_16x16x32_bf16 v[24:27], v[224:227], v[76:79], v[24:27]
	v_mfma_f32_16x16x32_bf16 v[20:23], v[100:103], v[84:87], v[20:23]
	v_mfma_f32_16x16x32_bf16 v[16:19], v[224:227], v[92:95], v[16:19]
	v_mfma_f32_16x16x32_bf16 v[12:15], v[100:103], v[196:199], v[12:15]
	v_mfma_f32_16x16x32_bf16 v[8:11], v[220:223], v[196:199], v[8:11]
	v_mfma_f32_16x16x32_bf16 v[4:7], v[108:111], v[208:211], v[4:7]
	v_mfma_f32_16x16x32_bf16 v[0:3], v[224:227], v[208:211], v[0:3]
	v_mfma_f32_16x16x32_bf16 v[146:149], v[108:111], v[76:79], v[28:31]
	v_mfma_f32_16x16x32_bf16 v[160:163], v[108:111], v[92:95], v[20:23]
	v_mfma_f32_16x16x32_bf16 v[178:181], v[108:111], v[200:203], v[12:15]
	v_mfma_f32_16x16x32_bf16 v[196:199], v[224:227], v[200:203], v[8:11]
	s_setprio 0
	s_barrier
	s_nop 0
	ds_read_b128 v[8:11], v158
	ds_read_b128 v[12:15], v158 offset:1024
	ds_read_b128 v[200:203], v158 offset:2048
	ds_read_b128 v[204:207], v158 offset:3072
	ds_read_b128 v[20:23], v155 offset:32768
	ds_read_b128 v[28:31], v155 offset:33792
	ds_read_b128 v[36:39], v173 offset:32768
	ds_read_b128 v[44:47], v173 offset:33792
	ds_read_b128 v[52:55], v174 offset:32768
	ds_read_b128 v[208:211], v174 offset:33792
	ds_read_b128 v[220:223], v175 offset:32768
	ds_read_b128 v[224:227], v175 offset:33792
	s_waitcnt vmcnt(2)
	s_barrier
; #define LDA(dst,b,h) _Pragma("unroll") for(int m=0;m<4;++m) _Pragma("unroll") for(int k=0;k<2;++k) \
;     dst[m][k]=*reinterpret_cast<const bf16x8*>((char*)SA(b,h)+lds_byte(wr*64+m*16+fr,k*32+fq*8))
; #define LDB(dst,b,h) _Pragma("unroll") for(int n=0;n<2;++n) _Pragma("unroll") for(int k=0;k<2;++k) \
;     dst[n][k]=*reinterpret_cast<const bf16x8*>((char*)SB(b,h)+lds_byte(wc*32+n*16+fr,k*32+fq*8))
; #define MMA(ai,bj,At_,Bt_) do{__builtin_amdgcn_s_setprio(1); \
;     _Pragma("unroll") for(int m=0;m<4;++m) _Pragma("unroll") for(int n=0;n<2;++n) _Pragma("unroll") for(int k=0;k<2;++k) \
;       acc[ai][bj][m][n]=__builtin_amdgcn_mfma_f32_16x16x32_bf16(Bt_[n][k],At_[m][k],acc[ai][bj][m][n],0,0,0); \
;     __builtin_amdgcn_s_setprio(0);}while(0)
; #define WAIT_V(n) asm volatile("s_waitcnt vmcnt(" #n ")":::"memory")
; #define WAIT_L(n) asm volatile("s_waitcnt lgkmcnt(" #n ")":::"memory")
; #define BAR __builtin_amdgcn_s_barrier()
; DEVINL void gemm8_mainloop(const u16* A, long lda, const u16* Bt, long ldb, int K, int brow, int bcol, f32x4 (&acc)[2][2][4][2], char* smem, int tid) {
;     ...
;   { LDB(B0,1,0); LDA(At,1,0); WAIT_V(2); BAR; WAIT_L(0); MMA(0,0,At,B0); BAR;
;     LDB(B1,1,1); WAIT_V(0); BAR; WAIT_L(0); MMA(0,1,At,B1); BAR;
;     LDA(At,1,1); BAR; WAIT_L(0); MMA(1,0,At,B0); MMA(1,1,At,B1); BAR; }
;   if(wr==0)BAR;
;   __syncthreads();
	s_waitcnt lgkmcnt(0)
	s_setprio 1
	v_mfma_f32_16x16x32_bf16 v[68:71], v[8:11], v[20:23], v[124:127]
	v_mfma_f32_16x16x32_bf16 v[124:127], v[12:15], v[28:31], v[68:71]
	v_mfma_f32_16x16x32_bf16 v[68:71], v[200:203], v[20:23], v[120:123]
	v_mfma_f32_16x16x32_bf16 v[120:123], v[204:207], v[28:31], v[68:71]
	v_mfma_f32_16x16x32_bf16 v[68:71], v[8:11], v[36:39], v[116:119]
	v_mfma_f32_16x16x32_bf16 v[108:111], v[12:15], v[44:47], v[68:71]
	v_mfma_f32_16x16x32_bf16 v[68:71], v[200:203], v[36:39], v[112:115]
	v_mfma_f32_16x16x32_bf16 v[100:103], v[204:207], v[44:47], v[68:71]
	v_mfma_f32_16x16x32_bf16 v[68:71], v[8:11], v[52:55], v[138:141]
	v_mfma_f32_16x16x32_bf16 v[92:95], v[12:15], v[208:211], v[68:71]
	v_mfma_f32_16x16x32_bf16 v[68:71], v[200:203], v[52:55], v[104:107]
	v_mfma_f32_16x16x32_bf16 v[84:87], v[204:207], v[208:211], v[68:71]
	v_mfma_f32_16x16x32_bf16 v[68:71], v[8:11], v[220:223], v[216:219]
	v_mfma_f32_16x16x32_bf16 v[76:79], v[12:15], v[224:227], v[68:71]
	v_mfma_f32_16x16x32_bf16 v[68:71], v[200:203], v[220:223], v[96:99]
	v_mfma_f32_16x16x32_bf16 v[68:71], v[204:207], v[224:227], v[68:71]
	s_setprio 0
	s_barrier
	ds_read_b128 v[138:141], v156
	ds_read_b128 v[216:219], v156 offset:1024
	ds_read_b128 v[236:239], v156 offset:2048
	ds_read_b128 v[156:159], v156 offset:3072
	s_waitcnt vmcnt(0)
	s_barrier
	s_waitcnt lgkmcnt(0)
	s_setprio 1
	v_mfma_f32_16x16x32_bf16 v[96:99], v[138:141], v[20:23], v[228:231]
	v_mfma_f32_16x16x32_bf16 v[20:23], v[236:239], v[20:23], v[88:91]
	v_mfma_f32_16x16x32_bf16 v[112:115], v[156:159], v[28:31], v[20:23]
	v_mfma_f32_16x16x32_bf16 v[20:23], v[138:141], v[36:39], v[184:187]
	v_mfma_f32_16x16x32_bf16 v[104:107], v[216:219], v[44:47], v[20:23]
	v_mfma_f32_16x16x32_bf16 v[20:23], v[236:239], v[36:39], v[80:83]
	v_mfma_f32_16x16x32_bf16 v[116:119], v[216:219], v[28:31], v[96:99]
	v_mfma_f32_16x16x32_bf16 v[96:99], v[156:159], v[44:47], v[20:23]
	v_mfma_f32_16x16x32_bf16 v[20:23], v[138:141], v[52:55], v[188:191]
	v_mfma_f32_16x16x32_bf16 v[88:91], v[216:219], v[208:211], v[20:23]
	v_mfma_f32_16x16x32_bf16 v[20:23], v[236:239], v[52:55], v[72:75]
	v_mfma_f32_16x16x32_bf16 v[80:83], v[156:159], v[208:211], v[20:23]
	v_mfma_f32_16x16x32_bf16 v[20:23], v[138:141], v[220:223], v[192:195]
	v_mfma_f32_16x16x32_bf16 v[72:75], v[216:219], v[224:227], v[20:23]
	v_mfma_f32_16x16x32_bf16 v[20:23], v[236:239], v[220:223], v[64:67]
	v_mfma_f32_16x16x32_bf16 v[64:67], v[156:159], v[224:227], v[20:23]
	s_setprio 0
	s_barrier
	ds_read_b128 v[182:185], v155 offset:49152
	ds_read_b128 v[186:189], v155 offset:50176
	ds_read_b128 v[190:193], v173 offset:49152
	ds_read_b128 v[208:211], v173 offset:50176
	ds_read_b128 v[220:223], v174 offset:49152
	ds_read_b128 v[224:227], v174 offset:50176
	ds_read_b128 v[228:231], v175 offset:49152
	ds_read_b128 v[240:243], v175 offset:50176
	s_barrier
	s_waitcnt lgkmcnt(0)
	s_setprio 1
	v_mfma_f32_16x16x32_bf16 v[20:23], v[8:11], v[182:185], v[60:63]
	v_mfma_f32_16x16x32_bf16 v[60:63], v[12:15], v[186:189], v[20:23]
	v_mfma_f32_16x16x32_bf16 v[20:23], v[200:203], v[182:185], v[56:59]
	v_mfma_f32_16x16x32_bf16 v[52:55], v[204:207], v[186:189], v[20:23]
	v_mfma_f32_16x16x32_bf16 v[20:23], v[8:11], v[190:193], v[212:215]
	v_mfma_f32_16x16x32_bf16 v[44:47], v[12:15], v[208:211], v[20:23]
	v_mfma_f32_16x16x32_bf16 v[20:23], v[200:203], v[190:193], v[48:51]
	v_mfma_f32_16x16x32_bf16 v[36:39], v[204:207], v[208:211], v[20:23]
	v_mfma_f32_16x16x32_bf16 v[20:23], v[8:11], v[220:223], v[232:235]
	v_mfma_f32_16x16x32_bf16 v[8:11], v[8:11], v[228:231], v[142:145]
	v_mfma_f32_16x16x32_bf16 v[28:31], v[12:15], v[224:227], v[20:23]
	v_mfma_f32_16x16x32_bf16 v[20:23], v[200:203], v[220:223], v[40:43]
	v_mfma_f32_16x16x32_bf16 v[12:15], v[12:15], v[240:243], v[8:11]
	v_mfma_f32_16x16x32_bf16 v[8:11], v[200:203], v[228:231], v[32:35]
	v_mfma_f32_16x16x32_bf16 v[20:23], v[204:207], v[224:227], v[20:23]
	v_mfma_f32_16x16x32_bf16 v[8:11], v[204:207], v[240:243], v[8:11]
	s_setprio 0
	s_setprio 1
	v_mfma_f32_16x16x32_bf16 v[32:35], v[138:141], v[182:185], v[146:149]
	v_mfma_f32_16x16x32_bf16 v[24:27], v[236:239], v[182:185], v[24:27]
	v_mfma_f32_16x16x32_bf16 v[16:19], v[236:239], v[190:193], v[16:19]
	v_mfma_f32_16x16x32_bf16 v[56:59], v[216:219], v[186:189], v[32:35]
	v_mfma_f32_16x16x32_bf16 v[48:51], v[156:159], v[186:189], v[24:27]
	v_mfma_f32_16x16x32_bf16 v[24:27], v[138:141], v[190:193], v[160:163]
	v_mfma_f32_16x16x32_bf16 v[32:35], v[156:159], v[208:211], v[16:19]
	v_mfma_f32_16x16x32_bf16 v[16:19], v[138:141], v[220:223], v[178:181]
	v_mfma_f32_16x16x32_bf16 v[40:43], v[216:219], v[208:211], v[24:27]
	v_mfma_f32_16x16x32_bf16 v[24:27], v[216:219], v[224:227], v[16:19]
	v_mfma_f32_16x16x32_bf16 v[16:19], v[236:239], v[220:223], v[196:199]
	v_mfma_f32_16x16x32_bf16 v[4:7], v[138:141], v[228:231], v[4:7]
	v_mfma_f32_16x16x32_bf16 v[0:3], v[236:239], v[228:231], v[0:3]
	v_mfma_f32_16x16x32_bf16 v[16:19], v[156:159], v[224:227], v[16:19]
	v_mfma_f32_16x16x32_bf16 v[4:7], v[216:219], v[240:243], v[4:7]
	v_mfma_f32_16x16x32_bf16 v[0:3], v[156:159], v[240:243], v[0:3]
	s_setprio 0
	s_cmpk_gt_u32 s37, 0xff
	s_barrier
	s_cbranch_scc1 .LBB0_1941
	s_barrier

; #define STAGE(P,BASE,LD,br,kt) do{long _g=(long)(br)*(LD)+(long)(kt)*BK; \
;     _Pragma("unroll") for(int _i=0;_i<2;++_i){int _b=tid*16+_i*8192;int _r,_c;stage_rc(_b,_r,_c); \
;       __builtin_amdgcn_global_load_lds((const unsigned*)((BASE)+_g+(long)_r*(LD)+_c), \
;         (unsigned*)((char*)(P)+_b),16,0,0);}}while(0)
; #define STAGE(P,BASE,LD,br,kt) do{long _g=(long)(br)*(LD)+(long)(kt)*BK; \
;     _Pragma("unroll") for(int _i=0;_i<2;++_i){int _b=tid*16+_i*8192;int _r,_c;stage_rc(_b,_r,_c); \
;       __builtin_amdgcn_global_load_lds((const unsigned*)((BASE)+_g+(long)_r*(LD)+_c), \
;         (unsigned*)((char*)(P)+_b),16,0,0);}}while(0)
; #define LDA(dst,b,h) _Pragma("unroll") for(int m=0;m<4;++m) _Pragma("unroll") for(int k=0;k<2;++k) \
;     dst[m][k]=*reinterpret_cast<const bf16x8*>((char*)SA(b,h)+lds_byte(wr*64+m*16+fr,k*32+fq*8))
; #define LDB(dst,b,h) _Pragma("unroll") for(int n=0;n<2;++n) _Pragma("unroll") for(int k=0;k<2;++k) \
;     dst[n][k]=*reinterpret_cast<const bf16x8*>((char*)SB(b,h)+lds_byte(wc*32+n*16+fr,k*32+fq*8))
; #define MMA(ai,bj,At_,Bt_) do{__builtin_amdgcn_s_setprio(1); \
;     _Pragma("unroll") for(int m=0;m<4;++m) _Pragma("unroll") for(int n=0;n<2;++n) _Pragma("unroll") for(int k=0;k<2;++k) \
;       acc[ai][bj][m][n]=__builtin_amdgcn_mfma_f32_16x16x32_bf16(Bt_[n][k],At_[m][k],acc[ai][bj][m][n],0,0,0); \
;     __builtin_amdgcn_s_setprio(0);}while(0)
; #define WAIT_L(n) asm volatile("s_waitcnt lgkmcnt(" #n ")":::"memory")
; #define BAR __builtin_amdgcn_s_barrier()
; #define SCHED __builtin_amdgcn_sched_barrier(0)
; DEVINL void gemm8_mainloop(const u16* A, long lda, const u16* Bt, long ldb, int K, int brow, int bcol, f32x4 (&acc)[2][2][4][2], char* smem, int tid) {
;     ...
;   for(int t=0;t<nt-2;t+=2){
;     LDB(B0,0,0); SCHED; LDA(At,0,0); STAGE(SA(1,1),A,lda,brow+HALF,t+1);
;     WAIT_L(8); BAR; WAIT_L(0); MMA(0,0,At,B0); BAR; SCHED;
;     LDB(B1,0,1); STAGE(SB(0,0),Bt,ldb,bcol,t+2);
;     BAR; WAIT_L(0); MMA(0,1,At,B1); BAR;
;     LDA(At,0,1); STAGE(SA(0,0),A,lda,brow,t+2);
;     BAR; WAIT_L(0); MMA(1,0,At,B0); BAR; SCHED;
.LBB0_1987:
	s_barrier
	ds_read_b128 v[178:181], v163
	ds_read_b128 v[182:185], v163 offset:1024
	ds_read_b128 v[186:189], v163 offset:2048
	ds_read_b128 v[190:193], v163 offset:3072
	v_add_u32_e32 v174, 0xc000, v152
	v_lshl_add_u64 v[242:243], s[94:95], 0, v[146:147]
	v_readfirstlane_b32 s25, v174
	v_add_u32_e32 v175, 0xe000, v152
	v_add_u32_e32 v171, s23, v162
	v_add_u32_e32 v172, s34, v162
	v_add_u32_e32 v173, s35, v162
	v_lshl_add_u64 v[164:165], v[242:243], 0, s[2:3]
	s_mov_b32 m0, s25
	v_lshl_add_u64 v[244:245], s[94:95], 0, v[148:149]
	v_readfirstlane_b32 s25, v175
	ds_read_b128 v[166:169], v153
	ds_read_b128 v[194:197], v153 offset:1024
	ds_read_b128 v[198:201], v171
	ds_read_b128 v[202:205], v171 offset:1024
	ds_read_b128 v[206:209], v172
	ds_read_b128 v[210:213], v172 offset:1024
	ds_read_b128 v[214:217], v173
	ds_read_b128 v[218:221], v173 offset:1024
	global_load_lds_dwordx4 v[164:165], off
	v_lshl_add_u64 v[164:165], v[244:245], 0, s[2:3]
	s_mov_b32 m0, s25
	s_nop 0
	global_load_lds_dwordx4 v[164:165], off
	s_waitcnt lgkmcnt(8)
	s_barrier
	s_waitcnt lgkmcnt(0)
	s_setprio 1
	v_mfma_f32_16x16x32_bf16 v[124:127], v[178:181], v[166:169], v[124:127]
	v_mfma_f32_16x16x32_bf16 v[120:123], v[186:189], v[166:169], v[120:123]
	v_mfma_f32_16x16x32_bf16 v[116:119], v[178:181], v[198:201], v[116:119]
	v_mfma_f32_16x16x32_bf16 v[112:115], v[186:189], v[198:201], v[112:115]
	v_mfma_f32_16x16x32_bf16 v[108:111], v[178:181], v[206:209], v[108:111]
	v_mfma_f32_16x16x32_bf16 v[104:107], v[186:189], v[206:209], v[104:107]
	v_mfma_f32_16x16x32_bf16 v[100:103], v[178:181], v[214:217], v[100:103]
	v_mfma_f32_16x16x32_bf16 v[96:99], v[186:189], v[214:217], v[96:99]
	v_mfma_f32_16x16x32_bf16 v[124:127], v[182:185], v[194:197], v[124:127]
	v_mfma_f32_16x16x32_bf16 v[120:123], v[190:193], v[194:197], v[120:123]
	v_mfma_f32_16x16x32_bf16 v[116:119], v[182:185], v[202:205], v[116:119]
	v_mfma_f32_16x16x32_bf16 v[112:115], v[190:193], v[202:205], v[112:115]
	v_mfma_f32_16x16x32_bf16 v[108:111], v[182:185], v[210:213], v[108:111]
	v_mfma_f32_16x16x32_bf16 v[104:107], v[190:193], v[210:213], v[104:107]
	v_mfma_f32_16x16x32_bf16 v[100:103], v[182:185], v[218:221], v[100:103]
	v_mfma_f32_16x16x32_bf16 v[96:99], v[190:193], v[218:221], v[96:99]
	s_setprio 0
	s_barrier
	v_add_u32_e32 v164, s28, v154
	v_lshl_add_u64 v[246:247], s[94:95], 0, v[142:143]
	v_readfirstlane_b32 s25, v164
	v_add_u32_e32 v165, 0x2000, v164
	v_lshl_add_u64 v[238:239], v[246:247], 0, s[4:5]
	s_mov_b32 m0, s25
	v_lshl_add_u64 v[248:249], s[94:95], 0, v[144:145]
	v_readfirstlane_b32 s25, v165
	ds_read_b128 v[222:225], v160
	ds_read_b128 v[226:229], v160 offset:1024
	ds_read_b128 v[230:233], v160 offset:2048
	ds_read_b128 v[234:237], v160 offset:3072
	global_load_lds_dwordx4 v[238:239], off
	v_lshl_add_u64 v[238:239], v[248:249], 0, s[4:5]
	s_mov_b32 m0, s25
	s_nop 0
	global_load_lds_dwordx4 v[238:239], off
	s_barrier
	s_waitcnt lgkmcnt(0)
	s_setprio 1
	v_mfma_f32_16x16x32_bf16 v[92:95], v[222:225], v[166:169], v[92:95]
	v_mfma_f32_16x16x32_bf16 v[88:91], v[230:233], v[166:169], v[88:91]
	v_mfma_f32_16x16x32_bf16 v[84:87], v[222:225], v[198:201], v[84:87]
	v_mfma_f32_16x16x32_bf16 v[80:83], v[230:233], v[198:201], v[80:83]
	v_mfma_f32_16x16x32_bf16 v[76:79], v[222:225], v[206:209], v[76:79]
	v_mfma_f32_16x16x32_bf16 v[72:75], v[230:233], v[206:209], v[72:75]
	v_mfma_f32_16x16x32_bf16 v[68:71], v[222:225], v[214:217], v[68:71]
	v_mfma_f32_16x16x32_bf16 v[64:67], v[230:233], v[214:217], v[64:67]
	v_mfma_f32_16x16x32_bf16 v[92:95], v[226:229], v[194:197], v[92:95]
	v_mfma_f32_16x16x32_bf16 v[88:91], v[234:237], v[194:197], v[88:91]
	v_mfma_f32_16x16x32_bf16 v[84:87], v[226:229], v[202:205], v[84:87]
	v_mfma_f32_16x16x32_bf16 v[80:83], v[234:237], v[202:205], v[80:83]
	v_mfma_f32_16x16x32_bf16 v[76:79], v[226:229], v[210:213], v[76:79]
	v_mfma_f32_16x16x32_bf16 v[72:75], v[234:237], v[210:213], v[72:75]
	v_mfma_f32_16x16x32_bf16 v[68:71], v[226:229], v[218:221], v[68:71]
	v_mfma_f32_16x16x32_bf16 v[64:67], v[234:237], v[218:221], v[64:67]
	s_setprio 0
	v_readfirstlane_b32 s25, v152
	v_lshl_add_u64 v[166:167], v[242:243], 0, s[6:7]
	s_mov_b32 m0, s25
	s_barrier
	ds_read_b128 v[194:197], v153 offset:16384
	ds_read_b128 v[198:201], v153 offset:17408
	ds_read_b128 v[202:205], v171 offset:16384
	ds_read_b128 v[206:209], v171 offset:17408
	ds_read_b128 v[210:213], v172 offset:16384
	ds_read_b128 v[214:217], v172 offset:17408
	ds_read_b128 v[218:221], v173 offset:16384
	ds_read_b128 v[238:241], v173 offset:17408
	global_load_lds_dwordx4 v[166:167], off
	v_add_u32_e32 v166, 0x2000, v152
	v_lshl_add_u64 v[168:169], v[244:245], 0, s[6:7]
	v_readfirstlane_b32 s25, v166
	s_mov_b32 m0, s25
	s_nop 0
	global_load_lds_dwordx4 v[168:169], off
	s_barrier
	s_waitcnt lgkmcnt(0)
	s_setprio 1
	v_mfma_f32_16x16x32_bf16 v[60:63], v[178:181], v[194:197], v[60:63]
	v_mfma_f32_16x16x32_bf16 v[56:59], v[186:189], v[194:197], v[56:59]
	v_mfma_f32_16x16x32_bf16 v[52:55], v[178:181], v[202:205], v[52:55]
	v_mfma_f32_16x16x32_bf16 v[48:51], v[186:189], v[202:205], v[48:51]
	v_mfma_f32_16x16x32_bf16 v[44:47], v[178:181], v[210:213], v[44:47]
	v_mfma_f32_16x16x32_bf16 v[40:43], v[186:189], v[210:213], v[40:43]
	v_mfma_f32_16x16x32_bf16 v[36:39], v[178:181], v[218:221], v[36:39]
	v_mfma_f32_16x16x32_bf16 v[32:35], v[186:189], v[218:221], v[32:35]
	v_mfma_f32_16x16x32_bf16 v[60:63], v[182:185], v[198:201], v[60:63]
	v_mfma_f32_16x16x32_bf16 v[56:59], v[190:193], v[198:201], v[56:59]
	v_mfma_f32_16x16x32_bf16 v[52:55], v[182:185], v[206:209], v[52:55]
	v_mfma_f32_16x16x32_bf16 v[48:51], v[190:193], v[206:209], v[48:51]
	v_mfma_f32_16x16x32_bf16 v[44:47], v[182:185], v[214:217], v[44:47]
	v_mfma_f32_16x16x32_bf16 v[40:43], v[190:193], v[214:217], v[40:43]
	v_mfma_f32_16x16x32_bf16 v[36:39], v[182:185], v[238:241], v[36:39]
	v_mfma_f32_16x16x32_bf16 v[32:35], v[190:193], v[238:241], v[32:35]
	s_setprio 0
	s_barrier
; #define STAGE(P,BASE,LD,br,kt) do{long _g=(long)(br)*(LD)+(long)(kt)*BK; \
;     _Pragma("unroll") for(int _i=0;_i<2;++_i){int _b=tid*16+_i*8192;int _r,_c;stage_rc(_b,_r,_c); \
;       __builtin_amdgcn_global_load_lds((const unsigned*)((BASE)+_g+(long)_r*(LD)+_c), \
;         (unsigned*)((char*)(P)+_b),16,0,0);}}while(0)
; #define STAGE(P,BASE,LD,br,kt) do{long _g=(long)(br)*(LD)+(long)(kt)*BK; \
;     _Pragma("unroll") for(int _i=0;_i<2;++_i){int _b=tid*16+_i*8192;int _r,_c;stage_rc(_b,_r,_c); \
;       __builtin_amdgcn_global_load_lds((const unsigned*)((BASE)+_g+(long)_r*(LD)+_c), \
;         (unsigned*)((char*)(P)+_b),16,0,0);}}while(0)
; #define LDA(dst,b,h) _Pragma("unroll") for(int m=0;m<4;++m) _Pragma("unroll") for(int k=0;k<2;++k) \
;     dst[m][k]=*reinterpret_cast<const bf16x8*>((char*)SA(b,h)+lds_byte(wr*64+m*16+fr,k*32+fq*8))
; #define LDB(dst,b,h) _Pragma("unroll") for(int n=0;n<2;++n) _Pragma("unroll") for(int k=0;k<2;++k) \
;     dst[n][k]=*reinterpret_cast<const bf16x8*>((char*)SB(b,h)+lds_byte(wc*32+n*16+fr,k*32+fq*8))
; #define MMA(ai,bj,At_,Bt_) do{__builtin_amdgcn_s_setprio(1); \
;     _Pragma("unroll") for(int m=0;m<4;++m) _Pragma("unroll") for(int n=0;n<2;++n) _Pragma("unroll") for(int k=0;k<2;++k) \
;       acc[ai][bj][m][n]=__builtin_amdgcn_mfma_f32_16x16x32_bf16(Bt_[n][k],At_[m][k],acc[ai][bj][m][n],0,0,0); \
;     __builtin_amdgcn_s_setprio(0);}while(0)
; #define WAIT_V(n) asm volatile("s_waitcnt vmcnt(" #n ")":::"memory")
; #define WAIT_L(n) asm volatile("s_waitcnt lgkmcnt(" #n ")":::"memory")
; #define BAR __builtin_amdgcn_s_barrier()
; #define SCHED __builtin_amdgcn_sched_barrier(0)
; DEVINL void gemm8_mainloop(const u16* A, long lda, const u16* Bt, long ldb, int K, int brow, int bcol, f32x4 (&acc)[2][2][4][2], char* smem, int tid) {
;     ...
;     STAGE(SB(0,1),Bt,ldb,bcol+HALF,t+2);
;     WAIT_V(6); BAR; MMA(1,1,At,B1); BAR;
;     LDB(B0,1,0); SCHED; LDA(At,1,0); STAGE(SA(0,1),A,lda,brow+HALF,t+2);
;     WAIT_L(8); BAR; WAIT_L(0); MMA(0,0,At,B0); BAR; SCHED;
;     LDB(B1,1,1); STAGE(SB(1,0),Bt,ldb,bcol,t+3);
;     BAR; WAIT_L(0); MMA(0,1,At,B1); BAR;
;     LDA(At,1,1); STAGE(SA(1,0),A,lda,brow,t+3);
	v_add_u32_e32 v167, s29, v154
	v_lshl_add_u64 v[168:169], v[246:247], 0, s[8:9]
	v_readfirstlane_b32 s25, v167
	s_mov_b32 m0, s25
	v_lshl_add_u64 v[178:179], v[248:249], 0, s[8:9]
	global_load_lds_dwordx4 v[168:169], off
	v_add_u32_e32 v168, 0x2000, v167
	s_nop 0
	v_readfirstlane_b32 s25, v168
	s_mov_b32 m0, s25
	s_nop 0
	global_load_lds_dwordx4 v[178:179], off
	s_waitcnt vmcnt(6)
	s_barrier
	s_setprio 1
	v_mfma_f32_16x16x32_bf16 v[28:31], v[222:225], v[194:197], v[28:31]
	v_mfma_f32_16x16x32_bf16 v[24:27], v[230:233], v[194:197], v[24:27]
	v_mfma_f32_16x16x32_bf16 v[20:23], v[222:225], v[202:205], v[20:23]
	v_mfma_f32_16x16x32_bf16 v[16:19], v[230:233], v[202:205], v[16:19]
	v_mfma_f32_16x16x32_bf16 v[12:15], v[222:225], v[210:213], v[12:15]
	v_mfma_f32_16x16x32_bf16 v[8:11], v[230:233], v[210:213], v[8:11]
	v_mfma_f32_16x16x32_bf16 v[4:7], v[222:225], v[218:221], v[4:7]
	v_mfma_f32_16x16x32_bf16 v[0:3], v[230:233], v[218:221], v[0:3]
	v_mfma_f32_16x16x32_bf16 v[28:31], v[226:229], v[198:201], v[28:31]
	v_mfma_f32_16x16x32_bf16 v[24:27], v[234:237], v[198:201], v[24:27]
	v_mfma_f32_16x16x32_bf16 v[20:23], v[226:229], v[206:209], v[20:23]
	v_mfma_f32_16x16x32_bf16 v[16:19], v[234:237], v[206:209], v[16:19]
	v_mfma_f32_16x16x32_bf16 v[12:15], v[226:229], v[214:217], v[12:15]
	v_mfma_f32_16x16x32_bf16 v[8:11], v[234:237], v[214:217], v[8:11]
	v_mfma_f32_16x16x32_bf16 v[4:7], v[226:229], v[238:241], v[4:7]
	v_mfma_f32_16x16x32_bf16 v[0:3], v[234:237], v[238:241], v[0:3]
	s_setprio 0
	s_barrier
	ds_read_b128 v[178:181], v156
	ds_read_b128 v[182:185], v156 offset:1024
	ds_read_b128 v[186:189], v156 offset:2048
	ds_read_b128 v[190:193], v156 offset:3072
	v_add_u32_e32 v169, 0x4000, v152
	v_add_u32_e32 v170, 0x6000, v152
	v_readfirstlane_b32 s25, v169
	v_lshl_add_u64 v[226:227], v[242:243], 0, s[10:11]
	s_mov_b32 m0, s25
	v_readfirstlane_b32 s25, v170
	ds_read_b128 v[194:197], v153 offset:32768
	ds_read_b128 v[198:201], v153 offset:33792
	ds_read_b128 v[202:205], v171 offset:32768
	ds_read_b128 v[206:209], v171 offset:33792
	ds_read_b128 v[210:213], v172 offset:32768
	ds_read_b128 v[214:217], v172 offset:33792
	ds_read_b128 v[218:221], v173 offset:32768
	ds_read_b128 v[222:225], v173 offset:33792
	global_load_lds_dwordx4 v[226:227], off
	v_lshl_add_u64 v[226:227], v[244:245], 0, s[10:11]
	s_mov_b32 m0, s25
	s_nop 0
	global_load_lds_dwordx4 v[226:227], off
	s_waitcnt lgkmcnt(8)
	s_barrier
	s_waitcnt lgkmcnt(0)
	s_setprio 1
	v_mfma_f32_16x16x32_bf16 v[124:127], v[178:181], v[194:197], v[124:127]
	v_mfma_f32_16x16x32_bf16 v[120:123], v[186:189], v[194:197], v[120:123]
	v_mfma_f32_16x16x32_bf16 v[116:119], v[178:181], v[202:205], v[116:119]
	v_mfma_f32_16x16x32_bf16 v[112:115], v[186:189], v[202:205], v[112:115]
	v_mfma_f32_16x16x32_bf16 v[108:111], v[178:181], v[210:213], v[108:111]
	v_mfma_f32_16x16x32_bf16 v[104:107], v[186:189], v[210:213], v[104:107]
	v_mfma_f32_16x16x32_bf16 v[100:103], v[178:181], v[218:221], v[100:103]
	v_mfma_f32_16x16x32_bf16 v[96:99], v[186:189], v[218:221], v[96:99]
	v_mfma_f32_16x16x32_bf16 v[124:127], v[182:185], v[198:201], v[124:127]
	v_mfma_f32_16x16x32_bf16 v[120:123], v[190:193], v[198:201], v[120:123]
	v_mfma_f32_16x16x32_bf16 v[116:119], v[182:185], v[206:209], v[116:119]
	v_mfma_f32_16x16x32_bf16 v[112:115], v[190:193], v[206:209], v[112:115]
	v_mfma_f32_16x16x32_bf16 v[108:111], v[182:185], v[214:217], v[108:111]
	v_mfma_f32_16x16x32_bf16 v[104:107], v[190:193], v[214:217], v[104:107]
	v_mfma_f32_16x16x32_bf16 v[100:103], v[182:185], v[222:225], v[100:103]
	v_mfma_f32_16x16x32_bf16 v[96:99], v[190:193], v[222:225], v[96:99]
	s_setprio 0
	s_barrier
	v_readfirstlane_b32 s25, v157
	v_add_u32_e32 v177, 0x2000, v157
	v_lshl_add_u64 v[250:251], v[246:247], 0, s[12:13]
	s_mov_b32 m0, s25
	v_readfirstlane_b32 s25, v177
	ds_read_b128 v[226:229], v155
	ds_read_b128 v[230:233], v155 offset:1024
	ds_read_b128 v[234:237], v155 offset:2048
	ds_read_b128 v[238:241], v155 offset:3072
	global_load_lds_dwordx4 v[250:251], off
	v_lshl_add_u64 v[250:251], v[248:249], 0, s[12:13]
	s_mov_b32 m0, s25
	s_nop 0
	global_load_lds_dwordx4 v[250:251], off
	s_barrier
	s_waitcnt lgkmcnt(0)
	s_setprio 1
	v_mfma_f32_16x16x32_bf16 v[92:95], v[226:229], v[194:197], v[92:95]
	v_mfma_f32_16x16x32_bf16 v[88:91], v[234:237], v[194:197], v[88:91]
	v_mfma_f32_16x16x32_bf16 v[84:87], v[226:229], v[202:205], v[84:87]
	v_mfma_f32_16x16x32_bf16 v[80:83], v[234:237], v[202:205], v[80:83]
	v_mfma_f32_16x16x32_bf16 v[76:79], v[226:229], v[210:213], v[76:79]
	v_mfma_f32_16x16x32_bf16 v[72:75], v[234:237], v[210:213], v[72:75]
	v_mfma_f32_16x16x32_bf16 v[68:71], v[226:229], v[218:221], v[68:71]
	v_mfma_f32_16x16x32_bf16 v[64:67], v[234:237], v[218:221], v[64:67]
	v_mfma_f32_16x16x32_bf16 v[92:95], v[230:233], v[198:201], v[92:95]
	v_mfma_f32_16x16x32_bf16 v[88:91], v[238:241], v[198:201], v[88:91]
	v_mfma_f32_16x16x32_bf16 v[84:87], v[230:233], v[206:209], v[84:87]
	v_mfma_f32_16x16x32_bf16 v[80:83], v[238:241], v[206:209], v[80:83]
	v_mfma_f32_16x16x32_bf16 v[76:79], v[230:233], v[214:217], v[76:79]
	v_mfma_f32_16x16x32_bf16 v[72:75], v[238:241], v[214:217], v[72:75]
	v_mfma_f32_16x16x32_bf16 v[68:71], v[230:233], v[222:225], v[68:71]
	v_mfma_f32_16x16x32_bf16 v[64:67], v[238:241], v[222:225], v[64:67]
	s_setprio 0
	v_readfirstlane_b32 s25, v158
	v_lshl_add_u64 v[242:243], v[242:243], 0, s[14:15]
	s_mov_b32 m0, s25
	v_readfirstlane_b32 s25, v159
	s_barrier
; #define STAGE(P,BASE,LD,br,kt) do{long _g=(long)(br)*(LD)+(long)(kt)*BK; \
;     _Pragma("unroll") for(int _i=0;_i<2;++_i){int _b=tid*16+_i*8192;int _r,_c;stage_rc(_b,_r,_c); \
;       __builtin_amdgcn_global_load_lds((const unsigned*)((BASE)+_g+(long)_r*(LD)+_c), \
;         (unsigned*)((char*)(P)+_b),16,0,0);}}while(0)
; #define STAGE(P,BASE,LD,br,kt) do{long _g=(long)(br)*(LD)+(long)(kt)*BK; \
;     _Pragma("unroll") for(int _i=0;_i<2;++_i){int _b=tid*16+_i*8192;int _r,_c;stage_rc(_b,_r,_c); \
;       __builtin_amdgcn_global_load_lds((const unsigned*)((BASE)+_g+(long)_r*(LD)+_c), \
;         (unsigned*)((char*)(P)+_b),16,0,0);}}while(0)
; #define LDA(dst,b,h) _Pragma("unroll") for(int m=0;m<4;++m) _Pragma("unroll") for(int k=0;k<2;++k) \
;     dst[m][k]=*reinterpret_cast<const bf16x8*>((char*)SA(b,h)+lds_byte(wr*64+m*16+fr,k*32+fq*8))
; #define LDB(dst,b,h) _Pragma("unroll") for(int n=0;n<2;++n) _Pragma("unroll") for(int k=0;k<2;++k) \
;     dst[n][k]=*reinterpret_cast<const bf16x8*>((char*)SB(b,h)+lds_byte(wc*32+n*16+fr,k*32+fq*8))
; #define MMA(ai,bj,At_,Bt_) do{__builtin_amdgcn_s_setprio(1); \
;     _Pragma("unroll") for(int m=0;m<4;++m) _Pragma("unroll") for(int n=0;n<2;++n) _Pragma("unroll") for(int k=0;k<2;++k) \
;       acc[ai][bj][m][n]=__builtin_amdgcn_mfma_f32_16x16x32_bf16(Bt_[n][k],At_[m][k],acc[ai][bj][m][n],0,0,0); \
;     __builtin_amdgcn_s_setprio(0);}while(0)
; #define WAIT_V(n) asm volatile("s_waitcnt vmcnt(" #n ")":::"memory")
; #define WAIT_L(n) asm volatile("s_waitcnt lgkmcnt(" #n ")":::"memory")
; #define BAR __builtin_amdgcn_s_barrier()
; #define SCHED __builtin_amdgcn_sched_barrier(0)
; DEVINL void gemm8_mainloop(const u16* A, long lda, const u16* Bt, long ldb, int K, int brow, int bcol, f32x4 (&acc)[2][2][4][2], char* smem, int tid) {
;     ...
;     WAIT_V(6); BAR; MMA(1,1,At,B1); BAR;
;     LDB(B0,1,0); SCHED; LDA(At,1,0); STAGE(SA(0,1),A,lda,brow+HALF,t+2);
;     WAIT_L(8); BAR; WAIT_L(0); MMA(0,0,At,B0); BAR; SCHED;
;     LDB(B1,1,1); STAGE(SB(1,0),Bt,ldb,bcol,t+3);
;     BAR; WAIT_L(0); MMA(0,1,At,B1); BAR;
;     LDA(At,1,1); STAGE(SA(1,0),A,lda,brow,t+3);
;     BAR; WAIT_L(0); MMA(1,0,At,B0); BAR; SCHED;
;     STAGE(SB(1,1),Bt,ldb,bcol+HALF,t+3);
;     WAIT_V(6); BAR; MMA(1,1,At,B1); BAR;
;   }
;   { LDB(B0,0,0); LDA(At,0,0); STAGE(SA(1,1),A,lda,brow+HALF,nt-1);
;     BAR; WAIT_L(0); MMA(0,0,At,B0); BAR;
	ds_read_b128 v[194:197], v153 offset:49152
	ds_read_b128 v[198:201], v153 offset:50176
	ds_read_b128 v[202:205], v171 offset:49152
	ds_read_b128 v[206:209], v171 offset:50176
	ds_read_b128 v[210:213], v172 offset:49152
	ds_read_b128 v[214:217], v172 offset:50176
	ds_read_b128 v[218:221], v173 offset:49152
	ds_read_b128 v[222:225], v173 offset:50176
	global_load_lds_dwordx4 v[242:243], off
	v_lshl_add_u64 v[242:243], v[244:245], 0, s[14:15]
	s_mov_b32 m0, s25
	s_nop 0
	global_load_lds_dwordx4 v[242:243], off
	s_barrier
	s_waitcnt lgkmcnt(0)
	s_setprio 1
	v_mfma_f32_16x16x32_bf16 v[60:63], v[178:181], v[194:197], v[60:63]
	v_mfma_f32_16x16x32_bf16 v[56:59], v[186:189], v[194:197], v[56:59]
	v_mfma_f32_16x16x32_bf16 v[52:55], v[178:181], v[202:205], v[52:55]
	v_mfma_f32_16x16x32_bf16 v[48:51], v[186:189], v[202:205], v[48:51]
	v_mfma_f32_16x16x32_bf16 v[44:47], v[178:181], v[210:213], v[44:47]
	v_mfma_f32_16x16x32_bf16 v[40:43], v[186:189], v[210:213], v[40:43]
	v_mfma_f32_16x16x32_bf16 v[36:39], v[178:181], v[218:221], v[36:39]
	v_mfma_f32_16x16x32_bf16 v[32:35], v[186:189], v[218:221], v[32:35]
	v_mfma_f32_16x16x32_bf16 v[60:63], v[182:185], v[198:201], v[60:63]
	v_mfma_f32_16x16x32_bf16 v[56:59], v[190:193], v[198:201], v[56:59]
	v_mfma_f32_16x16x32_bf16 v[52:55], v[182:185], v[206:209], v[52:55]
	v_mfma_f32_16x16x32_bf16 v[48:51], v[190:193], v[206:209], v[48:51]
	v_mfma_f32_16x16x32_bf16 v[44:47], v[182:185], v[214:217], v[44:47]
	v_mfma_f32_16x16x32_bf16 v[40:43], v[190:193], v[214:217], v[40:43]
	v_mfma_f32_16x16x32_bf16 v[36:39], v[182:185], v[222:225], v[36:39]
	v_mfma_f32_16x16x32_bf16 v[32:35], v[190:193], v[222:225], v[32:35]
	s_setprio 0
	s_barrier
	v_readfirstlane_b32 s25, v161
	v_add_u32_e32 v177, 0x2000, v161
	v_lshl_add_u64 v[178:179], v[246:247], 0, s[16:17]
	s_mov_b32 m0, s25
	v_readfirstlane_b32 s25, v177
	global_load_lds_dwordx4 v[178:179], off
	v_lshl_add_u64 v[178:179], v[248:249], 0, s[16:17]
	s_mov_b32 m0, s25
	s_nop 0
	global_load_lds_dwordx4 v[178:179], off
	s_waitcnt vmcnt(6)
	s_barrier
	s_setprio 1
	v_mfma_f32_16x16x32_bf16 v[28:31], v[226:229], v[194:197], v[28:31]
	v_mfma_f32_16x16x32_bf16 v[24:27], v[234:237], v[194:197], v[24:27]
	v_mfma_f32_16x16x32_bf16 v[20:23], v[226:229], v[202:205], v[20:23]
	v_mfma_f32_16x16x32_bf16 v[16:19], v[234:237], v[202:205], v[16:19]
	v_mfma_f32_16x16x32_bf16 v[12:15], v[226:229], v[210:213], v[12:15]
	v_mfma_f32_16x16x32_bf16 v[8:11], v[234:237], v[210:213], v[8:11]
	v_mfma_f32_16x16x32_bf16 v[4:7], v[226:229], v[218:221], v[4:7]
	v_mfma_f32_16x16x32_bf16 v[0:3], v[234:237], v[218:221], v[0:3]
	v_mfma_f32_16x16x32_bf16 v[28:31], v[230:233], v[198:201], v[28:31]
	v_mfma_f32_16x16x32_bf16 v[24:27], v[238:241], v[198:201], v[24:27]
	v_mfma_f32_16x16x32_bf16 v[20:23], v[230:233], v[206:209], v[20:23]
	v_mfma_f32_16x16x32_bf16 v[16:19], v[238:241], v[206:209], v[16:19]
	v_mfma_f32_16x16x32_bf16 v[12:15], v[230:233], v[214:217], v[12:15]
	v_mfma_f32_16x16x32_bf16 v[8:11], v[238:241], v[214:217], v[8:11]
	v_mfma_f32_16x16x32_bf16 v[4:7], v[230:233], v[222:225], v[4:7]
	v_mfma_f32_16x16x32_bf16 v[0:3], v[238:241], v[222:225], v[0:3]
	s_setprio 0
	s_add_i32 s24, s24, 2
	v_lshl_add_u64 v[142:143], v[142:143], 0, s[18:19]
	v_lshl_add_u64 v[144:145], v[144:145], 0, s[18:19]
	v_lshl_add_u64 v[146:147], v[146:147], 0, s[18:19]
	s_cmpk_lt_u32 s24, 0x7c
	v_lshl_add_u64 v[148:149], v[148:149], 0, s[18:19]
	s_cbranch_scc1 .LBB0_1987
	s_barrier
	s_or_b32 s24, s22, 0x80
	s_ashr_i32 s25, s24, 31
	s_lshl_b64 s[24:25], s[24:25], 14
	s_add_u32 s23, s62, s24
	s_addc_u32 s25, s63, s25
	s_add_u32 s24, s23, 0x3f80
	s_addc_u32 s25, s25, 0
	v_lshl_add_u64 v[158:159], v[134:135], 1, s[24:25]
	v_readfirstlane_b32 s23, v174
	v_lshl_add_u64 v[138:139], v[138:139], 1, v[158:159]
	s_mov_b32 m0, s23
	ds_read_b128 v[142:145], v163
	ds_read_b128 v[146:149], v163 offset:1024
	ds_read_b128 v[178:181], v163 offset:2048
	ds_read_b128 v[182:185], v163 offset:3072
	ds_read_b128 v[186:189], v153
	ds_read_b128 v[190:193], v153 offset:1024
	ds_read_b128 v[194:197], v171
	ds_read_b128 v[198:201], v171 offset:1024
	ds_read_b128 v[202:205], v172
	ds_read_b128 v[206:209], v172 offset:1024
	ds_read_b128 v[210:213], v173
	ds_read_b128 v[214:217], v173 offset:1024
	global_load_lds_dwordx4 v[138:139], off
	v_lshl_add_u64 v[138:139], v[136:137], 1, s[24:25]
	v_readfirstlane_b32 s23, v175
	v_lshl_add_u64 v[138:139], v[140:141], 1, v[138:139]
	s_mov_b32 m0, s23
	s_nop 0
	global_load_lds_dwordx4 v[138:139], off
	s_barrier
	s_waitcnt lgkmcnt(0)
	s_setprio 1
	v_mfma_f32_16x16x32_bf16 v[124:127], v[142:145], v[186:189], v[124:127]
	v_mfma_f32_16x16x32_bf16 v[120:123], v[178:181], v[186:189], v[120:123]
	v_mfma_f32_16x16x32_bf16 v[116:119], v[142:145], v[194:197], v[116:119]
	v_mfma_f32_16x16x32_bf16 v[112:115], v[178:181], v[194:197], v[112:115]
	v_mfma_f32_16x16x32_bf16 v[100:103], v[142:145], v[210:213], v[100:103]
	v_mfma_f32_16x16x32_bf16 v[96:99], v[178:181], v[210:213], v[96:99]
	v_mfma_f32_16x16x32_bf16 v[124:127], v[146:149], v[190:193], v[124:127]
	v_mfma_f32_16x16x32_bf16 v[120:123], v[182:185], v[190:193], v[120:123]
	v_mfma_f32_16x16x32_bf16 v[116:119], v[146:149], v[198:201], v[116:119]
	v_mfma_f32_16x16x32_bf16 v[112:115], v[182:185], v[198:201], v[112:115]
	v_mfma_f32_16x16x32_bf16 v[108:111], v[142:145], v[202:205], v[108:111]
	v_mfma_f32_16x16x32_bf16 v[104:107], v[178:181], v[202:205], v[104:107]
	v_mfma_f32_16x16x32_bf16 v[100:103], v[146:149], v[214:217], v[100:103]
	v_mfma_f32_16x16x32_bf16 v[96:99], v[182:185], v[214:217], v[96:99]
	v_mfma_f32_16x16x32_bf16 v[138:141], v[146:149], v[206:209], v[108:111]
	v_mfma_f32_16x16x32_bf16 v[218:221], v[182:185], v[206:209], v[104:107]
	s_setprio 0
	s_barrier
; #define LDA(dst,b,h) _Pragma("unroll") for(int m=0;m<4;++m) _Pragma("unroll") for(int k=0;k<2;++k) \
;     dst[m][k]=*reinterpret_cast<const bf16x8*>((char*)SA(b,h)+lds_byte(wr*64+m*16+fr,k*32+fq*8))
; #define LDB(dst,b,h) _Pragma("unroll") for(int n=0;n<2;++n) _Pragma("unroll") for(int k=0;k<2;++k) \
;     dst[n][k]=*reinterpret_cast<const bf16x8*>((char*)SB(b,h)+lds_byte(wc*32+n*16+fr,k*32+fq*8))
; #define MMA(ai,bj,At_,Bt_) do{__builtin_amdgcn_s_setprio(1); \
;     _Pragma("unroll") for(int m=0;m<4;++m) _Pragma("unroll") for(int n=0;n<2;++n) _Pragma("unroll") for(int k=0;k<2;++k) \
;       acc[ai][bj][m][n]=__builtin_amdgcn_mfma_f32_16x16x32_bf16(Bt_[n][k],At_[m][k],acc[ai][bj][m][n],0,0,0); \
;     __builtin_amdgcn_s_setprio(0);}while(0)
; #define WAIT_V(n) asm volatile("s_waitcnt vmcnt(" #n ")":::"memory")
; #define WAIT_L(n) asm volatile("s_waitcnt lgkmcnt(" #n ")":::"memory")
; #define BAR __builtin_amdgcn_s_barrier()
; DEVINL void gemm8_mainloop(const u16* A, long lda, const u16* Bt, long ldb, int K, int brow, int bcol, f32x4 (&acc)[2][2][4][2], char* smem, int tid) {
;     ...
;     BAR; WAIT_L(0); MMA(0,0,At,B0); BAR;
;     LDB(B1,0,1); BAR; WAIT_L(0); MMA(0,1,At,B1); BAR;
;     LDA(At,0,1); WAIT_V(4); BAR; WAIT_L(0); MMA(1,0,At,B0); MMA(1,1,At,B1); BAR; }
;   { LDB(B0,1,0); LDA(At,1,0); WAIT_V(2); BAR; WAIT_L(0); MMA(0,0,At,B0); BAR;
;     LDB(B1,1,1); WAIT_V(0); BAR; WAIT_L(0); MMA(0,1,At,B1); BAR;
	s_nop 1
	ds_read_b128 v[104:107], v160
	ds_read_b128 v[108:111], v160 offset:1024
	ds_read_b128 v[222:225], v160 offset:2048
	ds_read_b128 v[158:161], v160 offset:3072
	s_barrier
	s_waitcnt lgkmcnt(0)
	s_setprio 1
	v_mfma_f32_16x16x32_bf16 v[84:87], v[104:107], v[194:197], v[84:87]
	v_mfma_f32_16x16x32_bf16 v[80:83], v[222:225], v[194:197], v[80:83]
	v_mfma_f32_16x16x32_bf16 v[68:71], v[104:107], v[210:213], v[68:71]
	v_mfma_f32_16x16x32_bf16 v[92:95], v[104:107], v[186:189], v[92:95]
	v_mfma_f32_16x16x32_bf16 v[88:91], v[222:225], v[186:189], v[88:91]
	v_mfma_f32_16x16x32_bf16 v[84:87], v[108:111], v[198:201], v[84:87]
	v_mfma_f32_16x16x32_bf16 v[80:83], v[158:161], v[198:201], v[80:83]
	v_mfma_f32_16x16x32_bf16 v[76:79], v[104:107], v[202:205], v[76:79]
	v_mfma_f32_16x16x32_bf16 v[72:75], v[222:225], v[202:205], v[72:75]
	v_mfma_f32_16x16x32_bf16 v[68:71], v[108:111], v[214:217], v[68:71]
	v_mfma_f32_16x16x32_bf16 v[64:67], v[222:225], v[210:213], v[64:67]
	v_mfma_f32_16x16x32_bf16 v[226:229], v[108:111], v[190:193], v[92:95]
	v_mfma_f32_16x16x32_bf16 v[186:189], v[158:161], v[190:193], v[88:91]
	v_mfma_f32_16x16x32_bf16 v[190:193], v[108:111], v[206:209], v[76:79]
	v_mfma_f32_16x16x32_bf16 v[194:197], v[158:161], v[206:209], v[72:75]
	v_mfma_f32_16x16x32_bf16 v[198:201], v[158:161], v[214:217], v[64:67]
	s_setprio 0
	s_barrier
	s_nop 0
	ds_read_b128 v[64:67], v153 offset:16384
	ds_read_b128 v[72:75], v153 offset:17408
	ds_read_b128 v[76:79], v171 offset:16384
	ds_read_b128 v[88:91], v171 offset:17408
	ds_read_b128 v[92:95], v172 offset:16384
	ds_read_b128 v[202:205], v172 offset:17408
	ds_read_b128 v[206:209], v173 offset:16384
	ds_read_b128 v[210:213], v173 offset:17408
	s_waitcnt vmcnt(4)
	s_barrier
	s_waitcnt lgkmcnt(0)
	s_setprio 1
	v_mfma_f32_16x16x32_bf16 v[60:63], v[142:145], v[64:67], v[60:63]
	v_mfma_f32_16x16x32_bf16 v[56:59], v[178:181], v[64:67], v[56:59]
	v_mfma_f32_16x16x32_bf16 v[52:55], v[142:145], v[76:79], v[52:55]
	v_mfma_f32_16x16x32_bf16 v[48:51], v[178:181], v[76:79], v[48:51]
	v_mfma_f32_16x16x32_bf16 v[36:39], v[142:145], v[206:209], v[36:39]
	v_mfma_f32_16x16x32_bf16 v[32:35], v[178:181], v[206:209], v[32:35]
	v_mfma_f32_16x16x32_bf16 v[60:63], v[146:149], v[72:75], v[60:63]
	v_mfma_f32_16x16x32_bf16 v[56:59], v[182:185], v[72:75], v[56:59]
	v_mfma_f32_16x16x32_bf16 v[52:55], v[146:149], v[88:91], v[52:55]
	v_mfma_f32_16x16x32_bf16 v[48:51], v[182:185], v[88:91], v[48:51]
	v_mfma_f32_16x16x32_bf16 v[44:47], v[142:145], v[92:95], v[44:47]
	v_mfma_f32_16x16x32_bf16 v[40:43], v[178:181], v[92:95], v[40:43]
	v_mfma_f32_16x16x32_bf16 v[36:39], v[146:149], v[210:213], v[36:39]
	v_mfma_f32_16x16x32_bf16 v[32:35], v[182:185], v[210:213], v[32:35]
	v_mfma_f32_16x16x32_bf16 v[214:217], v[146:149], v[202:205], v[44:47]
	v_mfma_f32_16x16x32_bf16 v[230:233], v[182:185], v[202:205], v[40:43]
	s_setprio 0
	s_setprio 1
	v_mfma_f32_16x16x32_bf16 v[20:23], v[104:107], v[76:79], v[20:23]
	v_mfma_f32_16x16x32_bf16 v[16:19], v[222:225], v[76:79], v[16:19]
	v_mfma_f32_16x16x32_bf16 v[4:7], v[104:107], v[206:209], v[4:7]
	v_mfma_f32_16x16x32_bf16 v[28:31], v[104:107], v[64:67], v[28:31]
	v_mfma_f32_16x16x32_bf16 v[24:27], v[222:225], v[64:67], v[24:27]
	v_mfma_f32_16x16x32_bf16 v[20:23], v[108:111], v[88:91], v[20:23]
	v_mfma_f32_16x16x32_bf16 v[16:19], v[158:161], v[88:91], v[16:19]
	v_mfma_f32_16x16x32_bf16 v[12:15], v[104:107], v[92:95], v[12:15]
	v_mfma_f32_16x16x32_bf16 v[8:11], v[222:225], v[92:95], v[8:11]
	v_mfma_f32_16x16x32_bf16 v[4:7], v[108:111], v[210:213], v[4:7]
	v_mfma_f32_16x16x32_bf16 v[0:3], v[222:225], v[206:209], v[0:3]
	v_mfma_f32_16x16x32_bf16 v[142:145], v[108:111], v[72:75], v[28:31]
	v_mfma_f32_16x16x32_bf16 v[146:149], v[158:161], v[72:75], v[24:27]
	v_mfma_f32_16x16x32_bf16 v[178:181], v[108:111], v[202:205], v[12:15]
	v_mfma_f32_16x16x32_bf16 v[182:185], v[158:161], v[202:205], v[8:11]
	v_mfma_f32_16x16x32_bf16 v[158:161], v[158:161], v[210:213], v[0:3]
	s_setprio 0
	s_barrier
	s_nop 0
	ds_read_b128 v[0:3], v156
	ds_read_b128 v[8:11], v156 offset:1024
	ds_read_b128 v[202:205], v156 offset:2048
	ds_read_b128 v[206:209], v156 offset:3072
	ds_read_b128 v[12:15], v153 offset:32768
	ds_read_b128 v[24:27], v153 offset:33792
	ds_read_b128 v[28:31], v171 offset:32768
	ds_read_b128 v[40:43], v171 offset:33792
	ds_read_b128 v[44:47], v172 offset:32768
	ds_read_b128 v[64:67], v172 offset:33792
	ds_read_b128 v[210:213], v173 offset:32768
	ds_read_b128 v[222:225], v173 offset:33792
	s_waitcnt vmcnt(2)
	s_barrier
; #define LDA(dst,b,h) _Pragma("unroll") for(int m=0;m<4;++m) _Pragma("unroll") for(int k=0;k<2;++k) \
;     dst[m][k]=*reinterpret_cast<const bf16x8*>((char*)SA(b,h)+lds_byte(wr*64+m*16+fr,k*32+fq*8))
; #define LDB(dst,b,h) _Pragma("unroll") for(int n=0;n<2;++n) _Pragma("unroll") for(int k=0;k<2;++k) \
;     dst[n][k]=*reinterpret_cast<const bf16x8*>((char*)SB(b,h)+lds_byte(wc*32+n*16+fr,k*32+fq*8))
; #define MMA(ai,bj,At_,Bt_) do{__builtin_amdgcn_s_setprio(1); \
;     _Pragma("unroll") for(int m=0;m<4;++m) _Pragma("unroll") for(int n=0;n<2;++n) _Pragma("unroll") for(int k=0;k<2;++k) \
;       acc[ai][bj][m][n]=__builtin_amdgcn_mfma_f32_16x16x32_bf16(Bt_[n][k],At_[m][k],acc[ai][bj][m][n],0,0,0); \
;     __builtin_amdgcn_s_setprio(0);}while(0)
; #define WAIT_V(n) asm volatile("s_waitcnt vmcnt(" #n ")":::"memory")
; #define WAIT_L(n) asm volatile("s_waitcnt lgkmcnt(" #n ")":::"memory")
; #define BAR __builtin_amdgcn_s_barrier()
; DEVINL void gemm8_mainloop(const u16* A, long lda, const u16* Bt, long ldb, int K, int brow, int bcol, f32x4 (&acc)[2][2][4][2], char* smem, int tid) {
;     ...
;     LDA(At,0,1); WAIT_V(4); BAR; WAIT_L(0); MMA(1,0,At,B0); MMA(1,1,At,B1); BAR; }
;   { LDB(B0,1,0); LDA(At,1,0); WAIT_V(2); BAR; WAIT_L(0); MMA(0,0,At,B0); BAR;
;     LDB(B1,1,1); WAIT_V(0); BAR; WAIT_L(0); MMA(0,1,At,B1); BAR;
;     LDA(At,1,1); BAR; WAIT_L(0); MMA(1,0,At,B0); MMA(1,1,At,B1); BAR; }
;   if(wr==0)BAR;
;   __syncthreads();
	s_waitcnt lgkmcnt(0)
	s_setprio 1
	v_mfma_f32_16x16x32_bf16 v[72:75], v[0:3], v[12:15], v[124:127]
	v_mfma_f32_16x16x32_bf16 v[124:127], v[8:11], v[24:27], v[72:75]
	v_mfma_f32_16x16x32_bf16 v[72:75], v[202:205], v[12:15], v[120:123]
	v_mfma_f32_16x16x32_bf16 v[120:123], v[206:209], v[24:27], v[72:75]
	v_mfma_f32_16x16x32_bf16 v[72:75], v[0:3], v[28:31], v[116:119]
	v_mfma_f32_16x16x32_bf16 v[108:111], v[8:11], v[40:43], v[72:75]
	v_mfma_f32_16x16x32_bf16 v[72:75], v[202:205], v[28:31], v[112:115]
	v_mfma_f32_16x16x32_bf16 v[104:107], v[206:209], v[40:43], v[72:75]
	v_mfma_f32_16x16x32_bf16 v[72:75], v[0:3], v[44:47], v[138:141]
	v_mfma_f32_16x16x32_bf16 v[92:95], v[8:11], v[64:67], v[72:75]
	v_mfma_f32_16x16x32_bf16 v[72:75], v[202:205], v[44:47], v[218:221]
	v_mfma_f32_16x16x32_bf16 v[88:91], v[206:209], v[64:67], v[72:75]
	v_mfma_f32_16x16x32_bf16 v[72:75], v[0:3], v[210:213], v[100:103]
	v_mfma_f32_16x16x32_bf16 v[76:79], v[8:11], v[222:225], v[72:75]
	v_mfma_f32_16x16x32_bf16 v[72:75], v[202:205], v[210:213], v[96:99]
	v_mfma_f32_16x16x32_bf16 v[72:75], v[206:209], v[222:225], v[72:75]
	s_setprio 0
	s_barrier
	ds_read_b128 v[138:141], v155
	ds_read_b128 v[218:221], v155 offset:1024
	ds_read_b128 v[234:237], v155 offset:2048
	ds_read_b128 v[154:157], v155 offset:3072
	s_waitcnt vmcnt(0)
	s_barrier
	s_waitcnt lgkmcnt(0)
	s_setprio 1
	v_mfma_f32_16x16x32_bf16 v[96:99], v[138:141], v[12:15], v[226:229]
	v_mfma_f32_16x16x32_bf16 v[12:15], v[234:237], v[12:15], v[186:189]
	v_mfma_f32_16x16x32_bf16 v[116:119], v[154:157], v[24:27], v[12:15]
	v_mfma_f32_16x16x32_bf16 v[12:15], v[138:141], v[28:31], v[84:87]
	v_mfma_f32_16x16x32_bf16 v[112:115], v[218:221], v[24:27], v[96:99]
	v_mfma_f32_16x16x32_bf16 v[96:99], v[218:221], v[40:43], v[12:15]
	v_mfma_f32_16x16x32_bf16 v[12:15], v[234:237], v[28:31], v[80:83]
	v_mfma_f32_16x16x32_bf16 v[100:103], v[154:157], v[40:43], v[12:15]
	v_mfma_f32_16x16x32_bf16 v[12:15], v[138:141], v[44:47], v[190:193]
	v_mfma_f32_16x16x32_bf16 v[80:83], v[218:221], v[64:67], v[12:15]
	v_mfma_f32_16x16x32_bf16 v[12:15], v[234:237], v[44:47], v[194:197]
	v_mfma_f32_16x16x32_bf16 v[84:87], v[154:157], v[64:67], v[12:15]
	v_mfma_f32_16x16x32_bf16 v[12:15], v[138:141], v[210:213], v[68:71]
	v_mfma_f32_16x16x32_bf16 v[64:67], v[218:221], v[222:225], v[12:15]
	v_mfma_f32_16x16x32_bf16 v[12:15], v[234:237], v[210:213], v[198:201]
	v_mfma_f32_16x16x32_bf16 v[68:71], v[154:157], v[222:225], v[12:15]
	s_setprio 0
	s_barrier
	ds_read_b128 v[186:189], v153 offset:49152
	ds_read_b128 v[190:193], v153 offset:50176
	ds_read_b128 v[194:197], v171 offset:49152
	ds_read_b128 v[198:201], v171 offset:50176
	ds_read_b128 v[210:213], v172 offset:49152
	ds_read_b128 v[222:225], v172 offset:50176
	ds_read_b128 v[226:229], v173 offset:49152
	ds_read_b128 v[172:175], v173 offset:50176
	s_barrier
	s_waitcnt lgkmcnt(0)
	s_setprio 1
	v_mfma_f32_16x16x32_bf16 v[12:15], v[0:3], v[186:189], v[60:63]
	v_mfma_f32_16x16x32_bf16 v[60:63], v[8:11], v[190:193], v[12:15]
	v_mfma_f32_16x16x32_bf16 v[12:15], v[202:205], v[186:189], v[56:59]
	v_mfma_f32_16x16x32_bf16 v[56:59], v[206:209], v[190:193], v[12:15]
	v_mfma_f32_16x16x32_bf16 v[12:15], v[0:3], v[194:197], v[52:55]
	v_mfma_f32_16x16x32_bf16 v[44:47], v[8:11], v[198:201], v[12:15]
	v_mfma_f32_16x16x32_bf16 v[12:15], v[202:205], v[194:197], v[48:51]
	v_mfma_f32_16x16x32_bf16 v[40:43], v[206:209], v[198:201], v[12:15]
	v_mfma_f32_16x16x32_bf16 v[12:15], v[0:3], v[210:213], v[214:217]
	v_mfma_f32_16x16x32_bf16 v[28:31], v[8:11], v[222:225], v[12:15]
	v_mfma_f32_16x16x32_bf16 v[12:15], v[202:205], v[210:213], v[230:233]
	v_mfma_f32_16x16x32_bf16 v[0:3], v[0:3], v[226:229], v[36:39]
	v_mfma_f32_16x16x32_bf16 v[24:27], v[206:209], v[222:225], v[12:15]
	v_mfma_f32_16x16x32_bf16 v[12:15], v[8:11], v[172:175], v[0:3]
	v_mfma_f32_16x16x32_bf16 v[0:3], v[202:205], v[226:229], v[32:35]
	v_mfma_f32_16x16x32_bf16 v[8:11], v[206:209], v[172:175], v[0:3]
	s_setprio 0
	s_setprio 1
	v_mfma_f32_16x16x32_bf16 v[0:3], v[138:141], v[186:189], v[142:145]
	v_mfma_f32_16x16x32_bf16 v[48:51], v[218:221], v[190:193], v[0:3]
	v_mfma_f32_16x16x32_bf16 v[0:3], v[234:237], v[186:189], v[146:149]
	v_mfma_f32_16x16x32_bf16 v[52:55], v[154:157], v[190:193], v[0:3]
	v_mfma_f32_16x16x32_bf16 v[0:3], v[138:141], v[194:197], v[20:23]
	v_mfma_f32_16x16x32_bf16 v[32:35], v[218:221], v[198:201], v[0:3]
	v_mfma_f32_16x16x32_bf16 v[0:3], v[234:237], v[194:197], v[16:19]
	v_mfma_f32_16x16x32_bf16 v[36:39], v[154:157], v[198:201], v[0:3]
	v_mfma_f32_16x16x32_bf16 v[0:3], v[138:141], v[210:213], v[178:181]
	v_mfma_f32_16x16x32_bf16 v[16:19], v[218:221], v[222:225], v[0:3]
	v_mfma_f32_16x16x32_bf16 v[0:3], v[234:237], v[210:213], v[182:185]
	v_mfma_f32_16x16x32_bf16 v[20:23], v[154:157], v[222:225], v[0:3]
	v_mfma_f32_16x16x32_bf16 v[0:3], v[138:141], v[226:229], v[4:7]
	v_mfma_f32_16x16x32_bf16 v[4:7], v[234:237], v[226:229], v[158:161]
	v_mfma_f32_16x16x32_bf16 v[0:3], v[218:221], v[172:175], v[0:3]
	v_mfma_f32_16x16x32_bf16 v[4:7], v[154:157], v[172:175], v[4:7]
	s_setprio 0
	s_cmpk_gt_u32 s27, 0xff
	s_barrier
	s_cbranch_scc1 .LBB0_1990
	s_barrier
